# static priority raise (s_setprio 1) for waves 4-7 inside the hand-written GEMM cores (C1, C2, D, phase A part 1)
# speedup vs baseline: 1.0016x; 1.0016x over previous
.La1_mine:
	v_mov_b32_e32 v238, 0x200f0
	ds_read_b64 v[236:237], v238
	s_waitcnt lgkmcnt(0)
	v_readfirstlane_b32 s20, v236
	v_readfirstlane_b32 s21, v237
	s_barrier
	v_and_b32_e32 v236, 63, v0
	v_lshrrev_b32_e32 v237, 6, v0
	v_lshrrev_b32_e32 v238, 3, v236
	v_lshrrev_b32_e32 v239, 4, v236
	s_nop 0
	v_readfirstlane_b32 s0, v237
	v_add_u32_e32 v200, 0, v239
	v_xor_b32_e32 v200, v200, v236
	v_and_b32_e32 v200, 7, v200
	v_lshlrev_b32_e32 v200, 4, v200
	v_lshl_add_u32 v130, v237, 5, v238
	v_add_u32_e32 v130, 0, v130
	v_mul_u32_u24_e32 v130, 0x800, v130
	v_add_u32_e32 v200, v200, v130
	v_add_u32_e32 v201, 4, v239
	v_xor_b32_e32 v201, v201, v236
	v_and_b32_e32 v201, 7, v201
	v_lshlrev_b32_e32 v201, 4, v201
	v_lshl_add_u32 v130, v237, 5, v238
	v_add_u32_e32 v130, 8, v130
	v_mul_u32_u24_e32 v130, 0x800, v130
	v_add_u32_e32 v201, v201, v130
	v_add_u32_e32 v202, 8, v239
	v_xor_b32_e32 v202, v202, v236
	v_and_b32_e32 v202, 7, v202
	v_lshlrev_b32_e32 v202, 4, v202
	v_lshl_add_u32 v130, v237, 5, v238
	v_add_u32_e32 v130, 16, v130
	v_mul_u32_u24_e32 v130, 0x800, v130
	v_add_u32_e32 v202, v202, v130
	v_add_u32_e32 v203, 12, v239
	v_xor_b32_e32 v203, v203, v236
	v_and_b32_e32 v203, 7, v203
	v_lshlrev_b32_e32 v203, 4, v203
	v_lshl_add_u32 v130, v237, 5, v238
	v_add_u32_e32 v130, 24, v130
	v_mul_u32_u24_e32 v130, 0x800, v130
	v_add_u32_e32 v203, v203, v130
	v_add_u32_e32 v204, 0, v239
	v_xor_b32_e32 v204, v204, v236
	v_and_b32_e32 v204, 7, v204
	v_lshlrev_b32_e32 v204, 4, v204
	v_lshl_add_u32 v130, v237, 4, v238
	v_add_u32_e32 v130, 0, v130
	v_mul_u32_u24_e32 v130, 0x800, v130
	v_add_u32_e32 v204, v204, v130
	v_add_u32_e32 v205, 4, v239
	v_xor_b32_e32 v205, v205, v236
	v_and_b32_e32 v205, 7, v205
	v_lshlrev_b32_e32 v205, 4, v205
	v_lshl_add_u32 v130, v237, 4, v238
	v_add_u32_e32 v130, 8, v130
	v_mul_u32_u24_e32 v130, 0x800, v130
	v_add_u32_e32 v205, v205, v130
	v_and_b32_e32 v238, 15, v236
	v_lshrrev_b32_e32 v130, 1, v238
	v_xor_b32_e32 v130, v130, v239
	v_lshlrev_b32_e32 v130, 4, v130
	v_lshrrev_b32_e32 v236, 1, v237
	v_lshl_add_u32 v236, v236, 6, v238
	v_lshl_add_u32 v236, v236, 7, v130
	v_and_b32_e32 v237, 1, v237
	v_lshl_add_u32 v237, v237, 6, v238
	v_lshl_add_u32 v237, v237, 7, v130
	v_add_u32_e32 v218, 0x100, v236
	v_xor_b32_e32 v225, 64, v218
	v_add_u32_e32 v230, 0x8100, v237
	v_xor_b32_e32 v233, 64, v230
	v_add_u32_e32 v219, 0xc100, v236
	v_xor_b32_e32 v228, 64, v219
	v_add_u32_e32 v231, 0x14100, v237
	v_xor_b32_e32 v234, 64, v231
	v_add_u32_e32 v224, 0x18100, v236
	v_xor_b32_e32 v229, 64, v224
	v_add_u32_e32 v232, 0x20100, v237
	v_xor_b32_e32 v235, 64, v232
	s_lshl_b32 s1, s0, 12
	s_add_u32 s8, s1, 0x100
	s_lshl_b32 s1, s0, 11
	s_add_u32 s9, s1, 0x8100
	s_cmp_lt_u32 s0, 4
	s_cbranch_scc1 .Lgprio_4
	s_setprio 1
.Lgprio_4:
	v_and_b32_e32 v238, 63, v0
	v_lshrrev_b32_e32 v239, 6, v0
	v_and_b32_e32 v1, 15, v238
	v_lshrrev_b32_e32 v238, 4, v238
	v_lshrrev_b32_e32 v130, 1, v239
	v_lshl_add_u32 v1, v130, 6, v1
	v_and_b32_e32 v239, 1, v239
	v_lshlrev_b32_e32 v236, 11, v1
	v_lshl_add_u32 v236, v239, 7, v236
	v_lshl_add_u32 v236, v238, 3, v236
	v_mul_u32_u24_e32 v237, 0x2200, v1
	v_lshl_add_u32 v237, v239, 8, v237
	v_lshl_add_u32 v237, v238, 4, v237
	s_and_b32 s1, s2, 31
	s_lshr_b32 s22, s2, 5
	s_lshl_b32 s23, s1, 19
	s_add_u32 s4, s26, s23
	s_addc_u32 s5, s27, 0
	v_readlane_b32 s6, v254, 57
	v_readlane_b32 s7, v254, 58
	s_lshl_b32 s50, s22, 1
	s_add_u32 s50, s50, 1
	s_cmp_eq_u32 s22, 4
	s_cselect_b32 s50, 0, s50
	s_lshl_b32 s51, s50, 18
	s_add_u32 s51, s51, 0x400000
	s_add_u32 s6, s6, s51
	s_addc_u32 s7, s7, 0
	s_mov_b32 s12, 0xbfb8aa3b
	s_add_u32 s52, s28, 0x4400000
	s_addc_u32 s53, s29, 0
	s_add_u32 s52, s52, s23
	s_addc_u32 s53, s53, 0
	s_sub_u32 s51, s50, 1
	s_lshl_b32 s51, s51, 8
	s_add_u32 s52, s52, s51
	s_addc_u32 s53, s53, 0
	s_cmp_eq_u32 s22, 4
	s_cbranch_scc1 .La1_p
	s_mov_b32 m0, s8
	s_nop 0
	global_load_lds_dwordx4 v200, s[4:5]
	s_add_u32 m0, s8, 0x400
	s_nop 0
	global_load_lds_dwordx4 v201, s[4:5]
	s_add_u32 m0, s8, 0x800
	s_nop 0
	global_load_lds_dwordx4 v202, s[4:5]
	s_add_u32 m0, s8, 0xc00
	s_nop 0
	global_load_lds_dwordx4 v203, s[4:5]
	s_mov_b32 m0, s9
	s_nop 0
	global_load_lds_dwordx4 v204, s[6:7]
	s_add_u32 m0, s9, 0x400
	s_nop 0
	global_load_lds_dwordx4 v205, s[6:7]
	s_add_u32 s4, s4, 0x80
	s_addc_u32 s5, s5, 0
	s_add_u32 s6, s6, 0x80
	s_addc_u32 s7, s7, 0
	s_add_u32 m0, s8, 0xc000
	s_nop 0
	global_load_lds_dwordx4 v200, s[4:5]
	s_add_u32 m0, s8, 0xc400
	s_nop 0
	global_load_lds_dwordx4 v201, s[4:5]
	s_add_u32 m0, s8, 0xc800
	s_nop 0
	global_load_lds_dwordx4 v202, s[4:5]
	s_add_u32 m0, s8, 0xcc00
	s_nop 0
	global_load_lds_dwordx4 v203, s[4:5]
	s_add_u32 m0, s9, 0xc000
	s_nop 0
	global_load_lds_dwordx4 v204, s[6:7]
	s_add_u32 m0, s9, 0xc400
	s_nop 0
	global_load_lds_dwordx4 v205, s[6:7]
	s_add_u32 s4, s4, 0x80
	s_addc_u32 s5, s5, 0
	s_add_u32 s6, s6, 0x80
	s_addc_u32 s7, s7, 0
	s_add_u32 m0, s8, 0x18000
	s_nop 0
	global_load_lds_dwordx4 v200, s[4:5]
	s_add_u32 m0, s8, 0x18400
	s_nop 0
	global_load_lds_dwordx4 v201, s[4:5]
	s_add_u32 m0, s8, 0x18800
	s_nop 0
	global_load_lds_dwordx4 v202, s[4:5]
	s_add_u32 m0, s8, 0x18c00
	s_nop 0
	global_load_lds_dwordx4 v203, s[4:5]
	s_add_u32 m0, s9, 0x18000
	s_nop 0
	global_load_lds_dwordx4 v204, s[6:7]
	s_add_u32 m0, s9, 0x18400
	s_nop 0
	global_load_lds_dwordx4 v205, s[6:7]
	s_add_u32 s4, s4, 0x80
	s_addc_u32 s5, s5, 0
	s_add_u32 s6, s6, 0x80
	s_addc_u32 s7, s7, 0
	s_waitcnt vmcnt(12)
	s_barrier
	ds_read_b128 v[136:139], v218 offset:0
	ds_read_b128 v[140:143], v218 offset:2048
	ds_read_b128 v[144:147], v218 offset:4096
	ds_read_b128 v[148:151], v218 offset:6144
	ds_read_b128 v[152:155], v230 offset:0
	ds_read_b128 v[156:159], v230 offset:2048
	ds_read_b128 v[160:163], v230 offset:4096
	ds_read_b128 v[164:167], v230 offset:6144
	s_waitcnt lgkmcnt(0)
	v_mfma_f32_16x16x32_bf16 v[2:5], v[152:155], v[136:139], 0
	ds_read_b128 v[168:171], v225 offset:0
	v_mfma_f32_16x16x32_bf16 v[6:9], v[156:159], v[136:139], 0
	ds_read_b128 v[172:175], v225 offset:2048
	v_mfma_f32_16x16x32_bf16 v[10:13], v[160:163], v[136:139], 0
	ds_read_b128 v[176:179], v225 offset:4096
	v_mfma_f32_16x16x32_bf16 v[14:17], v[164:167], v[136:139], 0
	ds_read_b128 v[180:183], v225 offset:6144
	v_mfma_f32_16x16x32_bf16 v[18:21], v[152:155], v[140:143], 0
	ds_read_b128 v[184:187], v233 offset:0
	v_mfma_f32_16x16x32_bf16 v[22:25], v[156:159], v[140:143], 0
	ds_read_b128 v[188:191], v233 offset:2048
	v_mfma_f32_16x16x32_bf16 v[26:29], v[160:163], v[140:143], 0
	ds_read_b128 v[192:195], v233 offset:4096
	v_mfma_f32_16x16x32_bf16 v[30:33], v[164:167], v[140:143], 0
	ds_read_b128 v[196:199], v233 offset:6144
	v_mfma_f32_16x16x32_bf16 v[34:37], v[152:155], v[144:147], 0
	v_mfma_f32_16x16x32_bf16 v[38:41], v[156:159], v[144:147], 0
	v_mfma_f32_16x16x32_bf16 v[42:45], v[160:163], v[144:147], 0
	v_mfma_f32_16x16x32_bf16 v[46:49], v[164:167], v[144:147], 0
	v_mfma_f32_16x16x32_bf16 v[50:53], v[152:155], v[148:151], 0
	v_mfma_f32_16x16x32_bf16 v[54:57], v[156:159], v[148:151], 0
	v_mfma_f32_16x16x32_bf16 v[58:61], v[160:163], v[148:151], 0
	v_mfma_f32_16x16x32_bf16 v[62:65], v[164:167], v[148:151], 0
	s_waitcnt vmcnt(6) lgkmcnt(0)
	s_barrier
	v_mfma_f32_16x16x32_bf16 v[2:5], v[184:187], v[168:171], v[2:5]
	ds_read_b128 v[136:139], v219 offset:0
	v_mfma_f32_16x16x32_bf16 v[6:9], v[188:191], v[168:171], v[6:9]
	ds_read_b128 v[140:143], v219 offset:2048
	v_mfma_f32_16x16x32_bf16 v[10:13], v[192:195], v[168:171], v[10:13]
	ds_read_b128 v[144:147], v219 offset:4096
	v_mfma_f32_16x16x32_bf16 v[14:17], v[196:199], v[168:171], v[14:17]
	ds_read_b128 v[148:151], v219 offset:6144
	v_mfma_f32_16x16x32_bf16 v[18:21], v[184:187], v[172:175], v[18:21]
	ds_read_b128 v[152:155], v231 offset:0
	v_mfma_f32_16x16x32_bf16 v[22:25], v[188:191], v[172:175], v[22:25]
	ds_read_b128 v[156:159], v231 offset:2048
	v_mfma_f32_16x16x32_bf16 v[26:29], v[192:195], v[172:175], v[26:29]
	ds_read_b128 v[160:163], v231 offset:4096
	v_mfma_f32_16x16x32_bf16 v[30:33], v[196:199], v[172:175], v[30:33]
	ds_read_b128 v[164:167], v231 offset:6144
	s_mov_b32 m0, s8
	v_mfma_f32_16x16x32_bf16 v[34:37], v[184:187], v[176:179], v[34:37]
	global_load_lds_dwordx4 v200, s[4:5]
	s_add_u32 m0, s8, 0x400
	v_mfma_f32_16x16x32_bf16 v[38:41], v[188:191], v[176:179], v[38:41]
	global_load_lds_dwordx4 v201, s[4:5]
	s_add_u32 m0, s8, 0x800
	v_mfma_f32_16x16x32_bf16 v[42:45], v[192:195], v[176:179], v[42:45]
	global_load_lds_dwordx4 v202, s[4:5]
	s_add_u32 m0, s8, 0xc00
	v_mfma_f32_16x16x32_bf16 v[46:49], v[196:199], v[176:179], v[46:49]
	global_load_lds_dwordx4 v203, s[4:5]
	s_mov_b32 m0, s9
	v_mfma_f32_16x16x32_bf16 v[50:53], v[184:187], v[180:183], v[50:53]
	global_load_lds_dwordx4 v204, s[6:7]
	s_add_u32 m0, s9, 0x400
	v_mfma_f32_16x16x32_bf16 v[54:57], v[188:191], v[180:183], v[54:57]
	global_load_lds_dwordx4 v205, s[6:7]
	v_mfma_f32_16x16x32_bf16 v[58:61], v[192:195], v[180:183], v[58:61]
	s_add_u32 s4, s4, 0x80
	s_addc_u32 s5, s5, 0
	v_mfma_f32_16x16x32_bf16 v[62:65], v[196:199], v[180:183], v[62:65]
	s_add_u32 s6, s6, 0x80
	s_addc_u32 s7, s7, 0
	s_waitcnt lgkmcnt(0)
	v_mfma_f32_16x16x32_bf16 v[2:5], v[152:155], v[136:139], v[2:5]
	ds_read_b128 v[168:171], v228 offset:0
	v_mfma_f32_16x16x32_bf16 v[6:9], v[156:159], v[136:139], v[6:9]
	ds_read_b128 v[172:175], v228 offset:2048
	v_mfma_f32_16x16x32_bf16 v[10:13], v[160:163], v[136:139], v[10:13]
	ds_read_b128 v[176:179], v228 offset:4096
	v_mfma_f32_16x16x32_bf16 v[14:17], v[164:167], v[136:139], v[14:17]
	ds_read_b128 v[180:183], v228 offset:6144
	v_mfma_f32_16x16x32_bf16 v[18:21], v[152:155], v[140:143], v[18:21]
	ds_read_b128 v[184:187], v234 offset:0
	v_mfma_f32_16x16x32_bf16 v[22:25], v[156:159], v[140:143], v[22:25]
	ds_read_b128 v[188:191], v234 offset:2048
	v_mfma_f32_16x16x32_bf16 v[26:29], v[160:163], v[140:143], v[26:29]
	ds_read_b128 v[192:195], v234 offset:4096
	v_mfma_f32_16x16x32_bf16 v[30:33], v[164:167], v[140:143], v[30:33]
	ds_read_b128 v[196:199], v234 offset:6144
	v_mfma_f32_16x16x32_bf16 v[34:37], v[152:155], v[144:147], v[34:37]
	v_mfma_f32_16x16x32_bf16 v[38:41], v[156:159], v[144:147], v[38:41]
	v_mfma_f32_16x16x32_bf16 v[42:45], v[160:163], v[144:147], v[42:45]
	v_mfma_f32_16x16x32_bf16 v[46:49], v[164:167], v[144:147], v[46:49]
	v_mfma_f32_16x16x32_bf16 v[50:53], v[152:155], v[148:151], v[50:53]
	v_mfma_f32_16x16x32_bf16 v[54:57], v[156:159], v[148:151], v[54:57]
	v_mfma_f32_16x16x32_bf16 v[58:61], v[160:163], v[148:151], v[58:61]
	v_mfma_f32_16x16x32_bf16 v[62:65], v[164:167], v[148:151], v[62:65]
	s_waitcnt vmcnt(6) lgkmcnt(0)
	s_barrier
	v_mfma_f32_16x16x32_bf16 v[2:5], v[184:187], v[168:171], v[2:5]
	ds_read_b128 v[136:139], v224 offset:0
	v_mfma_f32_16x16x32_bf16 v[6:9], v[188:191], v[168:171], v[6:9]
	ds_read_b128 v[140:143], v224 offset:2048
	v_mfma_f32_16x16x32_bf16 v[10:13], v[192:195], v[168:171], v[10:13]
	ds_read_b128 v[144:147], v224 offset:4096
	v_mfma_f32_16x16x32_bf16 v[14:17], v[196:199], v[168:171], v[14:17]
	ds_read_b128 v[148:151], v224 offset:6144
	v_mfma_f32_16x16x32_bf16 v[18:21], v[184:187], v[172:175], v[18:21]
	ds_read_b128 v[152:155], v232 offset:0
	v_mfma_f32_16x16x32_bf16 v[22:25], v[188:191], v[172:175], v[22:25]
	ds_read_b128 v[156:159], v232 offset:2048
	v_mfma_f32_16x16x32_bf16 v[26:29], v[192:195], v[172:175], v[26:29]
	ds_read_b128 v[160:163], v232 offset:4096
	v_mfma_f32_16x16x32_bf16 v[30:33], v[196:199], v[172:175], v[30:33]
	ds_read_b128 v[164:167], v232 offset:6144
	s_add_u32 m0, s8, 0xc000
	v_mfma_f32_16x16x32_bf16 v[34:37], v[184:187], v[176:179], v[34:37]
	global_load_lds_dwordx4 v200, s[4:5]
	s_add_u32 m0, s8, 0xc400
	v_mfma_f32_16x16x32_bf16 v[38:41], v[188:191], v[176:179], v[38:41]
	global_load_lds_dwordx4 v201, s[4:5]
	s_add_u32 m0, s8, 0xc800
	v_mfma_f32_16x16x32_bf16 v[42:45], v[192:195], v[176:179], v[42:45]
	global_load_lds_dwordx4 v202, s[4:5]
	s_add_u32 m0, s8, 0xcc00
	v_mfma_f32_16x16x32_bf16 v[46:49], v[196:199], v[176:179], v[46:49]
	global_load_lds_dwordx4 v203, s[4:5]
	s_add_u32 m0, s9, 0xc000
	v_mfma_f32_16x16x32_bf16 v[50:53], v[184:187], v[180:183], v[50:53]
	global_load_lds_dwordx4 v204, s[6:7]
	s_add_u32 m0, s9, 0xc400
	v_mfma_f32_16x16x32_bf16 v[54:57], v[188:191], v[180:183], v[54:57]
	global_load_lds_dwordx4 v205, s[6:7]
	v_mfma_f32_16x16x32_bf16 v[58:61], v[192:195], v[180:183], v[58:61]
	s_add_u32 s4, s4, 0x80
	s_addc_u32 s5, s5, 0
	v_mfma_f32_16x16x32_bf16 v[62:65], v[196:199], v[180:183], v[62:65]
	s_add_u32 s6, s6, 0x80
	s_addc_u32 s7, s7, 0
	s_waitcnt lgkmcnt(0)
	v_mfma_f32_16x16x32_bf16 v[2:5], v[152:155], v[136:139], v[2:5]
	ds_read_b128 v[168:171], v229 offset:0
	v_mfma_f32_16x16x32_bf16 v[6:9], v[156:159], v[136:139], v[6:9]
	ds_read_b128 v[172:175], v229 offset:2048
	v_mfma_f32_16x16x32_bf16 v[10:13], v[160:163], v[136:139], v[10:13]
	ds_read_b128 v[176:179], v229 offset:4096
	v_mfma_f32_16x16x32_bf16 v[14:17], v[164:167], v[136:139], v[14:17]
	ds_read_b128 v[180:183], v229 offset:6144
	v_mfma_f32_16x16x32_bf16 v[18:21], v[152:155], v[140:143], v[18:21]
	ds_read_b128 v[184:187], v235 offset:0
	v_mfma_f32_16x16x32_bf16 v[22:25], v[156:159], v[140:143], v[22:25]
	ds_read_b128 v[188:191], v235 offset:2048
	v_mfma_f32_16x16x32_bf16 v[26:29], v[160:163], v[140:143], v[26:29]
	ds_read_b128 v[192:195], v235 offset:4096
	v_mfma_f32_16x16x32_bf16 v[30:33], v[164:167], v[140:143], v[30:33]
	ds_read_b128 v[196:199], v235 offset:6144
	v_mfma_f32_16x16x32_bf16 v[34:37], v[152:155], v[144:147], v[34:37]
	v_mfma_f32_16x16x32_bf16 v[38:41], v[156:159], v[144:147], v[38:41]
	v_mfma_f32_16x16x32_bf16 v[42:45], v[160:163], v[144:147], v[42:45]
	v_mfma_f32_16x16x32_bf16 v[46:49], v[164:167], v[144:147], v[46:49]
	v_mfma_f32_16x16x32_bf16 v[50:53], v[152:155], v[148:151], v[50:53]
	v_mfma_f32_16x16x32_bf16 v[54:57], v[156:159], v[148:151], v[54:57]
	v_mfma_f32_16x16x32_bf16 v[58:61], v[160:163], v[148:151], v[58:61]
	v_mfma_f32_16x16x32_bf16 v[62:65], v[164:167], v[148:151], v[62:65]
	s_waitcnt vmcnt(6) lgkmcnt(0)
	s_barrier
	v_mfma_f32_16x16x32_bf16 v[2:5], v[184:187], v[168:171], v[2:5]
	ds_read_b128 v[136:139], v218 offset:0
	v_mfma_f32_16x16x32_bf16 v[6:9], v[188:191], v[168:171], v[6:9]
	ds_read_b128 v[140:143], v218 offset:2048
	v_mfma_f32_16x16x32_bf16 v[10:13], v[192:195], v[168:171], v[10:13]
	ds_read_b128 v[144:147], v218 offset:4096
	v_mfma_f32_16x16x32_bf16 v[14:17], v[196:199], v[168:171], v[14:17]
	ds_read_b128 v[148:151], v218 offset:6144
	v_mfma_f32_16x16x32_bf16 v[18:21], v[184:187], v[172:175], v[18:21]
	ds_read_b128 v[152:155], v230 offset:0
	v_mfma_f32_16x16x32_bf16 v[22:25], v[188:191], v[172:175], v[22:25]
	ds_read_b128 v[156:159], v230 offset:2048
	v_mfma_f32_16x16x32_bf16 v[26:29], v[192:195], v[172:175], v[26:29]
	ds_read_b128 v[160:163], v230 offset:4096
	v_mfma_f32_16x16x32_bf16 v[30:33], v[196:199], v[172:175], v[30:33]
	ds_read_b128 v[164:167], v230 offset:6144
	s_add_u32 m0, s8, 0x18000
	v_mfma_f32_16x16x32_bf16 v[34:37], v[184:187], v[176:179], v[34:37]
	global_load_lds_dwordx4 v200, s[4:5]
	s_add_u32 m0, s8, 0x18400
	v_mfma_f32_16x16x32_bf16 v[38:41], v[188:191], v[176:179], v[38:41]
	global_load_lds_dwordx4 v201, s[4:5]
	s_add_u32 m0, s8, 0x18800
	v_mfma_f32_16x16x32_bf16 v[42:45], v[192:195], v[176:179], v[42:45]
	global_load_lds_dwordx4 v202, s[4:5]
	s_add_u32 m0, s8, 0x18c00
	v_mfma_f32_16x16x32_bf16 v[46:49], v[196:199], v[176:179], v[46:49]
	global_load_lds_dwordx4 v203, s[4:5]
	s_add_u32 m0, s9, 0x18000
	v_mfma_f32_16x16x32_bf16 v[50:53], v[184:187], v[180:183], v[50:53]
	global_load_lds_dwordx4 v204, s[6:7]
	s_add_u32 m0, s9, 0x18400
	v_mfma_f32_16x16x32_bf16 v[54:57], v[188:191], v[180:183], v[54:57]
	global_load_lds_dwordx4 v205, s[6:7]
	v_mfma_f32_16x16x32_bf16 v[58:61], v[192:195], v[180:183], v[58:61]
	s_add_u32 s4, s4, 0x80
	s_addc_u32 s5, s5, 0
	v_mfma_f32_16x16x32_bf16 v[62:65], v[196:199], v[180:183], v[62:65]
	s_add_u32 s6, s6, 0x80
	s_addc_u32 s7, s7, 0
	s_waitcnt lgkmcnt(0)
	v_mfma_f32_16x16x32_bf16 v[2:5], v[152:155], v[136:139], v[2:5]
	ds_read_b128 v[168:171], v225 offset:0
	v_mfma_f32_16x16x32_bf16 v[6:9], v[156:159], v[136:139], v[6:9]
	ds_read_b128 v[172:175], v225 offset:2048
	v_mfma_f32_16x16x32_bf16 v[10:13], v[160:163], v[136:139], v[10:13]
	ds_read_b128 v[176:179], v225 offset:4096
	v_mfma_f32_16x16x32_bf16 v[14:17], v[164:167], v[136:139], v[14:17]
	ds_read_b128 v[180:183], v225 offset:6144
	v_mfma_f32_16x16x32_bf16 v[18:21], v[152:155], v[140:143], v[18:21]
	ds_read_b128 v[184:187], v233 offset:0
	v_mfma_f32_16x16x32_bf16 v[22:25], v[156:159], v[140:143], v[22:25]
	ds_read_b128 v[188:191], v233 offset:2048
	v_mfma_f32_16x16x32_bf16 v[26:29], v[160:163], v[140:143], v[26:29]
	ds_read_b128 v[192:195], v233 offset:4096
	v_mfma_f32_16x16x32_bf16 v[30:33], v[164:167], v[140:143], v[30:33]
	ds_read_b128 v[196:199], v233 offset:6144
	v_mfma_f32_16x16x32_bf16 v[34:37], v[152:155], v[144:147], v[34:37]
	v_mfma_f32_16x16x32_bf16 v[38:41], v[156:159], v[144:147], v[38:41]
	v_mfma_f32_16x16x32_bf16 v[42:45], v[160:163], v[144:147], v[42:45]
	v_mfma_f32_16x16x32_bf16 v[46:49], v[164:167], v[144:147], v[46:49]
	v_mfma_f32_16x16x32_bf16 v[50:53], v[152:155], v[148:151], v[50:53]
	v_mfma_f32_16x16x32_bf16 v[54:57], v[156:159], v[148:151], v[54:57]
	v_mfma_f32_16x16x32_bf16 v[58:61], v[160:163], v[148:151], v[58:61]
	v_mfma_f32_16x16x32_bf16 v[62:65], v[164:167], v[148:151], v[62:65]
	s_waitcnt vmcnt(6) lgkmcnt(0)
	s_barrier
	v_mfma_f32_16x16x32_bf16 v[2:5], v[184:187], v[168:171], v[2:5]
	ds_read_b128 v[136:139], v219 offset:0
	v_mfma_f32_16x16x32_bf16 v[6:9], v[188:191], v[168:171], v[6:9]
	ds_read_b128 v[140:143], v219 offset:2048
	v_mfma_f32_16x16x32_bf16 v[10:13], v[192:195], v[168:171], v[10:13]
	ds_read_b128 v[144:147], v219 offset:4096
	v_mfma_f32_16x16x32_bf16 v[14:17], v[196:199], v[168:171], v[14:17]
	ds_read_b128 v[148:151], v219 offset:6144
	v_mfma_f32_16x16x32_bf16 v[18:21], v[184:187], v[172:175], v[18:21]
	ds_read_b128 v[152:155], v231 offset:0
	v_mfma_f32_16x16x32_bf16 v[22:25], v[188:191], v[172:175], v[22:25]
	ds_read_b128 v[156:159], v231 offset:2048
	v_mfma_f32_16x16x32_bf16 v[26:29], v[192:195], v[172:175], v[26:29]
	ds_read_b128 v[160:163], v231 offset:4096
	v_mfma_f32_16x16x32_bf16 v[30:33], v[196:199], v[172:175], v[30:33]
	ds_read_b128 v[164:167], v231 offset:6144
	s_mov_b32 m0, s8
	v_mfma_f32_16x16x32_bf16 v[34:37], v[184:187], v[176:179], v[34:37]
	global_load_lds_dwordx4 v200, s[4:5]
	s_add_u32 m0, s8, 0x400
	v_mfma_f32_16x16x32_bf16 v[38:41], v[188:191], v[176:179], v[38:41]
	global_load_lds_dwordx4 v201, s[4:5]
	s_add_u32 m0, s8, 0x800
	v_mfma_f32_16x16x32_bf16 v[42:45], v[192:195], v[176:179], v[42:45]
	global_load_lds_dwordx4 v202, s[4:5]
	s_add_u32 m0, s8, 0xc00
	v_mfma_f32_16x16x32_bf16 v[46:49], v[196:199], v[176:179], v[46:49]
	global_load_lds_dwordx4 v203, s[4:5]
	s_mov_b32 m0, s9
	v_mfma_f32_16x16x32_bf16 v[50:53], v[184:187], v[180:183], v[50:53]
	global_load_lds_dwordx4 v204, s[6:7]
	s_add_u32 m0, s9, 0x400
	v_mfma_f32_16x16x32_bf16 v[54:57], v[188:191], v[180:183], v[54:57]
	global_load_lds_dwordx4 v205, s[6:7]
	v_mfma_f32_16x16x32_bf16 v[58:61], v[192:195], v[180:183], v[58:61]
	s_add_u32 s4, s4, 0x80
	s_addc_u32 s5, s5, 0
	v_mfma_f32_16x16x32_bf16 v[62:65], v[196:199], v[180:183], v[62:65]
	s_add_u32 s6, s6, 0x80
	s_addc_u32 s7, s7, 0
	s_waitcnt lgkmcnt(0)
	v_mfma_f32_16x16x32_bf16 v[2:5], v[152:155], v[136:139], v[2:5]
	ds_read_b128 v[168:171], v228 offset:0
	v_mfma_f32_16x16x32_bf16 v[6:9], v[156:159], v[136:139], v[6:9]
	ds_read_b128 v[172:175], v228 offset:2048
	v_mfma_f32_16x16x32_bf16 v[10:13], v[160:163], v[136:139], v[10:13]
	ds_read_b128 v[176:179], v228 offset:4096
	v_mfma_f32_16x16x32_bf16 v[14:17], v[164:167], v[136:139], v[14:17]
	ds_read_b128 v[180:183], v228 offset:6144
	v_mfma_f32_16x16x32_bf16 v[18:21], v[152:155], v[140:143], v[18:21]
	ds_read_b128 v[184:187], v234 offset:0
	v_mfma_f32_16x16x32_bf16 v[22:25], v[156:159], v[140:143], v[22:25]
	ds_read_b128 v[188:191], v234 offset:2048
	v_mfma_f32_16x16x32_bf16 v[26:29], v[160:163], v[140:143], v[26:29]
	ds_read_b128 v[192:195], v234 offset:4096
	v_mfma_f32_16x16x32_bf16 v[30:33], v[164:167], v[140:143], v[30:33]
	ds_read_b128 v[196:199], v234 offset:6144
	v_mfma_f32_16x16x32_bf16 v[34:37], v[152:155], v[144:147], v[34:37]
	v_mfma_f32_16x16x32_bf16 v[38:41], v[156:159], v[144:147], v[38:41]
	v_mfma_f32_16x16x32_bf16 v[42:45], v[160:163], v[144:147], v[42:45]
	v_mfma_f32_16x16x32_bf16 v[46:49], v[164:167], v[144:147], v[46:49]
	v_mfma_f32_16x16x32_bf16 v[50:53], v[152:155], v[148:151], v[50:53]
	v_mfma_f32_16x16x32_bf16 v[54:57], v[156:159], v[148:151], v[54:57]
	v_mfma_f32_16x16x32_bf16 v[58:61], v[160:163], v[148:151], v[58:61]
	v_mfma_f32_16x16x32_bf16 v[62:65], v[164:167], v[148:151], v[62:65]
	s_waitcnt vmcnt(6) lgkmcnt(0)
	s_barrier
	v_mfma_f32_16x16x32_bf16 v[2:5], v[184:187], v[168:171], v[2:5]
	ds_read_b128 v[136:139], v224 offset:0
	v_mfma_f32_16x16x32_bf16 v[6:9], v[188:191], v[168:171], v[6:9]
	ds_read_b128 v[140:143], v224 offset:2048
	v_mfma_f32_16x16x32_bf16 v[10:13], v[192:195], v[168:171], v[10:13]
	ds_read_b128 v[144:147], v224 offset:4096
	v_mfma_f32_16x16x32_bf16 v[14:17], v[196:199], v[168:171], v[14:17]
	ds_read_b128 v[148:151], v224 offset:6144
	v_mfma_f32_16x16x32_bf16 v[18:21], v[184:187], v[172:175], v[18:21]
	ds_read_b128 v[152:155], v232 offset:0
	v_mfma_f32_16x16x32_bf16 v[22:25], v[188:191], v[172:175], v[22:25]
	ds_read_b128 v[156:159], v232 offset:2048
	v_mfma_f32_16x16x32_bf16 v[26:29], v[192:195], v[172:175], v[26:29]
	ds_read_b128 v[160:163], v232 offset:4096
	v_mfma_f32_16x16x32_bf16 v[30:33], v[196:199], v[172:175], v[30:33]
	ds_read_b128 v[164:167], v232 offset:6144
	s_add_u32 m0, s8, 0xc000
	v_mfma_f32_16x16x32_bf16 v[34:37], v[184:187], v[176:179], v[34:37]
	global_load_lds_dwordx4 v200, s[4:5]
	s_add_u32 m0, s8, 0xc400
	v_mfma_f32_16x16x32_bf16 v[38:41], v[188:191], v[176:179], v[38:41]
	global_load_lds_dwordx4 v201, s[4:5]
	s_add_u32 m0, s8, 0xc800
	v_mfma_f32_16x16x32_bf16 v[42:45], v[192:195], v[176:179], v[42:45]
	global_load_lds_dwordx4 v202, s[4:5]
	s_add_u32 m0, s8, 0xcc00
	v_mfma_f32_16x16x32_bf16 v[46:49], v[196:199], v[176:179], v[46:49]
	global_load_lds_dwordx4 v203, s[4:5]
	s_add_u32 m0, s9, 0xc000
	v_mfma_f32_16x16x32_bf16 v[50:53], v[184:187], v[180:183], v[50:53]
	global_load_lds_dwordx4 v204, s[6:7]
	s_add_u32 m0, s9, 0xc400
	v_mfma_f32_16x16x32_bf16 v[54:57], v[188:191], v[180:183], v[54:57]
	global_load_lds_dwordx4 v205, s[6:7]
	v_mfma_f32_16x16x32_bf16 v[58:61], v[192:195], v[180:183], v[58:61]
	s_add_u32 s4, s4, 0x80
	s_addc_u32 s5, s5, 0
	v_mfma_f32_16x16x32_bf16 v[62:65], v[196:199], v[180:183], v[62:65]
	s_add_u32 s6, s6, 0x80
	s_addc_u32 s7, s7, 0
	s_waitcnt lgkmcnt(0)
	v_mfma_f32_16x16x32_bf16 v[2:5], v[152:155], v[136:139], v[2:5]
	ds_read_b128 v[168:171], v229 offset:0
	v_mfma_f32_16x16x32_bf16 v[6:9], v[156:159], v[136:139], v[6:9]
	ds_read_b128 v[172:175], v229 offset:2048
	v_mfma_f32_16x16x32_bf16 v[10:13], v[160:163], v[136:139], v[10:13]
	ds_read_b128 v[176:179], v229 offset:4096
	v_mfma_f32_16x16x32_bf16 v[14:17], v[164:167], v[136:139], v[14:17]
	ds_read_b128 v[180:183], v229 offset:6144
	v_mfma_f32_16x16x32_bf16 v[18:21], v[152:155], v[140:143], v[18:21]
	ds_read_b128 v[184:187], v235 offset:0
	v_mfma_f32_16x16x32_bf16 v[22:25], v[156:159], v[140:143], v[22:25]
	ds_read_b128 v[188:191], v235 offset:2048
	v_mfma_f32_16x16x32_bf16 v[26:29], v[160:163], v[140:143], v[26:29]
	ds_read_b128 v[192:195], v235 offset:4096
	v_mfma_f32_16x16x32_bf16 v[30:33], v[164:167], v[140:143], v[30:33]
	ds_read_b128 v[196:199], v235 offset:6144
	v_mfma_f32_16x16x32_bf16 v[34:37], v[152:155], v[144:147], v[34:37]
	v_mfma_f32_16x16x32_bf16 v[38:41], v[156:159], v[144:147], v[38:41]
	v_mfma_f32_16x16x32_bf16 v[42:45], v[160:163], v[144:147], v[42:45]
	v_mfma_f32_16x16x32_bf16 v[46:49], v[164:167], v[144:147], v[46:49]
	v_mfma_f32_16x16x32_bf16 v[50:53], v[152:155], v[148:151], v[50:53]
	v_mfma_f32_16x16x32_bf16 v[54:57], v[156:159], v[148:151], v[54:57]
	v_mfma_f32_16x16x32_bf16 v[58:61], v[160:163], v[148:151], v[58:61]
	v_mfma_f32_16x16x32_bf16 v[62:65], v[164:167], v[148:151], v[62:65]
	s_waitcnt vmcnt(6) lgkmcnt(0)
	s_barrier
	v_mfma_f32_16x16x32_bf16 v[2:5], v[184:187], v[168:171], v[2:5]
	ds_read_b128 v[136:139], v218 offset:0
	v_mfma_f32_16x16x32_bf16 v[6:9], v[188:191], v[168:171], v[6:9]
	ds_read_b128 v[140:143], v218 offset:2048
	v_mfma_f32_16x16x32_bf16 v[10:13], v[192:195], v[168:171], v[10:13]
	ds_read_b128 v[144:147], v218 offset:4096
	v_mfma_f32_16x16x32_bf16 v[14:17], v[196:199], v[168:171], v[14:17]
	ds_read_b128 v[148:151], v218 offset:6144
	v_mfma_f32_16x16x32_bf16 v[18:21], v[184:187], v[172:175], v[18:21]
	ds_read_b128 v[152:155], v230 offset:0
	v_mfma_f32_16x16x32_bf16 v[22:25], v[188:191], v[172:175], v[22:25]
	ds_read_b128 v[156:159], v230 offset:2048
	v_mfma_f32_16x16x32_bf16 v[26:29], v[192:195], v[172:175], v[26:29]
	ds_read_b128 v[160:163], v230 offset:4096
	v_mfma_f32_16x16x32_bf16 v[30:33], v[196:199], v[172:175], v[30:33]
	ds_read_b128 v[164:167], v230 offset:6144
	s_add_u32 m0, s8, 0x18000
	v_mfma_f32_16x16x32_bf16 v[34:37], v[184:187], v[176:179], v[34:37]
	global_load_lds_dwordx4 v200, s[4:5]
	s_add_u32 m0, s8, 0x18400
	v_mfma_f32_16x16x32_bf16 v[38:41], v[188:191], v[176:179], v[38:41]
	global_load_lds_dwordx4 v201, s[4:5]
	s_add_u32 m0, s8, 0x18800
	v_mfma_f32_16x16x32_bf16 v[42:45], v[192:195], v[176:179], v[42:45]
	global_load_lds_dwordx4 v202, s[4:5]
	s_add_u32 m0, s8, 0x18c00
	v_mfma_f32_16x16x32_bf16 v[46:49], v[196:199], v[176:179], v[46:49]
	global_load_lds_dwordx4 v203, s[4:5]
	s_add_u32 m0, s9, 0x18000
	v_mfma_f32_16x16x32_bf16 v[50:53], v[184:187], v[180:183], v[50:53]
	global_load_lds_dwordx4 v204, s[6:7]
	s_add_u32 m0, s9, 0x18400
	v_mfma_f32_16x16x32_bf16 v[54:57], v[188:191], v[180:183], v[54:57]
	global_load_lds_dwordx4 v205, s[6:7]
	v_mfma_f32_16x16x32_bf16 v[58:61], v[192:195], v[180:183], v[58:61]
	s_add_u32 s4, s4, 0x80
	s_addc_u32 s5, s5, 0
	v_mfma_f32_16x16x32_bf16 v[62:65], v[196:199], v[180:183], v[62:65]
	s_add_u32 s6, s6, 0x80
	s_addc_u32 s7, s7, 0
	s_waitcnt lgkmcnt(0)
	v_mfma_f32_16x16x32_bf16 v[2:5], v[152:155], v[136:139], v[2:5]
	ds_read_b128 v[168:171], v225 offset:0
	v_mfma_f32_16x16x32_bf16 v[6:9], v[156:159], v[136:139], v[6:9]
	ds_read_b128 v[172:175], v225 offset:2048
	v_mfma_f32_16x16x32_bf16 v[10:13], v[160:163], v[136:139], v[10:13]
	ds_read_b128 v[176:179], v225 offset:4096
	v_mfma_f32_16x16x32_bf16 v[14:17], v[164:167], v[136:139], v[14:17]
	ds_read_b128 v[180:183], v225 offset:6144
	v_mfma_f32_16x16x32_bf16 v[18:21], v[152:155], v[140:143], v[18:21]
	ds_read_b128 v[184:187], v233 offset:0
	v_mfma_f32_16x16x32_bf16 v[22:25], v[156:159], v[140:143], v[22:25]
	ds_read_b128 v[188:191], v233 offset:2048
	v_mfma_f32_16x16x32_bf16 v[26:29], v[160:163], v[140:143], v[26:29]
	ds_read_b128 v[192:195], v233 offset:4096
	v_mfma_f32_16x16x32_bf16 v[30:33], v[164:167], v[140:143], v[30:33]
	ds_read_b128 v[196:199], v233 offset:6144
	v_mfma_f32_16x16x32_bf16 v[34:37], v[152:155], v[144:147], v[34:37]
	v_mfma_f32_16x16x32_bf16 v[38:41], v[156:159], v[144:147], v[38:41]
	v_mfma_f32_16x16x32_bf16 v[42:45], v[160:163], v[144:147], v[42:45]
	v_mfma_f32_16x16x32_bf16 v[46:49], v[164:167], v[144:147], v[46:49]
	v_mfma_f32_16x16x32_bf16 v[50:53], v[152:155], v[148:151], v[50:53]
	v_mfma_f32_16x16x32_bf16 v[54:57], v[156:159], v[148:151], v[54:57]
	v_mfma_f32_16x16x32_bf16 v[58:61], v[160:163], v[148:151], v[58:61]
	v_mfma_f32_16x16x32_bf16 v[62:65], v[164:167], v[148:151], v[62:65]
	s_waitcnt vmcnt(6) lgkmcnt(0)
	s_barrier
	v_mfma_f32_16x16x32_bf16 v[2:5], v[184:187], v[168:171], v[2:5]
	ds_read_b128 v[136:139], v219 offset:0
	v_mfma_f32_16x16x32_bf16 v[6:9], v[188:191], v[168:171], v[6:9]
	ds_read_b128 v[140:143], v219 offset:2048
	v_mfma_f32_16x16x32_bf16 v[10:13], v[192:195], v[168:171], v[10:13]
	ds_read_b128 v[144:147], v219 offset:4096
	v_mfma_f32_16x16x32_bf16 v[14:17], v[196:199], v[168:171], v[14:17]
	ds_read_b128 v[148:151], v219 offset:6144
	v_mfma_f32_16x16x32_bf16 v[18:21], v[184:187], v[172:175], v[18:21]
	ds_read_b128 v[152:155], v231 offset:0
	v_mfma_f32_16x16x32_bf16 v[22:25], v[188:191], v[172:175], v[22:25]
	ds_read_b128 v[156:159], v231 offset:2048
	v_mfma_f32_16x16x32_bf16 v[26:29], v[192:195], v[172:175], v[26:29]
	ds_read_b128 v[160:163], v231 offset:4096
	v_mfma_f32_16x16x32_bf16 v[30:33], v[196:199], v[172:175], v[30:33]
	ds_read_b128 v[164:167], v231 offset:6144
	s_mov_b32 m0, s8
	v_mfma_f32_16x16x32_bf16 v[34:37], v[184:187], v[176:179], v[34:37]
	global_load_lds_dwordx4 v200, s[4:5]
	s_add_u32 m0, s8, 0x400
	v_mfma_f32_16x16x32_bf16 v[38:41], v[188:191], v[176:179], v[38:41]
	global_load_lds_dwordx4 v201, s[4:5]
	s_add_u32 m0, s8, 0x800
	v_mfma_f32_16x16x32_bf16 v[42:45], v[192:195], v[176:179], v[42:45]
	global_load_lds_dwordx4 v202, s[4:5]
	s_add_u32 m0, s8, 0xc00
	v_mfma_f32_16x16x32_bf16 v[46:49], v[196:199], v[176:179], v[46:49]
	global_load_lds_dwordx4 v203, s[4:5]
	s_mov_b32 m0, s9
	v_mfma_f32_16x16x32_bf16 v[50:53], v[184:187], v[180:183], v[50:53]
	global_load_lds_dwordx4 v204, s[6:7]
	s_add_u32 m0, s9, 0x400
	v_mfma_f32_16x16x32_bf16 v[54:57], v[188:191], v[180:183], v[54:57]
	global_load_lds_dwordx4 v205, s[6:7]
	v_mfma_f32_16x16x32_bf16 v[58:61], v[192:195], v[180:183], v[58:61]
	s_add_u32 s4, s4, 0x80
	s_addc_u32 s5, s5, 0
	v_mfma_f32_16x16x32_bf16 v[62:65], v[196:199], v[180:183], v[62:65]
	s_add_u32 s6, s6, 0x80
	s_addc_u32 s7, s7, 0
	s_waitcnt lgkmcnt(0)
	v_mfma_f32_16x16x32_bf16 v[2:5], v[152:155], v[136:139], v[2:5]
	ds_read_b128 v[168:171], v228 offset:0
	v_mfma_f32_16x16x32_bf16 v[6:9], v[156:159], v[136:139], v[6:9]
	ds_read_b128 v[172:175], v228 offset:2048
	v_mfma_f32_16x16x32_bf16 v[10:13], v[160:163], v[136:139], v[10:13]
	ds_read_b128 v[176:179], v228 offset:4096
	v_mfma_f32_16x16x32_bf16 v[14:17], v[164:167], v[136:139], v[14:17]
	ds_read_b128 v[180:183], v228 offset:6144
	v_mfma_f32_16x16x32_bf16 v[18:21], v[152:155], v[140:143], v[18:21]
	ds_read_b128 v[184:187], v234 offset:0
	v_mfma_f32_16x16x32_bf16 v[22:25], v[156:159], v[140:143], v[22:25]
	ds_read_b128 v[188:191], v234 offset:2048
	v_mfma_f32_16x16x32_bf16 v[26:29], v[160:163], v[140:143], v[26:29]
	ds_read_b128 v[192:195], v234 offset:4096
	v_mfma_f32_16x16x32_bf16 v[30:33], v[164:167], v[140:143], v[30:33]
	ds_read_b128 v[196:199], v234 offset:6144
	v_mfma_f32_16x16x32_bf16 v[34:37], v[152:155], v[144:147], v[34:37]
	v_mfma_f32_16x16x32_bf16 v[38:41], v[156:159], v[144:147], v[38:41]
	v_mfma_f32_16x16x32_bf16 v[42:45], v[160:163], v[144:147], v[42:45]
	v_mfma_f32_16x16x32_bf16 v[46:49], v[164:167], v[144:147], v[46:49]
	v_mfma_f32_16x16x32_bf16 v[50:53], v[152:155], v[148:151], v[50:53]
	v_mfma_f32_16x16x32_bf16 v[54:57], v[156:159], v[148:151], v[54:57]
	v_mfma_f32_16x16x32_bf16 v[58:61], v[160:163], v[148:151], v[58:61]
	v_mfma_f32_16x16x32_bf16 v[62:65], v[164:167], v[148:151], v[62:65]
	s_waitcnt vmcnt(6) lgkmcnt(0)
	s_barrier
	v_mfma_f32_16x16x32_bf16 v[2:5], v[184:187], v[168:171], v[2:5]
	ds_read_b128 v[136:139], v224 offset:0
	v_mfma_f32_16x16x32_bf16 v[6:9], v[188:191], v[168:171], v[6:9]
	ds_read_b128 v[140:143], v224 offset:2048
	v_mfma_f32_16x16x32_bf16 v[10:13], v[192:195], v[168:171], v[10:13]
	ds_read_b128 v[144:147], v224 offset:4096
	v_mfma_f32_16x16x32_bf16 v[14:17], v[196:199], v[168:171], v[14:17]
	ds_read_b128 v[148:151], v224 offset:6144
	v_mfma_f32_16x16x32_bf16 v[18:21], v[184:187], v[172:175], v[18:21]
	ds_read_b128 v[152:155], v232 offset:0
	v_mfma_f32_16x16x32_bf16 v[22:25], v[188:191], v[172:175], v[22:25]
	ds_read_b128 v[156:159], v232 offset:2048
	v_mfma_f32_16x16x32_bf16 v[26:29], v[192:195], v[172:175], v[26:29]
	ds_read_b128 v[160:163], v232 offset:4096
	v_mfma_f32_16x16x32_bf16 v[30:33], v[196:199], v[172:175], v[30:33]
	ds_read_b128 v[164:167], v232 offset:6144
	s_add_u32 m0, s8, 0xc000
	v_mfma_f32_16x16x32_bf16 v[34:37], v[184:187], v[176:179], v[34:37]
	global_load_lds_dwordx4 v200, s[4:5]
	s_add_u32 m0, s8, 0xc400
	v_mfma_f32_16x16x32_bf16 v[38:41], v[188:191], v[176:179], v[38:41]
	global_load_lds_dwordx4 v201, s[4:5]
	s_add_u32 m0, s8, 0xc800
	v_mfma_f32_16x16x32_bf16 v[42:45], v[192:195], v[176:179], v[42:45]
	global_load_lds_dwordx4 v202, s[4:5]
	s_add_u32 m0, s8, 0xcc00
	v_mfma_f32_16x16x32_bf16 v[46:49], v[196:199], v[176:179], v[46:49]
	global_load_lds_dwordx4 v203, s[4:5]
	s_add_u32 m0, s9, 0xc000
	v_mfma_f32_16x16x32_bf16 v[50:53], v[184:187], v[180:183], v[50:53]
	global_load_lds_dwordx4 v204, s[6:7]
	s_add_u32 m0, s9, 0xc400
	v_mfma_f32_16x16x32_bf16 v[54:57], v[188:191], v[180:183], v[54:57]
	global_load_lds_dwordx4 v205, s[6:7]
	v_mfma_f32_16x16x32_bf16 v[58:61], v[192:195], v[180:183], v[58:61]
	s_add_u32 s4, s4, 0x80
	s_addc_u32 s5, s5, 0
	v_mfma_f32_16x16x32_bf16 v[62:65], v[196:199], v[180:183], v[62:65]
	s_add_u32 s6, s6, 0x80
	s_addc_u32 s7, s7, 0
	s_waitcnt lgkmcnt(0)
	v_mfma_f32_16x16x32_bf16 v[2:5], v[152:155], v[136:139], v[2:5]
	ds_read_b128 v[168:171], v229 offset:0
	v_mfma_f32_16x16x32_bf16 v[6:9], v[156:159], v[136:139], v[6:9]
	ds_read_b128 v[172:175], v229 offset:2048
	v_mfma_f32_16x16x32_bf16 v[10:13], v[160:163], v[136:139], v[10:13]
	ds_read_b128 v[176:179], v229 offset:4096
	v_mfma_f32_16x16x32_bf16 v[14:17], v[164:167], v[136:139], v[14:17]
	ds_read_b128 v[180:183], v229 offset:6144
	v_mfma_f32_16x16x32_bf16 v[18:21], v[152:155], v[140:143], v[18:21]
	ds_read_b128 v[184:187], v235 offset:0
	v_mfma_f32_16x16x32_bf16 v[22:25], v[156:159], v[140:143], v[22:25]
	ds_read_b128 v[188:191], v235 offset:2048
	v_mfma_f32_16x16x32_bf16 v[26:29], v[160:163], v[140:143], v[26:29]
	ds_read_b128 v[192:195], v235 offset:4096
	v_mfma_f32_16x16x32_bf16 v[30:33], v[164:167], v[140:143], v[30:33]
	ds_read_b128 v[196:199], v235 offset:6144
	v_mfma_f32_16x16x32_bf16 v[34:37], v[152:155], v[144:147], v[34:37]
	v_mfma_f32_16x16x32_bf16 v[38:41], v[156:159], v[144:147], v[38:41]
	v_mfma_f32_16x16x32_bf16 v[42:45], v[160:163], v[144:147], v[42:45]
	v_mfma_f32_16x16x32_bf16 v[46:49], v[164:167], v[144:147], v[46:49]
	v_mfma_f32_16x16x32_bf16 v[50:53], v[152:155], v[148:151], v[50:53]
	v_mfma_f32_16x16x32_bf16 v[54:57], v[156:159], v[148:151], v[54:57]
	v_mfma_f32_16x16x32_bf16 v[58:61], v[160:163], v[148:151], v[58:61]
	v_mfma_f32_16x16x32_bf16 v[62:65], v[164:167], v[148:151], v[62:65]
	s_waitcnt vmcnt(6) lgkmcnt(0)
	s_barrier
	v_mfma_f32_16x16x32_bf16 v[2:5], v[184:187], v[168:171], v[2:5]
	ds_read_b128 v[136:139], v218 offset:0
	v_mfma_f32_16x16x32_bf16 v[6:9], v[188:191], v[168:171], v[6:9]
	ds_read_b128 v[140:143], v218 offset:2048
	v_mfma_f32_16x16x32_bf16 v[10:13], v[192:195], v[168:171], v[10:13]
	ds_read_b128 v[144:147], v218 offset:4096
	v_mfma_f32_16x16x32_bf16 v[14:17], v[196:199], v[168:171], v[14:17]
	ds_read_b128 v[148:151], v218 offset:6144
	v_mfma_f32_16x16x32_bf16 v[18:21], v[184:187], v[172:175], v[18:21]
	ds_read_b128 v[152:155], v230 offset:0
	v_mfma_f32_16x16x32_bf16 v[22:25], v[188:191], v[172:175], v[22:25]
	ds_read_b128 v[156:159], v230 offset:2048
	v_mfma_f32_16x16x32_bf16 v[26:29], v[192:195], v[172:175], v[26:29]
	ds_read_b128 v[160:163], v230 offset:4096
	v_mfma_f32_16x16x32_bf16 v[30:33], v[196:199], v[172:175], v[30:33]
	ds_read_b128 v[164:167], v230 offset:6144
	s_add_u32 m0, s8, 0x18000
	v_mfma_f32_16x16x32_bf16 v[34:37], v[184:187], v[176:179], v[34:37]
	global_load_lds_dwordx4 v200, s[4:5]
	s_add_u32 m0, s8, 0x18400
	v_mfma_f32_16x16x32_bf16 v[38:41], v[188:191], v[176:179], v[38:41]
	global_load_lds_dwordx4 v201, s[4:5]
	s_add_u32 m0, s8, 0x18800
	v_mfma_f32_16x16x32_bf16 v[42:45], v[192:195], v[176:179], v[42:45]
	global_load_lds_dwordx4 v202, s[4:5]
	s_add_u32 m0, s8, 0x18c00
	v_mfma_f32_16x16x32_bf16 v[46:49], v[196:199], v[176:179], v[46:49]
	global_load_lds_dwordx4 v203, s[4:5]
	s_add_u32 m0, s9, 0x18000
	v_mfma_f32_16x16x32_bf16 v[50:53], v[184:187], v[180:183], v[50:53]
	global_load_lds_dwordx4 v204, s[6:7]
	s_add_u32 m0, s9, 0x18400
	v_mfma_f32_16x16x32_bf16 v[54:57], v[188:191], v[180:183], v[54:57]
	global_load_lds_dwordx4 v205, s[6:7]
	v_mfma_f32_16x16x32_bf16 v[58:61], v[192:195], v[180:183], v[58:61]
	s_add_u32 s4, s4, 0x80
	s_addc_u32 s5, s5, 0
	v_mfma_f32_16x16x32_bf16 v[62:65], v[196:199], v[180:183], v[62:65]
	s_add_u32 s6, s6, 0x80
	s_addc_u32 s7, s7, 0
	s_waitcnt lgkmcnt(0)
	v_mfma_f32_16x16x32_bf16 v[2:5], v[152:155], v[136:139], v[2:5]
	ds_read_b128 v[168:171], v225 offset:0
	v_mfma_f32_16x16x32_bf16 v[6:9], v[156:159], v[136:139], v[6:9]
	ds_read_b128 v[172:175], v225 offset:2048
	v_mfma_f32_16x16x32_bf16 v[10:13], v[160:163], v[136:139], v[10:13]
	ds_read_b128 v[176:179], v225 offset:4096
	v_mfma_f32_16x16x32_bf16 v[14:17], v[164:167], v[136:139], v[14:17]
	ds_read_b128 v[180:183], v225 offset:6144
	v_mfma_f32_16x16x32_bf16 v[18:21], v[152:155], v[140:143], v[18:21]
	ds_read_b128 v[184:187], v233 offset:0
	v_mfma_f32_16x16x32_bf16 v[22:25], v[156:159], v[140:143], v[22:25]
	ds_read_b128 v[188:191], v233 offset:2048
	v_mfma_f32_16x16x32_bf16 v[26:29], v[160:163], v[140:143], v[26:29]
	ds_read_b128 v[192:195], v233 offset:4096
	v_mfma_f32_16x16x32_bf16 v[30:33], v[164:167], v[140:143], v[30:33]
	ds_read_b128 v[196:199], v233 offset:6144
	v_mfma_f32_16x16x32_bf16 v[34:37], v[152:155], v[144:147], v[34:37]
	v_mfma_f32_16x16x32_bf16 v[38:41], v[156:159], v[144:147], v[38:41]
	v_mfma_f32_16x16x32_bf16 v[42:45], v[160:163], v[144:147], v[42:45]
	v_mfma_f32_16x16x32_bf16 v[46:49], v[164:167], v[144:147], v[46:49]
	v_mfma_f32_16x16x32_bf16 v[50:53], v[152:155], v[148:151], v[50:53]
	v_mfma_f32_16x16x32_bf16 v[54:57], v[156:159], v[148:151], v[54:57]
	v_mfma_f32_16x16x32_bf16 v[58:61], v[160:163], v[148:151], v[58:61]
	v_mfma_f32_16x16x32_bf16 v[62:65], v[164:167], v[148:151], v[62:65]
	s_waitcnt vmcnt(6) lgkmcnt(0)
	s_barrier
	v_mfma_f32_16x16x32_bf16 v[2:5], v[184:187], v[168:171], v[2:5]
	ds_read_b128 v[136:139], v219 offset:0
	v_mfma_f32_16x16x32_bf16 v[6:9], v[188:191], v[168:171], v[6:9]
	ds_read_b128 v[140:143], v219 offset:2048
	v_mfma_f32_16x16x32_bf16 v[10:13], v[192:195], v[168:171], v[10:13]
	ds_read_b128 v[144:147], v219 offset:4096
	v_mfma_f32_16x16x32_bf16 v[14:17], v[196:199], v[168:171], v[14:17]
	ds_read_b128 v[148:151], v219 offset:6144
	v_mfma_f32_16x16x32_bf16 v[18:21], v[184:187], v[172:175], v[18:21]
	ds_read_b128 v[152:155], v231 offset:0
	v_mfma_f32_16x16x32_bf16 v[22:25], v[188:191], v[172:175], v[22:25]
	ds_read_b128 v[156:159], v231 offset:2048
	v_mfma_f32_16x16x32_bf16 v[26:29], v[192:195], v[172:175], v[26:29]
	ds_read_b128 v[160:163], v231 offset:4096
	v_mfma_f32_16x16x32_bf16 v[30:33], v[196:199], v[172:175], v[30:33]
	ds_read_b128 v[164:167], v231 offset:6144
	s_mov_b32 m0, s8
	v_mfma_f32_16x16x32_bf16 v[34:37], v[184:187], v[176:179], v[34:37]
	global_load_lds_dwordx4 v200, s[4:5]
	s_add_u32 m0, s8, 0x400
	v_mfma_f32_16x16x32_bf16 v[38:41], v[188:191], v[176:179], v[38:41]
	global_load_lds_dwordx4 v201, s[4:5]
	s_add_u32 m0, s8, 0x800
	v_mfma_f32_16x16x32_bf16 v[42:45], v[192:195], v[176:179], v[42:45]
	global_load_lds_dwordx4 v202, s[4:5]
	s_add_u32 m0, s8, 0xc00
	v_mfma_f32_16x16x32_bf16 v[46:49], v[196:199], v[176:179], v[46:49]
	global_load_lds_dwordx4 v203, s[4:5]
	s_mov_b32 m0, s9
	v_mfma_f32_16x16x32_bf16 v[50:53], v[184:187], v[180:183], v[50:53]
	global_load_lds_dwordx4 v204, s[6:7]
	s_add_u32 m0, s9, 0x400
	v_mfma_f32_16x16x32_bf16 v[54:57], v[188:191], v[180:183], v[54:57]
	global_load_lds_dwordx4 v205, s[6:7]
	v_mfma_f32_16x16x32_bf16 v[58:61], v[192:195], v[180:183], v[58:61]
	s_add_u32 s4, s4, 0x80
	s_addc_u32 s5, s5, 0
	v_mfma_f32_16x16x32_bf16 v[62:65], v[196:199], v[180:183], v[62:65]
	s_add_u32 s6, s6, 0x80
	s_addc_u32 s7, s7, 0
	s_waitcnt lgkmcnt(0)
	v_mfma_f32_16x16x32_bf16 v[2:5], v[152:155], v[136:139], v[2:5]
	ds_read_b128 v[168:171], v228 offset:0
	v_mfma_f32_16x16x32_bf16 v[6:9], v[156:159], v[136:139], v[6:9]
	ds_read_b128 v[172:175], v228 offset:2048
	v_mfma_f32_16x16x32_bf16 v[10:13], v[160:163], v[136:139], v[10:13]
	ds_read_b128 v[176:179], v228 offset:4096
	v_mfma_f32_16x16x32_bf16 v[14:17], v[164:167], v[136:139], v[14:17]
	ds_read_b128 v[180:183], v228 offset:6144
	v_mfma_f32_16x16x32_bf16 v[18:21], v[152:155], v[140:143], v[18:21]
	ds_read_b128 v[184:187], v234 offset:0
	v_mfma_f32_16x16x32_bf16 v[22:25], v[156:159], v[140:143], v[22:25]
	ds_read_b128 v[188:191], v234 offset:2048
	v_mfma_f32_16x16x32_bf16 v[26:29], v[160:163], v[140:143], v[26:29]
	ds_read_b128 v[192:195], v234 offset:4096
	v_mfma_f32_16x16x32_bf16 v[30:33], v[164:167], v[140:143], v[30:33]
	ds_read_b128 v[196:199], v234 offset:6144
	v_mfma_f32_16x16x32_bf16 v[34:37], v[152:155], v[144:147], v[34:37]
	v_mfma_f32_16x16x32_bf16 v[38:41], v[156:159], v[144:147], v[38:41]
	v_mfma_f32_16x16x32_bf16 v[42:45], v[160:163], v[144:147], v[42:45]
	v_mfma_f32_16x16x32_bf16 v[46:49], v[164:167], v[144:147], v[46:49]
	v_mfma_f32_16x16x32_bf16 v[50:53], v[152:155], v[148:151], v[50:53]
	v_mfma_f32_16x16x32_bf16 v[54:57], v[156:159], v[148:151], v[54:57]
	v_mfma_f32_16x16x32_bf16 v[58:61], v[160:163], v[148:151], v[58:61]
	v_mfma_f32_16x16x32_bf16 v[62:65], v[164:167], v[148:151], v[62:65]
	s_waitcnt vmcnt(6) lgkmcnt(0)
	s_barrier
	v_mfma_f32_16x16x32_bf16 v[2:5], v[184:187], v[168:171], v[2:5]
	ds_read_b128 v[136:139], v224 offset:0
	v_mfma_f32_16x16x32_bf16 v[6:9], v[188:191], v[168:171], v[6:9]
	ds_read_b128 v[140:143], v224 offset:2048
	v_mfma_f32_16x16x32_bf16 v[10:13], v[192:195], v[168:171], v[10:13]
	ds_read_b128 v[144:147], v224 offset:4096
	v_mfma_f32_16x16x32_bf16 v[14:17], v[196:199], v[168:171], v[14:17]
	ds_read_b128 v[148:151], v224 offset:6144
	v_mfma_f32_16x16x32_bf16 v[18:21], v[184:187], v[172:175], v[18:21]
	ds_read_b128 v[152:155], v232 offset:0
	v_mfma_f32_16x16x32_bf16 v[22:25], v[188:191], v[172:175], v[22:25]
	ds_read_b128 v[156:159], v232 offset:2048
	v_mfma_f32_16x16x32_bf16 v[26:29], v[192:195], v[172:175], v[26:29]
	ds_read_b128 v[160:163], v232 offset:4096
	v_mfma_f32_16x16x32_bf16 v[30:33], v[196:199], v[172:175], v[30:33]
	ds_read_b128 v[164:167], v232 offset:6144
	s_add_u32 m0, s8, 0xc000
	v_mfma_f32_16x16x32_bf16 v[34:37], v[184:187], v[176:179], v[34:37]
	global_load_lds_dwordx4 v200, s[4:5]
	s_add_u32 m0, s8, 0xc400
	v_mfma_f32_16x16x32_bf16 v[38:41], v[188:191], v[176:179], v[38:41]
	global_load_lds_dwordx4 v201, s[4:5]
	s_add_u32 m0, s8, 0xc800
	v_mfma_f32_16x16x32_bf16 v[42:45], v[192:195], v[176:179], v[42:45]
	global_load_lds_dwordx4 v202, s[4:5]
	s_add_u32 m0, s8, 0xcc00
	v_mfma_f32_16x16x32_bf16 v[46:49], v[196:199], v[176:179], v[46:49]
	global_load_lds_dwordx4 v203, s[4:5]
	s_add_u32 m0, s9, 0xc000
	v_mfma_f32_16x16x32_bf16 v[50:53], v[184:187], v[180:183], v[50:53]
	global_load_lds_dwordx4 v204, s[6:7]
	s_add_u32 m0, s9, 0xc400
	v_mfma_f32_16x16x32_bf16 v[54:57], v[188:191], v[180:183], v[54:57]
	global_load_lds_dwordx4 v205, s[6:7]
	v_mfma_f32_16x16x32_bf16 v[58:61], v[192:195], v[180:183], v[58:61]
	s_add_u32 s4, s4, 0x80
	s_addc_u32 s5, s5, 0
	v_mfma_f32_16x16x32_bf16 v[62:65], v[196:199], v[180:183], v[62:65]
	s_add_u32 s6, s6, 0x80
	s_addc_u32 s7, s7, 0
	s_waitcnt lgkmcnt(0)
	v_mfma_f32_16x16x32_bf16 v[2:5], v[152:155], v[136:139], v[2:5]
	ds_read_b128 v[168:171], v229 offset:0
	v_mfma_f32_16x16x32_bf16 v[6:9], v[156:159], v[136:139], v[6:9]
	ds_read_b128 v[172:175], v229 offset:2048
	v_mfma_f32_16x16x32_bf16 v[10:13], v[160:163], v[136:139], v[10:13]
	ds_read_b128 v[176:179], v229 offset:4096
	v_mfma_f32_16x16x32_bf16 v[14:17], v[164:167], v[136:139], v[14:17]
	ds_read_b128 v[180:183], v229 offset:6144
	v_mfma_f32_16x16x32_bf16 v[18:21], v[152:155], v[140:143], v[18:21]
	ds_read_b128 v[184:187], v235 offset:0
	v_mfma_f32_16x16x32_bf16 v[22:25], v[156:159], v[140:143], v[22:25]
	ds_read_b128 v[188:191], v235 offset:2048
	v_mfma_f32_16x16x32_bf16 v[26:29], v[160:163], v[140:143], v[26:29]
	ds_read_b128 v[192:195], v235 offset:4096
	v_mfma_f32_16x16x32_bf16 v[30:33], v[164:167], v[140:143], v[30:33]
	ds_read_b128 v[196:199], v235 offset:6144
	v_mfma_f32_16x16x32_bf16 v[34:37], v[152:155], v[144:147], v[34:37]
	v_mfma_f32_16x16x32_bf16 v[38:41], v[156:159], v[144:147], v[38:41]
	v_mfma_f32_16x16x32_bf16 v[42:45], v[160:163], v[144:147], v[42:45]
	v_mfma_f32_16x16x32_bf16 v[46:49], v[164:167], v[144:147], v[46:49]
	v_mfma_f32_16x16x32_bf16 v[50:53], v[152:155], v[148:151], v[50:53]
	v_mfma_f32_16x16x32_bf16 v[54:57], v[156:159], v[148:151], v[54:57]
	v_mfma_f32_16x16x32_bf16 v[58:61], v[160:163], v[148:151], v[58:61]
	v_mfma_f32_16x16x32_bf16 v[62:65], v[164:167], v[148:151], v[62:65]
	s_waitcnt vmcnt(6) lgkmcnt(0)
	s_barrier
	v_mfma_f32_16x16x32_bf16 v[2:5], v[184:187], v[168:171], v[2:5]
	ds_read_b128 v[136:139], v218 offset:0
	v_mfma_f32_16x16x32_bf16 v[6:9], v[188:191], v[168:171], v[6:9]
	ds_read_b128 v[140:143], v218 offset:2048
	v_mfma_f32_16x16x32_bf16 v[10:13], v[192:195], v[168:171], v[10:13]
	ds_read_b128 v[144:147], v218 offset:4096
	v_mfma_f32_16x16x32_bf16 v[14:17], v[196:199], v[168:171], v[14:17]
	ds_read_b128 v[148:151], v218 offset:6144
	v_mfma_f32_16x16x32_bf16 v[18:21], v[184:187], v[172:175], v[18:21]
	ds_read_b128 v[152:155], v230 offset:0
	v_mfma_f32_16x16x32_bf16 v[22:25], v[188:191], v[172:175], v[22:25]
	ds_read_b128 v[156:159], v230 offset:2048
	v_mfma_f32_16x16x32_bf16 v[26:29], v[192:195], v[172:175], v[26:29]
	ds_read_b128 v[160:163], v230 offset:4096
	v_mfma_f32_16x16x32_bf16 v[30:33], v[196:199], v[172:175], v[30:33]
	ds_read_b128 v[164:167], v230 offset:6144
	s_add_u32 m0, s8, 0x18000
	v_mfma_f32_16x16x32_bf16 v[34:37], v[184:187], v[176:179], v[34:37]
	global_load_lds_dwordx4 v200, s[4:5]
	s_add_u32 m0, s8, 0x18400
	v_mfma_f32_16x16x32_bf16 v[38:41], v[188:191], v[176:179], v[38:41]
	global_load_lds_dwordx4 v201, s[4:5]
	s_add_u32 m0, s8, 0x18800
	v_mfma_f32_16x16x32_bf16 v[42:45], v[192:195], v[176:179], v[42:45]
	global_load_lds_dwordx4 v202, s[4:5]
	s_add_u32 m0, s8, 0x18c00
	v_mfma_f32_16x16x32_bf16 v[46:49], v[196:199], v[176:179], v[46:49]
	global_load_lds_dwordx4 v203, s[4:5]
	s_add_u32 m0, s9, 0x18000
	v_mfma_f32_16x16x32_bf16 v[50:53], v[184:187], v[180:183], v[50:53]
	global_load_lds_dwordx4 v204, s[6:7]
	s_add_u32 m0, s9, 0x18400
	v_mfma_f32_16x16x32_bf16 v[54:57], v[188:191], v[180:183], v[54:57]
	global_load_lds_dwordx4 v205, s[6:7]
	v_mfma_f32_16x16x32_bf16 v[58:61], v[192:195], v[180:183], v[58:61]
	s_add_u32 s4, s4, 0x80
	s_addc_u32 s5, s5, 0
	v_mfma_f32_16x16x32_bf16 v[62:65], v[196:199], v[180:183], v[62:65]
	s_add_u32 s6, s6, 0x80
	s_addc_u32 s7, s7, 0
	s_waitcnt lgkmcnt(0)
	v_mfma_f32_16x16x32_bf16 v[2:5], v[152:155], v[136:139], v[2:5]
	ds_read_b128 v[168:171], v225 offset:0
	v_mfma_f32_16x16x32_bf16 v[6:9], v[156:159], v[136:139], v[6:9]
	ds_read_b128 v[172:175], v225 offset:2048
	v_mfma_f32_16x16x32_bf16 v[10:13], v[160:163], v[136:139], v[10:13]
	ds_read_b128 v[176:179], v225 offset:4096
	v_mfma_f32_16x16x32_bf16 v[14:17], v[164:167], v[136:139], v[14:17]
	ds_read_b128 v[180:183], v225 offset:6144
	v_mfma_f32_16x16x32_bf16 v[18:21], v[152:155], v[140:143], v[18:21]
	ds_read_b128 v[184:187], v233 offset:0
	v_mfma_f32_16x16x32_bf16 v[22:25], v[156:159], v[140:143], v[22:25]
	ds_read_b128 v[188:191], v233 offset:2048
	v_mfma_f32_16x16x32_bf16 v[26:29], v[160:163], v[140:143], v[26:29]
	ds_read_b128 v[192:195], v233 offset:4096
	v_mfma_f32_16x16x32_bf16 v[30:33], v[164:167], v[140:143], v[30:33]
	ds_read_b128 v[196:199], v233 offset:6144
	v_mfma_f32_16x16x32_bf16 v[34:37], v[152:155], v[144:147], v[34:37]
	v_mfma_f32_16x16x32_bf16 v[38:41], v[156:159], v[144:147], v[38:41]
	v_mfma_f32_16x16x32_bf16 v[42:45], v[160:163], v[144:147], v[42:45]
	v_mfma_f32_16x16x32_bf16 v[46:49], v[164:167], v[144:147], v[46:49]
	v_mfma_f32_16x16x32_bf16 v[50:53], v[152:155], v[148:151], v[50:53]
	v_mfma_f32_16x16x32_bf16 v[54:57], v[156:159], v[148:151], v[54:57]
	v_mfma_f32_16x16x32_bf16 v[58:61], v[160:163], v[148:151], v[58:61]
	v_mfma_f32_16x16x32_bf16 v[62:65], v[164:167], v[148:151], v[62:65]
	s_waitcnt vmcnt(6) lgkmcnt(0)
	s_barrier
	v_mfma_f32_16x16x32_bf16 v[2:5], v[184:187], v[168:171], v[2:5]
	ds_read_b128 v[136:139], v219 offset:0
	v_mfma_f32_16x16x32_bf16 v[6:9], v[188:191], v[168:171], v[6:9]
	ds_read_b128 v[140:143], v219 offset:2048
	v_mfma_f32_16x16x32_bf16 v[10:13], v[192:195], v[168:171], v[10:13]
	ds_read_b128 v[144:147], v219 offset:4096
	v_mfma_f32_16x16x32_bf16 v[14:17], v[196:199], v[168:171], v[14:17]
	ds_read_b128 v[148:151], v219 offset:6144
	v_mfma_f32_16x16x32_bf16 v[18:21], v[184:187], v[172:175], v[18:21]
	ds_read_b128 v[152:155], v231 offset:0
	v_mfma_f32_16x16x32_bf16 v[22:25], v[188:191], v[172:175], v[22:25]
	ds_read_b128 v[156:159], v231 offset:2048
	v_mfma_f32_16x16x32_bf16 v[26:29], v[192:195], v[172:175], v[26:29]
	ds_read_b128 v[160:163], v231 offset:4096
	v_mfma_f32_16x16x32_bf16 v[30:33], v[196:199], v[172:175], v[30:33]
	ds_read_b128 v[164:167], v231 offset:6144
	s_mov_b32 m0, s8
	v_mfma_f32_16x16x32_bf16 v[34:37], v[184:187], v[176:179], v[34:37]
	global_load_lds_dwordx4 v200, s[4:5]
	s_add_u32 m0, s8, 0x400
	v_mfma_f32_16x16x32_bf16 v[38:41], v[188:191], v[176:179], v[38:41]
	global_load_lds_dwordx4 v201, s[4:5]
	s_add_u32 m0, s8, 0x800
	v_mfma_f32_16x16x32_bf16 v[42:45], v[192:195], v[176:179], v[42:45]
	global_load_lds_dwordx4 v202, s[4:5]
	s_add_u32 m0, s8, 0xc00
	v_mfma_f32_16x16x32_bf16 v[46:49], v[196:199], v[176:179], v[46:49]
	global_load_lds_dwordx4 v203, s[4:5]
	s_mov_b32 m0, s9
	v_mfma_f32_16x16x32_bf16 v[50:53], v[184:187], v[180:183], v[50:53]
	global_load_lds_dwordx4 v204, s[6:7]
	s_add_u32 m0, s9, 0x400
	v_mfma_f32_16x16x32_bf16 v[54:57], v[188:191], v[180:183], v[54:57]
	global_load_lds_dwordx4 v205, s[6:7]
	v_mfma_f32_16x16x32_bf16 v[58:61], v[192:195], v[180:183], v[58:61]
	s_sub_u32 s4, s4, 0x780
	s_subb_u32 s5, s5, 0
	v_mfma_f32_16x16x32_bf16 v[62:65], v[196:199], v[180:183], v[62:65]
	s_add_u32 s6, s6, 0x3f880
	s_addc_u32 s7, s7, 0
	s_waitcnt lgkmcnt(0)
	v_mfma_f32_16x16x32_bf16 v[2:5], v[152:155], v[136:139], v[2:5]
	ds_read_b128 v[168:171], v228 offset:0
	v_mfma_f32_16x16x32_bf16 v[6:9], v[156:159], v[136:139], v[6:9]
	ds_read_b128 v[172:175], v228 offset:2048
	v_mfma_f32_16x16x32_bf16 v[10:13], v[160:163], v[136:139], v[10:13]
	ds_read_b128 v[176:179], v228 offset:4096
	v_mfma_f32_16x16x32_bf16 v[14:17], v[164:167], v[136:139], v[14:17]
	ds_read_b128 v[180:183], v228 offset:6144
	v_mfma_f32_16x16x32_bf16 v[18:21], v[152:155], v[140:143], v[18:21]
	ds_read_b128 v[184:187], v234 offset:0
	v_mfma_f32_16x16x32_bf16 v[22:25], v[156:159], v[140:143], v[22:25]
	ds_read_b128 v[188:191], v234 offset:2048
	v_mfma_f32_16x16x32_bf16 v[26:29], v[160:163], v[140:143], v[26:29]
	ds_read_b128 v[192:195], v234 offset:4096
	v_mfma_f32_16x16x32_bf16 v[30:33], v[164:167], v[140:143], v[30:33]
	ds_read_b128 v[196:199], v234 offset:6144
	v_mfma_f32_16x16x32_bf16 v[34:37], v[152:155], v[144:147], v[34:37]
	v_mfma_f32_16x16x32_bf16 v[38:41], v[156:159], v[144:147], v[38:41]
	v_mfma_f32_16x16x32_bf16 v[42:45], v[160:163], v[144:147], v[42:45]
	v_mfma_f32_16x16x32_bf16 v[46:49], v[164:167], v[144:147], v[46:49]
	v_mfma_f32_16x16x32_bf16 v[50:53], v[152:155], v[148:151], v[50:53]
	v_mfma_f32_16x16x32_bf16 v[54:57], v[156:159], v[148:151], v[54:57]
	v_mfma_f32_16x16x32_bf16 v[58:61], v[160:163], v[148:151], v[58:61]
	v_mfma_f32_16x16x32_bf16 v[62:65], v[164:167], v[148:151], v[62:65]
	s_waitcnt vmcnt(6) lgkmcnt(0)
	s_barrier
	v_mfma_f32_16x16x32_bf16 v[2:5], v[184:187], v[168:171], v[2:5]
	ds_read_b128 v[136:139], v224 offset:0
	v_mfma_f32_16x16x32_bf16 v[6:9], v[188:191], v[168:171], v[6:9]
	ds_read_b128 v[140:143], v224 offset:2048
	v_mfma_f32_16x16x32_bf16 v[10:13], v[192:195], v[168:171], v[10:13]
	ds_read_b128 v[144:147], v224 offset:4096
	v_mfma_f32_16x16x32_bf16 v[14:17], v[196:199], v[168:171], v[14:17]
	ds_read_b128 v[148:151], v224 offset:6144
	v_mfma_f32_16x16x32_bf16 v[18:21], v[184:187], v[172:175], v[18:21]
	ds_read_b128 v[152:155], v232 offset:0
	v_mfma_f32_16x16x32_bf16 v[22:25], v[188:191], v[172:175], v[22:25]
	ds_read_b128 v[156:159], v232 offset:2048
	v_mfma_f32_16x16x32_bf16 v[26:29], v[192:195], v[172:175], v[26:29]
	ds_read_b128 v[160:163], v232 offset:4096
	v_mfma_f32_16x16x32_bf16 v[30:33], v[196:199], v[172:175], v[30:33]
	ds_read_b128 v[164:167], v232 offset:6144
	s_add_u32 m0, s8, 0xc000
	v_mfma_f32_16x16x32_bf16 v[34:37], v[184:187], v[176:179], v[34:37]
	global_load_lds_dwordx4 v200, s[4:5]
	s_add_u32 m0, s8, 0xc400
	v_mfma_f32_16x16x32_bf16 v[38:41], v[188:191], v[176:179], v[38:41]
	global_load_lds_dwordx4 v201, s[4:5]
	s_add_u32 m0, s8, 0xc800
	v_mfma_f32_16x16x32_bf16 v[42:45], v[192:195], v[176:179], v[42:45]
	global_load_lds_dwordx4 v202, s[4:5]
	s_add_u32 m0, s8, 0xcc00
	v_mfma_f32_16x16x32_bf16 v[46:49], v[196:199], v[176:179], v[46:49]
	global_load_lds_dwordx4 v203, s[4:5]
	s_add_u32 m0, s9, 0xc000
	v_mfma_f32_16x16x32_bf16 v[50:53], v[184:187], v[180:183], v[50:53]
	global_load_lds_dwordx4 v204, s[6:7]
	s_add_u32 m0, s9, 0xc400
	v_mfma_f32_16x16x32_bf16 v[54:57], v[188:191], v[180:183], v[54:57]
	global_load_lds_dwordx4 v205, s[6:7]
	v_mfma_f32_16x16x32_bf16 v[58:61], v[192:195], v[180:183], v[58:61]
	s_add_u32 s4, s4, 0x80
	s_addc_u32 s5, s5, 0
	v_mfma_f32_16x16x32_bf16 v[62:65], v[196:199], v[180:183], v[62:65]
	s_add_u32 s6, s6, 0x80
	s_addc_u32 s7, s7, 0
	s_waitcnt lgkmcnt(0)
	v_mfma_f32_16x16x32_bf16 v[2:5], v[152:155], v[136:139], v[2:5]
	ds_read_b128 v[168:171], v229 offset:0
	v_mfma_f32_16x16x32_bf16 v[6:9], v[156:159], v[136:139], v[6:9]
	ds_read_b128 v[172:175], v229 offset:2048
	v_mfma_f32_16x16x32_bf16 v[10:13], v[160:163], v[136:139], v[10:13]
	ds_read_b128 v[176:179], v229 offset:4096
	v_mfma_f32_16x16x32_bf16 v[14:17], v[164:167], v[136:139], v[14:17]
	ds_read_b128 v[180:183], v229 offset:6144
	v_mfma_f32_16x16x32_bf16 v[18:21], v[152:155], v[140:143], v[18:21]
	ds_read_b128 v[184:187], v235 offset:0
	v_mfma_f32_16x16x32_bf16 v[22:25], v[156:159], v[140:143], v[22:25]
	ds_read_b128 v[188:191], v235 offset:2048
	v_mfma_f32_16x16x32_bf16 v[26:29], v[160:163], v[140:143], v[26:29]
	ds_read_b128 v[192:195], v235 offset:4096
	v_mfma_f32_16x16x32_bf16 v[30:33], v[164:167], v[140:143], v[30:33]
	ds_read_b128 v[196:199], v235 offset:6144
	v_mfma_f32_16x16x32_bf16 v[34:37], v[152:155], v[144:147], v[34:37]
	v_mfma_f32_16x16x32_bf16 v[38:41], v[156:159], v[144:147], v[38:41]
	v_mfma_f32_16x16x32_bf16 v[42:45], v[160:163], v[144:147], v[42:45]
	v_mfma_f32_16x16x32_bf16 v[46:49], v[164:167], v[144:147], v[46:49]
	v_mfma_f32_16x16x32_bf16 v[50:53], v[152:155], v[148:151], v[50:53]
	v_mfma_f32_16x16x32_bf16 v[54:57], v[156:159], v[148:151], v[54:57]
	v_mfma_f32_16x16x32_bf16 v[58:61], v[160:163], v[148:151], v[58:61]
	v_mfma_f32_16x16x32_bf16 v[62:65], v[164:167], v[148:151], v[62:65]
	s_waitcnt vmcnt(6) lgkmcnt(0)
	s_barrier
	v_mfma_f32_16x16x32_bf16 v[2:5], v[184:187], v[168:171], v[2:5]
	ds_read_b128 v[136:139], v218 offset:0
	v_mfma_f32_16x16x32_bf16 v[6:9], v[188:191], v[168:171], v[6:9]
	ds_read_b128 v[140:143], v218 offset:2048
	v_mfma_f32_16x16x32_bf16 v[10:13], v[192:195], v[168:171], v[10:13]
	ds_read_b128 v[144:147], v218 offset:4096
	v_mfma_f32_16x16x32_bf16 v[14:17], v[196:199], v[168:171], v[14:17]
	ds_read_b128 v[148:151], v218 offset:6144
	v_mfma_f32_16x16x32_bf16 v[18:21], v[184:187], v[172:175], v[18:21]
	ds_read_b128 v[152:155], v230 offset:0
	v_mfma_f32_16x16x32_bf16 v[22:25], v[188:191], v[172:175], v[22:25]
	ds_read_b128 v[156:159], v230 offset:2048
	v_mfma_f32_16x16x32_bf16 v[26:29], v[192:195], v[172:175], v[26:29]
	ds_read_b128 v[160:163], v230 offset:4096
	v_mfma_f32_16x16x32_bf16 v[30:33], v[196:199], v[172:175], v[30:33]
	ds_read_b128 v[164:167], v230 offset:6144
	s_add_u32 m0, s8, 0x18000
	v_mfma_f32_16x16x32_bf16 v[34:37], v[184:187], v[176:179], v[34:37]
	global_load_lds_dwordx4 v200, s[4:5]
	s_add_u32 m0, s8, 0x18400
	v_mfma_f32_16x16x32_bf16 v[38:41], v[188:191], v[176:179], v[38:41]
	global_load_lds_dwordx4 v201, s[4:5]
	s_add_u32 m0, s8, 0x18800
	v_mfma_f32_16x16x32_bf16 v[42:45], v[192:195], v[176:179], v[42:45]
	global_load_lds_dwordx4 v202, s[4:5]
	s_add_u32 m0, s8, 0x18c00
	v_mfma_f32_16x16x32_bf16 v[46:49], v[196:199], v[176:179], v[46:49]
	global_load_lds_dwordx4 v203, s[4:5]
	s_add_u32 m0, s9, 0x18000
	v_mfma_f32_16x16x32_bf16 v[50:53], v[184:187], v[180:183], v[50:53]
	global_load_lds_dwordx4 v204, s[6:7]
	s_add_u32 m0, s9, 0x18400
	v_mfma_f32_16x16x32_bf16 v[54:57], v[188:191], v[180:183], v[54:57]
	global_load_lds_dwordx4 v205, s[6:7]
	v_mfma_f32_16x16x32_bf16 v[58:61], v[192:195], v[180:183], v[58:61]
	s_add_u32 s4, s4, 0x80
	s_addc_u32 s5, s5, 0
	v_mfma_f32_16x16x32_bf16 v[62:65], v[196:199], v[180:183], v[62:65]
	s_add_u32 s6, s6, 0x80
	s_addc_u32 s7, s7, 0
	s_waitcnt lgkmcnt(0)
	v_mfma_f32_16x16x32_bf16 v[2:5], v[152:155], v[136:139], v[2:5]
	ds_read_b128 v[168:171], v225 offset:0
	v_mfma_f32_16x16x32_bf16 v[6:9], v[156:159], v[136:139], v[6:9]
	ds_read_b128 v[172:175], v225 offset:2048
	v_mfma_f32_16x16x32_bf16 v[10:13], v[160:163], v[136:139], v[10:13]
	ds_read_b128 v[176:179], v225 offset:4096
	v_mfma_f32_16x16x32_bf16 v[14:17], v[164:167], v[136:139], v[14:17]
	ds_read_b128 v[180:183], v225 offset:6144
	v_mfma_f32_16x16x32_bf16 v[18:21], v[152:155], v[140:143], v[18:21]
	ds_read_b128 v[184:187], v233 offset:0
	v_mfma_f32_16x16x32_bf16 v[22:25], v[156:159], v[140:143], v[22:25]
	ds_read_b128 v[188:191], v233 offset:2048
	v_mfma_f32_16x16x32_bf16 v[26:29], v[160:163], v[140:143], v[26:29]
	ds_read_b128 v[192:195], v233 offset:4096
	v_mfma_f32_16x16x32_bf16 v[30:33], v[164:167], v[140:143], v[30:33]
	ds_read_b128 v[196:199], v233 offset:6144
	v_mfma_f32_16x16x32_bf16 v[34:37], v[152:155], v[144:147], v[34:37]
	v_mfma_f32_16x16x32_bf16 v[38:41], v[156:159], v[144:147], v[38:41]
	v_mfma_f32_16x16x32_bf16 v[42:45], v[160:163], v[144:147], v[42:45]
	v_mfma_f32_16x16x32_bf16 v[46:49], v[164:167], v[144:147], v[46:49]
	v_mfma_f32_16x16x32_bf16 v[50:53], v[152:155], v[148:151], v[50:53]
	v_mfma_f32_16x16x32_bf16 v[54:57], v[156:159], v[148:151], v[54:57]
	v_mfma_f32_16x16x32_bf16 v[58:61], v[160:163], v[148:151], v[58:61]
	v_mfma_f32_16x16x32_bf16 v[62:65], v[164:167], v[148:151], v[62:65]
	s_waitcnt vmcnt(6) lgkmcnt(0)
	s_barrier
	v_mfma_f32_16x16x32_bf16 v[2:5], v[184:187], v[168:171], v[2:5]
	ds_read_b128 v[136:139], v219 offset:0
	v_mfma_f32_16x16x32_bf16 v[6:9], v[188:191], v[168:171], v[6:9]
	ds_read_b128 v[140:143], v219 offset:2048
	v_mfma_f32_16x16x32_bf16 v[10:13], v[192:195], v[168:171], v[10:13]
	ds_read_b128 v[144:147], v219 offset:4096
	v_mfma_f32_16x16x32_bf16 v[14:17], v[196:199], v[168:171], v[14:17]
	ds_read_b128 v[148:151], v219 offset:6144
	v_mfma_f32_16x16x32_bf16 v[18:21], v[184:187], v[172:175], v[18:21]
	ds_read_b128 v[152:155], v231 offset:0
	v_mfma_f32_16x16x32_bf16 v[22:25], v[188:191], v[172:175], v[22:25]
	ds_read_b128 v[156:159], v231 offset:2048
	v_mfma_f32_16x16x32_bf16 v[26:29], v[192:195], v[172:175], v[26:29]
	ds_read_b128 v[160:163], v231 offset:4096
	v_mfma_f32_16x16x32_bf16 v[30:33], v[196:199], v[172:175], v[30:33]
	ds_read_b128 v[164:167], v231 offset:6144
	s_mov_b32 m0, s8
	v_mfma_f32_16x16x32_bf16 v[34:37], v[184:187], v[176:179], v[34:37]
	global_load_lds_dwordx4 v200, s[4:5]
	s_add_u32 m0, s8, 0x400
	v_mfma_f32_16x16x32_bf16 v[38:41], v[188:191], v[176:179], v[38:41]
	global_load_lds_dwordx4 v201, s[4:5]
	s_add_u32 m0, s8, 0x800
	v_mfma_f32_16x16x32_bf16 v[42:45], v[192:195], v[176:179], v[42:45]
	global_load_lds_dwordx4 v202, s[4:5]
	s_add_u32 m0, s8, 0xc00
	v_mfma_f32_16x16x32_bf16 v[46:49], v[196:199], v[176:179], v[46:49]
	global_load_lds_dwordx4 v203, s[4:5]
	s_mov_b32 m0, s9
	v_mfma_f32_16x16x32_bf16 v[50:53], v[184:187], v[180:183], v[50:53]
	global_load_lds_dwordx4 v204, s[6:7]
	s_add_u32 m0, s9, 0x400
	v_mfma_f32_16x16x32_bf16 v[54:57], v[188:191], v[180:183], v[54:57]
	global_load_lds_dwordx4 v205, s[6:7]
	v_mfma_f32_16x16x32_bf16 v[58:61], v[192:195], v[180:183], v[58:61]
	s_add_u32 s4, s4, 0x80
	s_addc_u32 s5, s5, 0
	v_mfma_f32_16x16x32_bf16 v[62:65], v[196:199], v[180:183], v[62:65]
	s_add_u32 s6, s6, 0x80
	s_addc_u32 s7, s7, 0
	s_waitcnt lgkmcnt(0)
	v_mfma_f32_16x16x32_bf16 v[66:69], v[152:155], v[136:139], 0
	ds_read_b128 v[168:171], v228 offset:0
	v_mfma_f32_16x16x32_bf16 v[70:73], v[156:159], v[136:139], 0
	ds_read_b128 v[172:175], v228 offset:2048
	s_add_u32 s10, s52, 0x0
	s_addc_u32 s11, s53, 0
	v_mfma_f32_16x16x32_bf16 v[74:77], v[160:163], v[136:139], 0
	ds_read_b128 v[176:179], v228 offset:4096
	v_mul_f32_e32 v1, s12, v2
	v_mfma_f32_16x16x32_bf16 v[78:81], v[164:167], v[136:139], 0
	ds_read_b128 v[180:183], v228 offset:6144
	v_mul_f32_e32 v130, s12, v3
	v_mfma_f32_16x16x32_bf16 v[82:85], v[152:155], v[140:143], 0
	ds_read_b128 v[184:187], v234 offset:0
	v_mul_f32_e32 v238, s12, v4
	v_mfma_f32_16x16x32_bf16 v[86:89], v[156:159], v[140:143], 0
	ds_read_b128 v[188:191], v234 offset:2048
	v_mul_f32_e32 v239, s12, v5
	v_mfma_f32_16x16x32_bf16 v[90:93], v[160:163], v[140:143], 0
	ds_read_b128 v[192:195], v234 offset:4096
	v_exp_f32_e32 v1, v1
	v_mfma_f32_16x16x32_bf16 v[94:97], v[164:167], v[140:143], 0
	ds_read_b128 v[196:199], v234 offset:6144
	v_exp_f32_e32 v130, v130
	v_mfma_f32_16x16x32_bf16 v[98:101], v[152:155], v[144:147], 0
	v_mfma_f32_16x16x32_bf16 v[102:105], v[156:159], v[144:147], 0
	v_exp_f32_e32 v238, v238
	v_mfma_f32_16x16x32_bf16 v[106:109], v[160:163], v[144:147], 0
	v_exp_f32_e32 v239, v239
	v_mfma_f32_16x16x32_bf16 v[110:113], v[164:167], v[144:147], 0
	v_add_f32_e32 v1, 1.0, v1
	v_mfma_f32_16x16x32_bf16 v[114:117], v[152:155], v[148:151], 0
	v_add_f32_e32 v130, 1.0, v130
	v_mfma_f32_16x16x32_bf16 v[118:121], v[156:159], v[148:151], 0
	v_add_f32_e32 v238, 1.0, v238
	v_mfma_f32_16x16x32_bf16 v[122:125], v[160:163], v[148:151], 0
	v_add_f32_e32 v239, 1.0, v239
	v_mfma_f32_16x16x32_bf16 v[126:129], v[164:167], v[148:151], 0
	v_rcp_f32_e32 v1, v1
	s_waitcnt vmcnt(6) lgkmcnt(0)
	s_barrier
	v_mfma_f32_16x16x32_bf16 v[66:69], v[184:187], v[168:171], v[66:69]
	ds_read_b128 v[136:139], v224 offset:0
	v_mfma_f32_16x16x32_bf16 v[70:73], v[188:191], v[168:171], v[70:73]
	ds_read_b128 v[140:143], v224 offset:2048
	v_rcp_f32_e32 v130, v130
	v_mfma_f32_16x16x32_bf16 v[74:77], v[192:195], v[168:171], v[74:77]
	ds_read_b128 v[144:147], v224 offset:4096
	v_mfma_f32_16x16x32_bf16 v[78:81], v[196:199], v[168:171], v[78:81]
	ds_read_b128 v[148:151], v224 offset:6144
	v_rcp_f32_e32 v238, v238
	v_mfma_f32_16x16x32_bf16 v[82:85], v[184:187], v[172:175], v[82:85]
	ds_read_b128 v[152:155], v232 offset:0
	v_rcp_f32_e32 v239, v239
	v_mfma_f32_16x16x32_bf16 v[86:89], v[188:191], v[172:175], v[86:89]
	ds_read_b128 v[156:159], v232 offset:2048
	v_mfma_f32_16x16x32_bf16 v[90:93], v[192:195], v[172:175], v[90:93]
	ds_read_b128 v[160:163], v232 offset:4096
	v_mul_f32_e32 v2, v2, v1
	v_mfma_f32_16x16x32_bf16 v[94:97], v[196:199], v[172:175], v[94:97]
	ds_read_b128 v[164:167], v232 offset:6144
	v_mul_f32_e32 v3, v3, v130
	s_add_u32 m0, s8, 0xc000
	v_mfma_f32_16x16x32_bf16 v[98:101], v[184:187], v[176:179], v[98:101]
	global_load_lds_dwordx4 v200, s[4:5]
	s_add_u32 m0, s8, 0xc400
	v_mfma_f32_16x16x32_bf16 v[102:105], v[188:191], v[176:179], v[102:105]
	global_load_lds_dwordx4 v201, s[4:5]
	v_mul_f32_e32 v4, v4, v238
	s_add_u32 m0, s8, 0xc800
	v_mfma_f32_16x16x32_bf16 v[106:109], v[192:195], v[176:179], v[106:109]
	global_load_lds_dwordx4 v202, s[4:5]
	s_add_u32 m0, s8, 0xcc00
	v_mfma_f32_16x16x32_bf16 v[110:113], v[196:199], v[176:179], v[110:113]
	global_load_lds_dwordx4 v203, s[4:5]
	v_mul_f32_e32 v5, v5, v239
	s_add_u32 m0, s9, 0xc000
	v_mfma_f32_16x16x32_bf16 v[114:117], v[184:187], v[180:183], v[114:117]
	global_load_lds_dwordx4 v204, s[6:7]
	v_cvt_pk_bf16_f32 v2, v2, v3
	s_add_u32 m0, s9, 0xc400
	v_mfma_f32_16x16x32_bf16 v[118:121], v[188:191], v[180:183], v[118:121]
	global_load_lds_dwordx4 v205, s[6:7]
	v_mfma_f32_16x16x32_bf16 v[122:125], v[192:195], v[180:183], v[122:125]
	s_add_u32 s4, s4, 0x80
	s_addc_u32 s5, s5, 0
	v_cvt_pk_bf16_f32 v3, v4, v5
	v_mfma_f32_16x16x32_bf16 v[126:129], v[196:199], v[180:183], v[126:129]
	s_add_u32 s6, s6, 0x80
	s_addc_u32 s7, s7, 0
	global_store_dwordx2 v236, v[2:3], s[10:11] offset:0 sc1
	s_waitcnt lgkmcnt(0)
	v_mfma_f32_16x16x32_bf16 v[66:69], v[152:155], v[136:139], v[66:69]
	ds_read_b128 v[168:171], v229 offset:0
	v_mfma_f32_16x16x32_bf16 v[70:73], v[156:159], v[136:139], v[70:73]
	ds_read_b128 v[172:175], v229 offset:2048
	v_mul_f32_e32 v1, s12, v6
	v_mfma_f32_16x16x32_bf16 v[74:77], v[160:163], v[136:139], v[74:77]
	ds_read_b128 v[176:179], v229 offset:4096
	v_mul_f32_e32 v130, s12, v7
	v_mfma_f32_16x16x32_bf16 v[78:81], v[164:167], v[136:139], v[78:81]
	ds_read_b128 v[180:183], v229 offset:6144
	v_mul_f32_e32 v238, s12, v8
	v_mfma_f32_16x16x32_bf16 v[82:85], v[152:155], v[140:143], v[82:85]
	ds_read_b128 v[184:187], v235 offset:0
	v_mul_f32_e32 v239, s12, v9
	v_mfma_f32_16x16x32_bf16 v[86:89], v[156:159], v[140:143], v[86:89]
	ds_read_b128 v[188:191], v235 offset:2048
	v_exp_f32_e32 v1, v1
	v_mfma_f32_16x16x32_bf16 v[90:93], v[160:163], v[140:143], v[90:93]
	ds_read_b128 v[192:195], v235 offset:4096
	v_exp_f32_e32 v130, v130
	v_mfma_f32_16x16x32_bf16 v[94:97], v[164:167], v[140:143], v[94:97]
	ds_read_b128 v[196:199], v235 offset:6144
	v_exp_f32_e32 v238, v238
	v_mfma_f32_16x16x32_bf16 v[98:101], v[152:155], v[144:147], v[98:101]
	v_mfma_f32_16x16x32_bf16 v[102:105], v[156:159], v[144:147], v[102:105]
	v_exp_f32_e32 v239, v239
	v_mfma_f32_16x16x32_bf16 v[106:109], v[160:163], v[144:147], v[106:109]
	v_add_f32_e32 v1, 1.0, v1
	v_mfma_f32_16x16x32_bf16 v[110:113], v[164:167], v[144:147], v[110:113]
	v_add_f32_e32 v130, 1.0, v130
	v_mfma_f32_16x16x32_bf16 v[114:117], v[152:155], v[148:151], v[114:117]
	v_add_f32_e32 v238, 1.0, v238
	v_mfma_f32_16x16x32_bf16 v[118:121], v[156:159], v[148:151], v[118:121]
	v_add_f32_e32 v239, 1.0, v239
	v_mfma_f32_16x16x32_bf16 v[122:125], v[160:163], v[148:151], v[122:125]
	v_rcp_f32_e32 v1, v1
	v_mfma_f32_16x16x32_bf16 v[126:129], v[164:167], v[148:151], v[126:129]
	v_rcp_f32_e32 v130, v130
	s_waitcnt vmcnt(7) lgkmcnt(0)
	s_barrier
	v_mfma_f32_16x16x32_bf16 v[66:69], v[184:187], v[168:171], v[66:69]
	ds_read_b128 v[136:139], v218 offset:0
	v_mfma_f32_16x16x32_bf16 v[70:73], v[188:191], v[168:171], v[70:73]
	ds_read_b128 v[140:143], v218 offset:2048
	v_rcp_f32_e32 v238, v238
	v_mfma_f32_16x16x32_bf16 v[74:77], v[192:195], v[168:171], v[74:77]
	ds_read_b128 v[144:147], v218 offset:4096
	v_mfma_f32_16x16x32_bf16 v[78:81], v[196:199], v[168:171], v[78:81]
	ds_read_b128 v[148:151], v218 offset:6144
	v_rcp_f32_e32 v239, v239
	v_mfma_f32_16x16x32_bf16 v[82:85], v[184:187], v[172:175], v[82:85]
	ds_read_b128 v[152:155], v230 offset:0
	v_mul_f32_e32 v6, v6, v1
	v_mfma_f32_16x16x32_bf16 v[86:89], v[188:191], v[172:175], v[86:89]
	ds_read_b128 v[156:159], v230 offset:2048
	v_mfma_f32_16x16x32_bf16 v[90:93], v[192:195], v[172:175], v[90:93]
	ds_read_b128 v[160:163], v230 offset:4096
	v_mul_f32_e32 v7, v7, v130
	v_mfma_f32_16x16x32_bf16 v[94:97], v[196:199], v[172:175], v[94:97]
	ds_read_b128 v[164:167], v230 offset:6144
	v_mul_f32_e32 v8, v8, v238
	s_add_u32 m0, s8, 0x18000
	v_mfma_f32_16x16x32_bf16 v[98:101], v[184:187], v[176:179], v[98:101]
	global_load_lds_dwordx4 v200, s[4:5]
	s_add_u32 m0, s8, 0x18400
	v_mfma_f32_16x16x32_bf16 v[102:105], v[188:191], v[176:179], v[102:105]
	global_load_lds_dwordx4 v201, s[4:5]
	v_mul_f32_e32 v9, v9, v239
	s_add_u32 m0, s8, 0x18800
	v_mfma_f32_16x16x32_bf16 v[106:109], v[192:195], v[176:179], v[106:109]
	global_load_lds_dwordx4 v202, s[4:5]
	s_add_u32 m0, s8, 0x18c00
	v_mfma_f32_16x16x32_bf16 v[110:113], v[196:199], v[176:179], v[110:113]
	global_load_lds_dwordx4 v203, s[4:5]
	v_cvt_pk_bf16_f32 v6, v6, v7
	s_add_u32 m0, s9, 0x18000
	v_mfma_f32_16x16x32_bf16 v[114:117], v[184:187], v[180:183], v[114:117]
	global_load_lds_dwordx4 v204, s[6:7]
	v_cvt_pk_bf16_f32 v7, v8, v9
	s_add_u32 m0, s9, 0x18400
	v_mfma_f32_16x16x32_bf16 v[118:121], v[188:191], v[180:183], v[118:121]
	global_load_lds_dwordx4 v205, s[6:7]
	v_mfma_f32_16x16x32_bf16 v[122:125], v[192:195], v[180:183], v[122:125]
	s_add_u32 s4, s4, 0x80
	s_addc_u32 s5, s5, 0
	global_store_dwordx2 v236, v[6:7], s[10:11] offset:32 sc1
	v_mfma_f32_16x16x32_bf16 v[126:129], v[196:199], v[180:183], v[126:129]
	s_add_u32 s6, s6, 0x80
	s_addc_u32 s7, s7, 0
	v_mul_f32_e32 v1, s12, v10
	s_waitcnt lgkmcnt(0)
	v_mfma_f32_16x16x32_bf16 v[66:69], v[152:155], v[136:139], v[66:69]
	ds_read_b128 v[168:171], v225 offset:0
	v_mfma_f32_16x16x32_bf16 v[70:73], v[156:159], v[136:139], v[70:73]
	ds_read_b128 v[172:175], v225 offset:2048
	v_mul_f32_e32 v130, s12, v11
	v_mfma_f32_16x16x32_bf16 v[74:77], v[160:163], v[136:139], v[74:77]
	ds_read_b128 v[176:179], v225 offset:4096
	v_mul_f32_e32 v238, s12, v12
	v_mfma_f32_16x16x32_bf16 v[78:81], v[164:167], v[136:139], v[78:81]
	ds_read_b128 v[180:183], v225 offset:6144
	v_mul_f32_e32 v239, s12, v13
	v_mfma_f32_16x16x32_bf16 v[82:85], v[152:155], v[140:143], v[82:85]
	ds_read_b128 v[184:187], v233 offset:0
	v_exp_f32_e32 v1, v1
	v_mfma_f32_16x16x32_bf16 v[86:89], v[156:159], v[140:143], v[86:89]
	ds_read_b128 v[188:191], v233 offset:2048
	v_exp_f32_e32 v130, v130
	v_mfma_f32_16x16x32_bf16 v[90:93], v[160:163], v[140:143], v[90:93]
	ds_read_b128 v[192:195], v233 offset:4096
	v_exp_f32_e32 v238, v238
	v_mfma_f32_16x16x32_bf16 v[94:97], v[164:167], v[140:143], v[94:97]
	ds_read_b128 v[196:199], v233 offset:6144
	v_exp_f32_e32 v239, v239
	v_mfma_f32_16x16x32_bf16 v[98:101], v[152:155], v[144:147], v[98:101]
	v_mfma_f32_16x16x32_bf16 v[102:105], v[156:159], v[144:147], v[102:105]
	v_add_f32_e32 v1, 1.0, v1
	v_mfma_f32_16x16x32_bf16 v[106:109], v[160:163], v[144:147], v[106:109]
	v_add_f32_e32 v130, 1.0, v130
	v_mfma_f32_16x16x32_bf16 v[110:113], v[164:167], v[144:147], v[110:113]
	v_add_f32_e32 v238, 1.0, v238
	v_mfma_f32_16x16x32_bf16 v[114:117], v[152:155], v[148:151], v[114:117]
	v_add_f32_e32 v239, 1.0, v239
	v_mfma_f32_16x16x32_bf16 v[118:121], v[156:159], v[148:151], v[118:121]
	v_rcp_f32_e32 v1, v1
	v_mfma_f32_16x16x32_bf16 v[122:125], v[160:163], v[148:151], v[122:125]
	v_rcp_f32_e32 v130, v130
	v_mfma_f32_16x16x32_bf16 v[126:129], v[164:167], v[148:151], v[126:129]
	v_rcp_f32_e32 v238, v238
	s_waitcnt vmcnt(8) lgkmcnt(0)
	s_barrier
	v_mfma_f32_16x16x32_bf16 v[66:69], v[184:187], v[168:171], v[66:69]
	ds_read_b128 v[136:139], v219 offset:0
	v_mfma_f32_16x16x32_bf16 v[70:73], v[188:191], v[168:171], v[70:73]
	ds_read_b128 v[140:143], v219 offset:2048
	v_rcp_f32_e32 v239, v239
	v_mfma_f32_16x16x32_bf16 v[74:77], v[192:195], v[168:171], v[74:77]
	ds_read_b128 v[144:147], v219 offset:4096
	v_mfma_f32_16x16x32_bf16 v[78:81], v[196:199], v[168:171], v[78:81]
	ds_read_b128 v[148:151], v219 offset:6144
	v_mul_f32_e32 v10, v10, v1
	v_mfma_f32_16x16x32_bf16 v[82:85], v[184:187], v[172:175], v[82:85]
	ds_read_b128 v[152:155], v231 offset:0
	v_mul_f32_e32 v11, v11, v130
	v_mfma_f32_16x16x32_bf16 v[86:89], v[188:191], v[172:175], v[86:89]
	ds_read_b128 v[156:159], v231 offset:2048
	v_mfma_f32_16x16x32_bf16 v[90:93], v[192:195], v[172:175], v[90:93]
	ds_read_b128 v[160:163], v231 offset:4096
	v_mul_f32_e32 v12, v12, v238
	v_mfma_f32_16x16x32_bf16 v[94:97], v[196:199], v[172:175], v[94:97]
	ds_read_b128 v[164:167], v231 offset:6144
	v_mul_f32_e32 v13, v13, v239
	s_mov_b32 m0, s8
	v_mfma_f32_16x16x32_bf16 v[98:101], v[184:187], v[176:179], v[98:101]
	global_load_lds_dwordx4 v200, s[4:5]
	s_add_u32 m0, s8, 0x400
	v_mfma_f32_16x16x32_bf16 v[102:105], v[188:191], v[176:179], v[102:105]
	global_load_lds_dwordx4 v201, s[4:5]
	v_cvt_pk_bf16_f32 v10, v10, v11
	s_add_u32 m0, s8, 0x800
	v_mfma_f32_16x16x32_bf16 v[106:109], v[192:195], v[176:179], v[106:109]
	global_load_lds_dwordx4 v202, s[4:5]
	s_add_u32 m0, s8, 0xc00
	v_mfma_f32_16x16x32_bf16 v[110:113], v[196:199], v[176:179], v[110:113]
	global_load_lds_dwordx4 v203, s[4:5]
	v_cvt_pk_bf16_f32 v11, v12, v13
	s_mov_b32 m0, s9
	v_mfma_f32_16x16x32_bf16 v[114:117], v[184:187], v[180:183], v[114:117]
	global_load_lds_dwordx4 v204, s[6:7]
	global_store_dwordx2 v236, v[10:11], s[10:11] offset:64 sc1
	s_add_u32 m0, s9, 0x400
	v_mfma_f32_16x16x32_bf16 v[118:121], v[188:191], v[180:183], v[118:121]
	global_load_lds_dwordx4 v205, s[6:7]
	v_mfma_f32_16x16x32_bf16 v[122:125], v[192:195], v[180:183], v[122:125]
	s_add_u32 s4, s4, 0x80
	s_addc_u32 s5, s5, 0
	v_mul_f32_e32 v1, s12, v14
	v_mfma_f32_16x16x32_bf16 v[126:129], v[196:199], v[180:183], v[126:129]
	s_add_u32 s6, s6, 0x80
	s_addc_u32 s7, s7, 0
	v_mul_f32_e32 v130, s12, v15
	s_waitcnt lgkmcnt(0)
	v_mfma_f32_16x16x32_bf16 v[66:69], v[152:155], v[136:139], v[66:69]
	ds_read_b128 v[168:171], v228 offset:0
	v_mfma_f32_16x16x32_bf16 v[70:73], v[156:159], v[136:139], v[70:73]
	ds_read_b128 v[172:175], v228 offset:2048
	v_mul_f32_e32 v238, s12, v16
	v_mfma_f32_16x16x32_bf16 v[74:77], v[160:163], v[136:139], v[74:77]
	ds_read_b128 v[176:179], v228 offset:4096
	v_mul_f32_e32 v239, s12, v17
	v_mfma_f32_16x16x32_bf16 v[78:81], v[164:167], v[136:139], v[78:81]
	ds_read_b128 v[180:183], v228 offset:6144
	v_exp_f32_e32 v1, v1
	v_mfma_f32_16x16x32_bf16 v[82:85], v[152:155], v[140:143], v[82:85]
	ds_read_b128 v[184:187], v234 offset:0
	v_exp_f32_e32 v130, v130
	v_mfma_f32_16x16x32_bf16 v[86:89], v[156:159], v[140:143], v[86:89]
	ds_read_b128 v[188:191], v234 offset:2048
	v_exp_f32_e32 v238, v238
	v_mfma_f32_16x16x32_bf16 v[90:93], v[160:163], v[140:143], v[90:93]
	ds_read_b128 v[192:195], v234 offset:4096
	v_exp_f32_e32 v239, v239
	v_mfma_f32_16x16x32_bf16 v[94:97], v[164:167], v[140:143], v[94:97]
	ds_read_b128 v[196:199], v234 offset:6144
	v_add_f32_e32 v1, 1.0, v1
	v_mfma_f32_16x16x32_bf16 v[98:101], v[152:155], v[144:147], v[98:101]
	v_mfma_f32_16x16x32_bf16 v[102:105], v[156:159], v[144:147], v[102:105]
	v_add_f32_e32 v130, 1.0, v130
	v_mfma_f32_16x16x32_bf16 v[106:109], v[160:163], v[144:147], v[106:109]
	v_add_f32_e32 v238, 1.0, v238
	v_mfma_f32_16x16x32_bf16 v[110:113], v[164:167], v[144:147], v[110:113]
	v_add_f32_e32 v239, 1.0, v239
	v_mfma_f32_16x16x32_bf16 v[114:117], v[152:155], v[148:151], v[114:117]
	v_rcp_f32_e32 v1, v1
	v_mfma_f32_16x16x32_bf16 v[118:121], v[156:159], v[148:151], v[118:121]
	v_rcp_f32_e32 v130, v130
	v_mfma_f32_16x16x32_bf16 v[122:125], v[160:163], v[148:151], v[122:125]
	v_rcp_f32_e32 v238, v238
	v_mfma_f32_16x16x32_bf16 v[126:129], v[164:167], v[148:151], v[126:129]
	v_rcp_f32_e32 v239, v239
	s_waitcnt vmcnt(8) lgkmcnt(0)
	s_barrier
	v_mfma_f32_16x16x32_bf16 v[66:69], v[184:187], v[168:171], v[66:69]
	ds_read_b128 v[136:139], v224 offset:0
	v_mfma_f32_16x16x32_bf16 v[70:73], v[188:191], v[168:171], v[70:73]
	ds_read_b128 v[140:143], v224 offset:2048
	v_mul_f32_e32 v14, v14, v1
	v_mfma_f32_16x16x32_bf16 v[74:77], v[192:195], v[168:171], v[74:77]
	ds_read_b128 v[144:147], v224 offset:4096
	v_mfma_f32_16x16x32_bf16 v[78:81], v[196:199], v[168:171], v[78:81]
	ds_read_b128 v[148:151], v224 offset:6144
	v_mul_f32_e32 v15, v15, v130
	v_mfma_f32_16x16x32_bf16 v[82:85], v[184:187], v[172:175], v[82:85]
	ds_read_b128 v[152:155], v232 offset:0
	v_mul_f32_e32 v16, v16, v238
	v_mfma_f32_16x16x32_bf16 v[86:89], v[188:191], v[172:175], v[86:89]
	ds_read_b128 v[156:159], v232 offset:2048
	v_mfma_f32_16x16x32_bf16 v[90:93], v[192:195], v[172:175], v[90:93]
	ds_read_b128 v[160:163], v232 offset:4096
	v_mul_f32_e32 v17, v17, v239
	v_mfma_f32_16x16x32_bf16 v[94:97], v[196:199], v[172:175], v[94:97]
	ds_read_b128 v[164:167], v232 offset:6144
	v_cvt_pk_bf16_f32 v14, v14, v15
	s_add_u32 m0, s8, 0xc000
	v_mfma_f32_16x16x32_bf16 v[98:101], v[184:187], v[176:179], v[98:101]
	global_load_lds_dwordx4 v200, s[4:5]
	s_add_u32 m0, s8, 0xc400
	v_mfma_f32_16x16x32_bf16 v[102:105], v[188:191], v[176:179], v[102:105]
	global_load_lds_dwordx4 v201, s[4:5]
	v_cvt_pk_bf16_f32 v15, v16, v17
	s_add_u32 m0, s8, 0xc800
	v_mfma_f32_16x16x32_bf16 v[106:109], v[192:195], v[176:179], v[106:109]
	global_load_lds_dwordx4 v202, s[4:5]
	s_add_u32 m0, s8, 0xcc00
	v_mfma_f32_16x16x32_bf16 v[110:113], v[196:199], v[176:179], v[110:113]
	global_load_lds_dwordx4 v203, s[4:5]
	global_store_dwordx2 v236, v[14:15], s[10:11] offset:96 sc1
	s_add_u32 m0, s9, 0xc000
	v_mfma_f32_16x16x32_bf16 v[114:117], v[184:187], v[180:183], v[114:117]
	global_load_lds_dwordx4 v204, s[6:7]
	s_add_u32 s10, s10, 0x8000
	s_addc_u32 s11, s11, 0
	s_add_u32 m0, s9, 0xc400
	v_mfma_f32_16x16x32_bf16 v[118:121], v[188:191], v[180:183], v[118:121]
	global_load_lds_dwordx4 v205, s[6:7]
	v_mfma_f32_16x16x32_bf16 v[122:125], v[192:195], v[180:183], v[122:125]
	s_add_u32 s4, s4, 0x80
	s_addc_u32 s5, s5, 0
	v_mul_f32_e32 v1, s12, v18
	v_mfma_f32_16x16x32_bf16 v[126:129], v[196:199], v[180:183], v[126:129]
	s_add_u32 s6, s6, 0x80
	s_addc_u32 s7, s7, 0
	v_mul_f32_e32 v130, s12, v19
	s_waitcnt lgkmcnt(0)
	v_mfma_f32_16x16x32_bf16 v[66:69], v[152:155], v[136:139], v[66:69]
	ds_read_b128 v[168:171], v229 offset:0
	v_mfma_f32_16x16x32_bf16 v[70:73], v[156:159], v[136:139], v[70:73]
	ds_read_b128 v[172:175], v229 offset:2048
	v_mul_f32_e32 v238, s12, v20
	v_mfma_f32_16x16x32_bf16 v[74:77], v[160:163], v[136:139], v[74:77]
	ds_read_b128 v[176:179], v229 offset:4096
	v_mul_f32_e32 v239, s12, v21
	v_mfma_f32_16x16x32_bf16 v[78:81], v[164:167], v[136:139], v[78:81]
	ds_read_b128 v[180:183], v229 offset:6144
	v_exp_f32_e32 v1, v1
	v_mfma_f32_16x16x32_bf16 v[82:85], v[152:155], v[140:143], v[82:85]
	ds_read_b128 v[184:187], v235 offset:0
	v_exp_f32_e32 v130, v130
	v_mfma_f32_16x16x32_bf16 v[86:89], v[156:159], v[140:143], v[86:89]
	ds_read_b128 v[188:191], v235 offset:2048
	v_exp_f32_e32 v238, v238
	v_mfma_f32_16x16x32_bf16 v[90:93], v[160:163], v[140:143], v[90:93]
	ds_read_b128 v[192:195], v235 offset:4096
	v_exp_f32_e32 v239, v239
	v_mfma_f32_16x16x32_bf16 v[94:97], v[164:167], v[140:143], v[94:97]
	ds_read_b128 v[196:199], v235 offset:6144
	v_add_f32_e32 v1, 1.0, v1
	v_mfma_f32_16x16x32_bf16 v[98:101], v[152:155], v[144:147], v[98:101]
	v_mfma_f32_16x16x32_bf16 v[102:105], v[156:159], v[144:147], v[102:105]
	v_add_f32_e32 v130, 1.0, v130
	v_mfma_f32_16x16x32_bf16 v[106:109], v[160:163], v[144:147], v[106:109]
	v_add_f32_e32 v238, 1.0, v238
	v_mfma_f32_16x16x32_bf16 v[110:113], v[164:167], v[144:147], v[110:113]
	v_add_f32_e32 v239, 1.0, v239
	v_mfma_f32_16x16x32_bf16 v[114:117], v[152:155], v[148:151], v[114:117]
	v_rcp_f32_e32 v1, v1
	v_mfma_f32_16x16x32_bf16 v[118:121], v[156:159], v[148:151], v[118:121]
	v_rcp_f32_e32 v130, v130
	v_mfma_f32_16x16x32_bf16 v[122:125], v[160:163], v[148:151], v[122:125]
	v_rcp_f32_e32 v238, v238
	v_mfma_f32_16x16x32_bf16 v[126:129], v[164:167], v[148:151], v[126:129]
	v_rcp_f32_e32 v239, v239
	s_waitcnt vmcnt(7) lgkmcnt(0)
	s_barrier
	v_mfma_f32_16x16x32_bf16 v[66:69], v[184:187], v[168:171], v[66:69]
	ds_read_b128 v[136:139], v218 offset:0
	v_mfma_f32_16x16x32_bf16 v[70:73], v[188:191], v[168:171], v[70:73]
	ds_read_b128 v[140:143], v218 offset:2048
	v_mul_f32_e32 v18, v18, v1
	v_mfma_f32_16x16x32_bf16 v[74:77], v[192:195], v[168:171], v[74:77]
	ds_read_b128 v[144:147], v218 offset:4096
	v_mfma_f32_16x16x32_bf16 v[78:81], v[196:199], v[168:171], v[78:81]
	ds_read_b128 v[148:151], v218 offset:6144
	v_mul_f32_e32 v19, v19, v130
	v_mfma_f32_16x16x32_bf16 v[82:85], v[184:187], v[172:175], v[82:85]
	ds_read_b128 v[152:155], v230 offset:0
	v_mul_f32_e32 v20, v20, v238
	v_mfma_f32_16x16x32_bf16 v[86:89], v[188:191], v[172:175], v[86:89]
	ds_read_b128 v[156:159], v230 offset:2048
	v_mfma_f32_16x16x32_bf16 v[90:93], v[192:195], v[172:175], v[90:93]
	ds_read_b128 v[160:163], v230 offset:4096
	v_mul_f32_e32 v21, v21, v239
	v_mfma_f32_16x16x32_bf16 v[94:97], v[196:199], v[172:175], v[94:97]
	ds_read_b128 v[164:167], v230 offset:6144
	v_cvt_pk_bf16_f32 v18, v18, v19
	s_add_u32 m0, s8, 0x18000
	v_mfma_f32_16x16x32_bf16 v[98:101], v[184:187], v[176:179], v[98:101]
	global_load_lds_dwordx4 v200, s[4:5]
	s_add_u32 m0, s8, 0x18400
	v_mfma_f32_16x16x32_bf16 v[102:105], v[188:191], v[176:179], v[102:105]
	global_load_lds_dwordx4 v201, s[4:5]
	v_cvt_pk_bf16_f32 v19, v20, v21
	s_add_u32 m0, s8, 0x18800
	v_mfma_f32_16x16x32_bf16 v[106:109], v[192:195], v[176:179], v[106:109]
	global_load_lds_dwordx4 v202, s[4:5]
	s_add_u32 m0, s8, 0x18c00
	v_mfma_f32_16x16x32_bf16 v[110:113], v[196:199], v[176:179], v[110:113]
	global_load_lds_dwordx4 v203, s[4:5]
	global_store_dwordx2 v236, v[18:19], s[10:11] offset:0 sc1
	s_add_u32 m0, s9, 0x18000
	v_mfma_f32_16x16x32_bf16 v[114:117], v[184:187], v[180:183], v[114:117]
	global_load_lds_dwordx4 v204, s[6:7]
	v_mul_f32_e32 v1, s12, v22
	s_add_u32 m0, s9, 0x18400
	v_mfma_f32_16x16x32_bf16 v[118:121], v[188:191], v[180:183], v[118:121]
	global_load_lds_dwordx4 v205, s[6:7]
	v_mfma_f32_16x16x32_bf16 v[122:125], v[192:195], v[180:183], v[122:125]
	s_add_u32 s4, s4, 0x80
	s_addc_u32 s5, s5, 0
	v_mul_f32_e32 v130, s12, v23
	v_mfma_f32_16x16x32_bf16 v[126:129], v[196:199], v[180:183], v[126:129]
	s_add_u32 s6, s6, 0x80
	s_addc_u32 s7, s7, 0
	v_mul_f32_e32 v238, s12, v24
	s_waitcnt lgkmcnt(0)
	v_mfma_f32_16x16x32_bf16 v[66:69], v[152:155], v[136:139], v[66:69]
	ds_read_b128 v[168:171], v225 offset:0
	v_mfma_f32_16x16x32_bf16 v[70:73], v[156:159], v[136:139], v[70:73]
	ds_read_b128 v[172:175], v225 offset:2048
	v_mul_f32_e32 v239, s12, v25
	v_mfma_f32_16x16x32_bf16 v[74:77], v[160:163], v[136:139], v[74:77]
	ds_read_b128 v[176:179], v225 offset:4096
	v_exp_f32_e32 v1, v1
	v_mfma_f32_16x16x32_bf16 v[78:81], v[164:167], v[136:139], v[78:81]
	ds_read_b128 v[180:183], v225 offset:6144
	v_exp_f32_e32 v130, v130
	v_mfma_f32_16x16x32_bf16 v[82:85], v[152:155], v[140:143], v[82:85]
	ds_read_b128 v[184:187], v233 offset:0
	v_exp_f32_e32 v238, v238
	v_mfma_f32_16x16x32_bf16 v[86:89], v[156:159], v[140:143], v[86:89]
	ds_read_b128 v[188:191], v233 offset:2048
	v_exp_f32_e32 v239, v239
	v_mfma_f32_16x16x32_bf16 v[90:93], v[160:163], v[140:143], v[90:93]
	ds_read_b128 v[192:195], v233 offset:4096
	v_add_f32_e32 v1, 1.0, v1
	v_mfma_f32_16x16x32_bf16 v[94:97], v[164:167], v[140:143], v[94:97]
	ds_read_b128 v[196:199], v233 offset:6144
	v_add_f32_e32 v130, 1.0, v130
	v_mfma_f32_16x16x32_bf16 v[98:101], v[152:155], v[144:147], v[98:101]
	v_mfma_f32_16x16x32_bf16 v[102:105], v[156:159], v[144:147], v[102:105]
	v_add_f32_e32 v238, 1.0, v238
	v_mfma_f32_16x16x32_bf16 v[106:109], v[160:163], v[144:147], v[106:109]
	v_add_f32_e32 v239, 1.0, v239
	v_mfma_f32_16x16x32_bf16 v[110:113], v[164:167], v[144:147], v[110:113]
	v_rcp_f32_e32 v1, v1
	v_mfma_f32_16x16x32_bf16 v[114:117], v[152:155], v[148:151], v[114:117]
	v_rcp_f32_e32 v130, v130
	v_mfma_f32_16x16x32_bf16 v[118:121], v[156:159], v[148:151], v[118:121]
	v_rcp_f32_e32 v238, v238
	v_mfma_f32_16x16x32_bf16 v[122:125], v[160:163], v[148:151], v[122:125]
	v_rcp_f32_e32 v239, v239
	v_mfma_f32_16x16x32_bf16 v[126:129], v[164:167], v[148:151], v[126:129]
	v_mul_f32_e32 v22, v22, v1
	s_waitcnt vmcnt(7) lgkmcnt(0)
	s_barrier
	v_mfma_f32_16x16x32_bf16 v[66:69], v[184:187], v[168:171], v[66:69]
	ds_read_b128 v[136:139], v219 offset:0
	v_mfma_f32_16x16x32_bf16 v[70:73], v[188:191], v[168:171], v[70:73]
	ds_read_b128 v[140:143], v219 offset:2048
	v_mul_f32_e32 v23, v23, v130
	v_mfma_f32_16x16x32_bf16 v[74:77], v[192:195], v[168:171], v[74:77]
	ds_read_b128 v[144:147], v219 offset:4096
	v_mfma_f32_16x16x32_bf16 v[78:81], v[196:199], v[168:171], v[78:81]
	ds_read_b128 v[148:151], v219 offset:6144
	v_mul_f32_e32 v24, v24, v238
	v_mfma_f32_16x16x32_bf16 v[82:85], v[184:187], v[172:175], v[82:85]
	ds_read_b128 v[152:155], v231 offset:0
	v_mul_f32_e32 v25, v25, v239
	v_mfma_f32_16x16x32_bf16 v[86:89], v[188:191], v[172:175], v[86:89]
	ds_read_b128 v[156:159], v231 offset:2048
	v_mfma_f32_16x16x32_bf16 v[90:93], v[192:195], v[172:175], v[90:93]
	ds_read_b128 v[160:163], v231 offset:4096
	v_cvt_pk_bf16_f32 v22, v22, v23
	v_mfma_f32_16x16x32_bf16 v[94:97], v[196:199], v[172:175], v[94:97]
	ds_read_b128 v[164:167], v231 offset:6144
	v_cvt_pk_bf16_f32 v23, v24, v25
	s_mov_b32 m0, s8
	v_mfma_f32_16x16x32_bf16 v[98:101], v[184:187], v[176:179], v[98:101]
	global_load_lds_dwordx4 v200, s[4:5]
	s_add_u32 m0, s8, 0x400
	v_mfma_f32_16x16x32_bf16 v[102:105], v[188:191], v[176:179], v[102:105]
	global_load_lds_dwordx4 v201, s[4:5]
	global_store_dwordx2 v236, v[22:23], s[10:11] offset:32 sc1
	s_add_u32 m0, s8, 0x800
	v_mfma_f32_16x16x32_bf16 v[106:109], v[192:195], v[176:179], v[106:109]
	global_load_lds_dwordx4 v202, s[4:5]
	s_add_u32 m0, s8, 0xc00
	v_mfma_f32_16x16x32_bf16 v[110:113], v[196:199], v[176:179], v[110:113]
	global_load_lds_dwordx4 v203, s[4:5]
	v_mul_f32_e32 v1, s12, v26
	s_mov_b32 m0, s9
	v_mfma_f32_16x16x32_bf16 v[114:117], v[184:187], v[180:183], v[114:117]
	global_load_lds_dwordx4 v204, s[6:7]
	v_mul_f32_e32 v130, s12, v27
	s_add_u32 m0, s9, 0x400
	v_mfma_f32_16x16x32_bf16 v[118:121], v[188:191], v[180:183], v[118:121]
	global_load_lds_dwordx4 v205, s[6:7]
	v_mfma_f32_16x16x32_bf16 v[122:125], v[192:195], v[180:183], v[122:125]
	s_add_u32 s4, s4, 0x80
	s_addc_u32 s5, s5, 0
	v_mul_f32_e32 v238, s12, v28
	v_mfma_f32_16x16x32_bf16 v[126:129], v[196:199], v[180:183], v[126:129]
	s_add_u32 s6, s6, 0x80
	s_addc_u32 s7, s7, 0
	v_mul_f32_e32 v239, s12, v29
	s_waitcnt lgkmcnt(0)
	v_mfma_f32_16x16x32_bf16 v[66:69], v[152:155], v[136:139], v[66:69]
	ds_read_b128 v[168:171], v228 offset:0
	v_mfma_f32_16x16x32_bf16 v[70:73], v[156:159], v[136:139], v[70:73]
	ds_read_b128 v[172:175], v228 offset:2048
	v_exp_f32_e32 v1, v1
	v_mfma_f32_16x16x32_bf16 v[74:77], v[160:163], v[136:139], v[74:77]
	ds_read_b128 v[176:179], v228 offset:4096
	v_exp_f32_e32 v130, v130
	v_mfma_f32_16x16x32_bf16 v[78:81], v[164:167], v[136:139], v[78:81]
	ds_read_b128 v[180:183], v228 offset:6144
	v_exp_f32_e32 v238, v238
	v_mfma_f32_16x16x32_bf16 v[82:85], v[152:155], v[140:143], v[82:85]
	ds_read_b128 v[184:187], v234 offset:0
	v_exp_f32_e32 v239, v239
	v_mfma_f32_16x16x32_bf16 v[86:89], v[156:159], v[140:143], v[86:89]
	ds_read_b128 v[188:191], v234 offset:2048
	v_add_f32_e32 v1, 1.0, v1
	v_mfma_f32_16x16x32_bf16 v[90:93], v[160:163], v[140:143], v[90:93]
	ds_read_b128 v[192:195], v234 offset:4096
	v_add_f32_e32 v130, 1.0, v130
	v_mfma_f32_16x16x32_bf16 v[94:97], v[164:167], v[140:143], v[94:97]
	ds_read_b128 v[196:199], v234 offset:6144
	v_add_f32_e32 v238, 1.0, v238
	v_mfma_f32_16x16x32_bf16 v[98:101], v[152:155], v[144:147], v[98:101]
	v_mfma_f32_16x16x32_bf16 v[102:105], v[156:159], v[144:147], v[102:105]
	v_add_f32_e32 v239, 1.0, v239
	v_mfma_f32_16x16x32_bf16 v[106:109], v[160:163], v[144:147], v[106:109]
	v_rcp_f32_e32 v1, v1
	v_mfma_f32_16x16x32_bf16 v[110:113], v[164:167], v[144:147], v[110:113]
	v_rcp_f32_e32 v130, v130
	v_mfma_f32_16x16x32_bf16 v[114:117], v[152:155], v[148:151], v[114:117]
	v_rcp_f32_e32 v238, v238
	v_mfma_f32_16x16x32_bf16 v[118:121], v[156:159], v[148:151], v[118:121]
	v_rcp_f32_e32 v239, v239
	v_mfma_f32_16x16x32_bf16 v[122:125], v[160:163], v[148:151], v[122:125]
	v_mul_f32_e32 v26, v26, v1
	v_mfma_f32_16x16x32_bf16 v[126:129], v[164:167], v[148:151], v[126:129]
	v_mul_f32_e32 v27, v27, v130
	s_waitcnt vmcnt(7) lgkmcnt(0)
	s_barrier
	v_mfma_f32_16x16x32_bf16 v[66:69], v[184:187], v[168:171], v[66:69]
	ds_read_b128 v[136:139], v224 offset:0
	v_mfma_f32_16x16x32_bf16 v[70:73], v[188:191], v[168:171], v[70:73]
	ds_read_b128 v[140:143], v224 offset:2048
	v_mul_f32_e32 v28, v28, v238
	v_mfma_f32_16x16x32_bf16 v[74:77], v[192:195], v[168:171], v[74:77]
	ds_read_b128 v[144:147], v224 offset:4096
	v_mfma_f32_16x16x32_bf16 v[78:81], v[196:199], v[168:171], v[78:81]
	ds_read_b128 v[148:151], v224 offset:6144
	v_mul_f32_e32 v29, v29, v239
	v_mfma_f32_16x16x32_bf16 v[82:85], v[184:187], v[172:175], v[82:85]
	ds_read_b128 v[152:155], v232 offset:0
	v_cvt_pk_bf16_f32 v26, v26, v27
	v_mfma_f32_16x16x32_bf16 v[86:89], v[188:191], v[172:175], v[86:89]
	ds_read_b128 v[156:159], v232 offset:2048
	v_mfma_f32_16x16x32_bf16 v[90:93], v[192:195], v[172:175], v[90:93]
	ds_read_b128 v[160:163], v232 offset:4096
	v_cvt_pk_bf16_f32 v27, v28, v29
	v_mfma_f32_16x16x32_bf16 v[94:97], v[196:199], v[172:175], v[94:97]
	ds_read_b128 v[164:167], v232 offset:6144
	global_store_dwordx2 v236, v[26:27], s[10:11] offset:64 sc1
	s_add_u32 m0, s8, 0xc000
	v_mfma_f32_16x16x32_bf16 v[98:101], v[184:187], v[176:179], v[98:101]
	global_load_lds_dwordx4 v200, s[4:5]
	s_add_u32 m0, s8, 0xc400
	v_mfma_f32_16x16x32_bf16 v[102:105], v[188:191], v[176:179], v[102:105]
	global_load_lds_dwordx4 v201, s[4:5]
	v_mul_f32_e32 v1, s12, v30
	s_add_u32 m0, s8, 0xc800
	v_mfma_f32_16x16x32_bf16 v[106:109], v[192:195], v[176:179], v[106:109]
	global_load_lds_dwordx4 v202, s[4:5]
	s_add_u32 m0, s8, 0xcc00
	v_mfma_f32_16x16x32_bf16 v[110:113], v[196:199], v[176:179], v[110:113]
	global_load_lds_dwordx4 v203, s[4:5]
	v_mul_f32_e32 v130, s12, v31
	s_add_u32 m0, s9, 0xc000
	v_mfma_f32_16x16x32_bf16 v[114:117], v[184:187], v[180:183], v[114:117]
	global_load_lds_dwordx4 v204, s[6:7]
	v_mul_f32_e32 v238, s12, v32
	s_add_u32 m0, s9, 0xc400
	v_mfma_f32_16x16x32_bf16 v[118:121], v[188:191], v[180:183], v[118:121]
	global_load_lds_dwordx4 v205, s[6:7]
	v_mfma_f32_16x16x32_bf16 v[122:125], v[192:195], v[180:183], v[122:125]
	s_add_u32 s4, s4, 0x80
	s_addc_u32 s5, s5, 0
	v_mul_f32_e32 v239, s12, v33
	v_mfma_f32_16x16x32_bf16 v[126:129], v[196:199], v[180:183], v[126:129]
	s_add_u32 s6, s6, 0x80
	s_addc_u32 s7, s7, 0
	v_exp_f32_e32 v1, v1
	s_waitcnt lgkmcnt(0)
	v_mfma_f32_16x16x32_bf16 v[66:69], v[152:155], v[136:139], v[66:69]
	ds_read_b128 v[168:171], v229 offset:0
	v_mfma_f32_16x16x32_bf16 v[70:73], v[156:159], v[136:139], v[70:73]
	ds_read_b128 v[172:175], v229 offset:2048
	v_exp_f32_e32 v130, v130
	v_mfma_f32_16x16x32_bf16 v[74:77], v[160:163], v[136:139], v[74:77]
	ds_read_b128 v[176:179], v229 offset:4096
	v_exp_f32_e32 v238, v238
	v_mfma_f32_16x16x32_bf16 v[78:81], v[164:167], v[136:139], v[78:81]
	ds_read_b128 v[180:183], v229 offset:6144
	v_exp_f32_e32 v239, v239
	v_mfma_f32_16x16x32_bf16 v[82:85], v[152:155], v[140:143], v[82:85]
	ds_read_b128 v[184:187], v235 offset:0
	v_add_f32_e32 v1, 1.0, v1
	v_mfma_f32_16x16x32_bf16 v[86:89], v[156:159], v[140:143], v[86:89]
	ds_read_b128 v[188:191], v235 offset:2048
	v_add_f32_e32 v130, 1.0, v130
	v_mfma_f32_16x16x32_bf16 v[90:93], v[160:163], v[140:143], v[90:93]
	ds_read_b128 v[192:195], v235 offset:4096
	v_add_f32_e32 v238, 1.0, v238
	v_mfma_f32_16x16x32_bf16 v[94:97], v[164:167], v[140:143], v[94:97]
	ds_read_b128 v[196:199], v235 offset:6144
	v_add_f32_e32 v239, 1.0, v239
	v_mfma_f32_16x16x32_bf16 v[98:101], v[152:155], v[144:147], v[98:101]
	v_mfma_f32_16x16x32_bf16 v[102:105], v[156:159], v[144:147], v[102:105]
	v_rcp_f32_e32 v1, v1
	v_mfma_f32_16x16x32_bf16 v[106:109], v[160:163], v[144:147], v[106:109]
	v_rcp_f32_e32 v130, v130
	v_mfma_f32_16x16x32_bf16 v[110:113], v[164:167], v[144:147], v[110:113]
	v_rcp_f32_e32 v238, v238
	v_mfma_f32_16x16x32_bf16 v[114:117], v[152:155], v[148:151], v[114:117]
	v_rcp_f32_e32 v239, v239
	v_mfma_f32_16x16x32_bf16 v[118:121], v[156:159], v[148:151], v[118:121]
	v_mul_f32_e32 v30, v30, v1
	v_mfma_f32_16x16x32_bf16 v[122:125], v[160:163], v[148:151], v[122:125]
	v_mul_f32_e32 v31, v31, v130
	v_mfma_f32_16x16x32_bf16 v[126:129], v[164:167], v[148:151], v[126:129]
	v_mul_f32_e32 v32, v32, v238
	s_waitcnt vmcnt(7) lgkmcnt(0)
	s_barrier
	v_mfma_f32_16x16x32_bf16 v[66:69], v[184:187], v[168:171], v[66:69]
	ds_read_b128 v[136:139], v218 offset:0
	v_mfma_f32_16x16x32_bf16 v[70:73], v[188:191], v[168:171], v[70:73]
	ds_read_b128 v[140:143], v218 offset:2048
	v_mul_f32_e32 v33, v33, v239
	v_mfma_f32_16x16x32_bf16 v[74:77], v[192:195], v[168:171], v[74:77]
	ds_read_b128 v[144:147], v218 offset:4096
	v_mfma_f32_16x16x32_bf16 v[78:81], v[196:199], v[168:171], v[78:81]
	ds_read_b128 v[148:151], v218 offset:6144
	v_cvt_pk_bf16_f32 v30, v30, v31
	v_mfma_f32_16x16x32_bf16 v[82:85], v[184:187], v[172:175], v[82:85]
	ds_read_b128 v[152:155], v230 offset:0
	v_cvt_pk_bf16_f32 v31, v32, v33
	v_mfma_f32_16x16x32_bf16 v[86:89], v[188:191], v[172:175], v[86:89]
	ds_read_b128 v[156:159], v230 offset:2048
	v_mfma_f32_16x16x32_bf16 v[90:93], v[192:195], v[172:175], v[90:93]
	ds_read_b128 v[160:163], v230 offset:4096
	global_store_dwordx2 v236, v[30:31], s[10:11] offset:96 sc1
	v_mfma_f32_16x16x32_bf16 v[94:97], v[196:199], v[172:175], v[94:97]
	ds_read_b128 v[164:167], v230 offset:6144
	s_add_u32 s10, s10, 0x8000
	s_addc_u32 s11, s11, 0
	s_add_u32 m0, s8, 0x18000
	v_mfma_f32_16x16x32_bf16 v[98:101], v[184:187], v[176:179], v[98:101]
	global_load_lds_dwordx4 v200, s[4:5]
	s_add_u32 m0, s8, 0x18400
	v_mfma_f32_16x16x32_bf16 v[102:105], v[188:191], v[176:179], v[102:105]
	global_load_lds_dwordx4 v201, s[4:5]
	v_mul_f32_e32 v1, s12, v34
	s_add_u32 m0, s8, 0x18800
	v_mfma_f32_16x16x32_bf16 v[106:109], v[192:195], v[176:179], v[106:109]
	global_load_lds_dwordx4 v202, s[4:5]
	s_add_u32 m0, s8, 0x18c00
	v_mfma_f32_16x16x32_bf16 v[110:113], v[196:199], v[176:179], v[110:113]
	global_load_lds_dwordx4 v203, s[4:5]
	v_mul_f32_e32 v130, s12, v35
	s_add_u32 m0, s9, 0x18000
	v_mfma_f32_16x16x32_bf16 v[114:117], v[184:187], v[180:183], v[114:117]
	global_load_lds_dwordx4 v204, s[6:7]
	v_mul_f32_e32 v238, s12, v36
	s_add_u32 m0, s9, 0x18400
	v_mfma_f32_16x16x32_bf16 v[118:121], v[188:191], v[180:183], v[118:121]
	global_load_lds_dwordx4 v205, s[6:7]
	v_mfma_f32_16x16x32_bf16 v[122:125], v[192:195], v[180:183], v[122:125]
	s_add_u32 s4, s4, 0x80
	s_addc_u32 s5, s5, 0
	v_mul_f32_e32 v239, s12, v37
	v_mfma_f32_16x16x32_bf16 v[126:129], v[196:199], v[180:183], v[126:129]
	s_add_u32 s6, s6, 0x80
	s_addc_u32 s7, s7, 0
	v_exp_f32_e32 v1, v1
	s_waitcnt lgkmcnt(0)
	v_mfma_f32_16x16x32_bf16 v[66:69], v[152:155], v[136:139], v[66:69]
	ds_read_b128 v[168:171], v225 offset:0
	v_mfma_f32_16x16x32_bf16 v[70:73], v[156:159], v[136:139], v[70:73]
	ds_read_b128 v[172:175], v225 offset:2048
	v_exp_f32_e32 v130, v130
	v_mfma_f32_16x16x32_bf16 v[74:77], v[160:163], v[136:139], v[74:77]
	ds_read_b128 v[176:179], v225 offset:4096
	v_exp_f32_e32 v238, v238
	v_mfma_f32_16x16x32_bf16 v[78:81], v[164:167], v[136:139], v[78:81]
	ds_read_b128 v[180:183], v225 offset:6144
	v_exp_f32_e32 v239, v239
	v_mfma_f32_16x16x32_bf16 v[82:85], v[152:155], v[140:143], v[82:85]
	ds_read_b128 v[184:187], v233 offset:0
	v_add_f32_e32 v1, 1.0, v1
	v_mfma_f32_16x16x32_bf16 v[86:89], v[156:159], v[140:143], v[86:89]
	ds_read_b128 v[188:191], v233 offset:2048
	v_add_f32_e32 v130, 1.0, v130
	v_mfma_f32_16x16x32_bf16 v[90:93], v[160:163], v[140:143], v[90:93]
	ds_read_b128 v[192:195], v233 offset:4096
	v_add_f32_e32 v238, 1.0, v238
	v_mfma_f32_16x16x32_bf16 v[94:97], v[164:167], v[140:143], v[94:97]
	ds_read_b128 v[196:199], v233 offset:6144
	v_add_f32_e32 v239, 1.0, v239
	v_mfma_f32_16x16x32_bf16 v[98:101], v[152:155], v[144:147], v[98:101]
	v_mfma_f32_16x16x32_bf16 v[102:105], v[156:159], v[144:147], v[102:105]
	v_rcp_f32_e32 v1, v1
	v_mfma_f32_16x16x32_bf16 v[106:109], v[160:163], v[144:147], v[106:109]
	v_rcp_f32_e32 v130, v130
	v_mfma_f32_16x16x32_bf16 v[110:113], v[164:167], v[144:147], v[110:113]
	v_rcp_f32_e32 v238, v238
	v_mfma_f32_16x16x32_bf16 v[114:117], v[152:155], v[148:151], v[114:117]
	v_rcp_f32_e32 v239, v239
	v_mfma_f32_16x16x32_bf16 v[118:121], v[156:159], v[148:151], v[118:121]
	v_mul_f32_e32 v34, v34, v1
	v_mfma_f32_16x16x32_bf16 v[122:125], v[160:163], v[148:151], v[122:125]
	v_mul_f32_e32 v35, v35, v130
	v_mfma_f32_16x16x32_bf16 v[126:129], v[164:167], v[148:151], v[126:129]
	v_mul_f32_e32 v36, v36, v238
	s_waitcnt vmcnt(7) lgkmcnt(0)
	s_barrier
	v_mfma_f32_16x16x32_bf16 v[66:69], v[184:187], v[168:171], v[66:69]
	ds_read_b128 v[136:139], v219 offset:0
	v_mfma_f32_16x16x32_bf16 v[70:73], v[188:191], v[168:171], v[70:73]
	ds_read_b128 v[140:143], v219 offset:2048
	v_mul_f32_e32 v37, v37, v239
	v_mfma_f32_16x16x32_bf16 v[74:77], v[192:195], v[168:171], v[74:77]
	ds_read_b128 v[144:147], v219 offset:4096
	v_mfma_f32_16x16x32_bf16 v[78:81], v[196:199], v[168:171], v[78:81]
	ds_read_b128 v[148:151], v219 offset:6144
	v_cvt_pk_bf16_f32 v34, v34, v35
	v_mfma_f32_16x16x32_bf16 v[82:85], v[184:187], v[172:175], v[82:85]
	ds_read_b128 v[152:155], v231 offset:0
	v_cvt_pk_bf16_f32 v35, v36, v37
	v_mfma_f32_16x16x32_bf16 v[86:89], v[188:191], v[172:175], v[86:89]
	ds_read_b128 v[156:159], v231 offset:2048
	v_mfma_f32_16x16x32_bf16 v[90:93], v[192:195], v[172:175], v[90:93]
	ds_read_b128 v[160:163], v231 offset:4096
	global_store_dwordx2 v236, v[34:35], s[10:11] offset:0 sc1
	v_mfma_f32_16x16x32_bf16 v[94:97], v[196:199], v[172:175], v[94:97]
	ds_read_b128 v[164:167], v231 offset:6144
	v_mul_f32_e32 v1, s12, v38
	s_mov_b32 m0, s8
	v_mfma_f32_16x16x32_bf16 v[98:101], v[184:187], v[176:179], v[98:101]
	global_load_lds_dwordx4 v200, s[4:5]
	s_add_u32 m0, s8, 0x400
	v_mfma_f32_16x16x32_bf16 v[102:105], v[188:191], v[176:179], v[102:105]
	global_load_lds_dwordx4 v201, s[4:5]
	v_mul_f32_e32 v130, s12, v39
	s_add_u32 m0, s8, 0x800
	v_mfma_f32_16x16x32_bf16 v[106:109], v[192:195], v[176:179], v[106:109]
	global_load_lds_dwordx4 v202, s[4:5]
	s_add_u32 m0, s8, 0xc00
	v_mfma_f32_16x16x32_bf16 v[110:113], v[196:199], v[176:179], v[110:113]
	global_load_lds_dwordx4 v203, s[4:5]
	v_mul_f32_e32 v238, s12, v40
	s_mov_b32 m0, s9
	v_mfma_f32_16x16x32_bf16 v[114:117], v[184:187], v[180:183], v[114:117]
	global_load_lds_dwordx4 v204, s[6:7]
	v_mul_f32_e32 v239, s12, v41
	s_add_u32 m0, s9, 0x400
	v_mfma_f32_16x16x32_bf16 v[118:121], v[188:191], v[180:183], v[118:121]
	global_load_lds_dwordx4 v205, s[6:7]
	v_mfma_f32_16x16x32_bf16 v[122:125], v[192:195], v[180:183], v[122:125]
	s_add_u32 s4, s4, 0x80
	s_addc_u32 s5, s5, 0
	v_exp_f32_e32 v1, v1
	v_mfma_f32_16x16x32_bf16 v[126:129], v[196:199], v[180:183], v[126:129]
	s_add_u32 s6, s6, 0x80
	s_addc_u32 s7, s7, 0
	v_exp_f32_e32 v130, v130
	s_waitcnt lgkmcnt(0)
	v_mfma_f32_16x16x32_bf16 v[66:69], v[152:155], v[136:139], v[66:69]
	ds_read_b128 v[168:171], v228 offset:0
	v_mfma_f32_16x16x32_bf16 v[70:73], v[156:159], v[136:139], v[70:73]
	ds_read_b128 v[172:175], v228 offset:2048
	v_exp_f32_e32 v238, v238
	v_mfma_f32_16x16x32_bf16 v[74:77], v[160:163], v[136:139], v[74:77]
	ds_read_b128 v[176:179], v228 offset:4096
	v_exp_f32_e32 v239, v239
	v_mfma_f32_16x16x32_bf16 v[78:81], v[164:167], v[136:139], v[78:81]
	ds_read_b128 v[180:183], v228 offset:6144
	v_add_f32_e32 v1, 1.0, v1
	v_mfma_f32_16x16x32_bf16 v[82:85], v[152:155], v[140:143], v[82:85]
	ds_read_b128 v[184:187], v234 offset:0
	v_add_f32_e32 v130, 1.0, v130
	v_mfma_f32_16x16x32_bf16 v[86:89], v[156:159], v[140:143], v[86:89]
	ds_read_b128 v[188:191], v234 offset:2048
	v_add_f32_e32 v238, 1.0, v238
	v_mfma_f32_16x16x32_bf16 v[90:93], v[160:163], v[140:143], v[90:93]
	ds_read_b128 v[192:195], v234 offset:4096
	v_add_f32_e32 v239, 1.0, v239
	v_mfma_f32_16x16x32_bf16 v[94:97], v[164:167], v[140:143], v[94:97]
	ds_read_b128 v[196:199], v234 offset:6144
	v_rcp_f32_e32 v1, v1
	v_mfma_f32_16x16x32_bf16 v[98:101], v[152:155], v[144:147], v[98:101]
	v_mfma_f32_16x16x32_bf16 v[102:105], v[156:159], v[144:147], v[102:105]
	v_rcp_f32_e32 v130, v130
	v_mfma_f32_16x16x32_bf16 v[106:109], v[160:163], v[144:147], v[106:109]
	v_rcp_f32_e32 v238, v238
	v_mfma_f32_16x16x32_bf16 v[110:113], v[164:167], v[144:147], v[110:113]
	v_rcp_f32_e32 v239, v239
	v_mfma_f32_16x16x32_bf16 v[114:117], v[152:155], v[148:151], v[114:117]
	v_mul_f32_e32 v38, v38, v1
	v_mfma_f32_16x16x32_bf16 v[118:121], v[156:159], v[148:151], v[118:121]
	v_mul_f32_e32 v39, v39, v130
	v_mfma_f32_16x16x32_bf16 v[122:125], v[160:163], v[148:151], v[122:125]
	v_mul_f32_e32 v40, v40, v238
	v_mfma_f32_16x16x32_bf16 v[126:129], v[164:167], v[148:151], v[126:129]
	v_mul_f32_e32 v41, v41, v239
	s_waitcnt vmcnt(7) lgkmcnt(0)
	s_barrier
	v_mfma_f32_16x16x32_bf16 v[66:69], v[184:187], v[168:171], v[66:69]
	ds_read_b128 v[136:139], v224 offset:0
	v_mfma_f32_16x16x32_bf16 v[70:73], v[188:191], v[168:171], v[70:73]
	ds_read_b128 v[140:143], v224 offset:2048
	v_cvt_pk_bf16_f32 v38, v38, v39
	v_mfma_f32_16x16x32_bf16 v[74:77], v[192:195], v[168:171], v[74:77]
	ds_read_b128 v[144:147], v224 offset:4096
	v_mfma_f32_16x16x32_bf16 v[78:81], v[196:199], v[168:171], v[78:81]
	ds_read_b128 v[148:151], v224 offset:6144
	v_cvt_pk_bf16_f32 v39, v40, v41
	v_mfma_f32_16x16x32_bf16 v[82:85], v[184:187], v[172:175], v[82:85]
	ds_read_b128 v[152:155], v232 offset:0
	global_store_dwordx2 v236, v[38:39], s[10:11] offset:32 sc1
	v_mfma_f32_16x16x32_bf16 v[86:89], v[188:191], v[172:175], v[86:89]
	ds_read_b128 v[156:159], v232 offset:2048
	v_mfma_f32_16x16x32_bf16 v[90:93], v[192:195], v[172:175], v[90:93]
	ds_read_b128 v[160:163], v232 offset:4096
	v_mul_f32_e32 v1, s12, v42
	v_mfma_f32_16x16x32_bf16 v[94:97], v[196:199], v[172:175], v[94:97]
	ds_read_b128 v[164:167], v232 offset:6144
	v_mul_f32_e32 v130, s12, v43
	s_add_u32 m0, s8, 0xc000
	v_mfma_f32_16x16x32_bf16 v[98:101], v[184:187], v[176:179], v[98:101]
	global_load_lds_dwordx4 v200, s[4:5]
	s_add_u32 m0, s8, 0xc400
	v_mfma_f32_16x16x32_bf16 v[102:105], v[188:191], v[176:179], v[102:105]
	global_load_lds_dwordx4 v201, s[4:5]
	v_mul_f32_e32 v238, s12, v44
	s_add_u32 m0, s8, 0xc800
	v_mfma_f32_16x16x32_bf16 v[106:109], v[192:195], v[176:179], v[106:109]
	global_load_lds_dwordx4 v202, s[4:5]
	s_add_u32 m0, s8, 0xcc00
	v_mfma_f32_16x16x32_bf16 v[110:113], v[196:199], v[176:179], v[110:113]
	global_load_lds_dwordx4 v203, s[4:5]
	v_mul_f32_e32 v239, s12, v45
	s_add_u32 m0, s9, 0xc000
	v_mfma_f32_16x16x32_bf16 v[114:117], v[184:187], v[180:183], v[114:117]
	global_load_lds_dwordx4 v204, s[6:7]
	v_exp_f32_e32 v1, v1
	s_add_u32 m0, s9, 0xc400
	v_mfma_f32_16x16x32_bf16 v[118:121], v[188:191], v[180:183], v[118:121]
	global_load_lds_dwordx4 v205, s[6:7]
	v_mfma_f32_16x16x32_bf16 v[122:125], v[192:195], v[180:183], v[122:125]
	s_add_u32 s4, s4, 0x80
	s_addc_u32 s5, s5, 0
	v_exp_f32_e32 v130, v130
	v_mfma_f32_16x16x32_bf16 v[126:129], v[196:199], v[180:183], v[126:129]
	s_add_u32 s6, s6, 0x80
	s_addc_u32 s7, s7, 0
	v_exp_f32_e32 v238, v238
	s_waitcnt lgkmcnt(0)
	v_mfma_f32_16x16x32_bf16 v[66:69], v[152:155], v[136:139], v[66:69]
	ds_read_b128 v[168:171], v229 offset:0
	v_mfma_f32_16x16x32_bf16 v[70:73], v[156:159], v[136:139], v[70:73]
	ds_read_b128 v[172:175], v229 offset:2048
	v_exp_f32_e32 v239, v239
	v_mfma_f32_16x16x32_bf16 v[74:77], v[160:163], v[136:139], v[74:77]
	ds_read_b128 v[176:179], v229 offset:4096
	v_add_f32_e32 v1, 1.0, v1
	v_mfma_f32_16x16x32_bf16 v[78:81], v[164:167], v[136:139], v[78:81]
	ds_read_b128 v[180:183], v229 offset:6144
	v_add_f32_e32 v130, 1.0, v130
	v_mfma_f32_16x16x32_bf16 v[82:85], v[152:155], v[140:143], v[82:85]
	ds_read_b128 v[184:187], v235 offset:0
	v_add_f32_e32 v238, 1.0, v238
	v_mfma_f32_16x16x32_bf16 v[86:89], v[156:159], v[140:143], v[86:89]
	ds_read_b128 v[188:191], v235 offset:2048
	v_add_f32_e32 v239, 1.0, v239
	v_mfma_f32_16x16x32_bf16 v[90:93], v[160:163], v[140:143], v[90:93]
	ds_read_b128 v[192:195], v235 offset:4096
	v_rcp_f32_e32 v1, v1
	v_mfma_f32_16x16x32_bf16 v[94:97], v[164:167], v[140:143], v[94:97]
	ds_read_b128 v[196:199], v235 offset:6144
	v_rcp_f32_e32 v130, v130
	v_mfma_f32_16x16x32_bf16 v[98:101], v[152:155], v[144:147], v[98:101]
	v_mfma_f32_16x16x32_bf16 v[102:105], v[156:159], v[144:147], v[102:105]
	v_rcp_f32_e32 v238, v238
	v_mfma_f32_16x16x32_bf16 v[106:109], v[160:163], v[144:147], v[106:109]
	v_rcp_f32_e32 v239, v239
	v_mfma_f32_16x16x32_bf16 v[110:113], v[164:167], v[144:147], v[110:113]
	v_mul_f32_e32 v42, v42, v1
	v_mfma_f32_16x16x32_bf16 v[114:117], v[152:155], v[148:151], v[114:117]
	v_mul_f32_e32 v43, v43, v130
	v_mfma_f32_16x16x32_bf16 v[118:121], v[156:159], v[148:151], v[118:121]
	v_mul_f32_e32 v44, v44, v238
	v_mfma_f32_16x16x32_bf16 v[122:125], v[160:163], v[148:151], v[122:125]
	v_mul_f32_e32 v45, v45, v239
	v_mfma_f32_16x16x32_bf16 v[126:129], v[164:167], v[148:151], v[126:129]
	v_cvt_pk_bf16_f32 v42, v42, v43
	s_waitcnt vmcnt(7) lgkmcnt(0)
	s_barrier
	v_mfma_f32_16x16x32_bf16 v[66:69], v[184:187], v[168:171], v[66:69]
	ds_read_b128 v[136:139], v218 offset:0
	v_mfma_f32_16x16x32_bf16 v[70:73], v[188:191], v[168:171], v[70:73]
	ds_read_b128 v[140:143], v218 offset:2048
	v_cvt_pk_bf16_f32 v43, v44, v45
	v_mfma_f32_16x16x32_bf16 v[74:77], v[192:195], v[168:171], v[74:77]
	ds_read_b128 v[144:147], v218 offset:4096
	v_mfma_f32_16x16x32_bf16 v[78:81], v[196:199], v[168:171], v[78:81]
	ds_read_b128 v[148:151], v218 offset:6144
	global_store_dwordx2 v236, v[42:43], s[10:11] offset:64 sc1
	v_mfma_f32_16x16x32_bf16 v[82:85], v[184:187], v[172:175], v[82:85]
	ds_read_b128 v[152:155], v230 offset:0
	v_mul_f32_e32 v1, s12, v46
	v_mfma_f32_16x16x32_bf16 v[86:89], v[188:191], v[172:175], v[86:89]
	ds_read_b128 v[156:159], v230 offset:2048
	v_mfma_f32_16x16x32_bf16 v[90:93], v[192:195], v[172:175], v[90:93]
	ds_read_b128 v[160:163], v230 offset:4096
	v_mul_f32_e32 v130, s12, v47
	v_mfma_f32_16x16x32_bf16 v[94:97], v[196:199], v[172:175], v[94:97]
	ds_read_b128 v[164:167], v230 offset:6144
	v_mul_f32_e32 v238, s12, v48
	s_add_u32 m0, s8, 0x18000
	v_mfma_f32_16x16x32_bf16 v[98:101], v[184:187], v[176:179], v[98:101]
	global_load_lds_dwordx4 v200, s[4:5]
	s_add_u32 m0, s8, 0x18400
	v_mfma_f32_16x16x32_bf16 v[102:105], v[188:191], v[176:179], v[102:105]
	global_load_lds_dwordx4 v201, s[4:5]
	v_mul_f32_e32 v239, s12, v49
	s_add_u32 m0, s8, 0x18800
	v_mfma_f32_16x16x32_bf16 v[106:109], v[192:195], v[176:179], v[106:109]
	global_load_lds_dwordx4 v202, s[4:5]
	s_add_u32 m0, s8, 0x18c00
	v_mfma_f32_16x16x32_bf16 v[110:113], v[196:199], v[176:179], v[110:113]
	global_load_lds_dwordx4 v203, s[4:5]
	v_exp_f32_e32 v1, v1
	s_add_u32 m0, s9, 0x18000
	v_mfma_f32_16x16x32_bf16 v[114:117], v[184:187], v[180:183], v[114:117]
	global_load_lds_dwordx4 v204, s[6:7]
	v_exp_f32_e32 v130, v130
	s_add_u32 m0, s9, 0x18400
	v_mfma_f32_16x16x32_bf16 v[118:121], v[188:191], v[180:183], v[118:121]
	global_load_lds_dwordx4 v205, s[6:7]
	v_mfma_f32_16x16x32_bf16 v[122:125], v[192:195], v[180:183], v[122:125]
	s_add_u32 s4, s4, 0x80
	s_addc_u32 s5, s5, 0
	v_exp_f32_e32 v238, v238
	v_mfma_f32_16x16x32_bf16 v[126:129], v[196:199], v[180:183], v[126:129]
	s_add_u32 s6, s6, 0x80
	s_addc_u32 s7, s7, 0
	v_exp_f32_e32 v239, v239
	s_waitcnt lgkmcnt(0)
	v_mfma_f32_16x16x32_bf16 v[66:69], v[152:155], v[136:139], v[66:69]
	ds_read_b128 v[168:171], v225 offset:0
	v_mfma_f32_16x16x32_bf16 v[70:73], v[156:159], v[136:139], v[70:73]
	ds_read_b128 v[172:175], v225 offset:2048
	v_add_f32_e32 v1, 1.0, v1
	v_mfma_f32_16x16x32_bf16 v[74:77], v[160:163], v[136:139], v[74:77]
	ds_read_b128 v[176:179], v225 offset:4096
	v_add_f32_e32 v130, 1.0, v130
	v_mfma_f32_16x16x32_bf16 v[78:81], v[164:167], v[136:139], v[78:81]
	ds_read_b128 v[180:183], v225 offset:6144
	v_add_f32_e32 v238, 1.0, v238
	v_mfma_f32_16x16x32_bf16 v[82:85], v[152:155], v[140:143], v[82:85]
	ds_read_b128 v[184:187], v233 offset:0
	v_add_f32_e32 v239, 1.0, v239
	v_mfma_f32_16x16x32_bf16 v[86:89], v[156:159], v[140:143], v[86:89]
	ds_read_b128 v[188:191], v233 offset:2048
	v_rcp_f32_e32 v1, v1
	v_mfma_f32_16x16x32_bf16 v[90:93], v[160:163], v[140:143], v[90:93]
	ds_read_b128 v[192:195], v233 offset:4096
	v_rcp_f32_e32 v130, v130
	v_mfma_f32_16x16x32_bf16 v[94:97], v[164:167], v[140:143], v[94:97]
	ds_read_b128 v[196:199], v233 offset:6144
	v_rcp_f32_e32 v238, v238
	v_mfma_f32_16x16x32_bf16 v[98:101], v[152:155], v[144:147], v[98:101]
	v_mfma_f32_16x16x32_bf16 v[102:105], v[156:159], v[144:147], v[102:105]
	v_rcp_f32_e32 v239, v239
	v_mfma_f32_16x16x32_bf16 v[106:109], v[160:163], v[144:147], v[106:109]
	v_mul_f32_e32 v46, v46, v1
	v_mfma_f32_16x16x32_bf16 v[110:113], v[164:167], v[144:147], v[110:113]
	v_mul_f32_e32 v47, v47, v130
	v_mfma_f32_16x16x32_bf16 v[114:117], v[152:155], v[148:151], v[114:117]
	v_mul_f32_e32 v48, v48, v238
	v_mfma_f32_16x16x32_bf16 v[118:121], v[156:159], v[148:151], v[118:121]
	v_mul_f32_e32 v49, v49, v239
	v_mfma_f32_16x16x32_bf16 v[122:125], v[160:163], v[148:151], v[122:125]
	v_cvt_pk_bf16_f32 v46, v46, v47
	v_mfma_f32_16x16x32_bf16 v[126:129], v[164:167], v[148:151], v[126:129]
	v_cvt_pk_bf16_f32 v47, v48, v49
	s_waitcnt vmcnt(7) lgkmcnt(0)
	s_barrier
	v_mfma_f32_16x16x32_bf16 v[66:69], v[184:187], v[168:171], v[66:69]
	ds_read_b128 v[136:139], v219 offset:0
	v_mfma_f32_16x16x32_bf16 v[70:73], v[188:191], v[168:171], v[70:73]
	ds_read_b128 v[140:143], v219 offset:2048
	global_store_dwordx2 v236, v[46:47], s[10:11] offset:96 sc1
	v_mfma_f32_16x16x32_bf16 v[74:77], v[192:195], v[168:171], v[74:77]
	ds_read_b128 v[144:147], v219 offset:4096
	v_mfma_f32_16x16x32_bf16 v[78:81], v[196:199], v[168:171], v[78:81]
	ds_read_b128 v[148:151], v219 offset:6144
	s_add_u32 s10, s10, 0x8000
	s_addc_u32 s11, s11, 0
	v_mfma_f32_16x16x32_bf16 v[82:85], v[184:187], v[172:175], v[82:85]
	ds_read_b128 v[152:155], v231 offset:0
	v_mul_f32_e32 v1, s12, v50
	v_mfma_f32_16x16x32_bf16 v[86:89], v[188:191], v[172:175], v[86:89]
	ds_read_b128 v[156:159], v231 offset:2048
	v_mfma_f32_16x16x32_bf16 v[90:93], v[192:195], v[172:175], v[90:93]
	ds_read_b128 v[160:163], v231 offset:4096
	v_mul_f32_e32 v130, s12, v51
	v_mfma_f32_16x16x32_bf16 v[94:97], v[196:199], v[172:175], v[94:97]
	ds_read_b128 v[164:167], v231 offset:6144
	v_mul_f32_e32 v238, s12, v52
	s_mov_b32 m0, s8
	v_mfma_f32_16x16x32_bf16 v[98:101], v[184:187], v[176:179], v[98:101]
	global_load_lds_dwordx4 v200, s[4:5]
	s_add_u32 m0, s8, 0x400
	v_mfma_f32_16x16x32_bf16 v[102:105], v[188:191], v[176:179], v[102:105]
	global_load_lds_dwordx4 v201, s[4:5]
	v_mul_f32_e32 v239, s12, v53
	s_add_u32 m0, s8, 0x800
	v_mfma_f32_16x16x32_bf16 v[106:109], v[192:195], v[176:179], v[106:109]
	global_load_lds_dwordx4 v202, s[4:5]
	s_add_u32 m0, s8, 0xc00
	v_mfma_f32_16x16x32_bf16 v[110:113], v[196:199], v[176:179], v[110:113]
	global_load_lds_dwordx4 v203, s[4:5]
	v_exp_f32_e32 v1, v1
	s_mov_b32 m0, s9
	v_mfma_f32_16x16x32_bf16 v[114:117], v[184:187], v[180:183], v[114:117]
	global_load_lds_dwordx4 v204, s[6:7]
	v_exp_f32_e32 v130, v130
	s_add_u32 m0, s9, 0x400
	v_mfma_f32_16x16x32_bf16 v[118:121], v[188:191], v[180:183], v[118:121]
	global_load_lds_dwordx4 v205, s[6:7]
	v_mfma_f32_16x16x32_bf16 v[122:125], v[192:195], v[180:183], v[122:125]
	s_add_u32 s4, s4, 0x80
	s_addc_u32 s5, s5, 0
	v_exp_f32_e32 v238, v238
	v_mfma_f32_16x16x32_bf16 v[126:129], v[196:199], v[180:183], v[126:129]
	s_add_u32 s6, s6, 0x80
	s_addc_u32 s7, s7, 0
	v_exp_f32_e32 v239, v239
	s_waitcnt lgkmcnt(0)
	v_mfma_f32_16x16x32_bf16 v[66:69], v[152:155], v[136:139], v[66:69]
	ds_read_b128 v[168:171], v228 offset:0
	v_mfma_f32_16x16x32_bf16 v[70:73], v[156:159], v[136:139], v[70:73]
	ds_read_b128 v[172:175], v228 offset:2048
	v_add_f32_e32 v1, 1.0, v1
	v_mfma_f32_16x16x32_bf16 v[74:77], v[160:163], v[136:139], v[74:77]
	ds_read_b128 v[176:179], v228 offset:4096
	v_add_f32_e32 v130, 1.0, v130
	v_mfma_f32_16x16x32_bf16 v[78:81], v[164:167], v[136:139], v[78:81]
	ds_read_b128 v[180:183], v228 offset:6144
	v_add_f32_e32 v238, 1.0, v238
	v_mfma_f32_16x16x32_bf16 v[82:85], v[152:155], v[140:143], v[82:85]
	ds_read_b128 v[184:187], v234 offset:0
	v_add_f32_e32 v239, 1.0, v239
	v_mfma_f32_16x16x32_bf16 v[86:89], v[156:159], v[140:143], v[86:89]
	ds_read_b128 v[188:191], v234 offset:2048
	v_rcp_f32_e32 v1, v1
	v_mfma_f32_16x16x32_bf16 v[90:93], v[160:163], v[140:143], v[90:93]
	ds_read_b128 v[192:195], v234 offset:4096
	v_rcp_f32_e32 v130, v130
	v_mfma_f32_16x16x32_bf16 v[94:97], v[164:167], v[140:143], v[94:97]
	ds_read_b128 v[196:199], v234 offset:6144
	v_rcp_f32_e32 v238, v238
	v_mfma_f32_16x16x32_bf16 v[98:101], v[152:155], v[144:147], v[98:101]
	v_mfma_f32_16x16x32_bf16 v[102:105], v[156:159], v[144:147], v[102:105]
	v_rcp_f32_e32 v239, v239
	v_mfma_f32_16x16x32_bf16 v[106:109], v[160:163], v[144:147], v[106:109]
	v_mul_f32_e32 v50, v50, v1
	v_mfma_f32_16x16x32_bf16 v[110:113], v[164:167], v[144:147], v[110:113]
	v_mul_f32_e32 v51, v51, v130
	v_mfma_f32_16x16x32_bf16 v[114:117], v[152:155], v[148:151], v[114:117]
	v_mul_f32_e32 v52, v52, v238
	v_mfma_f32_16x16x32_bf16 v[118:121], v[156:159], v[148:151], v[118:121]
	v_mul_f32_e32 v53, v53, v239
	v_mfma_f32_16x16x32_bf16 v[122:125], v[160:163], v[148:151], v[122:125]
	v_cvt_pk_bf16_f32 v50, v50, v51
	v_mfma_f32_16x16x32_bf16 v[126:129], v[164:167], v[148:151], v[126:129]
	v_cvt_pk_bf16_f32 v51, v52, v53
	s_waitcnt vmcnt(7) lgkmcnt(0)
	s_barrier
	v_mfma_f32_16x16x32_bf16 v[66:69], v[184:187], v[168:171], v[66:69]
	ds_read_b128 v[136:139], v224 offset:0
	v_mfma_f32_16x16x32_bf16 v[70:73], v[188:191], v[168:171], v[70:73]
	ds_read_b128 v[140:143], v224 offset:2048
	global_store_dwordx2 v236, v[50:51], s[10:11] offset:0 sc1
	v_mfma_f32_16x16x32_bf16 v[74:77], v[192:195], v[168:171], v[74:77]
	ds_read_b128 v[144:147], v224 offset:4096
	v_mfma_f32_16x16x32_bf16 v[78:81], v[196:199], v[168:171], v[78:81]
	ds_read_b128 v[148:151], v224 offset:6144
	v_mul_f32_e32 v1, s12, v54
	v_mfma_f32_16x16x32_bf16 v[82:85], v[184:187], v[172:175], v[82:85]
	ds_read_b128 v[152:155], v232 offset:0
	v_mul_f32_e32 v130, s12, v55
	v_mfma_f32_16x16x32_bf16 v[86:89], v[188:191], v[172:175], v[86:89]
	ds_read_b128 v[156:159], v232 offset:2048
	v_mfma_f32_16x16x32_bf16 v[90:93], v[192:195], v[172:175], v[90:93]
	ds_read_b128 v[160:163], v232 offset:4096
	v_mul_f32_e32 v238, s12, v56
	v_mfma_f32_16x16x32_bf16 v[94:97], v[196:199], v[172:175], v[94:97]
	ds_read_b128 v[164:167], v232 offset:6144
	v_mul_f32_e32 v239, s12, v57
	s_add_u32 m0, s8, 0xc000
	v_mfma_f32_16x16x32_bf16 v[98:101], v[184:187], v[176:179], v[98:101]
	global_load_lds_dwordx4 v200, s[4:5]
	s_add_u32 m0, s8, 0xc400
	v_mfma_f32_16x16x32_bf16 v[102:105], v[188:191], v[176:179], v[102:105]
	global_load_lds_dwordx4 v201, s[4:5]
	v_exp_f32_e32 v1, v1
	s_add_u32 m0, s8, 0xc800
	v_mfma_f32_16x16x32_bf16 v[106:109], v[192:195], v[176:179], v[106:109]
	global_load_lds_dwordx4 v202, s[4:5]
	s_add_u32 m0, s8, 0xcc00
	v_mfma_f32_16x16x32_bf16 v[110:113], v[196:199], v[176:179], v[110:113]
	global_load_lds_dwordx4 v203, s[4:5]
	v_exp_f32_e32 v130, v130
	s_add_u32 m0, s9, 0xc000
	v_mfma_f32_16x16x32_bf16 v[114:117], v[184:187], v[180:183], v[114:117]
	global_load_lds_dwordx4 v204, s[6:7]
	v_exp_f32_e32 v238, v238
	s_add_u32 m0, s9, 0xc400
	v_mfma_f32_16x16x32_bf16 v[118:121], v[188:191], v[180:183], v[118:121]
	global_load_lds_dwordx4 v205, s[6:7]
	v_mfma_f32_16x16x32_bf16 v[122:125], v[192:195], v[180:183], v[122:125]
	s_sub_u32 s4, s4, 0x780
	s_subb_u32 s5, s5, 0
	v_exp_f32_e32 v239, v239
	v_mfma_f32_16x16x32_bf16 v[126:129], v[196:199], v[180:183], v[126:129]
	s_add_u32 s6, s6, 0x3f880
	s_addc_u32 s7, s7, 0
	v_add_f32_e32 v1, 1.0, v1
	s_waitcnt lgkmcnt(0)
	v_mfma_f32_16x16x32_bf16 v[66:69], v[152:155], v[136:139], v[66:69]
	ds_read_b128 v[168:171], v229 offset:0
	v_mfma_f32_16x16x32_bf16 v[70:73], v[156:159], v[136:139], v[70:73]
	ds_read_b128 v[172:175], v229 offset:2048
	v_add_f32_e32 v130, 1.0, v130
	v_mfma_f32_16x16x32_bf16 v[74:77], v[160:163], v[136:139], v[74:77]
	ds_read_b128 v[176:179], v229 offset:4096
	v_add_f32_e32 v238, 1.0, v238
	v_mfma_f32_16x16x32_bf16 v[78:81], v[164:167], v[136:139], v[78:81]
	ds_read_b128 v[180:183], v229 offset:6144
	v_add_f32_e32 v239, 1.0, v239
	v_mfma_f32_16x16x32_bf16 v[82:85], v[152:155], v[140:143], v[82:85]
	ds_read_b128 v[184:187], v235 offset:0
	v_rcp_f32_e32 v1, v1
	v_mfma_f32_16x16x32_bf16 v[86:89], v[156:159], v[140:143], v[86:89]
	ds_read_b128 v[188:191], v235 offset:2048
	v_rcp_f32_e32 v130, v130
	v_mfma_f32_16x16x32_bf16 v[90:93], v[160:163], v[140:143], v[90:93]
	ds_read_b128 v[192:195], v235 offset:4096
	v_rcp_f32_e32 v238, v238
	v_mfma_f32_16x16x32_bf16 v[94:97], v[164:167], v[140:143], v[94:97]
	ds_read_b128 v[196:199], v235 offset:6144
	v_rcp_f32_e32 v239, v239
	v_mfma_f32_16x16x32_bf16 v[98:101], v[152:155], v[144:147], v[98:101]
	v_mfma_f32_16x16x32_bf16 v[102:105], v[156:159], v[144:147], v[102:105]
	v_mul_f32_e32 v54, v54, v1
	v_mfma_f32_16x16x32_bf16 v[106:109], v[160:163], v[144:147], v[106:109]
	v_mul_f32_e32 v55, v55, v130
	v_mfma_f32_16x16x32_bf16 v[110:113], v[164:167], v[144:147], v[110:113]
	v_mul_f32_e32 v56, v56, v238
	v_mfma_f32_16x16x32_bf16 v[114:117], v[152:155], v[148:151], v[114:117]
	v_mul_f32_e32 v57, v57, v239
	v_mfma_f32_16x16x32_bf16 v[118:121], v[156:159], v[148:151], v[118:121]
	v_cvt_pk_bf16_f32 v54, v54, v55
	v_mfma_f32_16x16x32_bf16 v[122:125], v[160:163], v[148:151], v[122:125]
	v_cvt_pk_bf16_f32 v55, v56, v57
	v_mfma_f32_16x16x32_bf16 v[126:129], v[164:167], v[148:151], v[126:129]
	global_store_dwordx2 v236, v[54:55], s[10:11] offset:32 sc1
	s_waitcnt vmcnt(8) lgkmcnt(0)
	s_barrier
	v_mfma_f32_16x16x32_bf16 v[66:69], v[184:187], v[168:171], v[66:69]
	ds_read_b128 v[136:139], v218 offset:0
	v_mfma_f32_16x16x32_bf16 v[70:73], v[188:191], v[168:171], v[70:73]
	ds_read_b128 v[140:143], v218 offset:2048
	v_mul_f32_e32 v1, s12, v58
	v_mfma_f32_16x16x32_bf16 v[74:77], v[192:195], v[168:171], v[74:77]
	ds_read_b128 v[144:147], v218 offset:4096
	v_mfma_f32_16x16x32_bf16 v[78:81], v[196:199], v[168:171], v[78:81]
	ds_read_b128 v[148:151], v218 offset:6144
	v_mul_f32_e32 v130, s12, v59
	v_mfma_f32_16x16x32_bf16 v[82:85], v[184:187], v[172:175], v[82:85]
	ds_read_b128 v[152:155], v230 offset:0
	v_mul_f32_e32 v238, s12, v60
	v_mfma_f32_16x16x32_bf16 v[86:89], v[188:191], v[172:175], v[86:89]
	ds_read_b128 v[156:159], v230 offset:2048
	v_mfma_f32_16x16x32_bf16 v[90:93], v[192:195], v[172:175], v[90:93]
	ds_read_b128 v[160:163], v230 offset:4096
	v_mul_f32_e32 v239, s12, v61
	v_mfma_f32_16x16x32_bf16 v[94:97], v[196:199], v[172:175], v[94:97]
	ds_read_b128 v[164:167], v230 offset:6144
	v_exp_f32_e32 v1, v1
	v_mfma_f32_16x16x32_bf16 v[98:101], v[184:187], v[176:179], v[98:101]
	v_mfma_f32_16x16x32_bf16 v[102:105], v[188:191], v[176:179], v[102:105]
	v_exp_f32_e32 v130, v130
	v_mfma_f32_16x16x32_bf16 v[106:109], v[192:195], v[176:179], v[106:109]
	v_mfma_f32_16x16x32_bf16 v[110:113], v[196:199], v[176:179], v[110:113]
	v_exp_f32_e32 v238, v238
	v_mfma_f32_16x16x32_bf16 v[114:117], v[184:187], v[180:183], v[114:117]
	v_exp_f32_e32 v239, v239
	v_mfma_f32_16x16x32_bf16 v[118:121], v[188:191], v[180:183], v[118:121]
	v_mfma_f32_16x16x32_bf16 v[122:125], v[192:195], v[180:183], v[122:125]
	v_add_f32_e32 v1, 1.0, v1
	v_mfma_f32_16x16x32_bf16 v[126:129], v[196:199], v[180:183], v[126:129]
	v_add_f32_e32 v130, 1.0, v130
	s_waitcnt lgkmcnt(0)
	v_mfma_f32_16x16x32_bf16 v[66:69], v[152:155], v[136:139], v[66:69]
	ds_read_b128 v[168:171], v225 offset:0
	v_mfma_f32_16x16x32_bf16 v[70:73], v[156:159], v[136:139], v[70:73]
	ds_read_b128 v[172:175], v225 offset:2048
	v_add_f32_e32 v238, 1.0, v238
	v_mfma_f32_16x16x32_bf16 v[74:77], v[160:163], v[136:139], v[74:77]
	ds_read_b128 v[176:179], v225 offset:4096
	v_add_f32_e32 v239, 1.0, v239
	v_mfma_f32_16x16x32_bf16 v[78:81], v[164:167], v[136:139], v[78:81]
	ds_read_b128 v[180:183], v225 offset:6144
	v_rcp_f32_e32 v1, v1
	v_mfma_f32_16x16x32_bf16 v[82:85], v[152:155], v[140:143], v[82:85]
	ds_read_b128 v[184:187], v233 offset:0
	v_rcp_f32_e32 v130, v130
	v_mfma_f32_16x16x32_bf16 v[86:89], v[156:159], v[140:143], v[86:89]
	ds_read_b128 v[188:191], v233 offset:2048
	v_rcp_f32_e32 v238, v238
	v_mfma_f32_16x16x32_bf16 v[90:93], v[160:163], v[140:143], v[90:93]
	ds_read_b128 v[192:195], v233 offset:4096
	v_rcp_f32_e32 v239, v239
	v_mfma_f32_16x16x32_bf16 v[94:97], v[164:167], v[140:143], v[94:97]
	ds_read_b128 v[196:199], v233 offset:6144
	v_mul_f32_e32 v58, v58, v1
	v_mfma_f32_16x16x32_bf16 v[98:101], v[152:155], v[144:147], v[98:101]
	v_mfma_f32_16x16x32_bf16 v[102:105], v[156:159], v[144:147], v[102:105]
	v_mul_f32_e32 v59, v59, v130
	v_mfma_f32_16x16x32_bf16 v[106:109], v[160:163], v[144:147], v[106:109]
	v_mul_f32_e32 v60, v60, v238
	v_mfma_f32_16x16x32_bf16 v[110:113], v[164:167], v[144:147], v[110:113]
	v_mul_f32_e32 v61, v61, v239
	v_mfma_f32_16x16x32_bf16 v[114:117], v[152:155], v[148:151], v[114:117]
	v_cvt_pk_bf16_f32 v58, v58, v59
	v_mfma_f32_16x16x32_bf16 v[118:121], v[156:159], v[148:151], v[118:121]
	v_cvt_pk_bf16_f32 v59, v60, v61
	v_mfma_f32_16x16x32_bf16 v[122:125], v[160:163], v[148:151], v[122:125]
	global_store_dwordx2 v236, v[58:59], s[10:11] offset:64 sc1
	v_mfma_f32_16x16x32_bf16 v[126:129], v[164:167], v[148:151], v[126:129]
	v_mul_f32_e32 v1, s12, v62
	s_waitcnt vmcnt(2) lgkmcnt(0)
	s_barrier
	v_mfma_f32_16x16x32_bf16 v[66:69], v[184:187], v[168:171], v[66:69]
	ds_read_b128 v[136:139], v219 offset:0
	v_mfma_f32_16x16x32_bf16 v[70:73], v[188:191], v[168:171], v[70:73]
	ds_read_b128 v[140:143], v219 offset:2048
	v_mul_f32_e32 v130, s12, v63
	v_mfma_f32_16x16x32_bf16 v[74:77], v[192:195], v[168:171], v[74:77]
	ds_read_b128 v[144:147], v219 offset:4096
	v_mfma_f32_16x16x32_bf16 v[78:81], v[196:199], v[168:171], v[78:81]
	ds_read_b128 v[148:151], v219 offset:6144
	v_mul_f32_e32 v238, s12, v64
	v_mfma_f32_16x16x32_bf16 v[82:85], v[184:187], v[172:175], v[82:85]
	ds_read_b128 v[152:155], v231 offset:0
	v_mul_f32_e32 v239, s12, v65
	v_mfma_f32_16x16x32_bf16 v[86:89], v[188:191], v[172:175], v[86:89]
	ds_read_b128 v[156:159], v231 offset:2048
	v_mfma_f32_16x16x32_bf16 v[90:93], v[192:195], v[172:175], v[90:93]
	ds_read_b128 v[160:163], v231 offset:4096
	v_exp_f32_e32 v1, v1
	v_mfma_f32_16x16x32_bf16 v[94:97], v[196:199], v[172:175], v[94:97]
	ds_read_b128 v[164:167], v231 offset:6144
	v_exp_f32_e32 v130, v130
	v_mfma_f32_16x16x32_bf16 v[98:101], v[184:187], v[176:179], v[98:101]
	v_mfma_f32_16x16x32_bf16 v[102:105], v[188:191], v[176:179], v[102:105]
	v_exp_f32_e32 v238, v238
	v_mfma_f32_16x16x32_bf16 v[106:109], v[192:195], v[176:179], v[106:109]
	v_mfma_f32_16x16x32_bf16 v[110:113], v[196:199], v[176:179], v[110:113]
	v_exp_f32_e32 v239, v239
	v_mfma_f32_16x16x32_bf16 v[114:117], v[184:187], v[180:183], v[114:117]
	v_add_f32_e32 v1, 1.0, v1
	v_mfma_f32_16x16x32_bf16 v[118:121], v[188:191], v[180:183], v[118:121]
	v_mfma_f32_16x16x32_bf16 v[122:125], v[192:195], v[180:183], v[122:125]
	v_add_f32_e32 v130, 1.0, v130
	v_mfma_f32_16x16x32_bf16 v[126:129], v[196:199], v[180:183], v[126:129]
	v_add_f32_e32 v238, 1.0, v238
	s_waitcnt lgkmcnt(0)
	v_mfma_f32_16x16x32_bf16 v[66:69], v[152:155], v[136:139], v[66:69]
	ds_read_b128 v[168:171], v228 offset:0
	v_mfma_f32_16x16x32_bf16 v[70:73], v[156:159], v[136:139], v[70:73]
	ds_read_b128 v[172:175], v228 offset:2048
	v_add_f32_e32 v239, 1.0, v239
	v_mfma_f32_16x16x32_bf16 v[74:77], v[160:163], v[136:139], v[74:77]
	ds_read_b128 v[176:179], v228 offset:4096
	v_rcp_f32_e32 v1, v1
	v_mfma_f32_16x16x32_bf16 v[78:81], v[164:167], v[136:139], v[78:81]
	ds_read_b128 v[180:183], v228 offset:6144
	v_rcp_f32_e32 v130, v130
	v_mfma_f32_16x16x32_bf16 v[82:85], v[152:155], v[140:143], v[82:85]
	ds_read_b128 v[184:187], v234 offset:0
	v_mfma_f32_16x16x32_bf16 v[86:89], v[156:159], v[140:143], v[86:89]
	ds_read_b128 v[188:191], v234 offset:2048
	v_rcp_f32_e32 v238, v238
	v_mfma_f32_16x16x32_bf16 v[90:93], v[160:163], v[140:143], v[90:93]
	ds_read_b128 v[192:195], v234 offset:4096
	v_rcp_f32_e32 v239, v239
	v_mfma_f32_16x16x32_bf16 v[94:97], v[164:167], v[140:143], v[94:97]
	ds_read_b128 v[196:199], v234 offset:6144
	v_mul_f32_e32 v62, v62, v1
	v_mfma_f32_16x16x32_bf16 v[98:101], v[152:155], v[144:147], v[98:101]
	v_mfma_f32_16x16x32_bf16 v[102:105], v[156:159], v[144:147], v[102:105]
	v_mul_f32_e32 v63, v63, v130
	v_mfma_f32_16x16x32_bf16 v[106:109], v[160:163], v[144:147], v[106:109]
	v_mul_f32_e32 v64, v64, v238
	v_mfma_f32_16x16x32_bf16 v[110:113], v[164:167], v[144:147], v[110:113]
	v_mul_f32_e32 v65, v65, v239
	v_mfma_f32_16x16x32_bf16 v[114:117], v[152:155], v[148:151], v[114:117]
	v_mfma_f32_16x16x32_bf16 v[118:121], v[156:159], v[148:151], v[118:121]
	v_cvt_pk_bf16_f32 v62, v62, v63
	v_mfma_f32_16x16x32_bf16 v[122:125], v[160:163], v[148:151], v[122:125]
	v_cvt_pk_bf16_f32 v63, v64, v65
	v_mfma_f32_16x16x32_bf16 v[126:129], v[164:167], v[148:151], v[126:129]
	global_store_dwordx2 v236, v[62:63], s[10:11] offset:96 sc1
	s_waitcnt lgkmcnt(0)
	v_mfma_f32_16x16x32_bf16 v[66:69], v[184:187], v[168:171], v[66:69]
	v_mfma_f32_16x16x32_bf16 v[70:73], v[188:191], v[168:171], v[70:73]
	v_mfma_f32_16x16x32_bf16 v[74:77], v[192:195], v[168:171], v[74:77]
	v_mfma_f32_16x16x32_bf16 v[78:81], v[196:199], v[168:171], v[78:81]
	v_mfma_f32_16x16x32_bf16 v[82:85], v[184:187], v[172:175], v[82:85]
	v_mfma_f32_16x16x32_bf16 v[86:89], v[188:191], v[172:175], v[86:89]
	v_mfma_f32_16x16x32_bf16 v[90:93], v[192:195], v[172:175], v[90:93]
	v_mfma_f32_16x16x32_bf16 v[94:97], v[196:199], v[172:175], v[94:97]
	v_mfma_f32_16x16x32_bf16 v[98:101], v[184:187], v[176:179], v[98:101]
	v_mfma_f32_16x16x32_bf16 v[102:105], v[188:191], v[176:179], v[102:105]
	v_mfma_f32_16x16x32_bf16 v[106:109], v[192:195], v[176:179], v[106:109]
	v_mfma_f32_16x16x32_bf16 v[110:113], v[196:199], v[176:179], v[110:113]
	v_mfma_f32_16x16x32_bf16 v[114:117], v[184:187], v[180:183], v[114:117]
	v_mfma_f32_16x16x32_bf16 v[118:121], v[188:191], v[180:183], v[118:121]
	v_mfma_f32_16x16x32_bf16 v[122:125], v[192:195], v[180:183], v[122:125]
	v_mfma_f32_16x16x32_bf16 v[126:129], v[196:199], v[180:183], v[126:129]
	s_nop 7
	s_add_u32 s10, s52, 0x100
	s_addc_u32 s11, s53, 0
	v_mul_f32_e32 v1, s12, v66
	v_mul_f32_e32 v130, s12, v67
	v_mul_f32_e32 v238, s12, v68
	v_mul_f32_e32 v239, s12, v69
	v_exp_f32_e32 v1, v1
	v_exp_f32_e32 v130, v130
	v_exp_f32_e32 v238, v238
	v_exp_f32_e32 v239, v239
	v_add_f32_e32 v1, 1.0, v1
	v_add_f32_e32 v130, 1.0, v130
	v_add_f32_e32 v238, 1.0, v238
	v_add_f32_e32 v239, 1.0, v239
	v_rcp_f32_e32 v1, v1
	v_rcp_f32_e32 v130, v130
	v_rcp_f32_e32 v238, v238
	v_rcp_f32_e32 v239, v239
	v_mul_f32_e32 v66, v66, v1
	v_mul_f32_e32 v67, v67, v130
	v_mul_f32_e32 v68, v68, v238
	v_mul_f32_e32 v69, v69, v239
	v_cvt_pk_bf16_f32 v66, v66, v67
	v_cvt_pk_bf16_f32 v67, v68, v69
	global_store_dwordx2 v236, v[66:67], s[10:11] offset:0 sc1
	v_mul_f32_e32 v1, s12, v70
	v_mul_f32_e32 v130, s12, v71
	v_mul_f32_e32 v238, s12, v72
	v_mul_f32_e32 v239, s12, v73
	v_exp_f32_e32 v1, v1
	v_exp_f32_e32 v130, v130
	v_exp_f32_e32 v238, v238
	v_exp_f32_e32 v239, v239
	v_add_f32_e32 v1, 1.0, v1
	v_add_f32_e32 v130, 1.0, v130
	v_add_f32_e32 v238, 1.0, v238
	v_add_f32_e32 v239, 1.0, v239
	v_rcp_f32_e32 v1, v1
	v_rcp_f32_e32 v130, v130
	v_rcp_f32_e32 v238, v238
	v_rcp_f32_e32 v239, v239
	v_mul_f32_e32 v70, v70, v1
	v_mul_f32_e32 v71, v71, v130
	v_mul_f32_e32 v72, v72, v238
	v_mul_f32_e32 v73, v73, v239
	v_cvt_pk_bf16_f32 v70, v70, v71
	v_cvt_pk_bf16_f32 v71, v72, v73
	global_store_dwordx2 v236, v[70:71], s[10:11] offset:32 sc1
	v_mul_f32_e32 v1, s12, v74
	v_mul_f32_e32 v130, s12, v75
	v_mul_f32_e32 v238, s12, v76
	v_mul_f32_e32 v239, s12, v77
	v_exp_f32_e32 v1, v1
	v_exp_f32_e32 v130, v130
	v_exp_f32_e32 v238, v238
	v_exp_f32_e32 v239, v239
	v_add_f32_e32 v1, 1.0, v1
	v_add_f32_e32 v130, 1.0, v130
	v_add_f32_e32 v238, 1.0, v238
	v_add_f32_e32 v239, 1.0, v239
	v_rcp_f32_e32 v1, v1
	v_rcp_f32_e32 v130, v130
	v_rcp_f32_e32 v238, v238
	v_rcp_f32_e32 v239, v239
	v_mul_f32_e32 v74, v74, v1
	v_mul_f32_e32 v75, v75, v130
	v_mul_f32_e32 v76, v76, v238
	v_mul_f32_e32 v77, v77, v239
	v_cvt_pk_bf16_f32 v74, v74, v75
	v_cvt_pk_bf16_f32 v75, v76, v77
	global_store_dwordx2 v236, v[74:75], s[10:11] offset:64 sc1
	v_mul_f32_e32 v1, s12, v78
	v_mul_f32_e32 v130, s12, v79
	v_mul_f32_e32 v238, s12, v80
	v_mul_f32_e32 v239, s12, v81
	v_exp_f32_e32 v1, v1
	v_exp_f32_e32 v130, v130
	v_exp_f32_e32 v238, v238
	v_exp_f32_e32 v239, v239
	v_add_f32_e32 v1, 1.0, v1
	v_add_f32_e32 v130, 1.0, v130
	v_add_f32_e32 v238, 1.0, v238
	v_add_f32_e32 v239, 1.0, v239
	v_rcp_f32_e32 v1, v1
	v_rcp_f32_e32 v130, v130
	v_rcp_f32_e32 v238, v238
	v_rcp_f32_e32 v239, v239
	v_mul_f32_e32 v78, v78, v1
	v_mul_f32_e32 v79, v79, v130
	v_mul_f32_e32 v80, v80, v238
	v_mul_f32_e32 v81, v81, v239
	v_cvt_pk_bf16_f32 v78, v78, v79
	v_cvt_pk_bf16_f32 v79, v80, v81
	global_store_dwordx2 v236, v[78:79], s[10:11] offset:96 sc1
	s_add_u32 s10, s10, 0x8000
	s_addc_u32 s11, s11, 0
	v_mul_f32_e32 v1, s12, v82
	v_mul_f32_e32 v130, s12, v83
	v_mul_f32_e32 v238, s12, v84
	v_mul_f32_e32 v239, s12, v85
	v_exp_f32_e32 v1, v1
	v_exp_f32_e32 v130, v130
	v_exp_f32_e32 v238, v238
	v_exp_f32_e32 v239, v239
	v_add_f32_e32 v1, 1.0, v1
	v_add_f32_e32 v130, 1.0, v130
	v_add_f32_e32 v238, 1.0, v238
	v_add_f32_e32 v239, 1.0, v239
	v_rcp_f32_e32 v1, v1
	v_rcp_f32_e32 v130, v130
	v_rcp_f32_e32 v238, v238
	v_rcp_f32_e32 v239, v239
	v_mul_f32_e32 v82, v82, v1
	v_mul_f32_e32 v83, v83, v130
	v_mul_f32_e32 v84, v84, v238
	v_mul_f32_e32 v85, v85, v239
	v_cvt_pk_bf16_f32 v82, v82, v83
	v_cvt_pk_bf16_f32 v83, v84, v85
	global_store_dwordx2 v236, v[82:83], s[10:11] offset:0 sc1
	v_mul_f32_e32 v1, s12, v86
	v_mul_f32_e32 v130, s12, v87
	v_mul_f32_e32 v238, s12, v88
	v_mul_f32_e32 v239, s12, v89
	v_exp_f32_e32 v1, v1
	v_exp_f32_e32 v130, v130
	v_exp_f32_e32 v238, v238
	v_exp_f32_e32 v239, v239
	v_add_f32_e32 v1, 1.0, v1
	v_add_f32_e32 v130, 1.0, v130
	v_add_f32_e32 v238, 1.0, v238
	v_add_f32_e32 v239, 1.0, v239
	v_rcp_f32_e32 v1, v1
	v_rcp_f32_e32 v130, v130
	v_rcp_f32_e32 v238, v238
	v_rcp_f32_e32 v239, v239
	v_mul_f32_e32 v86, v86, v1
	v_mul_f32_e32 v87, v87, v130
	v_mul_f32_e32 v88, v88, v238
	v_mul_f32_e32 v89, v89, v239
	v_cvt_pk_bf16_f32 v86, v86, v87
	v_cvt_pk_bf16_f32 v87, v88, v89
	global_store_dwordx2 v236, v[86:87], s[10:11] offset:32 sc1
	v_mul_f32_e32 v1, s12, v90
	v_mul_f32_e32 v130, s12, v91
	v_mul_f32_e32 v238, s12, v92
	v_mul_f32_e32 v239, s12, v93
	v_exp_f32_e32 v1, v1
	v_exp_f32_e32 v130, v130
	v_exp_f32_e32 v238, v238
	v_exp_f32_e32 v239, v239
	v_add_f32_e32 v1, 1.0, v1
	v_add_f32_e32 v130, 1.0, v130
	v_add_f32_e32 v238, 1.0, v238
	v_add_f32_e32 v239, 1.0, v239
	v_rcp_f32_e32 v1, v1
	v_rcp_f32_e32 v130, v130
	v_rcp_f32_e32 v238, v238
	v_rcp_f32_e32 v239, v239
	v_mul_f32_e32 v90, v90, v1
	v_mul_f32_e32 v91, v91, v130
	v_mul_f32_e32 v92, v92, v238
	v_mul_f32_e32 v93, v93, v239
	v_cvt_pk_bf16_f32 v90, v90, v91
	v_cvt_pk_bf16_f32 v91, v92, v93
	global_store_dwordx2 v236, v[90:91], s[10:11] offset:64 sc1
	v_mul_f32_e32 v1, s12, v94
	v_mul_f32_e32 v130, s12, v95
	v_mul_f32_e32 v238, s12, v96
	v_mul_f32_e32 v239, s12, v97
	v_exp_f32_e32 v1, v1
	v_exp_f32_e32 v130, v130
	v_exp_f32_e32 v238, v238
	v_exp_f32_e32 v239, v239
	v_add_f32_e32 v1, 1.0, v1
	v_add_f32_e32 v130, 1.0, v130
	v_add_f32_e32 v238, 1.0, v238
	v_add_f32_e32 v239, 1.0, v239
	v_rcp_f32_e32 v1, v1
	v_rcp_f32_e32 v130, v130
	v_rcp_f32_e32 v238, v238
	v_rcp_f32_e32 v239, v239
	v_mul_f32_e32 v94, v94, v1
	v_mul_f32_e32 v95, v95, v130
	v_mul_f32_e32 v96, v96, v238
	v_mul_f32_e32 v97, v97, v239
	v_cvt_pk_bf16_f32 v94, v94, v95
	v_cvt_pk_bf16_f32 v95, v96, v97
	global_store_dwordx2 v236, v[94:95], s[10:11] offset:96 sc1
	s_add_u32 s10, s10, 0x8000
	s_addc_u32 s11, s11, 0
	v_mul_f32_e32 v1, s12, v98
	v_mul_f32_e32 v130, s12, v99
	v_mul_f32_e32 v238, s12, v100
	v_mul_f32_e32 v239, s12, v101
	v_exp_f32_e32 v1, v1
	v_exp_f32_e32 v130, v130
	v_exp_f32_e32 v238, v238
	v_exp_f32_e32 v239, v239
	v_add_f32_e32 v1, 1.0, v1
	v_add_f32_e32 v130, 1.0, v130
	v_add_f32_e32 v238, 1.0, v238
	v_add_f32_e32 v239, 1.0, v239
	v_rcp_f32_e32 v1, v1
	v_rcp_f32_e32 v130, v130
	v_rcp_f32_e32 v238, v238
	v_rcp_f32_e32 v239, v239
	v_mul_f32_e32 v98, v98, v1
	v_mul_f32_e32 v99, v99, v130
	v_mul_f32_e32 v100, v100, v238
	v_mul_f32_e32 v101, v101, v239
	v_cvt_pk_bf16_f32 v98, v98, v99
	v_cvt_pk_bf16_f32 v99, v100, v101
	global_store_dwordx2 v236, v[98:99], s[10:11] offset:0 sc1
	v_mul_f32_e32 v1, s12, v102
	v_mul_f32_e32 v130, s12, v103
	v_mul_f32_e32 v238, s12, v104
	v_mul_f32_e32 v239, s12, v105
	v_exp_f32_e32 v1, v1
	v_exp_f32_e32 v130, v130
	v_exp_f32_e32 v238, v238
	v_exp_f32_e32 v239, v239
	v_add_f32_e32 v1, 1.0, v1
	v_add_f32_e32 v130, 1.0, v130
	v_add_f32_e32 v238, 1.0, v238
	v_add_f32_e32 v239, 1.0, v239
	v_rcp_f32_e32 v1, v1
	v_rcp_f32_e32 v130, v130
	v_rcp_f32_e32 v238, v238
	v_rcp_f32_e32 v239, v239
	v_mul_f32_e32 v102, v102, v1
	v_mul_f32_e32 v103, v103, v130
	v_mul_f32_e32 v104, v104, v238
	v_mul_f32_e32 v105, v105, v239
	v_cvt_pk_bf16_f32 v102, v102, v103
	v_cvt_pk_bf16_f32 v103, v104, v105
	global_store_dwordx2 v236, v[102:103], s[10:11] offset:32 sc1
	v_mul_f32_e32 v1, s12, v106
	v_mul_f32_e32 v130, s12, v107
	v_mul_f32_e32 v238, s12, v108
	v_mul_f32_e32 v239, s12, v109
	v_exp_f32_e32 v1, v1
	v_exp_f32_e32 v130, v130
	v_exp_f32_e32 v238, v238
	v_exp_f32_e32 v239, v239
	v_add_f32_e32 v1, 1.0, v1
	v_add_f32_e32 v130, 1.0, v130
	v_add_f32_e32 v238, 1.0, v238
	v_add_f32_e32 v239, 1.0, v239
	v_rcp_f32_e32 v1, v1
	v_rcp_f32_e32 v130, v130
	v_rcp_f32_e32 v238, v238
	v_rcp_f32_e32 v239, v239
	v_mul_f32_e32 v106, v106, v1
	v_mul_f32_e32 v107, v107, v130
	v_mul_f32_e32 v108, v108, v238
	v_mul_f32_e32 v109, v109, v239
	v_cvt_pk_bf16_f32 v106, v106, v107
	v_cvt_pk_bf16_f32 v107, v108, v109
	global_store_dwordx2 v236, v[106:107], s[10:11] offset:64 sc1
	v_mul_f32_e32 v1, s12, v110
	v_mul_f32_e32 v130, s12, v111
	v_mul_f32_e32 v238, s12, v112
	v_mul_f32_e32 v239, s12, v113
	v_exp_f32_e32 v1, v1
	v_exp_f32_e32 v130, v130
	v_exp_f32_e32 v238, v238
	v_exp_f32_e32 v239, v239
	v_add_f32_e32 v1, 1.0, v1
	v_add_f32_e32 v130, 1.0, v130
	v_add_f32_e32 v238, 1.0, v238
	v_add_f32_e32 v239, 1.0, v239
	v_rcp_f32_e32 v1, v1
	v_rcp_f32_e32 v130, v130
	v_rcp_f32_e32 v238, v238
	v_rcp_f32_e32 v239, v239
	v_mul_f32_e32 v110, v110, v1
	v_mul_f32_e32 v111, v111, v130
	v_mul_f32_e32 v112, v112, v238
	v_mul_f32_e32 v113, v113, v239
	v_cvt_pk_bf16_f32 v110, v110, v111
	v_cvt_pk_bf16_f32 v111, v112, v113
	global_store_dwordx2 v236, v[110:111], s[10:11] offset:96 sc1
	s_add_u32 s10, s10, 0x8000
	s_addc_u32 s11, s11, 0
	v_mul_f32_e32 v1, s12, v114
	v_mul_f32_e32 v130, s12, v115
	v_mul_f32_e32 v238, s12, v116
	v_mul_f32_e32 v239, s12, v117
	v_exp_f32_e32 v1, v1
	v_exp_f32_e32 v130, v130
	v_exp_f32_e32 v238, v238
	v_exp_f32_e32 v239, v239
	v_add_f32_e32 v1, 1.0, v1
	v_add_f32_e32 v130, 1.0, v130
	v_add_f32_e32 v238, 1.0, v238
	v_add_f32_e32 v239, 1.0, v239
	v_rcp_f32_e32 v1, v1
	v_rcp_f32_e32 v130, v130
	v_rcp_f32_e32 v238, v238
	v_rcp_f32_e32 v239, v239
	v_mul_f32_e32 v114, v114, v1
	v_mul_f32_e32 v115, v115, v130
	v_mul_f32_e32 v116, v116, v238
	v_mul_f32_e32 v117, v117, v239
	v_cvt_pk_bf16_f32 v114, v114, v115
	v_cvt_pk_bf16_f32 v115, v116, v117
	global_store_dwordx2 v236, v[114:115], s[10:11] offset:0 sc1
	v_mul_f32_e32 v1, s12, v118
	v_mul_f32_e32 v130, s12, v119
	v_mul_f32_e32 v238, s12, v120
	v_mul_f32_e32 v239, s12, v121
	v_exp_f32_e32 v1, v1
	v_exp_f32_e32 v130, v130
	v_exp_f32_e32 v238, v238
	v_exp_f32_e32 v239, v239
	v_add_f32_e32 v1, 1.0, v1
	v_add_f32_e32 v130, 1.0, v130
	v_add_f32_e32 v238, 1.0, v238
	v_add_f32_e32 v239, 1.0, v239
	v_rcp_f32_e32 v1, v1
	v_rcp_f32_e32 v130, v130
	v_rcp_f32_e32 v238, v238
	v_rcp_f32_e32 v239, v239
	v_mul_f32_e32 v118, v118, v1
	v_mul_f32_e32 v119, v119, v130
	v_mul_f32_e32 v120, v120, v238
	v_mul_f32_e32 v121, v121, v239
	v_cvt_pk_bf16_f32 v118, v118, v119
	v_cvt_pk_bf16_f32 v119, v120, v121
	global_store_dwordx2 v236, v[118:119], s[10:11] offset:32 sc1
	v_mul_f32_e32 v1, s12, v122
	v_mul_f32_e32 v130, s12, v123
	v_mul_f32_e32 v238, s12, v124
	v_mul_f32_e32 v239, s12, v125
	v_exp_f32_e32 v1, v1
	v_exp_f32_e32 v130, v130
	v_exp_f32_e32 v238, v238
	v_exp_f32_e32 v239, v239
	v_add_f32_e32 v1, 1.0, v1
	v_add_f32_e32 v130, 1.0, v130
	v_add_f32_e32 v238, 1.0, v238
	v_add_f32_e32 v239, 1.0, v239
	v_rcp_f32_e32 v1, v1
	v_rcp_f32_e32 v130, v130
	v_rcp_f32_e32 v238, v238
	v_rcp_f32_e32 v239, v239
	v_mul_f32_e32 v122, v122, v1
	v_mul_f32_e32 v123, v123, v130
	v_mul_f32_e32 v124, v124, v238
	v_mul_f32_e32 v125, v125, v239
	v_cvt_pk_bf16_f32 v122, v122, v123
	v_cvt_pk_bf16_f32 v123, v124, v125
	global_store_dwordx2 v236, v[122:123], s[10:11] offset:64 sc1
	v_mul_f32_e32 v1, s12, v126
	v_mul_f32_e32 v130, s12, v127
	v_mul_f32_e32 v238, s12, v128
	v_mul_f32_e32 v239, s12, v129
	v_exp_f32_e32 v1, v1
	v_exp_f32_e32 v130, v130
	v_exp_f32_e32 v238, v238
	v_exp_f32_e32 v239, v239
	v_add_f32_e32 v1, 1.0, v1
	v_add_f32_e32 v130, 1.0, v130
	v_add_f32_e32 v238, 1.0, v238
	v_add_f32_e32 v239, 1.0, v239
	v_rcp_f32_e32 v1, v1
	v_rcp_f32_e32 v130, v130
	v_rcp_f32_e32 v238, v238
	v_rcp_f32_e32 v239, v239
	v_mul_f32_e32 v126, v126, v1
	v_mul_f32_e32 v127, v127, v130
	v_mul_f32_e32 v128, v128, v238
	v_mul_f32_e32 v129, v129, v239
	v_cvt_pk_bf16_f32 v126, v126, v127
	v_cvt_pk_bf16_f32 v127, v128, v129
	global_store_dwordx2 v236, v[126:127], s[10:11] offset:96 sc1
	s_branch .La1_done

.La1_done:
	s_waitcnt vmcnt(0)
	s_barrier
	v_readlane_b32 s50, v253, 2
	v_readlane_b32 s51, v253, 3
	s_lshl_b32 s22, s80, 2
	s_add_u32 s22, s22, 16
	s_add_u32 s50, s50, s22
	s_addc_u32 s51, s51, 0
	v_cmp_eq_u32_e32 vcc, 0, v0
	s_and_saveexec_b64 s[52:53], vcc
	v_mov_b32_e32 v1, 1
	global_atomic_add v131, v1, s[50:51]
	s_or_b64 exec, exec, s[52:53]
	v_mov_b32_e32 v238, s20
	v_mov_b32_e32 v239, s21
	v_mov_b32_e32 v1, 0x200f0
	ds_write_b64 v1, v[238:239]
	v_readlane_b32 s60, v254, 32
	v_readlane_b32 s54, v254, 34
	v_readlane_b32 s62, v254, 36
	v_readlane_b32 s70, v254, 38
	v_readlane_b32 s76, v254, 40
	v_readlane_b32 s86, v254, 42
	v_readlane_b32 s94, v254, 44
	v_readlane_b32 s58, v254, 46
	v_readlane_b32 s56, v254, 48
	v_readlane_b32 s61, v254, 33
	v_readlane_b32 s55, v254, 35
	v_readlane_b32 s63, v254, 37
	v_readlane_b32 s71, v254, 39
	v_readlane_b32 s77, v254, 41
	v_readlane_b32 s87, v254, 43
	v_readlane_b32 s95, v254, 45
	v_readlane_b32 s59, v254, 47
	v_readlane_b32 s57, v254, 49
	s_waitcnt lgkmcnt(0)
	s_setprio 0
	s_branch .LBB0_419

.Lgprio_1:
	v_and_b32_e32 v236, 63, v0
	v_lshrrev_b32_e32 v237, 6, v0
	v_and_b32_e32 v238, 15, v236
	v_lshrrev_b32_e32 v239, 4, v236
	v_lshlrev_b32_e32 v240, 13, v237
	v_lshl_add_u32 v240, v236, 4, v240
	v_add_u32_e32 v241, 0x1000, v240
	s_and_b32 s1, s2, 7
	s_lshr_b32 s22, s2, 3
	s_and_b32 s23, s22, 3
	s_lshl_b32 s1, s1, 2
	s_add_u32 s1, s1, s23
	s_lshr_b32 s22, s22, 2
	s_lshl_b32 s23, s1, 19
	s_add_u32 s4, s26, s23
	s_addc_u32 s5, s27, 0
	v_readlane_b32 s6, v254, 57
	v_readlane_b32 s7, v254, 58
	s_lshl_b32 s23, s22, 20
	s_add_u32 s23, s23, 0x640000
	s_nop 0
	s_add_u32 s6, s6, s23
	s_addc_u32 s7, s7, 0
	s_lshr_b32 s23, s22, 1
	s_lshl_b32 s23, s23, 5
	s_add_u32 s23, s23, s1
	s_lshl_b32 s23, s23, 3
	s_and_b32 s24, s22, 1
	s_lshl_b32 s24, s24, 2
	s_add_u32 s23, s23, s24
	s_lshl_b32 s13, s23, 16
	s_mov_b32 s12, 0xbfb8aa3b
	s_mov_b32 m0, s8
	s_nop 0
	global_load_lds_dwordx4 v200, s[4:5]
	s_add_u32 m0, s8, 0x400
	s_nop 0
	global_load_lds_dwordx4 v201, s[4:5]
	s_add_u32 m0, s8, 0x800
	s_nop 0
	global_load_lds_dwordx4 v202, s[4:5]
	s_add_u32 m0, s8, 0xc00
	s_nop 0
	global_load_lds_dwordx4 v203, s[4:5]
	s_mov_b32 m0, s9
	s_nop 0
	global_load_lds_dwordx4 v204, s[6:7]
	s_add_u32 m0, s9, 0x400
	s_nop 0
	global_load_lds_dwordx4 v205, s[6:7]
	s_add_u32 s4, s4, 0x80
	s_addc_u32 s5, s5, 0
	s_add_u32 s6, s6, 0x80
	s_addc_u32 s7, s7, 0
	s_add_u32 m0, s8, 0xc000
	s_nop 0
	global_load_lds_dwordx4 v200, s[4:5]
	s_add_u32 m0, s8, 0xc400
	s_nop 0
	global_load_lds_dwordx4 v201, s[4:5]
	s_add_u32 m0, s8, 0xc800
	s_nop 0
	global_load_lds_dwordx4 v202, s[4:5]
	s_add_u32 m0, s8, 0xcc00
	s_nop 0
	global_load_lds_dwordx4 v203, s[4:5]
	s_add_u32 m0, s9, 0xc000
	s_nop 0
	global_load_lds_dwordx4 v204, s[6:7]
	s_add_u32 m0, s9, 0xc400
	s_nop 0
	global_load_lds_dwordx4 v205, s[6:7]
	s_add_u32 s4, s4, 0x80
	s_addc_u32 s5, s5, 0
	s_add_u32 s6, s6, 0x80
	s_addc_u32 s7, s7, 0
	s_add_u32 m0, s8, 0x18000
	s_nop 0
	global_load_lds_dwordx4 v200, s[4:5]
	s_add_u32 m0, s8, 0x18400
	s_nop 0
	global_load_lds_dwordx4 v201, s[4:5]
	s_add_u32 m0, s8, 0x18800
	s_nop 0
	global_load_lds_dwordx4 v202, s[4:5]
	s_add_u32 m0, s8, 0x18c00
	s_nop 0
	global_load_lds_dwordx4 v203, s[4:5]
	s_add_u32 m0, s9, 0x18000
	s_nop 0
	global_load_lds_dwordx4 v204, s[6:7]
	s_add_u32 m0, s9, 0x18400
	s_nop 0
	global_load_lds_dwordx4 v205, s[6:7]
	s_add_u32 s4, s4, 0x80
	s_addc_u32 s5, s5, 0
	s_add_u32 s6, s6, 0x80
	s_addc_u32 s7, s7, 0
	s_waitcnt vmcnt(12)
	s_barrier
	ds_read_b128 v[136:139], v218 offset:0
	ds_read_b128 v[140:143], v218 offset:2048
	ds_read_b128 v[144:147], v218 offset:4096
	ds_read_b128 v[148:151], v218 offset:6144
	ds_read_b128 v[152:155], v230 offset:0
	ds_read_b128 v[156:159], v230 offset:2048
	ds_read_b128 v[160:163], v230 offset:4096
	ds_read_b128 v[164:167], v230 offset:6144
	s_waitcnt lgkmcnt(0)
	v_mfma_f32_16x16x32_bf16 v[2:5], v[152:155], v[136:139], 0
	ds_read_b128 v[168:171], v225 offset:0
	v_mfma_f32_16x16x32_bf16 v[6:9], v[156:159], v[136:139], 0
	ds_read_b128 v[172:175], v225 offset:2048
	v_mfma_f32_16x16x32_bf16 v[10:13], v[160:163], v[136:139], 0
	ds_read_b128 v[176:179], v225 offset:4096
	v_mfma_f32_16x16x32_bf16 v[14:17], v[164:167], v[136:139], 0
	ds_read_b128 v[180:183], v225 offset:6144
	v_mfma_f32_16x16x32_bf16 v[18:21], v[152:155], v[140:143], 0
	ds_read_b128 v[184:187], v233 offset:0
	v_mfma_f32_16x16x32_bf16 v[22:25], v[156:159], v[140:143], 0
	ds_read_b128 v[188:191], v233 offset:2048
	v_mfma_f32_16x16x32_bf16 v[26:29], v[160:163], v[140:143], 0
	ds_read_b128 v[192:195], v233 offset:4096
	v_mfma_f32_16x16x32_bf16 v[30:33], v[164:167], v[140:143], 0
	ds_read_b128 v[196:199], v233 offset:6144
	v_mfma_f32_16x16x32_bf16 v[34:37], v[152:155], v[144:147], 0
	v_mfma_f32_16x16x32_bf16 v[38:41], v[156:159], v[144:147], 0
	v_mfma_f32_16x16x32_bf16 v[42:45], v[160:163], v[144:147], 0
	v_mfma_f32_16x16x32_bf16 v[46:49], v[164:167], v[144:147], 0
	v_mfma_f32_16x16x32_bf16 v[50:53], v[152:155], v[148:151], 0
	v_mfma_f32_16x16x32_bf16 v[54:57], v[156:159], v[148:151], 0
	v_mfma_f32_16x16x32_bf16 v[58:61], v[160:163], v[148:151], 0
	v_mfma_f32_16x16x32_bf16 v[62:65], v[164:167], v[148:151], 0
	s_waitcnt vmcnt(6) lgkmcnt(0)
	s_barrier
	v_mfma_f32_16x16x32_bf16 v[2:5], v[184:187], v[168:171], v[2:5]
	ds_read_b128 v[136:139], v219 offset:0
	v_mfma_f32_16x16x32_bf16 v[6:9], v[188:191], v[168:171], v[6:9]
	ds_read_b128 v[140:143], v219 offset:2048
	v_mfma_f32_16x16x32_bf16 v[10:13], v[192:195], v[168:171], v[10:13]
	ds_read_b128 v[144:147], v219 offset:4096
	v_mfma_f32_16x16x32_bf16 v[14:17], v[196:199], v[168:171], v[14:17]
	ds_read_b128 v[148:151], v219 offset:6144
	v_mfma_f32_16x16x32_bf16 v[18:21], v[184:187], v[172:175], v[18:21]
	ds_read_b128 v[152:155], v231 offset:0
	v_mfma_f32_16x16x32_bf16 v[22:25], v[188:191], v[172:175], v[22:25]
	ds_read_b128 v[156:159], v231 offset:2048
	v_mfma_f32_16x16x32_bf16 v[26:29], v[192:195], v[172:175], v[26:29]
	ds_read_b128 v[160:163], v231 offset:4096
	v_mfma_f32_16x16x32_bf16 v[30:33], v[196:199], v[172:175], v[30:33]
	ds_read_b128 v[164:167], v231 offset:6144
	s_mov_b32 m0, s8
	v_mfma_f32_16x16x32_bf16 v[34:37], v[184:187], v[176:179], v[34:37]
	global_load_lds_dwordx4 v200, s[4:5]
	s_add_u32 m0, s8, 0x400
	v_mfma_f32_16x16x32_bf16 v[38:41], v[188:191], v[176:179], v[38:41]
	global_load_lds_dwordx4 v201, s[4:5]
	s_add_u32 m0, s8, 0x800
	v_mfma_f32_16x16x32_bf16 v[42:45], v[192:195], v[176:179], v[42:45]
	global_load_lds_dwordx4 v202, s[4:5]
	s_add_u32 m0, s8, 0xc00
	v_mfma_f32_16x16x32_bf16 v[46:49], v[196:199], v[176:179], v[46:49]
	global_load_lds_dwordx4 v203, s[4:5]
	s_mov_b32 m0, s9
	v_mfma_f32_16x16x32_bf16 v[50:53], v[184:187], v[180:183], v[50:53]
	global_load_lds_dwordx4 v204, s[6:7]
	s_add_u32 m0, s9, 0x400
	v_mfma_f32_16x16x32_bf16 v[54:57], v[188:191], v[180:183], v[54:57]
	global_load_lds_dwordx4 v205, s[6:7]
	v_mfma_f32_16x16x32_bf16 v[58:61], v[192:195], v[180:183], v[58:61]
	s_add_u32 s4, s4, 0x80
	s_addc_u32 s5, s5, 0
	v_mfma_f32_16x16x32_bf16 v[62:65], v[196:199], v[180:183], v[62:65]
	s_add_u32 s6, s6, 0x80
	s_addc_u32 s7, s7, 0
	s_waitcnt lgkmcnt(0)
	v_mfma_f32_16x16x32_bf16 v[2:5], v[152:155], v[136:139], v[2:5]
	ds_read_b128 v[168:171], v228 offset:0
	v_mfma_f32_16x16x32_bf16 v[6:9], v[156:159], v[136:139], v[6:9]
	ds_read_b128 v[172:175], v228 offset:2048
	v_mfma_f32_16x16x32_bf16 v[10:13], v[160:163], v[136:139], v[10:13]
	ds_read_b128 v[176:179], v228 offset:4096
	v_mfma_f32_16x16x32_bf16 v[14:17], v[164:167], v[136:139], v[14:17]
	ds_read_b128 v[180:183], v228 offset:6144
	v_mfma_f32_16x16x32_bf16 v[18:21], v[152:155], v[140:143], v[18:21]
	ds_read_b128 v[184:187], v234 offset:0
	v_mfma_f32_16x16x32_bf16 v[22:25], v[156:159], v[140:143], v[22:25]
	ds_read_b128 v[188:191], v234 offset:2048
	v_mfma_f32_16x16x32_bf16 v[26:29], v[160:163], v[140:143], v[26:29]
	ds_read_b128 v[192:195], v234 offset:4096
	v_mfma_f32_16x16x32_bf16 v[30:33], v[164:167], v[140:143], v[30:33]
	ds_read_b128 v[196:199], v234 offset:6144
	v_mfma_f32_16x16x32_bf16 v[34:37], v[152:155], v[144:147], v[34:37]
	v_mfma_f32_16x16x32_bf16 v[38:41], v[156:159], v[144:147], v[38:41]
	v_mfma_f32_16x16x32_bf16 v[42:45], v[160:163], v[144:147], v[42:45]
	v_mfma_f32_16x16x32_bf16 v[46:49], v[164:167], v[144:147], v[46:49]
	v_mfma_f32_16x16x32_bf16 v[50:53], v[152:155], v[148:151], v[50:53]
	v_mfma_f32_16x16x32_bf16 v[54:57], v[156:159], v[148:151], v[54:57]
	v_mfma_f32_16x16x32_bf16 v[58:61], v[160:163], v[148:151], v[58:61]
	v_mfma_f32_16x16x32_bf16 v[62:65], v[164:167], v[148:151], v[62:65]
	s_waitcnt vmcnt(6) lgkmcnt(0)
	s_barrier
	v_mfma_f32_16x16x32_bf16 v[2:5], v[184:187], v[168:171], v[2:5]
	ds_read_b128 v[136:139], v224 offset:0
	v_mfma_f32_16x16x32_bf16 v[6:9], v[188:191], v[168:171], v[6:9]
	ds_read_b128 v[140:143], v224 offset:2048
	v_mfma_f32_16x16x32_bf16 v[10:13], v[192:195], v[168:171], v[10:13]
	ds_read_b128 v[144:147], v224 offset:4096
	v_mfma_f32_16x16x32_bf16 v[14:17], v[196:199], v[168:171], v[14:17]
	ds_read_b128 v[148:151], v224 offset:6144
	v_mfma_f32_16x16x32_bf16 v[18:21], v[184:187], v[172:175], v[18:21]
	ds_read_b128 v[152:155], v232 offset:0
	v_mfma_f32_16x16x32_bf16 v[22:25], v[188:191], v[172:175], v[22:25]
	ds_read_b128 v[156:159], v232 offset:2048
	v_mfma_f32_16x16x32_bf16 v[26:29], v[192:195], v[172:175], v[26:29]
	ds_read_b128 v[160:163], v232 offset:4096
	v_mfma_f32_16x16x32_bf16 v[30:33], v[196:199], v[172:175], v[30:33]
	ds_read_b128 v[164:167], v232 offset:6144
	s_add_u32 m0, s8, 0xc000
	v_mfma_f32_16x16x32_bf16 v[34:37], v[184:187], v[176:179], v[34:37]
	global_load_lds_dwordx4 v200, s[4:5]
	s_add_u32 m0, s8, 0xc400
	v_mfma_f32_16x16x32_bf16 v[38:41], v[188:191], v[176:179], v[38:41]
	global_load_lds_dwordx4 v201, s[4:5]
	s_add_u32 m0, s8, 0xc800
	v_mfma_f32_16x16x32_bf16 v[42:45], v[192:195], v[176:179], v[42:45]
	global_load_lds_dwordx4 v202, s[4:5]
	s_add_u32 m0, s8, 0xcc00
	v_mfma_f32_16x16x32_bf16 v[46:49], v[196:199], v[176:179], v[46:49]
	global_load_lds_dwordx4 v203, s[4:5]
	s_add_u32 m0, s9, 0xc000
	v_mfma_f32_16x16x32_bf16 v[50:53], v[184:187], v[180:183], v[50:53]
	global_load_lds_dwordx4 v204, s[6:7]
	s_add_u32 m0, s9, 0xc400
	v_mfma_f32_16x16x32_bf16 v[54:57], v[188:191], v[180:183], v[54:57]
	global_load_lds_dwordx4 v205, s[6:7]
	v_mfma_f32_16x16x32_bf16 v[58:61], v[192:195], v[180:183], v[58:61]
	s_add_u32 s4, s4, 0x80
	s_addc_u32 s5, s5, 0
	v_mfma_f32_16x16x32_bf16 v[62:65], v[196:199], v[180:183], v[62:65]
	s_add_u32 s6, s6, 0x80
	s_addc_u32 s7, s7, 0
	s_waitcnt lgkmcnt(0)
	v_mfma_f32_16x16x32_bf16 v[2:5], v[152:155], v[136:139], v[2:5]
	ds_read_b128 v[168:171], v229 offset:0
	v_mfma_f32_16x16x32_bf16 v[6:9], v[156:159], v[136:139], v[6:9]
	ds_read_b128 v[172:175], v229 offset:2048
	v_mfma_f32_16x16x32_bf16 v[10:13], v[160:163], v[136:139], v[10:13]
	ds_read_b128 v[176:179], v229 offset:4096
	v_mfma_f32_16x16x32_bf16 v[14:17], v[164:167], v[136:139], v[14:17]
	ds_read_b128 v[180:183], v229 offset:6144
	v_mfma_f32_16x16x32_bf16 v[18:21], v[152:155], v[140:143], v[18:21]
	ds_read_b128 v[184:187], v235 offset:0
	v_mfma_f32_16x16x32_bf16 v[22:25], v[156:159], v[140:143], v[22:25]
	ds_read_b128 v[188:191], v235 offset:2048
	v_mfma_f32_16x16x32_bf16 v[26:29], v[160:163], v[140:143], v[26:29]
	ds_read_b128 v[192:195], v235 offset:4096
	v_mfma_f32_16x16x32_bf16 v[30:33], v[164:167], v[140:143], v[30:33]
	ds_read_b128 v[196:199], v235 offset:6144
	v_mfma_f32_16x16x32_bf16 v[34:37], v[152:155], v[144:147], v[34:37]
	v_mfma_f32_16x16x32_bf16 v[38:41], v[156:159], v[144:147], v[38:41]
	v_mfma_f32_16x16x32_bf16 v[42:45], v[160:163], v[144:147], v[42:45]
	v_mfma_f32_16x16x32_bf16 v[46:49], v[164:167], v[144:147], v[46:49]
	v_mfma_f32_16x16x32_bf16 v[50:53], v[152:155], v[148:151], v[50:53]
	v_mfma_f32_16x16x32_bf16 v[54:57], v[156:159], v[148:151], v[54:57]
	v_mfma_f32_16x16x32_bf16 v[58:61], v[160:163], v[148:151], v[58:61]
	v_mfma_f32_16x16x32_bf16 v[62:65], v[164:167], v[148:151], v[62:65]
	s_waitcnt vmcnt(6) lgkmcnt(0)
	s_barrier
	v_mfma_f32_16x16x32_bf16 v[2:5], v[184:187], v[168:171], v[2:5]
	ds_read_b128 v[136:139], v218 offset:0
	v_mfma_f32_16x16x32_bf16 v[6:9], v[188:191], v[168:171], v[6:9]
	ds_read_b128 v[140:143], v218 offset:2048
	v_mfma_f32_16x16x32_bf16 v[10:13], v[192:195], v[168:171], v[10:13]
	ds_read_b128 v[144:147], v218 offset:4096
	v_mfma_f32_16x16x32_bf16 v[14:17], v[196:199], v[168:171], v[14:17]
	ds_read_b128 v[148:151], v218 offset:6144
	v_mfma_f32_16x16x32_bf16 v[18:21], v[184:187], v[172:175], v[18:21]
	ds_read_b128 v[152:155], v230 offset:0
	v_mfma_f32_16x16x32_bf16 v[22:25], v[188:191], v[172:175], v[22:25]
	ds_read_b128 v[156:159], v230 offset:2048
	v_mfma_f32_16x16x32_bf16 v[26:29], v[192:195], v[172:175], v[26:29]
	ds_read_b128 v[160:163], v230 offset:4096
	v_mfma_f32_16x16x32_bf16 v[30:33], v[196:199], v[172:175], v[30:33]
	ds_read_b128 v[164:167], v230 offset:6144
	s_add_u32 m0, s8, 0x18000
	v_mfma_f32_16x16x32_bf16 v[34:37], v[184:187], v[176:179], v[34:37]
	global_load_lds_dwordx4 v200, s[4:5]
	s_add_u32 m0, s8, 0x18400
	v_mfma_f32_16x16x32_bf16 v[38:41], v[188:191], v[176:179], v[38:41]
	global_load_lds_dwordx4 v201, s[4:5]
	s_add_u32 m0, s8, 0x18800
	v_mfma_f32_16x16x32_bf16 v[42:45], v[192:195], v[176:179], v[42:45]
	global_load_lds_dwordx4 v202, s[4:5]
	s_add_u32 m0, s8, 0x18c00
	v_mfma_f32_16x16x32_bf16 v[46:49], v[196:199], v[176:179], v[46:49]
	global_load_lds_dwordx4 v203, s[4:5]
	s_add_u32 m0, s9, 0x18000
	v_mfma_f32_16x16x32_bf16 v[50:53], v[184:187], v[180:183], v[50:53]
	global_load_lds_dwordx4 v204, s[6:7]
	s_add_u32 m0, s9, 0x18400
	v_mfma_f32_16x16x32_bf16 v[54:57], v[188:191], v[180:183], v[54:57]
	global_load_lds_dwordx4 v205, s[6:7]
	v_mfma_f32_16x16x32_bf16 v[58:61], v[192:195], v[180:183], v[58:61]
	s_add_u32 s4, s4, 0x80
	s_addc_u32 s5, s5, 0
	v_mfma_f32_16x16x32_bf16 v[62:65], v[196:199], v[180:183], v[62:65]
	s_add_u32 s6, s6, 0x80
	s_addc_u32 s7, s7, 0
	s_waitcnt lgkmcnt(0)
	v_mfma_f32_16x16x32_bf16 v[2:5], v[152:155], v[136:139], v[2:5]
	ds_read_b128 v[168:171], v225 offset:0
	v_mfma_f32_16x16x32_bf16 v[6:9], v[156:159], v[136:139], v[6:9]
	ds_read_b128 v[172:175], v225 offset:2048
	v_mfma_f32_16x16x32_bf16 v[10:13], v[160:163], v[136:139], v[10:13]
	ds_read_b128 v[176:179], v225 offset:4096
	v_mfma_f32_16x16x32_bf16 v[14:17], v[164:167], v[136:139], v[14:17]
	ds_read_b128 v[180:183], v225 offset:6144
	v_mfma_f32_16x16x32_bf16 v[18:21], v[152:155], v[140:143], v[18:21]
	ds_read_b128 v[184:187], v233 offset:0
	v_mfma_f32_16x16x32_bf16 v[22:25], v[156:159], v[140:143], v[22:25]
	ds_read_b128 v[188:191], v233 offset:2048
	v_mfma_f32_16x16x32_bf16 v[26:29], v[160:163], v[140:143], v[26:29]
	ds_read_b128 v[192:195], v233 offset:4096
	v_mfma_f32_16x16x32_bf16 v[30:33], v[164:167], v[140:143], v[30:33]
	ds_read_b128 v[196:199], v233 offset:6144
	v_mfma_f32_16x16x32_bf16 v[34:37], v[152:155], v[144:147], v[34:37]
	v_mfma_f32_16x16x32_bf16 v[38:41], v[156:159], v[144:147], v[38:41]
	v_mfma_f32_16x16x32_bf16 v[42:45], v[160:163], v[144:147], v[42:45]
	v_mfma_f32_16x16x32_bf16 v[46:49], v[164:167], v[144:147], v[46:49]
	v_mfma_f32_16x16x32_bf16 v[50:53], v[152:155], v[148:151], v[50:53]
	v_mfma_f32_16x16x32_bf16 v[54:57], v[156:159], v[148:151], v[54:57]
	v_mfma_f32_16x16x32_bf16 v[58:61], v[160:163], v[148:151], v[58:61]
	v_mfma_f32_16x16x32_bf16 v[62:65], v[164:167], v[148:151], v[62:65]
	s_waitcnt vmcnt(6) lgkmcnt(0)
	s_barrier
	v_mfma_f32_16x16x32_bf16 v[2:5], v[184:187], v[168:171], v[2:5]
	ds_read_b128 v[136:139], v219 offset:0
	v_mfma_f32_16x16x32_bf16 v[6:9], v[188:191], v[168:171], v[6:9]
	ds_read_b128 v[140:143], v219 offset:2048
	v_mfma_f32_16x16x32_bf16 v[10:13], v[192:195], v[168:171], v[10:13]
	ds_read_b128 v[144:147], v219 offset:4096
	v_mfma_f32_16x16x32_bf16 v[14:17], v[196:199], v[168:171], v[14:17]
	ds_read_b128 v[148:151], v219 offset:6144
	v_mfma_f32_16x16x32_bf16 v[18:21], v[184:187], v[172:175], v[18:21]
	ds_read_b128 v[152:155], v231 offset:0
	v_mfma_f32_16x16x32_bf16 v[22:25], v[188:191], v[172:175], v[22:25]
	ds_read_b128 v[156:159], v231 offset:2048
	v_mfma_f32_16x16x32_bf16 v[26:29], v[192:195], v[172:175], v[26:29]
	ds_read_b128 v[160:163], v231 offset:4096
	v_mfma_f32_16x16x32_bf16 v[30:33], v[196:199], v[172:175], v[30:33]
	ds_read_b128 v[164:167], v231 offset:6144
	s_mov_b32 m0, s8
	v_mfma_f32_16x16x32_bf16 v[34:37], v[184:187], v[176:179], v[34:37]
	global_load_lds_dwordx4 v200, s[4:5]
	s_add_u32 m0, s8, 0x400
	v_mfma_f32_16x16x32_bf16 v[38:41], v[188:191], v[176:179], v[38:41]
	global_load_lds_dwordx4 v201, s[4:5]
	s_add_u32 m0, s8, 0x800
	v_mfma_f32_16x16x32_bf16 v[42:45], v[192:195], v[176:179], v[42:45]
	global_load_lds_dwordx4 v202, s[4:5]
	s_add_u32 m0, s8, 0xc00
	v_mfma_f32_16x16x32_bf16 v[46:49], v[196:199], v[176:179], v[46:49]
	global_load_lds_dwordx4 v203, s[4:5]
	s_mov_b32 m0, s9
	v_mfma_f32_16x16x32_bf16 v[50:53], v[184:187], v[180:183], v[50:53]
	global_load_lds_dwordx4 v204, s[6:7]
	s_add_u32 m0, s9, 0x400
	v_mfma_f32_16x16x32_bf16 v[54:57], v[188:191], v[180:183], v[54:57]
	global_load_lds_dwordx4 v205, s[6:7]
	v_mfma_f32_16x16x32_bf16 v[58:61], v[192:195], v[180:183], v[58:61]
	s_add_u32 s4, s4, 0x80
	s_addc_u32 s5, s5, 0
	v_mfma_f32_16x16x32_bf16 v[62:65], v[196:199], v[180:183], v[62:65]
	s_add_u32 s6, s6, 0x80
	s_addc_u32 s7, s7, 0
	s_waitcnt lgkmcnt(0)
	v_mfma_f32_16x16x32_bf16 v[2:5], v[152:155], v[136:139], v[2:5]
	ds_read_b128 v[168:171], v228 offset:0
	v_mfma_f32_16x16x32_bf16 v[6:9], v[156:159], v[136:139], v[6:9]
	ds_read_b128 v[172:175], v228 offset:2048
	v_mfma_f32_16x16x32_bf16 v[10:13], v[160:163], v[136:139], v[10:13]
	ds_read_b128 v[176:179], v228 offset:4096
	v_mfma_f32_16x16x32_bf16 v[14:17], v[164:167], v[136:139], v[14:17]
	ds_read_b128 v[180:183], v228 offset:6144
	v_mfma_f32_16x16x32_bf16 v[18:21], v[152:155], v[140:143], v[18:21]
	ds_read_b128 v[184:187], v234 offset:0
	v_mfma_f32_16x16x32_bf16 v[22:25], v[156:159], v[140:143], v[22:25]
	ds_read_b128 v[188:191], v234 offset:2048
	v_mfma_f32_16x16x32_bf16 v[26:29], v[160:163], v[140:143], v[26:29]
	ds_read_b128 v[192:195], v234 offset:4096
	v_mfma_f32_16x16x32_bf16 v[30:33], v[164:167], v[140:143], v[30:33]
	ds_read_b128 v[196:199], v234 offset:6144
	v_mfma_f32_16x16x32_bf16 v[34:37], v[152:155], v[144:147], v[34:37]
	v_mfma_f32_16x16x32_bf16 v[38:41], v[156:159], v[144:147], v[38:41]
	v_mfma_f32_16x16x32_bf16 v[42:45], v[160:163], v[144:147], v[42:45]
	v_mfma_f32_16x16x32_bf16 v[46:49], v[164:167], v[144:147], v[46:49]
	v_mfma_f32_16x16x32_bf16 v[50:53], v[152:155], v[148:151], v[50:53]
	v_mfma_f32_16x16x32_bf16 v[54:57], v[156:159], v[148:151], v[54:57]
	v_mfma_f32_16x16x32_bf16 v[58:61], v[160:163], v[148:151], v[58:61]
	v_mfma_f32_16x16x32_bf16 v[62:65], v[164:167], v[148:151], v[62:65]
	s_waitcnt vmcnt(6) lgkmcnt(0)
	s_barrier
	v_mfma_f32_16x16x32_bf16 v[2:5], v[184:187], v[168:171], v[2:5]
	ds_read_b128 v[136:139], v224 offset:0
	v_mfma_f32_16x16x32_bf16 v[6:9], v[188:191], v[168:171], v[6:9]
	ds_read_b128 v[140:143], v224 offset:2048
	v_mfma_f32_16x16x32_bf16 v[10:13], v[192:195], v[168:171], v[10:13]
	ds_read_b128 v[144:147], v224 offset:4096
	v_mfma_f32_16x16x32_bf16 v[14:17], v[196:199], v[168:171], v[14:17]
	ds_read_b128 v[148:151], v224 offset:6144
	v_mfma_f32_16x16x32_bf16 v[18:21], v[184:187], v[172:175], v[18:21]
	ds_read_b128 v[152:155], v232 offset:0
	v_mfma_f32_16x16x32_bf16 v[22:25], v[188:191], v[172:175], v[22:25]
	ds_read_b128 v[156:159], v232 offset:2048
	v_mfma_f32_16x16x32_bf16 v[26:29], v[192:195], v[172:175], v[26:29]
	ds_read_b128 v[160:163], v232 offset:4096
	v_mfma_f32_16x16x32_bf16 v[30:33], v[196:199], v[172:175], v[30:33]
	ds_read_b128 v[164:167], v232 offset:6144
	s_add_u32 m0, s8, 0xc000
	v_mfma_f32_16x16x32_bf16 v[34:37], v[184:187], v[176:179], v[34:37]
	global_load_lds_dwordx4 v200, s[4:5]
	s_add_u32 m0, s8, 0xc400
	v_mfma_f32_16x16x32_bf16 v[38:41], v[188:191], v[176:179], v[38:41]
	global_load_lds_dwordx4 v201, s[4:5]
	s_add_u32 m0, s8, 0xc800
	v_mfma_f32_16x16x32_bf16 v[42:45], v[192:195], v[176:179], v[42:45]
	global_load_lds_dwordx4 v202, s[4:5]
	s_add_u32 m0, s8, 0xcc00
	v_mfma_f32_16x16x32_bf16 v[46:49], v[196:199], v[176:179], v[46:49]
	global_load_lds_dwordx4 v203, s[4:5]
	s_add_u32 m0, s9, 0xc000
	v_mfma_f32_16x16x32_bf16 v[50:53], v[184:187], v[180:183], v[50:53]
	global_load_lds_dwordx4 v204, s[6:7]
	s_add_u32 m0, s9, 0xc400
	v_mfma_f32_16x16x32_bf16 v[54:57], v[188:191], v[180:183], v[54:57]
	global_load_lds_dwordx4 v205, s[6:7]
	v_mfma_f32_16x16x32_bf16 v[58:61], v[192:195], v[180:183], v[58:61]
	s_add_u32 s4, s4, 0x80
	s_addc_u32 s5, s5, 0
	v_mfma_f32_16x16x32_bf16 v[62:65], v[196:199], v[180:183], v[62:65]
	s_add_u32 s6, s6, 0x80
	s_addc_u32 s7, s7, 0
	s_waitcnt lgkmcnt(0)
	v_mfma_f32_16x16x32_bf16 v[2:5], v[152:155], v[136:139], v[2:5]
	ds_read_b128 v[168:171], v229 offset:0
	v_mfma_f32_16x16x32_bf16 v[6:9], v[156:159], v[136:139], v[6:9]
	ds_read_b128 v[172:175], v229 offset:2048
	v_mfma_f32_16x16x32_bf16 v[10:13], v[160:163], v[136:139], v[10:13]
	ds_read_b128 v[176:179], v229 offset:4096
	v_mfma_f32_16x16x32_bf16 v[14:17], v[164:167], v[136:139], v[14:17]
	ds_read_b128 v[180:183], v229 offset:6144
	v_mfma_f32_16x16x32_bf16 v[18:21], v[152:155], v[140:143], v[18:21]
	ds_read_b128 v[184:187], v235 offset:0
	v_mfma_f32_16x16x32_bf16 v[22:25], v[156:159], v[140:143], v[22:25]
	ds_read_b128 v[188:191], v235 offset:2048
	v_mfma_f32_16x16x32_bf16 v[26:29], v[160:163], v[140:143], v[26:29]
	ds_read_b128 v[192:195], v235 offset:4096
	v_mfma_f32_16x16x32_bf16 v[30:33], v[164:167], v[140:143], v[30:33]
	ds_read_b128 v[196:199], v235 offset:6144
	v_mfma_f32_16x16x32_bf16 v[34:37], v[152:155], v[144:147], v[34:37]
	v_mfma_f32_16x16x32_bf16 v[38:41], v[156:159], v[144:147], v[38:41]
	v_mfma_f32_16x16x32_bf16 v[42:45], v[160:163], v[144:147], v[42:45]
	v_mfma_f32_16x16x32_bf16 v[46:49], v[164:167], v[144:147], v[46:49]
	v_mfma_f32_16x16x32_bf16 v[50:53], v[152:155], v[148:151], v[50:53]
	v_mfma_f32_16x16x32_bf16 v[54:57], v[156:159], v[148:151], v[54:57]
	v_mfma_f32_16x16x32_bf16 v[58:61], v[160:163], v[148:151], v[58:61]
	v_mfma_f32_16x16x32_bf16 v[62:65], v[164:167], v[148:151], v[62:65]
	s_waitcnt vmcnt(6) lgkmcnt(0)
	s_barrier
	v_mfma_f32_16x16x32_bf16 v[2:5], v[184:187], v[168:171], v[2:5]
	ds_read_b128 v[136:139], v218 offset:0
	v_mfma_f32_16x16x32_bf16 v[6:9], v[188:191], v[168:171], v[6:9]
	ds_read_b128 v[140:143], v218 offset:2048
	v_mfma_f32_16x16x32_bf16 v[10:13], v[192:195], v[168:171], v[10:13]
	ds_read_b128 v[144:147], v218 offset:4096
	v_mfma_f32_16x16x32_bf16 v[14:17], v[196:199], v[168:171], v[14:17]
	ds_read_b128 v[148:151], v218 offset:6144
	v_mfma_f32_16x16x32_bf16 v[18:21], v[184:187], v[172:175], v[18:21]
	ds_read_b128 v[152:155], v230 offset:0
	v_mfma_f32_16x16x32_bf16 v[22:25], v[188:191], v[172:175], v[22:25]
	ds_read_b128 v[156:159], v230 offset:2048
	v_mfma_f32_16x16x32_bf16 v[26:29], v[192:195], v[172:175], v[26:29]
	ds_read_b128 v[160:163], v230 offset:4096
	v_mfma_f32_16x16x32_bf16 v[30:33], v[196:199], v[172:175], v[30:33]
	ds_read_b128 v[164:167], v230 offset:6144
	s_add_u32 m0, s8, 0x18000
	v_mfma_f32_16x16x32_bf16 v[34:37], v[184:187], v[176:179], v[34:37]
	global_load_lds_dwordx4 v200, s[4:5]
	s_add_u32 m0, s8, 0x18400
	v_mfma_f32_16x16x32_bf16 v[38:41], v[188:191], v[176:179], v[38:41]
	global_load_lds_dwordx4 v201, s[4:5]
	s_add_u32 m0, s8, 0x18800
	v_mfma_f32_16x16x32_bf16 v[42:45], v[192:195], v[176:179], v[42:45]
	global_load_lds_dwordx4 v202, s[4:5]
	s_add_u32 m0, s8, 0x18c00
	v_mfma_f32_16x16x32_bf16 v[46:49], v[196:199], v[176:179], v[46:49]
	global_load_lds_dwordx4 v203, s[4:5]
	s_add_u32 m0, s9, 0x18000
	v_mfma_f32_16x16x32_bf16 v[50:53], v[184:187], v[180:183], v[50:53]
	global_load_lds_dwordx4 v204, s[6:7]
	s_add_u32 m0, s9, 0x18400
	v_mfma_f32_16x16x32_bf16 v[54:57], v[188:191], v[180:183], v[54:57]
	global_load_lds_dwordx4 v205, s[6:7]
	v_mfma_f32_16x16x32_bf16 v[58:61], v[192:195], v[180:183], v[58:61]
	s_add_u32 s4, s4, 0x80
	s_addc_u32 s5, s5, 0
	v_mfma_f32_16x16x32_bf16 v[62:65], v[196:199], v[180:183], v[62:65]
	s_add_u32 s6, s6, 0x80
	s_addc_u32 s7, s7, 0
	s_waitcnt lgkmcnt(0)
	v_mfma_f32_16x16x32_bf16 v[2:5], v[152:155], v[136:139], v[2:5]
	ds_read_b128 v[168:171], v225 offset:0
	v_mfma_f32_16x16x32_bf16 v[6:9], v[156:159], v[136:139], v[6:9]
	ds_read_b128 v[172:175], v225 offset:2048
	v_mfma_f32_16x16x32_bf16 v[10:13], v[160:163], v[136:139], v[10:13]
	ds_read_b128 v[176:179], v225 offset:4096
	v_mfma_f32_16x16x32_bf16 v[14:17], v[164:167], v[136:139], v[14:17]
	ds_read_b128 v[180:183], v225 offset:6144
	v_mfma_f32_16x16x32_bf16 v[18:21], v[152:155], v[140:143], v[18:21]
	ds_read_b128 v[184:187], v233 offset:0
	v_mfma_f32_16x16x32_bf16 v[22:25], v[156:159], v[140:143], v[22:25]
	ds_read_b128 v[188:191], v233 offset:2048
	v_mfma_f32_16x16x32_bf16 v[26:29], v[160:163], v[140:143], v[26:29]
	ds_read_b128 v[192:195], v233 offset:4096
	v_mfma_f32_16x16x32_bf16 v[30:33], v[164:167], v[140:143], v[30:33]
	ds_read_b128 v[196:199], v233 offset:6144
	v_mfma_f32_16x16x32_bf16 v[34:37], v[152:155], v[144:147], v[34:37]
	v_mfma_f32_16x16x32_bf16 v[38:41], v[156:159], v[144:147], v[38:41]
	v_mfma_f32_16x16x32_bf16 v[42:45], v[160:163], v[144:147], v[42:45]
	v_mfma_f32_16x16x32_bf16 v[46:49], v[164:167], v[144:147], v[46:49]
	v_mfma_f32_16x16x32_bf16 v[50:53], v[152:155], v[148:151], v[50:53]
	v_mfma_f32_16x16x32_bf16 v[54:57], v[156:159], v[148:151], v[54:57]
	v_mfma_f32_16x16x32_bf16 v[58:61], v[160:163], v[148:151], v[58:61]
	v_mfma_f32_16x16x32_bf16 v[62:65], v[164:167], v[148:151], v[62:65]
	s_waitcnt vmcnt(6) lgkmcnt(0)
	s_barrier
	v_mfma_f32_16x16x32_bf16 v[2:5], v[184:187], v[168:171], v[2:5]
	ds_read_b128 v[136:139], v219 offset:0
	v_mfma_f32_16x16x32_bf16 v[6:9], v[188:191], v[168:171], v[6:9]
	ds_read_b128 v[140:143], v219 offset:2048
	v_mfma_f32_16x16x32_bf16 v[10:13], v[192:195], v[168:171], v[10:13]
	ds_read_b128 v[144:147], v219 offset:4096
	v_mfma_f32_16x16x32_bf16 v[14:17], v[196:199], v[168:171], v[14:17]
	ds_read_b128 v[148:151], v219 offset:6144
	v_mfma_f32_16x16x32_bf16 v[18:21], v[184:187], v[172:175], v[18:21]
	ds_read_b128 v[152:155], v231 offset:0
	v_mfma_f32_16x16x32_bf16 v[22:25], v[188:191], v[172:175], v[22:25]
	ds_read_b128 v[156:159], v231 offset:2048
	v_mfma_f32_16x16x32_bf16 v[26:29], v[192:195], v[172:175], v[26:29]
	ds_read_b128 v[160:163], v231 offset:4096
	v_mfma_f32_16x16x32_bf16 v[30:33], v[196:199], v[172:175], v[30:33]
	ds_read_b128 v[164:167], v231 offset:6144
	s_mov_b32 m0, s8
	v_mfma_f32_16x16x32_bf16 v[34:37], v[184:187], v[176:179], v[34:37]
	global_load_lds_dwordx4 v200, s[4:5]
	s_add_u32 m0, s8, 0x400
	v_mfma_f32_16x16x32_bf16 v[38:41], v[188:191], v[176:179], v[38:41]
	global_load_lds_dwordx4 v201, s[4:5]
	s_add_u32 m0, s8, 0x800
	v_mfma_f32_16x16x32_bf16 v[42:45], v[192:195], v[176:179], v[42:45]
	global_load_lds_dwordx4 v202, s[4:5]
	s_add_u32 m0, s8, 0xc00
	v_mfma_f32_16x16x32_bf16 v[46:49], v[196:199], v[176:179], v[46:49]
	global_load_lds_dwordx4 v203, s[4:5]
	s_mov_b32 m0, s9
	v_mfma_f32_16x16x32_bf16 v[50:53], v[184:187], v[180:183], v[50:53]
	global_load_lds_dwordx4 v204, s[6:7]
	s_add_u32 m0, s9, 0x400
	v_mfma_f32_16x16x32_bf16 v[54:57], v[188:191], v[180:183], v[54:57]
	global_load_lds_dwordx4 v205, s[6:7]
	v_mfma_f32_16x16x32_bf16 v[58:61], v[192:195], v[180:183], v[58:61]
	s_add_u32 s4, s4, 0x80
	s_addc_u32 s5, s5, 0
	v_mfma_f32_16x16x32_bf16 v[62:65], v[196:199], v[180:183], v[62:65]
	s_add_u32 s6, s6, 0x80
	s_addc_u32 s7, s7, 0
	s_waitcnt lgkmcnt(0)
	v_mfma_f32_16x16x32_bf16 v[2:5], v[152:155], v[136:139], v[2:5]
	ds_read_b128 v[168:171], v228 offset:0
	v_mfma_f32_16x16x32_bf16 v[6:9], v[156:159], v[136:139], v[6:9]
	ds_read_b128 v[172:175], v228 offset:2048
	v_mfma_f32_16x16x32_bf16 v[10:13], v[160:163], v[136:139], v[10:13]
	ds_read_b128 v[176:179], v228 offset:4096
	v_mfma_f32_16x16x32_bf16 v[14:17], v[164:167], v[136:139], v[14:17]
	ds_read_b128 v[180:183], v228 offset:6144
	v_mfma_f32_16x16x32_bf16 v[18:21], v[152:155], v[140:143], v[18:21]
	ds_read_b128 v[184:187], v234 offset:0
	v_mfma_f32_16x16x32_bf16 v[22:25], v[156:159], v[140:143], v[22:25]
	ds_read_b128 v[188:191], v234 offset:2048
	v_mfma_f32_16x16x32_bf16 v[26:29], v[160:163], v[140:143], v[26:29]
	ds_read_b128 v[192:195], v234 offset:4096
	v_mfma_f32_16x16x32_bf16 v[30:33], v[164:167], v[140:143], v[30:33]
	ds_read_b128 v[196:199], v234 offset:6144
	v_mfma_f32_16x16x32_bf16 v[34:37], v[152:155], v[144:147], v[34:37]
	v_mfma_f32_16x16x32_bf16 v[38:41], v[156:159], v[144:147], v[38:41]
	v_mfma_f32_16x16x32_bf16 v[42:45], v[160:163], v[144:147], v[42:45]
	v_mfma_f32_16x16x32_bf16 v[46:49], v[164:167], v[144:147], v[46:49]
	v_mfma_f32_16x16x32_bf16 v[50:53], v[152:155], v[148:151], v[50:53]
	v_mfma_f32_16x16x32_bf16 v[54:57], v[156:159], v[148:151], v[54:57]
	v_mfma_f32_16x16x32_bf16 v[58:61], v[160:163], v[148:151], v[58:61]
	v_mfma_f32_16x16x32_bf16 v[62:65], v[164:167], v[148:151], v[62:65]
	s_waitcnt vmcnt(6) lgkmcnt(0)
	s_barrier
	v_mfma_f32_16x16x32_bf16 v[2:5], v[184:187], v[168:171], v[2:5]
	ds_read_b128 v[136:139], v224 offset:0
	v_mfma_f32_16x16x32_bf16 v[6:9], v[188:191], v[168:171], v[6:9]
	ds_read_b128 v[140:143], v224 offset:2048
	v_mfma_f32_16x16x32_bf16 v[10:13], v[192:195], v[168:171], v[10:13]
	ds_read_b128 v[144:147], v224 offset:4096
	v_mfma_f32_16x16x32_bf16 v[14:17], v[196:199], v[168:171], v[14:17]
	ds_read_b128 v[148:151], v224 offset:6144
	v_mfma_f32_16x16x32_bf16 v[18:21], v[184:187], v[172:175], v[18:21]
	ds_read_b128 v[152:155], v232 offset:0
	v_mfma_f32_16x16x32_bf16 v[22:25], v[188:191], v[172:175], v[22:25]
	ds_read_b128 v[156:159], v232 offset:2048
	v_mfma_f32_16x16x32_bf16 v[26:29], v[192:195], v[172:175], v[26:29]
	ds_read_b128 v[160:163], v232 offset:4096
	v_mfma_f32_16x16x32_bf16 v[30:33], v[196:199], v[172:175], v[30:33]
	ds_read_b128 v[164:167], v232 offset:6144
	s_add_u32 m0, s8, 0xc000
	v_mfma_f32_16x16x32_bf16 v[34:37], v[184:187], v[176:179], v[34:37]
	global_load_lds_dwordx4 v200, s[4:5]
	s_add_u32 m0, s8, 0xc400
	v_mfma_f32_16x16x32_bf16 v[38:41], v[188:191], v[176:179], v[38:41]
	global_load_lds_dwordx4 v201, s[4:5]
	s_add_u32 m0, s8, 0xc800
	v_mfma_f32_16x16x32_bf16 v[42:45], v[192:195], v[176:179], v[42:45]
	global_load_lds_dwordx4 v202, s[4:5]
	s_add_u32 m0, s8, 0xcc00
	v_mfma_f32_16x16x32_bf16 v[46:49], v[196:199], v[176:179], v[46:49]
	global_load_lds_dwordx4 v203, s[4:5]
	s_add_u32 m0, s9, 0xc000
	v_mfma_f32_16x16x32_bf16 v[50:53], v[184:187], v[180:183], v[50:53]
	global_load_lds_dwordx4 v204, s[6:7]
	s_add_u32 m0, s9, 0xc400
	v_mfma_f32_16x16x32_bf16 v[54:57], v[188:191], v[180:183], v[54:57]
	global_load_lds_dwordx4 v205, s[6:7]
	v_mfma_f32_16x16x32_bf16 v[58:61], v[192:195], v[180:183], v[58:61]
	s_add_u32 s4, s4, 0x80
	s_addc_u32 s5, s5, 0
	v_mfma_f32_16x16x32_bf16 v[62:65], v[196:199], v[180:183], v[62:65]
	s_add_u32 s6, s6, 0x80
	s_addc_u32 s7, s7, 0
	s_waitcnt lgkmcnt(0)
	v_mfma_f32_16x16x32_bf16 v[2:5], v[152:155], v[136:139], v[2:5]
	ds_read_b128 v[168:171], v229 offset:0
	v_mfma_f32_16x16x32_bf16 v[6:9], v[156:159], v[136:139], v[6:9]
	ds_read_b128 v[172:175], v229 offset:2048
	v_mfma_f32_16x16x32_bf16 v[10:13], v[160:163], v[136:139], v[10:13]
	ds_read_b128 v[176:179], v229 offset:4096
	v_mfma_f32_16x16x32_bf16 v[14:17], v[164:167], v[136:139], v[14:17]
	ds_read_b128 v[180:183], v229 offset:6144
	v_mfma_f32_16x16x32_bf16 v[18:21], v[152:155], v[140:143], v[18:21]
	ds_read_b128 v[184:187], v235 offset:0
	v_mfma_f32_16x16x32_bf16 v[22:25], v[156:159], v[140:143], v[22:25]
	ds_read_b128 v[188:191], v235 offset:2048
	v_mfma_f32_16x16x32_bf16 v[26:29], v[160:163], v[140:143], v[26:29]
	ds_read_b128 v[192:195], v235 offset:4096
	v_mfma_f32_16x16x32_bf16 v[30:33], v[164:167], v[140:143], v[30:33]
	ds_read_b128 v[196:199], v235 offset:6144
	v_mfma_f32_16x16x32_bf16 v[34:37], v[152:155], v[144:147], v[34:37]
	v_mfma_f32_16x16x32_bf16 v[38:41], v[156:159], v[144:147], v[38:41]
	v_mfma_f32_16x16x32_bf16 v[42:45], v[160:163], v[144:147], v[42:45]
	v_mfma_f32_16x16x32_bf16 v[46:49], v[164:167], v[144:147], v[46:49]
	v_mfma_f32_16x16x32_bf16 v[50:53], v[152:155], v[148:151], v[50:53]
	v_mfma_f32_16x16x32_bf16 v[54:57], v[156:159], v[148:151], v[54:57]
	v_mfma_f32_16x16x32_bf16 v[58:61], v[160:163], v[148:151], v[58:61]
	v_mfma_f32_16x16x32_bf16 v[62:65], v[164:167], v[148:151], v[62:65]
	s_waitcnt vmcnt(6) lgkmcnt(0)
	s_barrier
	v_mfma_f32_16x16x32_bf16 v[2:5], v[184:187], v[168:171], v[2:5]
	ds_read_b128 v[136:139], v218 offset:0
	v_mfma_f32_16x16x32_bf16 v[6:9], v[188:191], v[168:171], v[6:9]
	ds_read_b128 v[140:143], v218 offset:2048
	v_mfma_f32_16x16x32_bf16 v[10:13], v[192:195], v[168:171], v[10:13]
	ds_read_b128 v[144:147], v218 offset:4096
	v_mfma_f32_16x16x32_bf16 v[14:17], v[196:199], v[168:171], v[14:17]
	ds_read_b128 v[148:151], v218 offset:6144
	v_mfma_f32_16x16x32_bf16 v[18:21], v[184:187], v[172:175], v[18:21]
	ds_read_b128 v[152:155], v230 offset:0
	v_mfma_f32_16x16x32_bf16 v[22:25], v[188:191], v[172:175], v[22:25]
	ds_read_b128 v[156:159], v230 offset:2048
	v_mfma_f32_16x16x32_bf16 v[26:29], v[192:195], v[172:175], v[26:29]
	ds_read_b128 v[160:163], v230 offset:4096
	v_mfma_f32_16x16x32_bf16 v[30:33], v[196:199], v[172:175], v[30:33]
	ds_read_b128 v[164:167], v230 offset:6144
	s_add_u32 m0, s8, 0x18000
	v_mfma_f32_16x16x32_bf16 v[34:37], v[184:187], v[176:179], v[34:37]
	global_load_lds_dwordx4 v200, s[4:5]
	s_add_u32 m0, s8, 0x18400
	v_mfma_f32_16x16x32_bf16 v[38:41], v[188:191], v[176:179], v[38:41]
	global_load_lds_dwordx4 v201, s[4:5]
	s_add_u32 m0, s8, 0x18800
	v_mfma_f32_16x16x32_bf16 v[42:45], v[192:195], v[176:179], v[42:45]
	global_load_lds_dwordx4 v202, s[4:5]
	s_add_u32 m0, s8, 0x18c00
	v_mfma_f32_16x16x32_bf16 v[46:49], v[196:199], v[176:179], v[46:49]
	global_load_lds_dwordx4 v203, s[4:5]
	s_add_u32 m0, s9, 0x18000
	v_mfma_f32_16x16x32_bf16 v[50:53], v[184:187], v[180:183], v[50:53]
	global_load_lds_dwordx4 v204, s[6:7]
	s_add_u32 m0, s9, 0x18400
	v_mfma_f32_16x16x32_bf16 v[54:57], v[188:191], v[180:183], v[54:57]
	global_load_lds_dwordx4 v205, s[6:7]
	v_mfma_f32_16x16x32_bf16 v[58:61], v[192:195], v[180:183], v[58:61]
	s_add_u32 s4, s4, 0x80
	s_addc_u32 s5, s5, 0
	v_mfma_f32_16x16x32_bf16 v[62:65], v[196:199], v[180:183], v[62:65]
	s_add_u32 s6, s6, 0x80
	s_addc_u32 s7, s7, 0
	s_waitcnt lgkmcnt(0)
	v_mfma_f32_16x16x32_bf16 v[2:5], v[152:155], v[136:139], v[2:5]
	ds_read_b128 v[168:171], v225 offset:0
	v_mfma_f32_16x16x32_bf16 v[6:9], v[156:159], v[136:139], v[6:9]
	ds_read_b128 v[172:175], v225 offset:2048
	v_mfma_f32_16x16x32_bf16 v[10:13], v[160:163], v[136:139], v[10:13]
	ds_read_b128 v[176:179], v225 offset:4096
	v_mfma_f32_16x16x32_bf16 v[14:17], v[164:167], v[136:139], v[14:17]
	ds_read_b128 v[180:183], v225 offset:6144
	v_mfma_f32_16x16x32_bf16 v[18:21], v[152:155], v[140:143], v[18:21]
	ds_read_b128 v[184:187], v233 offset:0
	v_mfma_f32_16x16x32_bf16 v[22:25], v[156:159], v[140:143], v[22:25]
	ds_read_b128 v[188:191], v233 offset:2048
	v_mfma_f32_16x16x32_bf16 v[26:29], v[160:163], v[140:143], v[26:29]
	ds_read_b128 v[192:195], v233 offset:4096
	v_mfma_f32_16x16x32_bf16 v[30:33], v[164:167], v[140:143], v[30:33]
	ds_read_b128 v[196:199], v233 offset:6144
	v_mfma_f32_16x16x32_bf16 v[34:37], v[152:155], v[144:147], v[34:37]
	v_mfma_f32_16x16x32_bf16 v[38:41], v[156:159], v[144:147], v[38:41]
	v_mfma_f32_16x16x32_bf16 v[42:45], v[160:163], v[144:147], v[42:45]
	v_mfma_f32_16x16x32_bf16 v[46:49], v[164:167], v[144:147], v[46:49]
	v_mfma_f32_16x16x32_bf16 v[50:53], v[152:155], v[148:151], v[50:53]
	v_mfma_f32_16x16x32_bf16 v[54:57], v[156:159], v[148:151], v[54:57]
	v_mfma_f32_16x16x32_bf16 v[58:61], v[160:163], v[148:151], v[58:61]
	v_mfma_f32_16x16x32_bf16 v[62:65], v[164:167], v[148:151], v[62:65]
	s_waitcnt vmcnt(6) lgkmcnt(0)
	s_barrier
	v_mfma_f32_16x16x32_bf16 v[2:5], v[184:187], v[168:171], v[2:5]
	ds_read_b128 v[136:139], v219 offset:0
	v_mfma_f32_16x16x32_bf16 v[6:9], v[188:191], v[168:171], v[6:9]
	ds_read_b128 v[140:143], v219 offset:2048
	v_mfma_f32_16x16x32_bf16 v[10:13], v[192:195], v[168:171], v[10:13]
	ds_read_b128 v[144:147], v219 offset:4096
	v_mfma_f32_16x16x32_bf16 v[14:17], v[196:199], v[168:171], v[14:17]
	ds_read_b128 v[148:151], v219 offset:6144
	v_mfma_f32_16x16x32_bf16 v[18:21], v[184:187], v[172:175], v[18:21]
	ds_read_b128 v[152:155], v231 offset:0
	v_mfma_f32_16x16x32_bf16 v[22:25], v[188:191], v[172:175], v[22:25]
	ds_read_b128 v[156:159], v231 offset:2048
	v_mfma_f32_16x16x32_bf16 v[26:29], v[192:195], v[172:175], v[26:29]
	ds_read_b128 v[160:163], v231 offset:4096
	v_mfma_f32_16x16x32_bf16 v[30:33], v[196:199], v[172:175], v[30:33]
	ds_read_b128 v[164:167], v231 offset:6144
	s_mov_b32 m0, s8
	v_mfma_f32_16x16x32_bf16 v[34:37], v[184:187], v[176:179], v[34:37]
	global_load_lds_dwordx4 v200, s[4:5]
	s_add_u32 m0, s8, 0x400
	v_mfma_f32_16x16x32_bf16 v[38:41], v[188:191], v[176:179], v[38:41]
	global_load_lds_dwordx4 v201, s[4:5]
	s_add_u32 m0, s8, 0x800
	v_mfma_f32_16x16x32_bf16 v[42:45], v[192:195], v[176:179], v[42:45]
	global_load_lds_dwordx4 v202, s[4:5]
	s_add_u32 m0, s8, 0xc00
	v_mfma_f32_16x16x32_bf16 v[46:49], v[196:199], v[176:179], v[46:49]
	global_load_lds_dwordx4 v203, s[4:5]
	s_mov_b32 m0, s9
	v_mfma_f32_16x16x32_bf16 v[50:53], v[184:187], v[180:183], v[50:53]
	global_load_lds_dwordx4 v204, s[6:7]
	s_add_u32 m0, s9, 0x400
	v_mfma_f32_16x16x32_bf16 v[54:57], v[188:191], v[180:183], v[54:57]
	global_load_lds_dwordx4 v205, s[6:7]
	v_mfma_f32_16x16x32_bf16 v[58:61], v[192:195], v[180:183], v[58:61]
	s_add_u32 s4, s4, 0x80
	s_addc_u32 s5, s5, 0
	v_mfma_f32_16x16x32_bf16 v[62:65], v[196:199], v[180:183], v[62:65]
	s_add_u32 s6, s6, 0x80
	s_addc_u32 s7, s7, 0
	s_waitcnt lgkmcnt(0)
	v_mfma_f32_16x16x32_bf16 v[2:5], v[152:155], v[136:139], v[2:5]
	ds_read_b128 v[168:171], v228 offset:0
	v_mfma_f32_16x16x32_bf16 v[6:9], v[156:159], v[136:139], v[6:9]
	ds_read_b128 v[172:175], v228 offset:2048
	v_mfma_f32_16x16x32_bf16 v[10:13], v[160:163], v[136:139], v[10:13]
	ds_read_b128 v[176:179], v228 offset:4096
	v_mfma_f32_16x16x32_bf16 v[14:17], v[164:167], v[136:139], v[14:17]
	ds_read_b128 v[180:183], v228 offset:6144
	v_mfma_f32_16x16x32_bf16 v[18:21], v[152:155], v[140:143], v[18:21]
	ds_read_b128 v[184:187], v234 offset:0
	v_mfma_f32_16x16x32_bf16 v[22:25], v[156:159], v[140:143], v[22:25]
	ds_read_b128 v[188:191], v234 offset:2048
	v_mfma_f32_16x16x32_bf16 v[26:29], v[160:163], v[140:143], v[26:29]
	ds_read_b128 v[192:195], v234 offset:4096
	v_mfma_f32_16x16x32_bf16 v[30:33], v[164:167], v[140:143], v[30:33]
	ds_read_b128 v[196:199], v234 offset:6144
	v_mfma_f32_16x16x32_bf16 v[34:37], v[152:155], v[144:147], v[34:37]
	v_mfma_f32_16x16x32_bf16 v[38:41], v[156:159], v[144:147], v[38:41]
	v_mfma_f32_16x16x32_bf16 v[42:45], v[160:163], v[144:147], v[42:45]
	v_mfma_f32_16x16x32_bf16 v[46:49], v[164:167], v[144:147], v[46:49]
	v_mfma_f32_16x16x32_bf16 v[50:53], v[152:155], v[148:151], v[50:53]
	v_mfma_f32_16x16x32_bf16 v[54:57], v[156:159], v[148:151], v[54:57]
	v_mfma_f32_16x16x32_bf16 v[58:61], v[160:163], v[148:151], v[58:61]
	v_mfma_f32_16x16x32_bf16 v[62:65], v[164:167], v[148:151], v[62:65]
	s_waitcnt vmcnt(6) lgkmcnt(0)
	s_barrier
	v_mfma_f32_16x16x32_bf16 v[2:5], v[184:187], v[168:171], v[2:5]
	ds_read_b128 v[136:139], v224 offset:0
	v_mfma_f32_16x16x32_bf16 v[6:9], v[188:191], v[168:171], v[6:9]
	ds_read_b128 v[140:143], v224 offset:2048
	v_mfma_f32_16x16x32_bf16 v[10:13], v[192:195], v[168:171], v[10:13]
	ds_read_b128 v[144:147], v224 offset:4096
	v_mfma_f32_16x16x32_bf16 v[14:17], v[196:199], v[168:171], v[14:17]
	ds_read_b128 v[148:151], v224 offset:6144
	v_mfma_f32_16x16x32_bf16 v[18:21], v[184:187], v[172:175], v[18:21]
	ds_read_b128 v[152:155], v232 offset:0
	v_mfma_f32_16x16x32_bf16 v[22:25], v[188:191], v[172:175], v[22:25]
	ds_read_b128 v[156:159], v232 offset:2048
	v_mfma_f32_16x16x32_bf16 v[26:29], v[192:195], v[172:175], v[26:29]
	ds_read_b128 v[160:163], v232 offset:4096
	v_mfma_f32_16x16x32_bf16 v[30:33], v[196:199], v[172:175], v[30:33]
	ds_read_b128 v[164:167], v232 offset:6144
	s_add_u32 m0, s8, 0xc000
	v_mfma_f32_16x16x32_bf16 v[34:37], v[184:187], v[176:179], v[34:37]
	global_load_lds_dwordx4 v200, s[4:5]
	s_add_u32 m0, s8, 0xc400
	v_mfma_f32_16x16x32_bf16 v[38:41], v[188:191], v[176:179], v[38:41]
	global_load_lds_dwordx4 v201, s[4:5]
	s_add_u32 m0, s8, 0xc800
	v_mfma_f32_16x16x32_bf16 v[42:45], v[192:195], v[176:179], v[42:45]
	global_load_lds_dwordx4 v202, s[4:5]
	s_add_u32 m0, s8, 0xcc00
	v_mfma_f32_16x16x32_bf16 v[46:49], v[196:199], v[176:179], v[46:49]
	global_load_lds_dwordx4 v203, s[4:5]
	s_add_u32 m0, s9, 0xc000
	v_mfma_f32_16x16x32_bf16 v[50:53], v[184:187], v[180:183], v[50:53]
	global_load_lds_dwordx4 v204, s[6:7]
	s_add_u32 m0, s9, 0xc400
	v_mfma_f32_16x16x32_bf16 v[54:57], v[188:191], v[180:183], v[54:57]
	global_load_lds_dwordx4 v205, s[6:7]
	v_mfma_f32_16x16x32_bf16 v[58:61], v[192:195], v[180:183], v[58:61]
	s_add_u32 s4, s4, 0x80
	s_addc_u32 s5, s5, 0
	v_mfma_f32_16x16x32_bf16 v[62:65], v[196:199], v[180:183], v[62:65]
	s_add_u32 s6, s6, 0x80
	s_addc_u32 s7, s7, 0
	s_waitcnt lgkmcnt(0)
	v_mfma_f32_16x16x32_bf16 v[2:5], v[152:155], v[136:139], v[2:5]
	ds_read_b128 v[168:171], v229 offset:0
	v_mfma_f32_16x16x32_bf16 v[6:9], v[156:159], v[136:139], v[6:9]
	ds_read_b128 v[172:175], v229 offset:2048
	v_mfma_f32_16x16x32_bf16 v[10:13], v[160:163], v[136:139], v[10:13]
	ds_read_b128 v[176:179], v229 offset:4096
	v_mfma_f32_16x16x32_bf16 v[14:17], v[164:167], v[136:139], v[14:17]
	ds_read_b128 v[180:183], v229 offset:6144
	v_mfma_f32_16x16x32_bf16 v[18:21], v[152:155], v[140:143], v[18:21]
	ds_read_b128 v[184:187], v235 offset:0
	v_mfma_f32_16x16x32_bf16 v[22:25], v[156:159], v[140:143], v[22:25]
	ds_read_b128 v[188:191], v235 offset:2048
	v_mfma_f32_16x16x32_bf16 v[26:29], v[160:163], v[140:143], v[26:29]
	ds_read_b128 v[192:195], v235 offset:4096
	v_mfma_f32_16x16x32_bf16 v[30:33], v[164:167], v[140:143], v[30:33]
	ds_read_b128 v[196:199], v235 offset:6144
	v_mfma_f32_16x16x32_bf16 v[34:37], v[152:155], v[144:147], v[34:37]
	v_mfma_f32_16x16x32_bf16 v[38:41], v[156:159], v[144:147], v[38:41]
	v_mfma_f32_16x16x32_bf16 v[42:45], v[160:163], v[144:147], v[42:45]
	v_mfma_f32_16x16x32_bf16 v[46:49], v[164:167], v[144:147], v[46:49]
	v_mfma_f32_16x16x32_bf16 v[50:53], v[152:155], v[148:151], v[50:53]
	v_mfma_f32_16x16x32_bf16 v[54:57], v[156:159], v[148:151], v[54:57]
	v_mfma_f32_16x16x32_bf16 v[58:61], v[160:163], v[148:151], v[58:61]
	v_mfma_f32_16x16x32_bf16 v[62:65], v[164:167], v[148:151], v[62:65]
	s_waitcnt vmcnt(6) lgkmcnt(0)
	s_barrier
	v_mfma_f32_16x16x32_bf16 v[2:5], v[184:187], v[168:171], v[2:5]
	ds_read_b128 v[136:139], v218 offset:0
	v_mfma_f32_16x16x32_bf16 v[6:9], v[188:191], v[168:171], v[6:9]
	ds_read_b128 v[140:143], v218 offset:2048
	v_mfma_f32_16x16x32_bf16 v[10:13], v[192:195], v[168:171], v[10:13]
	ds_read_b128 v[144:147], v218 offset:4096
	v_mfma_f32_16x16x32_bf16 v[14:17], v[196:199], v[168:171], v[14:17]
	ds_read_b128 v[148:151], v218 offset:6144
	v_mfma_f32_16x16x32_bf16 v[18:21], v[184:187], v[172:175], v[18:21]
	ds_read_b128 v[152:155], v230 offset:0
	v_mfma_f32_16x16x32_bf16 v[22:25], v[188:191], v[172:175], v[22:25]
	ds_read_b128 v[156:159], v230 offset:2048
	v_mfma_f32_16x16x32_bf16 v[26:29], v[192:195], v[172:175], v[26:29]
	ds_read_b128 v[160:163], v230 offset:4096
	v_mfma_f32_16x16x32_bf16 v[30:33], v[196:199], v[172:175], v[30:33]
	ds_read_b128 v[164:167], v230 offset:6144
	s_add_u32 m0, s8, 0x18000
	v_mfma_f32_16x16x32_bf16 v[34:37], v[184:187], v[176:179], v[34:37]
	global_load_lds_dwordx4 v200, s[4:5]
	s_add_u32 m0, s8, 0x18400
	v_mfma_f32_16x16x32_bf16 v[38:41], v[188:191], v[176:179], v[38:41]
	global_load_lds_dwordx4 v201, s[4:5]
	s_add_u32 m0, s8, 0x18800
	v_mfma_f32_16x16x32_bf16 v[42:45], v[192:195], v[176:179], v[42:45]
	global_load_lds_dwordx4 v202, s[4:5]
	s_add_u32 m0, s8, 0x18c00
	v_mfma_f32_16x16x32_bf16 v[46:49], v[196:199], v[176:179], v[46:49]
	global_load_lds_dwordx4 v203, s[4:5]
	s_add_u32 m0, s9, 0x18000
	v_mfma_f32_16x16x32_bf16 v[50:53], v[184:187], v[180:183], v[50:53]
	global_load_lds_dwordx4 v204, s[6:7]
	s_add_u32 m0, s9, 0x18400
	v_mfma_f32_16x16x32_bf16 v[54:57], v[188:191], v[180:183], v[54:57]
	global_load_lds_dwordx4 v205, s[6:7]
	v_mfma_f32_16x16x32_bf16 v[58:61], v[192:195], v[180:183], v[58:61]
	s_add_u32 s4, s4, 0x80
	s_addc_u32 s5, s5, 0
	v_mfma_f32_16x16x32_bf16 v[62:65], v[196:199], v[180:183], v[62:65]
	s_add_u32 s6, s6, 0x80
	s_addc_u32 s7, s7, 0
	s_waitcnt lgkmcnt(0)
	v_mfma_f32_16x16x32_bf16 v[2:5], v[152:155], v[136:139], v[2:5]
	ds_read_b128 v[168:171], v225 offset:0
	v_mfma_f32_16x16x32_bf16 v[6:9], v[156:159], v[136:139], v[6:9]
	ds_read_b128 v[172:175], v225 offset:2048
	v_mfma_f32_16x16x32_bf16 v[10:13], v[160:163], v[136:139], v[10:13]
	ds_read_b128 v[176:179], v225 offset:4096
	v_mfma_f32_16x16x32_bf16 v[14:17], v[164:167], v[136:139], v[14:17]
	ds_read_b128 v[180:183], v225 offset:6144
	v_mfma_f32_16x16x32_bf16 v[18:21], v[152:155], v[140:143], v[18:21]
	ds_read_b128 v[184:187], v233 offset:0
	v_mfma_f32_16x16x32_bf16 v[22:25], v[156:159], v[140:143], v[22:25]
	ds_read_b128 v[188:191], v233 offset:2048
	v_mfma_f32_16x16x32_bf16 v[26:29], v[160:163], v[140:143], v[26:29]
	ds_read_b128 v[192:195], v233 offset:4096
	v_mfma_f32_16x16x32_bf16 v[30:33], v[164:167], v[140:143], v[30:33]
	ds_read_b128 v[196:199], v233 offset:6144
	v_mfma_f32_16x16x32_bf16 v[34:37], v[152:155], v[144:147], v[34:37]
	v_mfma_f32_16x16x32_bf16 v[38:41], v[156:159], v[144:147], v[38:41]
	v_mfma_f32_16x16x32_bf16 v[42:45], v[160:163], v[144:147], v[42:45]
	v_mfma_f32_16x16x32_bf16 v[46:49], v[164:167], v[144:147], v[46:49]
	v_mfma_f32_16x16x32_bf16 v[50:53], v[152:155], v[148:151], v[50:53]
	v_mfma_f32_16x16x32_bf16 v[54:57], v[156:159], v[148:151], v[54:57]
	v_mfma_f32_16x16x32_bf16 v[58:61], v[160:163], v[148:151], v[58:61]
	v_mfma_f32_16x16x32_bf16 v[62:65], v[164:167], v[148:151], v[62:65]
	s_waitcnt vmcnt(6) lgkmcnt(0)
	s_barrier
	v_mfma_f32_16x16x32_bf16 v[2:5], v[184:187], v[168:171], v[2:5]
	ds_read_b128 v[136:139], v219 offset:0
	v_mfma_f32_16x16x32_bf16 v[6:9], v[188:191], v[168:171], v[6:9]
	ds_read_b128 v[140:143], v219 offset:2048
	v_mfma_f32_16x16x32_bf16 v[10:13], v[192:195], v[168:171], v[10:13]
	ds_read_b128 v[144:147], v219 offset:4096
	v_mfma_f32_16x16x32_bf16 v[14:17], v[196:199], v[168:171], v[14:17]
	ds_read_b128 v[148:151], v219 offset:6144
	v_mfma_f32_16x16x32_bf16 v[18:21], v[184:187], v[172:175], v[18:21]
	ds_read_b128 v[152:155], v231 offset:0
	v_mfma_f32_16x16x32_bf16 v[22:25], v[188:191], v[172:175], v[22:25]
	ds_read_b128 v[156:159], v231 offset:2048
	v_mfma_f32_16x16x32_bf16 v[26:29], v[192:195], v[172:175], v[26:29]
	ds_read_b128 v[160:163], v231 offset:4096
	v_mfma_f32_16x16x32_bf16 v[30:33], v[196:199], v[172:175], v[30:33]
	ds_read_b128 v[164:167], v231 offset:6144
	s_mov_b32 m0, s8
	v_mfma_f32_16x16x32_bf16 v[34:37], v[184:187], v[176:179], v[34:37]
	global_load_lds_dwordx4 v200, s[4:5]
	s_add_u32 m0, s8, 0x400
	v_mfma_f32_16x16x32_bf16 v[38:41], v[188:191], v[176:179], v[38:41]
	global_load_lds_dwordx4 v201, s[4:5]
	s_add_u32 m0, s8, 0x800
	v_mfma_f32_16x16x32_bf16 v[42:45], v[192:195], v[176:179], v[42:45]
	global_load_lds_dwordx4 v202, s[4:5]
	s_add_u32 m0, s8, 0xc00
	v_mfma_f32_16x16x32_bf16 v[46:49], v[196:199], v[176:179], v[46:49]
	global_load_lds_dwordx4 v203, s[4:5]
	s_mov_b32 m0, s9
	v_mfma_f32_16x16x32_bf16 v[50:53], v[184:187], v[180:183], v[50:53]
	global_load_lds_dwordx4 v204, s[6:7]
	s_add_u32 m0, s9, 0x400
	v_mfma_f32_16x16x32_bf16 v[54:57], v[188:191], v[180:183], v[54:57]
	global_load_lds_dwordx4 v205, s[6:7]
	v_mfma_f32_16x16x32_bf16 v[58:61], v[192:195], v[180:183], v[58:61]
	s_sub_u32 s4, s4, 0x780
	s_subb_u32 s5, s5, 0
	v_mfma_f32_16x16x32_bf16 v[62:65], v[196:199], v[180:183], v[62:65]
	s_add_u32 s6, s6, 0x3f880
	s_addc_u32 s7, s7, 0
	s_waitcnt lgkmcnt(0)
	v_mfma_f32_16x16x32_bf16 v[2:5], v[152:155], v[136:139], v[2:5]
	ds_read_b128 v[168:171], v228 offset:0
	v_mfma_f32_16x16x32_bf16 v[6:9], v[156:159], v[136:139], v[6:9]
	ds_read_b128 v[172:175], v228 offset:2048
	v_mfma_f32_16x16x32_bf16 v[10:13], v[160:163], v[136:139], v[10:13]
	ds_read_b128 v[176:179], v228 offset:4096
	v_mfma_f32_16x16x32_bf16 v[14:17], v[164:167], v[136:139], v[14:17]
	ds_read_b128 v[180:183], v228 offset:6144
	v_mfma_f32_16x16x32_bf16 v[18:21], v[152:155], v[140:143], v[18:21]
	ds_read_b128 v[184:187], v234 offset:0
	v_mfma_f32_16x16x32_bf16 v[22:25], v[156:159], v[140:143], v[22:25]
	ds_read_b128 v[188:191], v234 offset:2048
	v_mfma_f32_16x16x32_bf16 v[26:29], v[160:163], v[140:143], v[26:29]
	ds_read_b128 v[192:195], v234 offset:4096
	v_mfma_f32_16x16x32_bf16 v[30:33], v[164:167], v[140:143], v[30:33]
	ds_read_b128 v[196:199], v234 offset:6144
	v_mfma_f32_16x16x32_bf16 v[34:37], v[152:155], v[144:147], v[34:37]
	v_mfma_f32_16x16x32_bf16 v[38:41], v[156:159], v[144:147], v[38:41]
	v_mfma_f32_16x16x32_bf16 v[42:45], v[160:163], v[144:147], v[42:45]
	v_mfma_f32_16x16x32_bf16 v[46:49], v[164:167], v[144:147], v[46:49]
	v_mfma_f32_16x16x32_bf16 v[50:53], v[152:155], v[148:151], v[50:53]
	v_mfma_f32_16x16x32_bf16 v[54:57], v[156:159], v[148:151], v[54:57]
	v_mfma_f32_16x16x32_bf16 v[58:61], v[160:163], v[148:151], v[58:61]
	v_mfma_f32_16x16x32_bf16 v[62:65], v[164:167], v[148:151], v[62:65]
	s_waitcnt vmcnt(6) lgkmcnt(0)
	s_barrier
	v_mfma_f32_16x16x32_bf16 v[2:5], v[184:187], v[168:171], v[2:5]
	ds_read_b128 v[136:139], v224 offset:0
	v_mfma_f32_16x16x32_bf16 v[6:9], v[188:191], v[168:171], v[6:9]
	ds_read_b128 v[140:143], v224 offset:2048
	v_mfma_f32_16x16x32_bf16 v[10:13], v[192:195], v[168:171], v[10:13]
	ds_read_b128 v[144:147], v224 offset:4096
	v_mfma_f32_16x16x32_bf16 v[14:17], v[196:199], v[168:171], v[14:17]
	ds_read_b128 v[148:151], v224 offset:6144
	v_mfma_f32_16x16x32_bf16 v[18:21], v[184:187], v[172:175], v[18:21]
	ds_read_b128 v[152:155], v232 offset:0
	v_mfma_f32_16x16x32_bf16 v[22:25], v[188:191], v[172:175], v[22:25]
	ds_read_b128 v[156:159], v232 offset:2048
	v_mfma_f32_16x16x32_bf16 v[26:29], v[192:195], v[172:175], v[26:29]
	ds_read_b128 v[160:163], v232 offset:4096
	v_mfma_f32_16x16x32_bf16 v[30:33], v[196:199], v[172:175], v[30:33]
	ds_read_b128 v[164:167], v232 offset:6144
	s_add_u32 m0, s8, 0xc000
	v_mfma_f32_16x16x32_bf16 v[34:37], v[184:187], v[176:179], v[34:37]
	global_load_lds_dwordx4 v200, s[4:5]
	s_add_u32 m0, s8, 0xc400
	v_mfma_f32_16x16x32_bf16 v[38:41], v[188:191], v[176:179], v[38:41]
	global_load_lds_dwordx4 v201, s[4:5]
	s_add_u32 m0, s8, 0xc800
	v_mfma_f32_16x16x32_bf16 v[42:45], v[192:195], v[176:179], v[42:45]
	global_load_lds_dwordx4 v202, s[4:5]
	s_add_u32 m0, s8, 0xcc00
	v_mfma_f32_16x16x32_bf16 v[46:49], v[196:199], v[176:179], v[46:49]
	global_load_lds_dwordx4 v203, s[4:5]
	s_add_u32 m0, s9, 0xc000
	v_mfma_f32_16x16x32_bf16 v[50:53], v[184:187], v[180:183], v[50:53]
	global_load_lds_dwordx4 v204, s[6:7]
	s_add_u32 m0, s9, 0xc400
	v_mfma_f32_16x16x32_bf16 v[54:57], v[188:191], v[180:183], v[54:57]
	global_load_lds_dwordx4 v205, s[6:7]
	v_mfma_f32_16x16x32_bf16 v[58:61], v[192:195], v[180:183], v[58:61]
	s_add_u32 s4, s4, 0x80
	s_addc_u32 s5, s5, 0
	v_mfma_f32_16x16x32_bf16 v[62:65], v[196:199], v[180:183], v[62:65]
	s_add_u32 s6, s6, 0x80
	s_addc_u32 s7, s7, 0
	s_waitcnt lgkmcnt(0)
	v_mfma_f32_16x16x32_bf16 v[2:5], v[152:155], v[136:139], v[2:5]
	ds_read_b128 v[168:171], v229 offset:0
	v_mfma_f32_16x16x32_bf16 v[6:9], v[156:159], v[136:139], v[6:9]
	ds_read_b128 v[172:175], v229 offset:2048
	v_mfma_f32_16x16x32_bf16 v[10:13], v[160:163], v[136:139], v[10:13]
	ds_read_b128 v[176:179], v229 offset:4096
	v_mfma_f32_16x16x32_bf16 v[14:17], v[164:167], v[136:139], v[14:17]
	ds_read_b128 v[180:183], v229 offset:6144
	v_mfma_f32_16x16x32_bf16 v[18:21], v[152:155], v[140:143], v[18:21]
	ds_read_b128 v[184:187], v235 offset:0
	v_mfma_f32_16x16x32_bf16 v[22:25], v[156:159], v[140:143], v[22:25]
	ds_read_b128 v[188:191], v235 offset:2048
	v_mfma_f32_16x16x32_bf16 v[26:29], v[160:163], v[140:143], v[26:29]
	ds_read_b128 v[192:195], v235 offset:4096
	v_mfma_f32_16x16x32_bf16 v[30:33], v[164:167], v[140:143], v[30:33]
	ds_read_b128 v[196:199], v235 offset:6144
	v_mfma_f32_16x16x32_bf16 v[34:37], v[152:155], v[144:147], v[34:37]
	v_mfma_f32_16x16x32_bf16 v[38:41], v[156:159], v[144:147], v[38:41]
	v_mfma_f32_16x16x32_bf16 v[42:45], v[160:163], v[144:147], v[42:45]
	v_mfma_f32_16x16x32_bf16 v[46:49], v[164:167], v[144:147], v[46:49]
	v_mfma_f32_16x16x32_bf16 v[50:53], v[152:155], v[148:151], v[50:53]
	v_mfma_f32_16x16x32_bf16 v[54:57], v[156:159], v[148:151], v[54:57]
	v_mfma_f32_16x16x32_bf16 v[58:61], v[160:163], v[148:151], v[58:61]
	v_mfma_f32_16x16x32_bf16 v[62:65], v[164:167], v[148:151], v[62:65]
	s_waitcnt vmcnt(6) lgkmcnt(0)
	s_barrier
	v_mfma_f32_16x16x32_bf16 v[2:5], v[184:187], v[168:171], v[2:5]
	ds_read_b128 v[136:139], v218 offset:0
	v_mfma_f32_16x16x32_bf16 v[6:9], v[188:191], v[168:171], v[6:9]
	ds_read_b128 v[140:143], v218 offset:2048
	v_mfma_f32_16x16x32_bf16 v[10:13], v[192:195], v[168:171], v[10:13]
	ds_read_b128 v[144:147], v218 offset:4096
	v_mfma_f32_16x16x32_bf16 v[14:17], v[196:199], v[168:171], v[14:17]
	ds_read_b128 v[148:151], v218 offset:6144
	v_mfma_f32_16x16x32_bf16 v[18:21], v[184:187], v[172:175], v[18:21]
	ds_read_b128 v[152:155], v230 offset:0
	v_mfma_f32_16x16x32_bf16 v[22:25], v[188:191], v[172:175], v[22:25]
	ds_read_b128 v[156:159], v230 offset:2048
	v_mfma_f32_16x16x32_bf16 v[26:29], v[192:195], v[172:175], v[26:29]
	ds_read_b128 v[160:163], v230 offset:4096
	v_mfma_f32_16x16x32_bf16 v[30:33], v[196:199], v[172:175], v[30:33]
	ds_read_b128 v[164:167], v230 offset:6144
	s_add_u32 m0, s8, 0x18000
	v_mfma_f32_16x16x32_bf16 v[34:37], v[184:187], v[176:179], v[34:37]
	global_load_lds_dwordx4 v200, s[4:5]
	s_add_u32 m0, s8, 0x18400
	v_mfma_f32_16x16x32_bf16 v[38:41], v[188:191], v[176:179], v[38:41]
	global_load_lds_dwordx4 v201, s[4:5]
	s_add_u32 m0, s8, 0x18800
	v_mfma_f32_16x16x32_bf16 v[42:45], v[192:195], v[176:179], v[42:45]
	global_load_lds_dwordx4 v202, s[4:5]
	s_add_u32 m0, s8, 0x18c00
	v_mfma_f32_16x16x32_bf16 v[46:49], v[196:199], v[176:179], v[46:49]
	global_load_lds_dwordx4 v203, s[4:5]
	s_add_u32 m0, s9, 0x18000
	v_mfma_f32_16x16x32_bf16 v[50:53], v[184:187], v[180:183], v[50:53]
	global_load_lds_dwordx4 v204, s[6:7]
	s_add_u32 m0, s9, 0x18400
	v_mfma_f32_16x16x32_bf16 v[54:57], v[188:191], v[180:183], v[54:57]
	global_load_lds_dwordx4 v205, s[6:7]
	v_mfma_f32_16x16x32_bf16 v[58:61], v[192:195], v[180:183], v[58:61]
	s_add_u32 s4, s4, 0x80
	s_addc_u32 s5, s5, 0
	v_mfma_f32_16x16x32_bf16 v[62:65], v[196:199], v[180:183], v[62:65]
	s_add_u32 s6, s6, 0x80
	s_addc_u32 s7, s7, 0
	s_waitcnt lgkmcnt(0)
	v_mfma_f32_16x16x32_bf16 v[2:5], v[152:155], v[136:139], v[2:5]
	ds_read_b128 v[168:171], v225 offset:0
	v_mfma_f32_16x16x32_bf16 v[6:9], v[156:159], v[136:139], v[6:9]
	ds_read_b128 v[172:175], v225 offset:2048
	v_mfma_f32_16x16x32_bf16 v[10:13], v[160:163], v[136:139], v[10:13]
	ds_read_b128 v[176:179], v225 offset:4096
	v_mfma_f32_16x16x32_bf16 v[14:17], v[164:167], v[136:139], v[14:17]
	ds_read_b128 v[180:183], v225 offset:6144
	v_mfma_f32_16x16x32_bf16 v[18:21], v[152:155], v[140:143], v[18:21]
	ds_read_b128 v[184:187], v233 offset:0
	v_mfma_f32_16x16x32_bf16 v[22:25], v[156:159], v[140:143], v[22:25]
	ds_read_b128 v[188:191], v233 offset:2048
	v_mfma_f32_16x16x32_bf16 v[26:29], v[160:163], v[140:143], v[26:29]
	ds_read_b128 v[192:195], v233 offset:4096
	v_mfma_f32_16x16x32_bf16 v[30:33], v[164:167], v[140:143], v[30:33]
	ds_read_b128 v[196:199], v233 offset:6144
	v_mfma_f32_16x16x32_bf16 v[34:37], v[152:155], v[144:147], v[34:37]
	v_mfma_f32_16x16x32_bf16 v[38:41], v[156:159], v[144:147], v[38:41]
	v_mfma_f32_16x16x32_bf16 v[42:45], v[160:163], v[144:147], v[42:45]
	v_mfma_f32_16x16x32_bf16 v[46:49], v[164:167], v[144:147], v[46:49]
	v_mfma_f32_16x16x32_bf16 v[50:53], v[152:155], v[148:151], v[50:53]
	v_mfma_f32_16x16x32_bf16 v[54:57], v[156:159], v[148:151], v[54:57]
	v_mfma_f32_16x16x32_bf16 v[58:61], v[160:163], v[148:151], v[58:61]
	v_mfma_f32_16x16x32_bf16 v[62:65], v[164:167], v[148:151], v[62:65]
	s_waitcnt vmcnt(6) lgkmcnt(0)
	s_barrier
	v_mfma_f32_16x16x32_bf16 v[2:5], v[184:187], v[168:171], v[2:5]
	ds_read_b128 v[136:139], v219 offset:0
	v_mfma_f32_16x16x32_bf16 v[6:9], v[188:191], v[168:171], v[6:9]
	ds_read_b128 v[140:143], v219 offset:2048
	v_mfma_f32_16x16x32_bf16 v[10:13], v[192:195], v[168:171], v[10:13]
	ds_read_b128 v[144:147], v219 offset:4096
	v_mfma_f32_16x16x32_bf16 v[14:17], v[196:199], v[168:171], v[14:17]
	ds_read_b128 v[148:151], v219 offset:6144
	v_mfma_f32_16x16x32_bf16 v[18:21], v[184:187], v[172:175], v[18:21]
	ds_read_b128 v[152:155], v231 offset:0
	v_mfma_f32_16x16x32_bf16 v[22:25], v[188:191], v[172:175], v[22:25]
	ds_read_b128 v[156:159], v231 offset:2048
	v_mfma_f32_16x16x32_bf16 v[26:29], v[192:195], v[172:175], v[26:29]
	ds_read_b128 v[160:163], v231 offset:4096
	v_mfma_f32_16x16x32_bf16 v[30:33], v[196:199], v[172:175], v[30:33]
	ds_read_b128 v[164:167], v231 offset:6144
	s_mov_b32 m0, s8
	v_mfma_f32_16x16x32_bf16 v[34:37], v[184:187], v[176:179], v[34:37]
	global_load_lds_dwordx4 v200, s[4:5]
	s_add_u32 m0, s8, 0x400
	v_mfma_f32_16x16x32_bf16 v[38:41], v[188:191], v[176:179], v[38:41]
	global_load_lds_dwordx4 v201, s[4:5]
	s_add_u32 m0, s8, 0x800
	v_mfma_f32_16x16x32_bf16 v[42:45], v[192:195], v[176:179], v[42:45]
	global_load_lds_dwordx4 v202, s[4:5]
	s_add_u32 m0, s8, 0xc00
	v_mfma_f32_16x16x32_bf16 v[46:49], v[196:199], v[176:179], v[46:49]
	global_load_lds_dwordx4 v203, s[4:5]
	s_mov_b32 m0, s9
	v_mfma_f32_16x16x32_bf16 v[50:53], v[184:187], v[180:183], v[50:53]
	global_load_lds_dwordx4 v204, s[6:7]
	s_add_u32 m0, s9, 0x400
	v_mfma_f32_16x16x32_bf16 v[54:57], v[188:191], v[180:183], v[54:57]
	global_load_lds_dwordx4 v205, s[6:7]
	v_mfma_f32_16x16x32_bf16 v[58:61], v[192:195], v[180:183], v[58:61]
	s_add_u32 s4, s4, 0x80
	s_addc_u32 s5, s5, 0
	v_mfma_f32_16x16x32_bf16 v[62:65], v[196:199], v[180:183], v[62:65]
	s_add_u32 s6, s6, 0x80
	s_addc_u32 s7, s7, 0
	s_waitcnt lgkmcnt(0)
	v_mfma_f32_16x16x32_bf16 v[66:69], v[152:155], v[136:139], 0
	ds_read_b128 v[168:171], v228 offset:0
	v_mfma_f32_16x16x32_bf16 v[70:73], v[156:159], v[136:139], 0
	ds_read_b128 v[172:175], v228 offset:2048
	s_add_u32 s10, s28, s13
	s_addc_u32 s11, s29, 0
	v_mfma_f32_16x16x32_bf16 v[74:77], v[160:163], v[136:139], 0
	ds_read_b128 v[176:179], v228 offset:4096
	s_add_u32 s13, s13, 0x10000
	v_mfma_f32_16x16x32_bf16 v[78:81], v[164:167], v[136:139], 0
	ds_read_b128 v[180:183], v228 offset:6144
	v_mul_f32_e32 v2, s12, v2
	v_mfma_f32_16x16x32_bf16 v[82:85], v[152:155], v[140:143], 0
	ds_read_b128 v[184:187], v234 offset:0
	v_mfma_f32_16x16x32_bf16 v[86:89], v[156:159], v[140:143], 0
	ds_read_b128 v[188:191], v234 offset:2048
	v_mul_f32_e32 v3, s12, v3
	v_mfma_f32_16x16x32_bf16 v[90:93], v[160:163], v[140:143], 0
	ds_read_b128 v[192:195], v234 offset:4096
	v_mul_f32_e32 v4, s12, v4
	v_mfma_f32_16x16x32_bf16 v[94:97], v[164:167], v[140:143], 0
	ds_read_b128 v[196:199], v234 offset:6144
	v_mul_f32_e32 v5, s12, v5
	v_mfma_f32_16x16x32_bf16 v[98:101], v[152:155], v[144:147], 0
	v_mfma_f32_16x16x32_bf16 v[102:105], v[156:159], v[144:147], 0
	v_mul_f32_e32 v6, s12, v6
	v_mfma_f32_16x16x32_bf16 v[106:109], v[160:163], v[144:147], 0
	v_mul_f32_e32 v7, s12, v7
	v_mfma_f32_16x16x32_bf16 v[110:113], v[164:167], v[144:147], 0
	v_mul_f32_e32 v8, s12, v8
	v_mfma_f32_16x16x32_bf16 v[114:117], v[152:155], v[148:151], 0
	v_mfma_f32_16x16x32_bf16 v[118:121], v[156:159], v[148:151], 0
	v_mul_f32_e32 v9, s12, v9
	v_mfma_f32_16x16x32_bf16 v[122:125], v[160:163], v[148:151], 0
	v_exp_f32_e32 v2, v2
	v_mfma_f32_16x16x32_bf16 v[126:129], v[164:167], v[148:151], 0
	v_exp_f32_e32 v3, v3
	s_waitcnt vmcnt(6) lgkmcnt(0)
	s_barrier
	v_mfma_f32_16x16x32_bf16 v[66:69], v[184:187], v[168:171], v[66:69]
	ds_read_b128 v[136:139], v224 offset:0
	v_mfma_f32_16x16x32_bf16 v[70:73], v[188:191], v[168:171], v[70:73]
	ds_read_b128 v[140:143], v224 offset:2048
	v_mfma_f32_16x16x32_bf16 v[74:77], v[192:195], v[168:171], v[74:77]
	ds_read_b128 v[144:147], v224 offset:4096
	v_exp_f32_e32 v4, v4
	v_mfma_f32_16x16x32_bf16 v[78:81], v[196:199], v[168:171], v[78:81]
	ds_read_b128 v[148:151], v224 offset:6144
	v_mfma_f32_16x16x32_bf16 v[82:85], v[184:187], v[172:175], v[82:85]
	ds_read_b128 v[152:155], v232 offset:0
	v_exp_f32_e32 v5, v5
	v_mfma_f32_16x16x32_bf16 v[86:89], v[188:191], v[172:175], v[86:89]
	ds_read_b128 v[156:159], v232 offset:2048
	v_mfma_f32_16x16x32_bf16 v[90:93], v[192:195], v[172:175], v[90:93]
	ds_read_b128 v[160:163], v232 offset:4096
	v_exp_f32_e32 v6, v6
	v_mfma_f32_16x16x32_bf16 v[94:97], v[196:199], v[172:175], v[94:97]
	ds_read_b128 v[164:167], v232 offset:6144
	s_add_u32 m0, s8, 0xc000
	v_mfma_f32_16x16x32_bf16 v[98:101], v[184:187], v[176:179], v[98:101]
	global_load_lds_dwordx4 v200, s[4:5]
	s_add_u32 m0, s8, 0xc400
	v_mfma_f32_16x16x32_bf16 v[102:105], v[188:191], v[176:179], v[102:105]
	global_load_lds_dwordx4 v201, s[4:5]
	v_exp_f32_e32 v7, v7
	s_add_u32 m0, s8, 0xc800
	v_mfma_f32_16x16x32_bf16 v[106:109], v[192:195], v[176:179], v[106:109]
	global_load_lds_dwordx4 v202, s[4:5]
	s_add_u32 m0, s8, 0xcc00
	v_mfma_f32_16x16x32_bf16 v[110:113], v[196:199], v[176:179], v[110:113]
	global_load_lds_dwordx4 v203, s[4:5]
	v_exp_f32_e32 v8, v8
	s_add_u32 m0, s9, 0xc000
	v_mfma_f32_16x16x32_bf16 v[114:117], v[184:187], v[180:183], v[114:117]
	global_load_lds_dwordx4 v204, s[6:7]
	s_add_u32 m0, s9, 0xc400
	v_mfma_f32_16x16x32_bf16 v[118:121], v[188:191], v[180:183], v[118:121]
	global_load_lds_dwordx4 v205, s[6:7]
	v_exp_f32_e32 v9, v9
	v_mfma_f32_16x16x32_bf16 v[122:125], v[192:195], v[180:183], v[122:125]
	s_add_u32 s4, s4, 0x80
	s_addc_u32 s5, s5, 0
	v_mfma_f32_16x16x32_bf16 v[126:129], v[196:199], v[180:183], v[126:129]
	s_add_u32 s6, s6, 0x80
	s_addc_u32 s7, s7, 0
	v_add_f32_e32 v2, 1.0, v2
	s_waitcnt lgkmcnt(0)
	v_mfma_f32_16x16x32_bf16 v[66:69], v[152:155], v[136:139], v[66:69]
	ds_read_b128 v[168:171], v229 offset:0
	v_mfma_f32_16x16x32_bf16 v[70:73], v[156:159], v[136:139], v[70:73]
	ds_read_b128 v[172:175], v229 offset:2048
	v_add_f32_e32 v3, 1.0, v3
	v_mfma_f32_16x16x32_bf16 v[74:77], v[160:163], v[136:139], v[74:77]
	ds_read_b128 v[176:179], v229 offset:4096
	v_add_f32_e32 v4, 1.0, v4
	v_mfma_f32_16x16x32_bf16 v[78:81], v[164:167], v[136:139], v[78:81]
	ds_read_b128 v[180:183], v229 offset:6144
	v_add_f32_e32 v5, 1.0, v5
	v_mfma_f32_16x16x32_bf16 v[82:85], v[152:155], v[140:143], v[82:85]
	ds_read_b128 v[184:187], v235 offset:0
	v_mfma_f32_16x16x32_bf16 v[86:89], v[156:159], v[140:143], v[86:89]
	ds_read_b128 v[188:191], v235 offset:2048
	v_add_f32_e32 v6, 1.0, v6
	v_mfma_f32_16x16x32_bf16 v[90:93], v[160:163], v[140:143], v[90:93]
	ds_read_b128 v[192:195], v235 offset:4096
	v_add_f32_e32 v7, 1.0, v7
	v_mfma_f32_16x16x32_bf16 v[94:97], v[164:167], v[140:143], v[94:97]
	ds_read_b128 v[196:199], v235 offset:6144
	v_add_f32_e32 v8, 1.0, v8
	v_mfma_f32_16x16x32_bf16 v[98:101], v[152:155], v[144:147], v[98:101]
	v_mfma_f32_16x16x32_bf16 v[102:105], v[156:159], v[144:147], v[102:105]
	v_add_f32_e32 v9, 1.0, v9
	v_mfma_f32_16x16x32_bf16 v[106:109], v[160:163], v[144:147], v[106:109]
	v_rcp_f32_e32 v2, v2
	v_mfma_f32_16x16x32_bf16 v[110:113], v[164:167], v[144:147], v[110:113]
	v_rcp_f32_e32 v3, v3
	v_mfma_f32_16x16x32_bf16 v[114:117], v[152:155], v[148:151], v[114:117]
	v_mfma_f32_16x16x32_bf16 v[118:121], v[156:159], v[148:151], v[118:121]
	v_rcp_f32_e32 v4, v4
	v_mfma_f32_16x16x32_bf16 v[122:125], v[160:163], v[148:151], v[122:125]
	v_rcp_f32_e32 v5, v5
	v_mfma_f32_16x16x32_bf16 v[126:129], v[164:167], v[148:151], v[126:129]
	v_rcp_f32_e32 v6, v6
	s_waitcnt vmcnt(6) lgkmcnt(0)
	s_barrier
	v_mfma_f32_16x16x32_bf16 v[66:69], v[184:187], v[168:171], v[66:69]
	ds_read_b128 v[136:139], v218 offset:0
	v_mfma_f32_16x16x32_bf16 v[70:73], v[188:191], v[168:171], v[70:73]
	ds_read_b128 v[140:143], v218 offset:2048
	v_mfma_f32_16x16x32_bf16 v[74:77], v[192:195], v[168:171], v[74:77]
	ds_read_b128 v[144:147], v218 offset:4096
	v_rcp_f32_e32 v7, v7
	v_mfma_f32_16x16x32_bf16 v[78:81], v[196:199], v[168:171], v[78:81]
	ds_read_b128 v[148:151], v218 offset:6144
	v_mfma_f32_16x16x32_bf16 v[82:85], v[184:187], v[172:175], v[82:85]
	ds_read_b128 v[152:155], v230 offset:0
	v_rcp_f32_e32 v8, v8
	v_mfma_f32_16x16x32_bf16 v[86:89], v[188:191], v[172:175], v[86:89]
	ds_read_b128 v[156:159], v230 offset:2048
	v_mfma_f32_16x16x32_bf16 v[90:93], v[192:195], v[172:175], v[90:93]
	ds_read_b128 v[160:163], v230 offset:4096
	v_rcp_f32_e32 v9, v9
	v_mfma_f32_16x16x32_bf16 v[94:97], v[196:199], v[172:175], v[94:97]
	ds_read_b128 v[164:167], v230 offset:6144
	s_add_u32 m0, s8, 0x18000
	v_mfma_f32_16x16x32_bf16 v[98:101], v[184:187], v[176:179], v[98:101]
	global_load_lds_dwordx4 v200, s[4:5]
	s_add_u32 m0, s8, 0x18400
	v_mfma_f32_16x16x32_bf16 v[102:105], v[188:191], v[176:179], v[102:105]
	global_load_lds_dwordx4 v201, s[4:5]
	v_cvt_pk_bf16_f32 v2, v2, v3
	s_add_u32 m0, s8, 0x18800
	v_mfma_f32_16x16x32_bf16 v[106:109], v[192:195], v[176:179], v[106:109]
	global_load_lds_dwordx4 v202, s[4:5]
	s_add_u32 m0, s8, 0x18c00
	v_mfma_f32_16x16x32_bf16 v[110:113], v[196:199], v[176:179], v[110:113]
	global_load_lds_dwordx4 v203, s[4:5]
	v_cvt_pk_bf16_f32 v3, v4, v5
	s_add_u32 m0, s9, 0x18000
	v_mfma_f32_16x16x32_bf16 v[114:117], v[184:187], v[180:183], v[114:117]
	global_load_lds_dwordx4 v204, s[6:7]
	s_add_u32 m0, s9, 0x18400
	v_mfma_f32_16x16x32_bf16 v[118:121], v[188:191], v[180:183], v[118:121]
	global_load_lds_dwordx4 v205, s[6:7]
	v_cvt_pk_bf16_f32 v4, v6, v7
	v_mfma_f32_16x16x32_bf16 v[122:125], v[192:195], v[180:183], v[122:125]
	s_add_u32 s4, s4, 0x80
	s_addc_u32 s5, s5, 0
	v_mfma_f32_16x16x32_bf16 v[126:129], v[196:199], v[180:183], v[126:129]
	s_add_u32 s6, s6, 0x80
	s_addc_u32 s7, s7, 0
	v_cvt_pk_bf16_f32 v5, v8, v9
	s_waitcnt lgkmcnt(0)
	v_mfma_f32_16x16x32_bf16 v[66:69], v[152:155], v[136:139], v[66:69]
	ds_read_b128 v[168:171], v225 offset:0
	v_mfma_f32_16x16x32_bf16 v[70:73], v[156:159], v[136:139], v[70:73]
	ds_read_b128 v[172:175], v225 offset:2048
	global_store_dwordx4 v240, v[2:5], s[10:11] offset:0 sc1
	v_mfma_f32_16x16x32_bf16 v[74:77], v[160:163], v[136:139], v[74:77]
	ds_read_b128 v[176:179], v225 offset:4096
	v_mul_f32_e32 v10, s12, v10
	v_mfma_f32_16x16x32_bf16 v[78:81], v[164:167], v[136:139], v[78:81]
	ds_read_b128 v[180:183], v225 offset:6144
	v_mul_f32_e32 v11, s12, v11
	v_mfma_f32_16x16x32_bf16 v[82:85], v[152:155], v[140:143], v[82:85]
	ds_read_b128 v[184:187], v233 offset:0
	v_mfma_f32_16x16x32_bf16 v[86:89], v[156:159], v[140:143], v[86:89]
	ds_read_b128 v[188:191], v233 offset:2048
	v_mul_f32_e32 v12, s12, v12
	v_mfma_f32_16x16x32_bf16 v[90:93], v[160:163], v[140:143], v[90:93]
	ds_read_b128 v[192:195], v233 offset:4096
	v_mul_f32_e32 v13, s12, v13
	v_mfma_f32_16x16x32_bf16 v[94:97], v[164:167], v[140:143], v[94:97]
	ds_read_b128 v[196:199], v233 offset:6144
	v_mul_f32_e32 v14, s12, v14
	v_mfma_f32_16x16x32_bf16 v[98:101], v[152:155], v[144:147], v[98:101]
	v_mfma_f32_16x16x32_bf16 v[102:105], v[156:159], v[144:147], v[102:105]
	v_mul_f32_e32 v15, s12, v15
	v_mfma_f32_16x16x32_bf16 v[106:109], v[160:163], v[144:147], v[106:109]
	v_mul_f32_e32 v16, s12, v16
	v_mfma_f32_16x16x32_bf16 v[110:113], v[164:167], v[144:147], v[110:113]
	v_mul_f32_e32 v17, s12, v17
	v_mfma_f32_16x16x32_bf16 v[114:117], v[152:155], v[148:151], v[114:117]
	v_mfma_f32_16x16x32_bf16 v[118:121], v[156:159], v[148:151], v[118:121]
	v_exp_f32_e32 v10, v10
	v_mfma_f32_16x16x32_bf16 v[122:125], v[160:163], v[148:151], v[122:125]
	v_exp_f32_e32 v11, v11
	v_mfma_f32_16x16x32_bf16 v[126:129], v[164:167], v[148:151], v[126:129]
	v_exp_f32_e32 v12, v12
	s_waitcnt vmcnt(7) lgkmcnt(0)
	s_barrier
	v_mfma_f32_16x16x32_bf16 v[66:69], v[184:187], v[168:171], v[66:69]
	ds_read_b128 v[136:139], v219 offset:0
	v_mfma_f32_16x16x32_bf16 v[70:73], v[188:191], v[168:171], v[70:73]
	ds_read_b128 v[140:143], v219 offset:2048
	v_mfma_f32_16x16x32_bf16 v[74:77], v[192:195], v[168:171], v[74:77]
	ds_read_b128 v[144:147], v219 offset:4096
	v_exp_f32_e32 v13, v13
	v_mfma_f32_16x16x32_bf16 v[78:81], v[196:199], v[168:171], v[78:81]
	ds_read_b128 v[148:151], v219 offset:6144
	v_mfma_f32_16x16x32_bf16 v[82:85], v[184:187], v[172:175], v[82:85]
	ds_read_b128 v[152:155], v231 offset:0
	v_exp_f32_e32 v14, v14
	v_mfma_f32_16x16x32_bf16 v[86:89], v[188:191], v[172:175], v[86:89]
	ds_read_b128 v[156:159], v231 offset:2048
	v_mfma_f32_16x16x32_bf16 v[90:93], v[192:195], v[172:175], v[90:93]
	ds_read_b128 v[160:163], v231 offset:4096
	v_exp_f32_e32 v15, v15
	v_mfma_f32_16x16x32_bf16 v[94:97], v[196:199], v[172:175], v[94:97]
	ds_read_b128 v[164:167], v231 offset:6144
	s_mov_b32 m0, s8
	v_mfma_f32_16x16x32_bf16 v[98:101], v[184:187], v[176:179], v[98:101]
	global_load_lds_dwordx4 v200, s[4:5]
	s_add_u32 m0, s8, 0x400
	v_mfma_f32_16x16x32_bf16 v[102:105], v[188:191], v[176:179], v[102:105]
	global_load_lds_dwordx4 v201, s[4:5]
	v_exp_f32_e32 v16, v16
	s_add_u32 m0, s8, 0x800
	v_mfma_f32_16x16x32_bf16 v[106:109], v[192:195], v[176:179], v[106:109]
	global_load_lds_dwordx4 v202, s[4:5]
	s_add_u32 m0, s8, 0xc00
	v_mfma_f32_16x16x32_bf16 v[110:113], v[196:199], v[176:179], v[110:113]
	global_load_lds_dwordx4 v203, s[4:5]
	v_exp_f32_e32 v17, v17
	s_mov_b32 m0, s9
	v_mfma_f32_16x16x32_bf16 v[114:117], v[184:187], v[180:183], v[114:117]
	global_load_lds_dwordx4 v204, s[6:7]
	s_add_u32 m0, s9, 0x400
	v_mfma_f32_16x16x32_bf16 v[118:121], v[188:191], v[180:183], v[118:121]
	global_load_lds_dwordx4 v205, s[6:7]
	v_add_f32_e32 v10, 1.0, v10
	v_mfma_f32_16x16x32_bf16 v[122:125], v[192:195], v[180:183], v[122:125]
	s_add_u32 s4, s4, 0x80
	s_addc_u32 s5, s5, 0
	v_mfma_f32_16x16x32_bf16 v[126:129], v[196:199], v[180:183], v[126:129]
	s_add_u32 s6, s6, 0x80
	s_addc_u32 s7, s7, 0
	v_add_f32_e32 v11, 1.0, v11
	s_waitcnt lgkmcnt(0)
	v_mfma_f32_16x16x32_bf16 v[66:69], v[152:155], v[136:139], v[66:69]
	ds_read_b128 v[168:171], v228 offset:0
	v_mfma_f32_16x16x32_bf16 v[70:73], v[156:159], v[136:139], v[70:73]
	ds_read_b128 v[172:175], v228 offset:2048
	v_add_f32_e32 v12, 1.0, v12
	v_mfma_f32_16x16x32_bf16 v[74:77], v[160:163], v[136:139], v[74:77]
	ds_read_b128 v[176:179], v228 offset:4096
	v_add_f32_e32 v13, 1.0, v13
	v_mfma_f32_16x16x32_bf16 v[78:81], v[164:167], v[136:139], v[78:81]
	ds_read_b128 v[180:183], v228 offset:6144
	v_add_f32_e32 v14, 1.0, v14
	v_mfma_f32_16x16x32_bf16 v[82:85], v[152:155], v[140:143], v[82:85]
	ds_read_b128 v[184:187], v234 offset:0
	v_mfma_f32_16x16x32_bf16 v[86:89], v[156:159], v[140:143], v[86:89]
	ds_read_b128 v[188:191], v234 offset:2048
	v_add_f32_e32 v15, 1.0, v15
	v_mfma_f32_16x16x32_bf16 v[90:93], v[160:163], v[140:143], v[90:93]
	ds_read_b128 v[192:195], v234 offset:4096
	v_add_f32_e32 v16, 1.0, v16
	v_mfma_f32_16x16x32_bf16 v[94:97], v[164:167], v[140:143], v[94:97]
	ds_read_b128 v[196:199], v234 offset:6144
	v_add_f32_e32 v17, 1.0, v17
	v_mfma_f32_16x16x32_bf16 v[98:101], v[152:155], v[144:147], v[98:101]
	v_mfma_f32_16x16x32_bf16 v[102:105], v[156:159], v[144:147], v[102:105]
	v_rcp_f32_e32 v10, v10
	v_mfma_f32_16x16x32_bf16 v[106:109], v[160:163], v[144:147], v[106:109]
	v_rcp_f32_e32 v11, v11
	v_mfma_f32_16x16x32_bf16 v[110:113], v[164:167], v[144:147], v[110:113]
	v_rcp_f32_e32 v12, v12
	v_mfma_f32_16x16x32_bf16 v[114:117], v[152:155], v[148:151], v[114:117]
	v_mfma_f32_16x16x32_bf16 v[118:121], v[156:159], v[148:151], v[118:121]
	v_rcp_f32_e32 v13, v13
	v_mfma_f32_16x16x32_bf16 v[122:125], v[160:163], v[148:151], v[122:125]
	v_rcp_f32_e32 v14, v14
	v_mfma_f32_16x16x32_bf16 v[126:129], v[164:167], v[148:151], v[126:129]
	v_rcp_f32_e32 v15, v15
	s_waitcnt vmcnt(7) lgkmcnt(0)
	s_barrier
	v_mfma_f32_16x16x32_bf16 v[66:69], v[184:187], v[168:171], v[66:69]
	ds_read_b128 v[136:139], v224 offset:0
	v_mfma_f32_16x16x32_bf16 v[70:73], v[188:191], v[168:171], v[70:73]
	ds_read_b128 v[140:143], v224 offset:2048
	v_mfma_f32_16x16x32_bf16 v[74:77], v[192:195], v[168:171], v[74:77]
	ds_read_b128 v[144:147], v224 offset:4096
	v_rcp_f32_e32 v16, v16
	v_mfma_f32_16x16x32_bf16 v[78:81], v[196:199], v[168:171], v[78:81]
	ds_read_b128 v[148:151], v224 offset:6144
	v_mfma_f32_16x16x32_bf16 v[82:85], v[184:187], v[172:175], v[82:85]
	ds_read_b128 v[152:155], v232 offset:0
	v_rcp_f32_e32 v17, v17
	v_mfma_f32_16x16x32_bf16 v[86:89], v[188:191], v[172:175], v[86:89]
	ds_read_b128 v[156:159], v232 offset:2048
	v_mfma_f32_16x16x32_bf16 v[90:93], v[192:195], v[172:175], v[90:93]
	ds_read_b128 v[160:163], v232 offset:4096
	v_cvt_pk_bf16_f32 v10, v10, v11
	v_mfma_f32_16x16x32_bf16 v[94:97], v[196:199], v[172:175], v[94:97]
	ds_read_b128 v[164:167], v232 offset:6144
	s_add_u32 m0, s8, 0xc000
	v_mfma_f32_16x16x32_bf16 v[98:101], v[184:187], v[176:179], v[98:101]
	global_load_lds_dwordx4 v200, s[4:5]
	s_add_u32 m0, s8, 0xc400
	v_mfma_f32_16x16x32_bf16 v[102:105], v[188:191], v[176:179], v[102:105]
	global_load_lds_dwordx4 v201, s[4:5]
	v_cvt_pk_bf16_f32 v11, v12, v13
	s_add_u32 m0, s8, 0xc800
	v_mfma_f32_16x16x32_bf16 v[106:109], v[192:195], v[176:179], v[106:109]
	global_load_lds_dwordx4 v202, s[4:5]
	s_add_u32 m0, s8, 0xcc00
	v_mfma_f32_16x16x32_bf16 v[110:113], v[196:199], v[176:179], v[110:113]
	global_load_lds_dwordx4 v203, s[4:5]
	v_cvt_pk_bf16_f32 v12, v14, v15
	s_add_u32 m0, s9, 0xc000
	v_mfma_f32_16x16x32_bf16 v[114:117], v[184:187], v[180:183], v[114:117]
	global_load_lds_dwordx4 v204, s[6:7]
	s_add_u32 m0, s9, 0xc400
	v_mfma_f32_16x16x32_bf16 v[118:121], v[188:191], v[180:183], v[118:121]
	global_load_lds_dwordx4 v205, s[6:7]
	v_cvt_pk_bf16_f32 v13, v16, v17
	v_mfma_f32_16x16x32_bf16 v[122:125], v[192:195], v[180:183], v[122:125]
	s_add_u32 s4, s4, 0x80
	s_addc_u32 s5, s5, 0
	v_mfma_f32_16x16x32_bf16 v[126:129], v[196:199], v[180:183], v[126:129]
	s_add_u32 s6, s6, 0x80
	s_addc_u32 s7, s7, 0
	global_store_dwordx4 v240, v[10:13], s[10:11] offset:1024 sc1
	s_waitcnt lgkmcnt(0)
	v_mfma_f32_16x16x32_bf16 v[66:69], v[152:155], v[136:139], v[66:69]
	ds_read_b128 v[168:171], v229 offset:0
	v_mfma_f32_16x16x32_bf16 v[70:73], v[156:159], v[136:139], v[70:73]
	ds_read_b128 v[172:175], v229 offset:2048
	v_mul_f32_e32 v18, s12, v18
	v_mfma_f32_16x16x32_bf16 v[74:77], v[160:163], v[136:139], v[74:77]
	ds_read_b128 v[176:179], v229 offset:4096
	v_mul_f32_e32 v19, s12, v19
	v_mfma_f32_16x16x32_bf16 v[78:81], v[164:167], v[136:139], v[78:81]
	ds_read_b128 v[180:183], v229 offset:6144
	v_mul_f32_e32 v20, s12, v20
	v_mfma_f32_16x16x32_bf16 v[82:85], v[152:155], v[140:143], v[82:85]
	ds_read_b128 v[184:187], v235 offset:0
	v_mfma_f32_16x16x32_bf16 v[86:89], v[156:159], v[140:143], v[86:89]
	ds_read_b128 v[188:191], v235 offset:2048
	v_mul_f32_e32 v21, s12, v21
	v_mfma_f32_16x16x32_bf16 v[90:93], v[160:163], v[140:143], v[90:93]
	ds_read_b128 v[192:195], v235 offset:4096
	v_mul_f32_e32 v22, s12, v22
	v_mfma_f32_16x16x32_bf16 v[94:97], v[164:167], v[140:143], v[94:97]
	ds_read_b128 v[196:199], v235 offset:6144
	v_mul_f32_e32 v23, s12, v23
	v_mfma_f32_16x16x32_bf16 v[98:101], v[152:155], v[144:147], v[98:101]
	v_mfma_f32_16x16x32_bf16 v[102:105], v[156:159], v[144:147], v[102:105]
	v_mul_f32_e32 v24, s12, v24
	v_mfma_f32_16x16x32_bf16 v[106:109], v[160:163], v[144:147], v[106:109]
	v_mul_f32_e32 v25, s12, v25
	v_mfma_f32_16x16x32_bf16 v[110:113], v[164:167], v[144:147], v[110:113]
	v_exp_f32_e32 v18, v18
	v_mfma_f32_16x16x32_bf16 v[114:117], v[152:155], v[148:151], v[114:117]
	v_mfma_f32_16x16x32_bf16 v[118:121], v[156:159], v[148:151], v[118:121]
	v_exp_f32_e32 v19, v19
	v_mfma_f32_16x16x32_bf16 v[122:125], v[160:163], v[148:151], v[122:125]
	v_exp_f32_e32 v20, v20
	v_mfma_f32_16x16x32_bf16 v[126:129], v[164:167], v[148:151], v[126:129]
	v_exp_f32_e32 v21, v21
	s_waitcnt vmcnt(7) lgkmcnt(0)
	s_barrier
	v_mfma_f32_16x16x32_bf16 v[66:69], v[184:187], v[168:171], v[66:69]
	ds_read_b128 v[136:139], v218 offset:0
	v_mfma_f32_16x16x32_bf16 v[70:73], v[188:191], v[168:171], v[70:73]
	ds_read_b128 v[140:143], v218 offset:2048
	v_mfma_f32_16x16x32_bf16 v[74:77], v[192:195], v[168:171], v[74:77]
	ds_read_b128 v[144:147], v218 offset:4096
	v_exp_f32_e32 v22, v22
	v_mfma_f32_16x16x32_bf16 v[78:81], v[196:199], v[168:171], v[78:81]
	ds_read_b128 v[148:151], v218 offset:6144
	v_mfma_f32_16x16x32_bf16 v[82:85], v[184:187], v[172:175], v[82:85]
	ds_read_b128 v[152:155], v230 offset:0
	v_exp_f32_e32 v23, v23
	v_mfma_f32_16x16x32_bf16 v[86:89], v[188:191], v[172:175], v[86:89]
	ds_read_b128 v[156:159], v230 offset:2048
	v_mfma_f32_16x16x32_bf16 v[90:93], v[192:195], v[172:175], v[90:93]
	ds_read_b128 v[160:163], v230 offset:4096
	v_exp_f32_e32 v24, v24
	v_mfma_f32_16x16x32_bf16 v[94:97], v[196:199], v[172:175], v[94:97]
	ds_read_b128 v[164:167], v230 offset:6144
	s_add_u32 m0, s8, 0x18000
	v_mfma_f32_16x16x32_bf16 v[98:101], v[184:187], v[176:179], v[98:101]
	global_load_lds_dwordx4 v200, s[4:5]
	s_add_u32 m0, s8, 0x18400
	v_mfma_f32_16x16x32_bf16 v[102:105], v[188:191], v[176:179], v[102:105]
	global_load_lds_dwordx4 v201, s[4:5]
	v_exp_f32_e32 v25, v25
	s_add_u32 m0, s8, 0x18800
	v_mfma_f32_16x16x32_bf16 v[106:109], v[192:195], v[176:179], v[106:109]
	global_load_lds_dwordx4 v202, s[4:5]
	s_add_u32 m0, s8, 0x18c00
	v_mfma_f32_16x16x32_bf16 v[110:113], v[196:199], v[176:179], v[110:113]
	global_load_lds_dwordx4 v203, s[4:5]
	v_add_f32_e32 v18, 1.0, v18
	s_add_u32 m0, s9, 0x18000
	v_mfma_f32_16x16x32_bf16 v[114:117], v[184:187], v[180:183], v[114:117]
	global_load_lds_dwordx4 v204, s[6:7]
	s_add_u32 m0, s9, 0x18400
	v_mfma_f32_16x16x32_bf16 v[118:121], v[188:191], v[180:183], v[118:121]
	global_load_lds_dwordx4 v205, s[6:7]
	v_add_f32_e32 v19, 1.0, v19
	v_mfma_f32_16x16x32_bf16 v[122:125], v[192:195], v[180:183], v[122:125]
	s_add_u32 s4, s4, 0x80
	s_addc_u32 s5, s5, 0
	v_mfma_f32_16x16x32_bf16 v[126:129], v[196:199], v[180:183], v[126:129]
	s_add_u32 s6, s6, 0x80
	s_addc_u32 s7, s7, 0
	v_add_f32_e32 v20, 1.0, v20
	s_waitcnt lgkmcnt(0)
	v_mfma_f32_16x16x32_bf16 v[66:69], v[152:155], v[136:139], v[66:69]
	ds_read_b128 v[168:171], v225 offset:0
	v_mfma_f32_16x16x32_bf16 v[70:73], v[156:159], v[136:139], v[70:73]
	ds_read_b128 v[172:175], v225 offset:2048
	v_add_f32_e32 v21, 1.0, v21
	v_mfma_f32_16x16x32_bf16 v[74:77], v[160:163], v[136:139], v[74:77]
	ds_read_b128 v[176:179], v225 offset:4096
	v_add_f32_e32 v22, 1.0, v22
	v_mfma_f32_16x16x32_bf16 v[78:81], v[164:167], v[136:139], v[78:81]
	ds_read_b128 v[180:183], v225 offset:6144
	v_add_f32_e32 v23, 1.0, v23
	v_mfma_f32_16x16x32_bf16 v[82:85], v[152:155], v[140:143], v[82:85]
	ds_read_b128 v[184:187], v233 offset:0
	v_mfma_f32_16x16x32_bf16 v[86:89], v[156:159], v[140:143], v[86:89]
	ds_read_b128 v[188:191], v233 offset:2048
	v_add_f32_e32 v24, 1.0, v24
	v_mfma_f32_16x16x32_bf16 v[90:93], v[160:163], v[140:143], v[90:93]
	ds_read_b128 v[192:195], v233 offset:4096
	v_add_f32_e32 v25, 1.0, v25
	v_mfma_f32_16x16x32_bf16 v[94:97], v[164:167], v[140:143], v[94:97]
	ds_read_b128 v[196:199], v233 offset:6144
	v_rcp_f32_e32 v18, v18
	v_mfma_f32_16x16x32_bf16 v[98:101], v[152:155], v[144:147], v[98:101]
	v_mfma_f32_16x16x32_bf16 v[102:105], v[156:159], v[144:147], v[102:105]
	v_rcp_f32_e32 v19, v19
	v_mfma_f32_16x16x32_bf16 v[106:109], v[160:163], v[144:147], v[106:109]
	v_rcp_f32_e32 v20, v20
	v_mfma_f32_16x16x32_bf16 v[110:113], v[164:167], v[144:147], v[110:113]
	v_rcp_f32_e32 v21, v21
	v_mfma_f32_16x16x32_bf16 v[114:117], v[152:155], v[148:151], v[114:117]
	v_mfma_f32_16x16x32_bf16 v[118:121], v[156:159], v[148:151], v[118:121]
	v_rcp_f32_e32 v22, v22
	v_mfma_f32_16x16x32_bf16 v[122:125], v[160:163], v[148:151], v[122:125]
	v_rcp_f32_e32 v23, v23
	v_mfma_f32_16x16x32_bf16 v[126:129], v[164:167], v[148:151], v[126:129]
	v_rcp_f32_e32 v24, v24
	s_waitcnt vmcnt(7) lgkmcnt(0)
	s_barrier
	v_mfma_f32_16x16x32_bf16 v[66:69], v[184:187], v[168:171], v[66:69]
	ds_read_b128 v[136:139], v219 offset:0
	v_mfma_f32_16x16x32_bf16 v[70:73], v[188:191], v[168:171], v[70:73]
	ds_read_b128 v[140:143], v219 offset:2048
	v_mfma_f32_16x16x32_bf16 v[74:77], v[192:195], v[168:171], v[74:77]
	ds_read_b128 v[144:147], v219 offset:4096
	v_rcp_f32_e32 v25, v25
	v_mfma_f32_16x16x32_bf16 v[78:81], v[196:199], v[168:171], v[78:81]
	ds_read_b128 v[148:151], v219 offset:6144
	v_mfma_f32_16x16x32_bf16 v[82:85], v[184:187], v[172:175], v[82:85]
	ds_read_b128 v[152:155], v231 offset:0
	v_cvt_pk_bf16_f32 v18, v18, v19
	v_mfma_f32_16x16x32_bf16 v[86:89], v[188:191], v[172:175], v[86:89]
	ds_read_b128 v[156:159], v231 offset:2048
	v_mfma_f32_16x16x32_bf16 v[90:93], v[192:195], v[172:175], v[90:93]
	ds_read_b128 v[160:163], v231 offset:4096
	v_cvt_pk_bf16_f32 v19, v20, v21
	v_mfma_f32_16x16x32_bf16 v[94:97], v[196:199], v[172:175], v[94:97]
	ds_read_b128 v[164:167], v231 offset:6144
	s_mov_b32 m0, s8
	v_mfma_f32_16x16x32_bf16 v[98:101], v[184:187], v[176:179], v[98:101]
	global_load_lds_dwordx4 v200, s[4:5]
	s_add_u32 m0, s8, 0x400
	v_mfma_f32_16x16x32_bf16 v[102:105], v[188:191], v[176:179], v[102:105]
	global_load_lds_dwordx4 v201, s[4:5]
	v_cvt_pk_bf16_f32 v20, v22, v23
	s_add_u32 m0, s8, 0x800
	v_mfma_f32_16x16x32_bf16 v[106:109], v[192:195], v[176:179], v[106:109]
	global_load_lds_dwordx4 v202, s[4:5]
	s_add_u32 m0, s8, 0xc00
	v_mfma_f32_16x16x32_bf16 v[110:113], v[196:199], v[176:179], v[110:113]
	global_load_lds_dwordx4 v203, s[4:5]
	v_cvt_pk_bf16_f32 v21, v24, v25
	s_mov_b32 m0, s9
	v_mfma_f32_16x16x32_bf16 v[114:117], v[184:187], v[180:183], v[114:117]
	global_load_lds_dwordx4 v204, s[6:7]
	s_add_u32 m0, s9, 0x400
	v_mfma_f32_16x16x32_bf16 v[118:121], v[188:191], v[180:183], v[118:121]
	global_load_lds_dwordx4 v205, s[6:7]
	global_store_dwordx4 v240, v[18:21], s[10:11] offset:2048 sc1
	v_mfma_f32_16x16x32_bf16 v[122:125], v[192:195], v[180:183], v[122:125]
	s_add_u32 s4, s4, 0x80
	s_addc_u32 s5, s5, 0
	v_mfma_f32_16x16x32_bf16 v[126:129], v[196:199], v[180:183], v[126:129]
	s_add_u32 s6, s6, 0x80
	s_addc_u32 s7, s7, 0
	v_mul_f32_e32 v26, s12, v26
	s_waitcnt lgkmcnt(0)
	v_mfma_f32_16x16x32_bf16 v[66:69], v[152:155], v[136:139], v[66:69]
	ds_read_b128 v[168:171], v228 offset:0
	v_mfma_f32_16x16x32_bf16 v[70:73], v[156:159], v[136:139], v[70:73]
	ds_read_b128 v[172:175], v228 offset:2048
	v_mul_f32_e32 v27, s12, v27
	v_mfma_f32_16x16x32_bf16 v[74:77], v[160:163], v[136:139], v[74:77]
	ds_read_b128 v[176:179], v228 offset:4096
	v_mul_f32_e32 v28, s12, v28
	v_mfma_f32_16x16x32_bf16 v[78:81], v[164:167], v[136:139], v[78:81]
	ds_read_b128 v[180:183], v228 offset:6144
	v_mul_f32_e32 v29, s12, v29
	v_mfma_f32_16x16x32_bf16 v[82:85], v[152:155], v[140:143], v[82:85]
	ds_read_b128 v[184:187], v234 offset:0
	v_mfma_f32_16x16x32_bf16 v[86:89], v[156:159], v[140:143], v[86:89]
	ds_read_b128 v[188:191], v234 offset:2048
	v_mul_f32_e32 v30, s12, v30
	v_mfma_f32_16x16x32_bf16 v[90:93], v[160:163], v[140:143], v[90:93]
	ds_read_b128 v[192:195], v234 offset:4096
	v_mul_f32_e32 v31, s12, v31
	v_mfma_f32_16x16x32_bf16 v[94:97], v[164:167], v[140:143], v[94:97]
	ds_read_b128 v[196:199], v234 offset:6144
	v_mul_f32_e32 v32, s12, v32
	v_mfma_f32_16x16x32_bf16 v[98:101], v[152:155], v[144:147], v[98:101]
	v_mfma_f32_16x16x32_bf16 v[102:105], v[156:159], v[144:147], v[102:105]
	v_mul_f32_e32 v33, s12, v33
	v_mfma_f32_16x16x32_bf16 v[106:109], v[160:163], v[144:147], v[106:109]
	v_exp_f32_e32 v26, v26
	v_mfma_f32_16x16x32_bf16 v[110:113], v[164:167], v[144:147], v[110:113]
	v_exp_f32_e32 v27, v27
	v_mfma_f32_16x16x32_bf16 v[114:117], v[152:155], v[148:151], v[114:117]
	v_mfma_f32_16x16x32_bf16 v[118:121], v[156:159], v[148:151], v[118:121]
	v_exp_f32_e32 v28, v28
	v_mfma_f32_16x16x32_bf16 v[122:125], v[160:163], v[148:151], v[122:125]
	v_exp_f32_e32 v29, v29
	v_mfma_f32_16x16x32_bf16 v[126:129], v[164:167], v[148:151], v[126:129]
	v_exp_f32_e32 v30, v30
	s_waitcnt vmcnt(7) lgkmcnt(0)
	s_barrier
	v_mfma_f32_16x16x32_bf16 v[66:69], v[184:187], v[168:171], v[66:69]
	ds_read_b128 v[136:139], v224 offset:0
	v_mfma_f32_16x16x32_bf16 v[70:73], v[188:191], v[168:171], v[70:73]
	ds_read_b128 v[140:143], v224 offset:2048
	v_mfma_f32_16x16x32_bf16 v[74:77], v[192:195], v[168:171], v[74:77]
	ds_read_b128 v[144:147], v224 offset:4096
	v_exp_f32_e32 v31, v31
	v_mfma_f32_16x16x32_bf16 v[78:81], v[196:199], v[168:171], v[78:81]
	ds_read_b128 v[148:151], v224 offset:6144
	v_mfma_f32_16x16x32_bf16 v[82:85], v[184:187], v[172:175], v[82:85]
	ds_read_b128 v[152:155], v232 offset:0
	v_exp_f32_e32 v32, v32
	v_mfma_f32_16x16x32_bf16 v[86:89], v[188:191], v[172:175], v[86:89]
	ds_read_b128 v[156:159], v232 offset:2048
	v_mfma_f32_16x16x32_bf16 v[90:93], v[192:195], v[172:175], v[90:93]
	ds_read_b128 v[160:163], v232 offset:4096
	v_exp_f32_e32 v33, v33
	v_mfma_f32_16x16x32_bf16 v[94:97], v[196:199], v[172:175], v[94:97]
	ds_read_b128 v[164:167], v232 offset:6144
	s_add_u32 m0, s8, 0xc000
	v_mfma_f32_16x16x32_bf16 v[98:101], v[184:187], v[176:179], v[98:101]
	global_load_lds_dwordx4 v200, s[4:5]
	s_add_u32 m0, s8, 0xc400
	v_mfma_f32_16x16x32_bf16 v[102:105], v[188:191], v[176:179], v[102:105]
	global_load_lds_dwordx4 v201, s[4:5]
	v_add_f32_e32 v26, 1.0, v26
	s_add_u32 m0, s8, 0xc800
	v_mfma_f32_16x16x32_bf16 v[106:109], v[192:195], v[176:179], v[106:109]
	global_load_lds_dwordx4 v202, s[4:5]
	s_add_u32 m0, s8, 0xcc00
	v_mfma_f32_16x16x32_bf16 v[110:113], v[196:199], v[176:179], v[110:113]
	global_load_lds_dwordx4 v203, s[4:5]
	v_add_f32_e32 v27, 1.0, v27
	s_add_u32 m0, s9, 0xc000
	v_mfma_f32_16x16x32_bf16 v[114:117], v[184:187], v[180:183], v[114:117]
	global_load_lds_dwordx4 v204, s[6:7]
	s_add_u32 m0, s9, 0xc400
	v_mfma_f32_16x16x32_bf16 v[118:121], v[188:191], v[180:183], v[118:121]
	global_load_lds_dwordx4 v205, s[6:7]
	v_add_f32_e32 v28, 1.0, v28
	v_mfma_f32_16x16x32_bf16 v[122:125], v[192:195], v[180:183], v[122:125]
	s_add_u32 s4, s4, 0x80
	s_addc_u32 s5, s5, 0
	v_mfma_f32_16x16x32_bf16 v[126:129], v[196:199], v[180:183], v[126:129]
	s_add_u32 s6, s6, 0x80
	s_addc_u32 s7, s7, 0
	v_add_f32_e32 v29, 1.0, v29
	s_waitcnt lgkmcnt(0)
	v_mfma_f32_16x16x32_bf16 v[66:69], v[152:155], v[136:139], v[66:69]
	ds_read_b128 v[168:171], v229 offset:0
	v_mfma_f32_16x16x32_bf16 v[70:73], v[156:159], v[136:139], v[70:73]
	ds_read_b128 v[172:175], v229 offset:2048
	v_add_f32_e32 v30, 1.0, v30
	v_mfma_f32_16x16x32_bf16 v[74:77], v[160:163], v[136:139], v[74:77]
	ds_read_b128 v[176:179], v229 offset:4096
	v_add_f32_e32 v31, 1.0, v31
	v_mfma_f32_16x16x32_bf16 v[78:81], v[164:167], v[136:139], v[78:81]
	ds_read_b128 v[180:183], v229 offset:6144
	v_add_f32_e32 v32, 1.0, v32
	v_mfma_f32_16x16x32_bf16 v[82:85], v[152:155], v[140:143], v[82:85]
	ds_read_b128 v[184:187], v235 offset:0
	v_mfma_f32_16x16x32_bf16 v[86:89], v[156:159], v[140:143], v[86:89]
	ds_read_b128 v[188:191], v235 offset:2048
	v_add_f32_e32 v33, 1.0, v33
	v_mfma_f32_16x16x32_bf16 v[90:93], v[160:163], v[140:143], v[90:93]
	ds_read_b128 v[192:195], v235 offset:4096
	v_rcp_f32_e32 v26, v26
	v_mfma_f32_16x16x32_bf16 v[94:97], v[164:167], v[140:143], v[94:97]
	ds_read_b128 v[196:199], v235 offset:6144
	v_rcp_f32_e32 v27, v27
	v_mfma_f32_16x16x32_bf16 v[98:101], v[152:155], v[144:147], v[98:101]
	v_mfma_f32_16x16x32_bf16 v[102:105], v[156:159], v[144:147], v[102:105]
	v_rcp_f32_e32 v28, v28
	v_mfma_f32_16x16x32_bf16 v[106:109], v[160:163], v[144:147], v[106:109]
	v_rcp_f32_e32 v29, v29
	v_mfma_f32_16x16x32_bf16 v[110:113], v[164:167], v[144:147], v[110:113]
	v_rcp_f32_e32 v30, v30
	v_mfma_f32_16x16x32_bf16 v[114:117], v[152:155], v[148:151], v[114:117]
	v_mfma_f32_16x16x32_bf16 v[118:121], v[156:159], v[148:151], v[118:121]
	v_rcp_f32_e32 v31, v31
	v_mfma_f32_16x16x32_bf16 v[122:125], v[160:163], v[148:151], v[122:125]
	v_rcp_f32_e32 v32, v32
	v_mfma_f32_16x16x32_bf16 v[126:129], v[164:167], v[148:151], v[126:129]
	v_rcp_f32_e32 v33, v33
	s_waitcnt vmcnt(7) lgkmcnt(0)
	s_barrier
	v_mfma_f32_16x16x32_bf16 v[66:69], v[184:187], v[168:171], v[66:69]
	ds_read_b128 v[136:139], v218 offset:0
	v_mfma_f32_16x16x32_bf16 v[70:73], v[188:191], v[168:171], v[70:73]
	ds_read_b128 v[140:143], v218 offset:2048
	v_mfma_f32_16x16x32_bf16 v[74:77], v[192:195], v[168:171], v[74:77]
	ds_read_b128 v[144:147], v218 offset:4096
	v_cvt_pk_bf16_f32 v26, v26, v27
	v_mfma_f32_16x16x32_bf16 v[78:81], v[196:199], v[168:171], v[78:81]
	ds_read_b128 v[148:151], v218 offset:6144
	v_mfma_f32_16x16x32_bf16 v[82:85], v[184:187], v[172:175], v[82:85]
	ds_read_b128 v[152:155], v230 offset:0
	v_cvt_pk_bf16_f32 v27, v28, v29
	v_mfma_f32_16x16x32_bf16 v[86:89], v[188:191], v[172:175], v[86:89]
	ds_read_b128 v[156:159], v230 offset:2048
	v_mfma_f32_16x16x32_bf16 v[90:93], v[192:195], v[172:175], v[90:93]
	ds_read_b128 v[160:163], v230 offset:4096
	v_cvt_pk_bf16_f32 v28, v30, v31
	v_mfma_f32_16x16x32_bf16 v[94:97], v[196:199], v[172:175], v[94:97]
	ds_read_b128 v[164:167], v230 offset:6144
	s_add_u32 m0, s8, 0x18000
	v_mfma_f32_16x16x32_bf16 v[98:101], v[184:187], v[176:179], v[98:101]
	global_load_lds_dwordx4 v200, s[4:5]
	s_add_u32 m0, s8, 0x18400
	v_mfma_f32_16x16x32_bf16 v[102:105], v[188:191], v[176:179], v[102:105]
	global_load_lds_dwordx4 v201, s[4:5]
	v_cvt_pk_bf16_f32 v29, v32, v33
	s_add_u32 m0, s8, 0x18800
	v_mfma_f32_16x16x32_bf16 v[106:109], v[192:195], v[176:179], v[106:109]
	global_load_lds_dwordx4 v202, s[4:5]
	s_add_u32 m0, s8, 0x18c00
	v_mfma_f32_16x16x32_bf16 v[110:113], v[196:199], v[176:179], v[110:113]
	global_load_lds_dwordx4 v203, s[4:5]
	global_store_dwordx4 v240, v[26:29], s[10:11] offset:3072 sc1
	s_add_u32 m0, s9, 0x18000
	v_mfma_f32_16x16x32_bf16 v[114:117], v[184:187], v[180:183], v[114:117]
	global_load_lds_dwordx4 v204, s[6:7]
	s_add_u32 m0, s9, 0x18400
	v_mfma_f32_16x16x32_bf16 v[118:121], v[188:191], v[180:183], v[118:121]
	global_load_lds_dwordx4 v205, s[6:7]
	v_mul_f32_e32 v34, s12, v34
	v_mfma_f32_16x16x32_bf16 v[122:125], v[192:195], v[180:183], v[122:125]
	s_add_u32 s4, s4, 0x80
	s_addc_u32 s5, s5, 0
	v_mfma_f32_16x16x32_bf16 v[126:129], v[196:199], v[180:183], v[126:129]
	s_add_u32 s6, s6, 0x80
	s_addc_u32 s7, s7, 0
	v_mul_f32_e32 v35, s12, v35
	s_waitcnt lgkmcnt(0)
	v_mfma_f32_16x16x32_bf16 v[66:69], v[152:155], v[136:139], v[66:69]
	ds_read_b128 v[168:171], v225 offset:0
	v_mfma_f32_16x16x32_bf16 v[70:73], v[156:159], v[136:139], v[70:73]
	ds_read_b128 v[172:175], v225 offset:2048
	v_mul_f32_e32 v36, s12, v36
	v_mfma_f32_16x16x32_bf16 v[74:77], v[160:163], v[136:139], v[74:77]
	ds_read_b128 v[176:179], v225 offset:4096
	v_mul_f32_e32 v37, s12, v37
	v_mfma_f32_16x16x32_bf16 v[78:81], v[164:167], v[136:139], v[78:81]
	ds_read_b128 v[180:183], v225 offset:6144
	v_mul_f32_e32 v38, s12, v38
	v_mfma_f32_16x16x32_bf16 v[82:85], v[152:155], v[140:143], v[82:85]
	ds_read_b128 v[184:187], v233 offset:0
	v_mfma_f32_16x16x32_bf16 v[86:89], v[156:159], v[140:143], v[86:89]
	ds_read_b128 v[188:191], v233 offset:2048
	v_mul_f32_e32 v39, s12, v39
	v_mfma_f32_16x16x32_bf16 v[90:93], v[160:163], v[140:143], v[90:93]
	ds_read_b128 v[192:195], v233 offset:4096
	v_mul_f32_e32 v40, s12, v40
	v_mfma_f32_16x16x32_bf16 v[94:97], v[164:167], v[140:143], v[94:97]
	ds_read_b128 v[196:199], v233 offset:6144
	v_mul_f32_e32 v41, s12, v41
	v_mfma_f32_16x16x32_bf16 v[98:101], v[152:155], v[144:147], v[98:101]
	v_mfma_f32_16x16x32_bf16 v[102:105], v[156:159], v[144:147], v[102:105]
	v_exp_f32_e32 v34, v34
	v_mfma_f32_16x16x32_bf16 v[106:109], v[160:163], v[144:147], v[106:109]
	v_exp_f32_e32 v35, v35
	v_mfma_f32_16x16x32_bf16 v[110:113], v[164:167], v[144:147], v[110:113]
	v_exp_f32_e32 v36, v36
	v_mfma_f32_16x16x32_bf16 v[114:117], v[152:155], v[148:151], v[114:117]
	v_mfma_f32_16x16x32_bf16 v[118:121], v[156:159], v[148:151], v[118:121]
	v_exp_f32_e32 v37, v37
	v_mfma_f32_16x16x32_bf16 v[122:125], v[160:163], v[148:151], v[122:125]
	v_exp_f32_e32 v38, v38
	v_mfma_f32_16x16x32_bf16 v[126:129], v[164:167], v[148:151], v[126:129]
	v_exp_f32_e32 v39, v39
	s_waitcnt vmcnt(7) lgkmcnt(0)
	s_barrier
	v_mfma_f32_16x16x32_bf16 v[66:69], v[184:187], v[168:171], v[66:69]
	ds_read_b128 v[136:139], v219 offset:0
	v_mfma_f32_16x16x32_bf16 v[70:73], v[188:191], v[168:171], v[70:73]
	ds_read_b128 v[140:143], v219 offset:2048
	v_mfma_f32_16x16x32_bf16 v[74:77], v[192:195], v[168:171], v[74:77]
	ds_read_b128 v[144:147], v219 offset:4096
	v_exp_f32_e32 v40, v40
	v_mfma_f32_16x16x32_bf16 v[78:81], v[196:199], v[168:171], v[78:81]
	ds_read_b128 v[148:151], v219 offset:6144
	v_mfma_f32_16x16x32_bf16 v[82:85], v[184:187], v[172:175], v[82:85]
	ds_read_b128 v[152:155], v231 offset:0
	v_exp_f32_e32 v41, v41
	v_mfma_f32_16x16x32_bf16 v[86:89], v[188:191], v[172:175], v[86:89]
	ds_read_b128 v[156:159], v231 offset:2048
	v_mfma_f32_16x16x32_bf16 v[90:93], v[192:195], v[172:175], v[90:93]
	ds_read_b128 v[160:163], v231 offset:4096
	v_add_f32_e32 v34, 1.0, v34
	v_mfma_f32_16x16x32_bf16 v[94:97], v[196:199], v[172:175], v[94:97]
	ds_read_b128 v[164:167], v231 offset:6144
	s_mov_b32 m0, s8
	v_mfma_f32_16x16x32_bf16 v[98:101], v[184:187], v[176:179], v[98:101]
	global_load_lds_dwordx4 v200, s[4:5]
	s_add_u32 m0, s8, 0x400
	v_mfma_f32_16x16x32_bf16 v[102:105], v[188:191], v[176:179], v[102:105]
	global_load_lds_dwordx4 v201, s[4:5]
	v_add_f32_e32 v35, 1.0, v35
	s_add_u32 m0, s8, 0x800
	v_mfma_f32_16x16x32_bf16 v[106:109], v[192:195], v[176:179], v[106:109]
	global_load_lds_dwordx4 v202, s[4:5]
	s_add_u32 m0, s8, 0xc00
	v_mfma_f32_16x16x32_bf16 v[110:113], v[196:199], v[176:179], v[110:113]
	global_load_lds_dwordx4 v203, s[4:5]
	v_add_f32_e32 v36, 1.0, v36
	s_mov_b32 m0, s9
	v_mfma_f32_16x16x32_bf16 v[114:117], v[184:187], v[180:183], v[114:117]
	global_load_lds_dwordx4 v204, s[6:7]
	s_add_u32 m0, s9, 0x400
	v_mfma_f32_16x16x32_bf16 v[118:121], v[188:191], v[180:183], v[118:121]
	global_load_lds_dwordx4 v205, s[6:7]
	v_add_f32_e32 v37, 1.0, v37
	v_mfma_f32_16x16x32_bf16 v[122:125], v[192:195], v[180:183], v[122:125]
	s_add_u32 s4, s4, 0x80
	s_addc_u32 s5, s5, 0
	v_mfma_f32_16x16x32_bf16 v[126:129], v[196:199], v[180:183], v[126:129]
	s_add_u32 s6, s6, 0x80
	s_addc_u32 s7, s7, 0
	v_add_f32_e32 v38, 1.0, v38
	s_waitcnt lgkmcnt(0)
	v_mfma_f32_16x16x32_bf16 v[66:69], v[152:155], v[136:139], v[66:69]
	ds_read_b128 v[168:171], v228 offset:0
	v_mfma_f32_16x16x32_bf16 v[70:73], v[156:159], v[136:139], v[70:73]
	ds_read_b128 v[172:175], v228 offset:2048
	v_add_f32_e32 v39, 1.0, v39
	v_mfma_f32_16x16x32_bf16 v[74:77], v[160:163], v[136:139], v[74:77]
	ds_read_b128 v[176:179], v228 offset:4096
	v_add_f32_e32 v40, 1.0, v40
	v_mfma_f32_16x16x32_bf16 v[78:81], v[164:167], v[136:139], v[78:81]
	ds_read_b128 v[180:183], v228 offset:6144
	v_add_f32_e32 v41, 1.0, v41
	v_mfma_f32_16x16x32_bf16 v[82:85], v[152:155], v[140:143], v[82:85]
	ds_read_b128 v[184:187], v234 offset:0
	v_mfma_f32_16x16x32_bf16 v[86:89], v[156:159], v[140:143], v[86:89]
	ds_read_b128 v[188:191], v234 offset:2048
	v_rcp_f32_e32 v34, v34
	v_mfma_f32_16x16x32_bf16 v[90:93], v[160:163], v[140:143], v[90:93]
	ds_read_b128 v[192:195], v234 offset:4096
	v_rcp_f32_e32 v35, v35
	v_mfma_f32_16x16x32_bf16 v[94:97], v[164:167], v[140:143], v[94:97]
	ds_read_b128 v[196:199], v234 offset:6144
	v_rcp_f32_e32 v36, v36
	v_mfma_f32_16x16x32_bf16 v[98:101], v[152:155], v[144:147], v[98:101]
	v_mfma_f32_16x16x32_bf16 v[102:105], v[156:159], v[144:147], v[102:105]
	v_rcp_f32_e32 v37, v37
	v_mfma_f32_16x16x32_bf16 v[106:109], v[160:163], v[144:147], v[106:109]
	v_rcp_f32_e32 v38, v38
	v_mfma_f32_16x16x32_bf16 v[110:113], v[164:167], v[144:147], v[110:113]
	v_rcp_f32_e32 v39, v39
	v_mfma_f32_16x16x32_bf16 v[114:117], v[152:155], v[148:151], v[114:117]
	v_mfma_f32_16x16x32_bf16 v[118:121], v[156:159], v[148:151], v[118:121]
	v_rcp_f32_e32 v40, v40
	v_mfma_f32_16x16x32_bf16 v[122:125], v[160:163], v[148:151], v[122:125]
	v_rcp_f32_e32 v41, v41
	v_mfma_f32_16x16x32_bf16 v[126:129], v[164:167], v[148:151], v[126:129]
	v_cvt_pk_bf16_f32 v34, v34, v35
	s_waitcnt vmcnt(6) lgkmcnt(0)
	s_barrier
	v_mfma_f32_16x16x32_bf16 v[66:69], v[184:187], v[168:171], v[66:69]
	ds_read_b128 v[136:139], v224 offset:0
	v_mfma_f32_16x16x32_bf16 v[70:73], v[188:191], v[168:171], v[70:73]
	ds_read_b128 v[140:143], v224 offset:2048
	v_mfma_f32_16x16x32_bf16 v[74:77], v[192:195], v[168:171], v[74:77]
	ds_read_b128 v[144:147], v224 offset:4096
	v_cvt_pk_bf16_f32 v35, v36, v37
	v_mfma_f32_16x16x32_bf16 v[78:81], v[196:199], v[168:171], v[78:81]
	ds_read_b128 v[148:151], v224 offset:6144
	v_mfma_f32_16x16x32_bf16 v[82:85], v[184:187], v[172:175], v[82:85]
	ds_read_b128 v[152:155], v232 offset:0
	v_cvt_pk_bf16_f32 v36, v38, v39
	v_mfma_f32_16x16x32_bf16 v[86:89], v[188:191], v[172:175], v[86:89]
	ds_read_b128 v[156:159], v232 offset:2048
	v_mfma_f32_16x16x32_bf16 v[90:93], v[192:195], v[172:175], v[90:93]
	ds_read_b128 v[160:163], v232 offset:4096
	v_cvt_pk_bf16_f32 v37, v40, v41
	v_mfma_f32_16x16x32_bf16 v[94:97], v[196:199], v[172:175], v[94:97]
	ds_read_b128 v[164:167], v232 offset:6144
	s_add_u32 m0, s8, 0xc000
	v_mfma_f32_16x16x32_bf16 v[98:101], v[184:187], v[176:179], v[98:101]
	global_load_lds_dwordx4 v200, s[4:5]
	s_add_u32 m0, s8, 0xc400
	v_mfma_f32_16x16x32_bf16 v[102:105], v[188:191], v[176:179], v[102:105]
	global_load_lds_dwordx4 v201, s[4:5]
	global_store_dwordx4 v241, v[34:37], s[10:11] offset:0 sc1
	s_add_u32 m0, s8, 0xc800
	v_mfma_f32_16x16x32_bf16 v[106:109], v[192:195], v[176:179], v[106:109]
	global_load_lds_dwordx4 v202, s[4:5]
	s_add_u32 m0, s8, 0xcc00
	v_mfma_f32_16x16x32_bf16 v[110:113], v[196:199], v[176:179], v[110:113]
	global_load_lds_dwordx4 v203, s[4:5]
	v_mul_f32_e32 v42, s12, v42
	s_add_u32 m0, s9, 0xc000
	v_mfma_f32_16x16x32_bf16 v[114:117], v[184:187], v[180:183], v[114:117]
	global_load_lds_dwordx4 v204, s[6:7]
	s_add_u32 m0, s9, 0xc400
	v_mfma_f32_16x16x32_bf16 v[118:121], v[188:191], v[180:183], v[118:121]
	global_load_lds_dwordx4 v205, s[6:7]
	v_mul_f32_e32 v43, s12, v43
	v_mfma_f32_16x16x32_bf16 v[122:125], v[192:195], v[180:183], v[122:125]
	s_add_u32 s4, s4, 0x80
	s_addc_u32 s5, s5, 0
	v_mfma_f32_16x16x32_bf16 v[126:129], v[196:199], v[180:183], v[126:129]
	s_add_u32 s6, s6, 0x80
	s_addc_u32 s7, s7, 0
	v_mul_f32_e32 v44, s12, v44
	s_waitcnt lgkmcnt(0)
	v_mfma_f32_16x16x32_bf16 v[66:69], v[152:155], v[136:139], v[66:69]
	ds_read_b128 v[168:171], v229 offset:0
	v_mfma_f32_16x16x32_bf16 v[70:73], v[156:159], v[136:139], v[70:73]
	ds_read_b128 v[172:175], v229 offset:2048
	v_mul_f32_e32 v45, s12, v45
	v_mfma_f32_16x16x32_bf16 v[74:77], v[160:163], v[136:139], v[74:77]
	ds_read_b128 v[176:179], v229 offset:4096
	v_mul_f32_e32 v46, s12, v46
	v_mfma_f32_16x16x32_bf16 v[78:81], v[164:167], v[136:139], v[78:81]
	ds_read_b128 v[180:183], v229 offset:6144
	v_mul_f32_e32 v47, s12, v47
	v_mfma_f32_16x16x32_bf16 v[82:85], v[152:155], v[140:143], v[82:85]
	ds_read_b128 v[184:187], v235 offset:0
	v_mfma_f32_16x16x32_bf16 v[86:89], v[156:159], v[140:143], v[86:89]
	ds_read_b128 v[188:191], v235 offset:2048
	v_mul_f32_e32 v48, s12, v48
	v_mfma_f32_16x16x32_bf16 v[90:93], v[160:163], v[140:143], v[90:93]
	ds_read_b128 v[192:195], v235 offset:4096
	v_mul_f32_e32 v49, s12, v49
	v_mfma_f32_16x16x32_bf16 v[94:97], v[164:167], v[140:143], v[94:97]
	ds_read_b128 v[196:199], v235 offset:6144
	v_exp_f32_e32 v42, v42
	v_mfma_f32_16x16x32_bf16 v[98:101], v[152:155], v[144:147], v[98:101]
	v_mfma_f32_16x16x32_bf16 v[102:105], v[156:159], v[144:147], v[102:105]
	v_exp_f32_e32 v43, v43
	v_mfma_f32_16x16x32_bf16 v[106:109], v[160:163], v[144:147], v[106:109]
	v_exp_f32_e32 v44, v44
	v_mfma_f32_16x16x32_bf16 v[110:113], v[164:167], v[144:147], v[110:113]
	v_exp_f32_e32 v45, v45
	v_mfma_f32_16x16x32_bf16 v[114:117], v[152:155], v[148:151], v[114:117]
	v_mfma_f32_16x16x32_bf16 v[118:121], v[156:159], v[148:151], v[118:121]
	v_exp_f32_e32 v46, v46
	v_mfma_f32_16x16x32_bf16 v[122:125], v[160:163], v[148:151], v[122:125]
	v_exp_f32_e32 v47, v47
	v_mfma_f32_16x16x32_bf16 v[126:129], v[164:167], v[148:151], v[126:129]
	v_exp_f32_e32 v48, v48
	s_waitcnt vmcnt(7) lgkmcnt(0)
	s_barrier
	v_mfma_f32_16x16x32_bf16 v[66:69], v[184:187], v[168:171], v[66:69]
	ds_read_b128 v[136:139], v218 offset:0
	v_mfma_f32_16x16x32_bf16 v[70:73], v[188:191], v[168:171], v[70:73]
	ds_read_b128 v[140:143], v218 offset:2048
	v_mfma_f32_16x16x32_bf16 v[74:77], v[192:195], v[168:171], v[74:77]
	ds_read_b128 v[144:147], v218 offset:4096
	v_exp_f32_e32 v49, v49
	v_mfma_f32_16x16x32_bf16 v[78:81], v[196:199], v[168:171], v[78:81]
	ds_read_b128 v[148:151], v218 offset:6144
	v_mfma_f32_16x16x32_bf16 v[82:85], v[184:187], v[172:175], v[82:85]
	ds_read_b128 v[152:155], v230 offset:0
	v_add_f32_e32 v42, 1.0, v42
	v_mfma_f32_16x16x32_bf16 v[86:89], v[188:191], v[172:175], v[86:89]
	ds_read_b128 v[156:159], v230 offset:2048
	v_mfma_f32_16x16x32_bf16 v[90:93], v[192:195], v[172:175], v[90:93]
	ds_read_b128 v[160:163], v230 offset:4096
	v_add_f32_e32 v43, 1.0, v43
	v_mfma_f32_16x16x32_bf16 v[94:97], v[196:199], v[172:175], v[94:97]
	ds_read_b128 v[164:167], v230 offset:6144
	s_add_u32 m0, s8, 0x18000
	v_mfma_f32_16x16x32_bf16 v[98:101], v[184:187], v[176:179], v[98:101]
	global_load_lds_dwordx4 v200, s[4:5]
	s_add_u32 m0, s8, 0x18400
	v_mfma_f32_16x16x32_bf16 v[102:105], v[188:191], v[176:179], v[102:105]
	global_load_lds_dwordx4 v201, s[4:5]
	v_add_f32_e32 v44, 1.0, v44
	s_add_u32 m0, s8, 0x18800
	v_mfma_f32_16x16x32_bf16 v[106:109], v[192:195], v[176:179], v[106:109]
	global_load_lds_dwordx4 v202, s[4:5]
	s_add_u32 m0, s8, 0x18c00
	v_mfma_f32_16x16x32_bf16 v[110:113], v[196:199], v[176:179], v[110:113]
	global_load_lds_dwordx4 v203, s[4:5]
	v_add_f32_e32 v45, 1.0, v45
	s_add_u32 m0, s9, 0x18000
	v_mfma_f32_16x16x32_bf16 v[114:117], v[184:187], v[180:183], v[114:117]
	global_load_lds_dwordx4 v204, s[6:7]
	s_add_u32 m0, s9, 0x18400
	v_mfma_f32_16x16x32_bf16 v[118:121], v[188:191], v[180:183], v[118:121]
	global_load_lds_dwordx4 v205, s[6:7]
	v_add_f32_e32 v46, 1.0, v46
	v_mfma_f32_16x16x32_bf16 v[122:125], v[192:195], v[180:183], v[122:125]
	s_add_u32 s4, s4, 0x80
	s_addc_u32 s5, s5, 0
	v_mfma_f32_16x16x32_bf16 v[126:129], v[196:199], v[180:183], v[126:129]
	s_add_u32 s6, s6, 0x80
	s_addc_u32 s7, s7, 0
	v_add_f32_e32 v47, 1.0, v47
	s_waitcnt lgkmcnt(0)
	v_mfma_f32_16x16x32_bf16 v[66:69], v[152:155], v[136:139], v[66:69]
	ds_read_b128 v[168:171], v225 offset:0
	v_mfma_f32_16x16x32_bf16 v[70:73], v[156:159], v[136:139], v[70:73]
	ds_read_b128 v[172:175], v225 offset:2048
	v_add_f32_e32 v48, 1.0, v48
	v_mfma_f32_16x16x32_bf16 v[74:77], v[160:163], v[136:139], v[74:77]
	ds_read_b128 v[176:179], v225 offset:4096
	v_add_f32_e32 v49, 1.0, v49
	v_mfma_f32_16x16x32_bf16 v[78:81], v[164:167], v[136:139], v[78:81]
	ds_read_b128 v[180:183], v225 offset:6144
	v_rcp_f32_e32 v42, v42
	v_mfma_f32_16x16x32_bf16 v[82:85], v[152:155], v[140:143], v[82:85]
	ds_read_b128 v[184:187], v233 offset:0
	v_mfma_f32_16x16x32_bf16 v[86:89], v[156:159], v[140:143], v[86:89]
	ds_read_b128 v[188:191], v233 offset:2048
	v_rcp_f32_e32 v43, v43
	v_mfma_f32_16x16x32_bf16 v[90:93], v[160:163], v[140:143], v[90:93]
	ds_read_b128 v[192:195], v233 offset:4096
	v_rcp_f32_e32 v44, v44
	v_mfma_f32_16x16x32_bf16 v[94:97], v[164:167], v[140:143], v[94:97]
	ds_read_b128 v[196:199], v233 offset:6144
	v_rcp_f32_e32 v45, v45
	v_mfma_f32_16x16x32_bf16 v[98:101], v[152:155], v[144:147], v[98:101]
	v_mfma_f32_16x16x32_bf16 v[102:105], v[156:159], v[144:147], v[102:105]
	v_rcp_f32_e32 v46, v46
	v_mfma_f32_16x16x32_bf16 v[106:109], v[160:163], v[144:147], v[106:109]
	v_rcp_f32_e32 v47, v47
	v_mfma_f32_16x16x32_bf16 v[110:113], v[164:167], v[144:147], v[110:113]
	v_rcp_f32_e32 v48, v48
	v_mfma_f32_16x16x32_bf16 v[114:117], v[152:155], v[148:151], v[114:117]
	v_mfma_f32_16x16x32_bf16 v[118:121], v[156:159], v[148:151], v[118:121]
	v_rcp_f32_e32 v49, v49
	v_mfma_f32_16x16x32_bf16 v[122:125], v[160:163], v[148:151], v[122:125]
	v_cvt_pk_bf16_f32 v42, v42, v43
	v_mfma_f32_16x16x32_bf16 v[126:129], v[164:167], v[148:151], v[126:129]
	v_cvt_pk_bf16_f32 v43, v44, v45
	s_waitcnt vmcnt(6) lgkmcnt(0)
	s_barrier
	v_mfma_f32_16x16x32_bf16 v[66:69], v[184:187], v[168:171], v[66:69]
	ds_read_b128 v[136:139], v219 offset:0
	v_mfma_f32_16x16x32_bf16 v[70:73], v[188:191], v[168:171], v[70:73]
	ds_read_b128 v[140:143], v219 offset:2048
	v_mfma_f32_16x16x32_bf16 v[74:77], v[192:195], v[168:171], v[74:77]
	ds_read_b128 v[144:147], v219 offset:4096
	v_cvt_pk_bf16_f32 v44, v46, v47
	v_mfma_f32_16x16x32_bf16 v[78:81], v[196:199], v[168:171], v[78:81]
	ds_read_b128 v[148:151], v219 offset:6144
	v_mfma_f32_16x16x32_bf16 v[82:85], v[184:187], v[172:175], v[82:85]
	ds_read_b128 v[152:155], v231 offset:0
	v_cvt_pk_bf16_f32 v45, v48, v49
	v_mfma_f32_16x16x32_bf16 v[86:89], v[188:191], v[172:175], v[86:89]
	ds_read_b128 v[156:159], v231 offset:2048
	v_mfma_f32_16x16x32_bf16 v[90:93], v[192:195], v[172:175], v[90:93]
	ds_read_b128 v[160:163], v231 offset:4096
	global_store_dwordx4 v241, v[42:45], s[10:11] offset:1024 sc1
	v_mfma_f32_16x16x32_bf16 v[94:97], v[196:199], v[172:175], v[94:97]
	ds_read_b128 v[164:167], v231 offset:6144
	s_mov_b32 m0, s8
	v_mfma_f32_16x16x32_bf16 v[98:101], v[184:187], v[176:179], v[98:101]
	global_load_lds_dwordx4 v200, s[4:5]
	s_add_u32 m0, s8, 0x400
	v_mfma_f32_16x16x32_bf16 v[102:105], v[188:191], v[176:179], v[102:105]
	global_load_lds_dwordx4 v201, s[4:5]
	v_mul_f32_e32 v50, s12, v50
	s_add_u32 m0, s8, 0x800
	v_mfma_f32_16x16x32_bf16 v[106:109], v[192:195], v[176:179], v[106:109]
	global_load_lds_dwordx4 v202, s[4:5]
	s_add_u32 m0, s8, 0xc00
	v_mfma_f32_16x16x32_bf16 v[110:113], v[196:199], v[176:179], v[110:113]
	global_load_lds_dwordx4 v203, s[4:5]
	v_mul_f32_e32 v51, s12, v51
	s_mov_b32 m0, s9
	v_mfma_f32_16x16x32_bf16 v[114:117], v[184:187], v[180:183], v[114:117]
	global_load_lds_dwordx4 v204, s[6:7]
	s_add_u32 m0, s9, 0x400
	v_mfma_f32_16x16x32_bf16 v[118:121], v[188:191], v[180:183], v[118:121]
	global_load_lds_dwordx4 v205, s[6:7]
	v_mul_f32_e32 v52, s12, v52
	v_mfma_f32_16x16x32_bf16 v[122:125], v[192:195], v[180:183], v[122:125]
	s_add_u32 s4, s4, 0x80
	s_addc_u32 s5, s5, 0
	v_mfma_f32_16x16x32_bf16 v[126:129], v[196:199], v[180:183], v[126:129]
	s_add_u32 s6, s6, 0x80
	s_addc_u32 s7, s7, 0
	v_mul_f32_e32 v53, s12, v53
	s_waitcnt lgkmcnt(0)
	v_mfma_f32_16x16x32_bf16 v[66:69], v[152:155], v[136:139], v[66:69]
	ds_read_b128 v[168:171], v228 offset:0
	v_mfma_f32_16x16x32_bf16 v[70:73], v[156:159], v[136:139], v[70:73]
	ds_read_b128 v[172:175], v228 offset:2048
	v_mul_f32_e32 v54, s12, v54
	v_mfma_f32_16x16x32_bf16 v[74:77], v[160:163], v[136:139], v[74:77]
	ds_read_b128 v[176:179], v228 offset:4096
	v_mul_f32_e32 v55, s12, v55
	v_mfma_f32_16x16x32_bf16 v[78:81], v[164:167], v[136:139], v[78:81]
	ds_read_b128 v[180:183], v228 offset:6144
	v_mul_f32_e32 v56, s12, v56
	v_mfma_f32_16x16x32_bf16 v[82:85], v[152:155], v[140:143], v[82:85]
	ds_read_b128 v[184:187], v234 offset:0
	v_mfma_f32_16x16x32_bf16 v[86:89], v[156:159], v[140:143], v[86:89]
	ds_read_b128 v[188:191], v234 offset:2048
	v_mul_f32_e32 v57, s12, v57
	v_mfma_f32_16x16x32_bf16 v[90:93], v[160:163], v[140:143], v[90:93]
	ds_read_b128 v[192:195], v234 offset:4096
	v_exp_f32_e32 v50, v50
	v_mfma_f32_16x16x32_bf16 v[94:97], v[164:167], v[140:143], v[94:97]
	ds_read_b128 v[196:199], v234 offset:6144
	v_exp_f32_e32 v51, v51
	v_mfma_f32_16x16x32_bf16 v[98:101], v[152:155], v[144:147], v[98:101]
	v_mfma_f32_16x16x32_bf16 v[102:105], v[156:159], v[144:147], v[102:105]
	v_exp_f32_e32 v52, v52
	v_mfma_f32_16x16x32_bf16 v[106:109], v[160:163], v[144:147], v[106:109]
	v_exp_f32_e32 v53, v53
	v_mfma_f32_16x16x32_bf16 v[110:113], v[164:167], v[144:147], v[110:113]
	v_exp_f32_e32 v54, v54
	v_mfma_f32_16x16x32_bf16 v[114:117], v[152:155], v[148:151], v[114:117]
	v_mfma_f32_16x16x32_bf16 v[118:121], v[156:159], v[148:151], v[118:121]
	v_exp_f32_e32 v55, v55
	v_mfma_f32_16x16x32_bf16 v[122:125], v[160:163], v[148:151], v[122:125]
	v_exp_f32_e32 v56, v56
	v_mfma_f32_16x16x32_bf16 v[126:129], v[164:167], v[148:151], v[126:129]
	v_exp_f32_e32 v57, v57
	s_waitcnt vmcnt(7) lgkmcnt(0)
	s_barrier
	v_mfma_f32_16x16x32_bf16 v[66:69], v[184:187], v[168:171], v[66:69]
	ds_read_b128 v[136:139], v224 offset:0
	v_mfma_f32_16x16x32_bf16 v[70:73], v[188:191], v[168:171], v[70:73]
	ds_read_b128 v[140:143], v224 offset:2048
	v_mfma_f32_16x16x32_bf16 v[74:77], v[192:195], v[168:171], v[74:77]
	ds_read_b128 v[144:147], v224 offset:4096
	v_add_f32_e32 v50, 1.0, v50
	v_mfma_f32_16x16x32_bf16 v[78:81], v[196:199], v[168:171], v[78:81]
	ds_read_b128 v[148:151], v224 offset:6144
	v_mfma_f32_16x16x32_bf16 v[82:85], v[184:187], v[172:175], v[82:85]
	ds_read_b128 v[152:155], v232 offset:0
	v_add_f32_e32 v51, 1.0, v51
	v_mfma_f32_16x16x32_bf16 v[86:89], v[188:191], v[172:175], v[86:89]
	ds_read_b128 v[156:159], v232 offset:2048
	v_mfma_f32_16x16x32_bf16 v[90:93], v[192:195], v[172:175], v[90:93]
	ds_read_b128 v[160:163], v232 offset:4096
	v_add_f32_e32 v52, 1.0, v52
	v_mfma_f32_16x16x32_bf16 v[94:97], v[196:199], v[172:175], v[94:97]
	ds_read_b128 v[164:167], v232 offset:6144
	s_add_u32 m0, s8, 0xc000
	v_mfma_f32_16x16x32_bf16 v[98:101], v[184:187], v[176:179], v[98:101]
	global_load_lds_dwordx4 v200, s[4:5]
	s_add_u32 m0, s8, 0xc400
	v_mfma_f32_16x16x32_bf16 v[102:105], v[188:191], v[176:179], v[102:105]
	global_load_lds_dwordx4 v201, s[4:5]
	v_add_f32_e32 v53, 1.0, v53
	s_add_u32 m0, s8, 0xc800
	v_mfma_f32_16x16x32_bf16 v[106:109], v[192:195], v[176:179], v[106:109]
	global_load_lds_dwordx4 v202, s[4:5]
	s_add_u32 m0, s8, 0xcc00
	v_mfma_f32_16x16x32_bf16 v[110:113], v[196:199], v[176:179], v[110:113]
	global_load_lds_dwordx4 v203, s[4:5]
	v_add_f32_e32 v54, 1.0, v54
	s_add_u32 m0, s9, 0xc000
	v_mfma_f32_16x16x32_bf16 v[114:117], v[184:187], v[180:183], v[114:117]
	global_load_lds_dwordx4 v204, s[6:7]
	s_add_u32 m0, s9, 0xc400
	v_mfma_f32_16x16x32_bf16 v[118:121], v[188:191], v[180:183], v[118:121]
	global_load_lds_dwordx4 v205, s[6:7]
	v_add_f32_e32 v55, 1.0, v55
	v_mfma_f32_16x16x32_bf16 v[122:125], v[192:195], v[180:183], v[122:125]
	s_sub_u32 s4, s4, 0x780
	s_subb_u32 s5, s5, 0
	v_mfma_f32_16x16x32_bf16 v[126:129], v[196:199], v[180:183], v[126:129]
	s_add_u32 s6, s6, 0x3f880
	s_addc_u32 s7, s7, 0
	v_add_f32_e32 v56, 1.0, v56
	s_waitcnt lgkmcnt(0)
	v_mfma_f32_16x16x32_bf16 v[66:69], v[152:155], v[136:139], v[66:69]
	ds_read_b128 v[168:171], v229 offset:0
	v_mfma_f32_16x16x32_bf16 v[70:73], v[156:159], v[136:139], v[70:73]
	ds_read_b128 v[172:175], v229 offset:2048
	v_add_f32_e32 v57, 1.0, v57
	v_mfma_f32_16x16x32_bf16 v[74:77], v[160:163], v[136:139], v[74:77]
	ds_read_b128 v[176:179], v229 offset:4096
	v_rcp_f32_e32 v50, v50
	v_mfma_f32_16x16x32_bf16 v[78:81], v[164:167], v[136:139], v[78:81]
	ds_read_b128 v[180:183], v229 offset:6144
	v_rcp_f32_e32 v51, v51
	v_mfma_f32_16x16x32_bf16 v[82:85], v[152:155], v[140:143], v[82:85]
	ds_read_b128 v[184:187], v235 offset:0
	v_mfma_f32_16x16x32_bf16 v[86:89], v[156:159], v[140:143], v[86:89]
	ds_read_b128 v[188:191], v235 offset:2048
	v_rcp_f32_e32 v52, v52
	v_mfma_f32_16x16x32_bf16 v[90:93], v[160:163], v[140:143], v[90:93]
	ds_read_b128 v[192:195], v235 offset:4096
	v_rcp_f32_e32 v53, v53
	v_mfma_f32_16x16x32_bf16 v[94:97], v[164:167], v[140:143], v[94:97]
	ds_read_b128 v[196:199], v235 offset:6144
	v_rcp_f32_e32 v54, v54
	v_mfma_f32_16x16x32_bf16 v[98:101], v[152:155], v[144:147], v[98:101]
	v_mfma_f32_16x16x32_bf16 v[102:105], v[156:159], v[144:147], v[102:105]
	v_rcp_f32_e32 v55, v55
	v_mfma_f32_16x16x32_bf16 v[106:109], v[160:163], v[144:147], v[106:109]
	v_rcp_f32_e32 v56, v56
	v_mfma_f32_16x16x32_bf16 v[110:113], v[164:167], v[144:147], v[110:113]
	v_rcp_f32_e32 v57, v57
	v_mfma_f32_16x16x32_bf16 v[114:117], v[152:155], v[148:151], v[114:117]
	v_mfma_f32_16x16x32_bf16 v[118:121], v[156:159], v[148:151], v[118:121]
	v_cvt_pk_bf16_f32 v50, v50, v51
	v_mfma_f32_16x16x32_bf16 v[122:125], v[160:163], v[148:151], v[122:125]
	v_cvt_pk_bf16_f32 v51, v52, v53
	v_mfma_f32_16x16x32_bf16 v[126:129], v[164:167], v[148:151], v[126:129]
	v_cvt_pk_bf16_f32 v52, v54, v55
	s_waitcnt vmcnt(6) lgkmcnt(0)
	s_barrier
	v_mfma_f32_16x16x32_bf16 v[66:69], v[184:187], v[168:171], v[66:69]
	ds_read_b128 v[136:139], v218 offset:0
	v_mfma_f32_16x16x32_bf16 v[70:73], v[188:191], v[168:171], v[70:73]
	ds_read_b128 v[140:143], v218 offset:2048
	v_mfma_f32_16x16x32_bf16 v[74:77], v[192:195], v[168:171], v[74:77]
	ds_read_b128 v[144:147], v218 offset:4096
	v_cvt_pk_bf16_f32 v53, v56, v57
	v_mfma_f32_16x16x32_bf16 v[78:81], v[196:199], v[168:171], v[78:81]
	ds_read_b128 v[148:151], v218 offset:6144
	v_mfma_f32_16x16x32_bf16 v[82:85], v[184:187], v[172:175], v[82:85]
	ds_read_b128 v[152:155], v230 offset:0
	global_store_dwordx4 v241, v[50:53], s[10:11] offset:2048 sc1
	v_mfma_f32_16x16x32_bf16 v[86:89], v[188:191], v[172:175], v[86:89]
	ds_read_b128 v[156:159], v230 offset:2048
	v_mfma_f32_16x16x32_bf16 v[90:93], v[192:195], v[172:175], v[90:93]
	ds_read_b128 v[160:163], v230 offset:4096
	v_mul_f32_e32 v58, s12, v58
	v_mfma_f32_16x16x32_bf16 v[94:97], v[196:199], v[172:175], v[94:97]
	ds_read_b128 v[164:167], v230 offset:6144
	s_add_u32 m0, s8, 0x18000
	v_mfma_f32_16x16x32_bf16 v[98:101], v[184:187], v[176:179], v[98:101]
	global_load_lds_dwordx4 v200, s[4:5]
	s_add_u32 m0, s8, 0x18400
	v_mfma_f32_16x16x32_bf16 v[102:105], v[188:191], v[176:179], v[102:105]
	global_load_lds_dwordx4 v201, s[4:5]
	v_mul_f32_e32 v59, s12, v59
	s_add_u32 m0, s8, 0x18800
	v_mfma_f32_16x16x32_bf16 v[106:109], v[192:195], v[176:179], v[106:109]
	global_load_lds_dwordx4 v202, s[4:5]
	s_add_u32 m0, s8, 0x18c00
	v_mfma_f32_16x16x32_bf16 v[110:113], v[196:199], v[176:179], v[110:113]
	global_load_lds_dwordx4 v203, s[4:5]
	v_mul_f32_e32 v60, s12, v60
	s_add_u32 m0, s9, 0x18000
	v_mfma_f32_16x16x32_bf16 v[114:117], v[184:187], v[180:183], v[114:117]
	global_load_lds_dwordx4 v204, s[6:7]
	s_add_u32 m0, s9, 0x18400
	v_mfma_f32_16x16x32_bf16 v[118:121], v[188:191], v[180:183], v[118:121]
	global_load_lds_dwordx4 v205, s[6:7]
	v_mul_f32_e32 v61, s12, v61
	v_mfma_f32_16x16x32_bf16 v[122:125], v[192:195], v[180:183], v[122:125]
	s_add_u32 s4, s4, 0x80
	s_addc_u32 s5, s5, 0
	v_mfma_f32_16x16x32_bf16 v[126:129], v[196:199], v[180:183], v[126:129]
	s_add_u32 s6, s6, 0x80
	s_addc_u32 s7, s7, 0
	v_mul_f32_e32 v62, s12, v62
	s_waitcnt lgkmcnt(0)
	v_mfma_f32_16x16x32_bf16 v[66:69], v[152:155], v[136:139], v[66:69]
	ds_read_b128 v[168:171], v225 offset:0
	v_mfma_f32_16x16x32_bf16 v[70:73], v[156:159], v[136:139], v[70:73]
	ds_read_b128 v[172:175], v225 offset:2048
	v_mul_f32_e32 v63, s12, v63
	v_mfma_f32_16x16x32_bf16 v[74:77], v[160:163], v[136:139], v[74:77]
	ds_read_b128 v[176:179], v225 offset:4096
	v_mul_f32_e32 v64, s12, v64
	v_mfma_f32_16x16x32_bf16 v[78:81], v[164:167], v[136:139], v[78:81]
	ds_read_b128 v[180:183], v225 offset:6144
	v_mul_f32_e32 v65, s12, v65
	v_mfma_f32_16x16x32_bf16 v[82:85], v[152:155], v[140:143], v[82:85]
	ds_read_b128 v[184:187], v233 offset:0
	v_mfma_f32_16x16x32_bf16 v[86:89], v[156:159], v[140:143], v[86:89]
	ds_read_b128 v[188:191], v233 offset:2048
	v_exp_f32_e32 v58, v58
	v_mfma_f32_16x16x32_bf16 v[90:93], v[160:163], v[140:143], v[90:93]
	ds_read_b128 v[192:195], v233 offset:4096
	v_exp_f32_e32 v59, v59
	v_mfma_f32_16x16x32_bf16 v[94:97], v[164:167], v[140:143], v[94:97]
	ds_read_b128 v[196:199], v233 offset:6144
	v_exp_f32_e32 v60, v60
	v_mfma_f32_16x16x32_bf16 v[98:101], v[152:155], v[144:147], v[98:101]
	v_mfma_f32_16x16x32_bf16 v[102:105], v[156:159], v[144:147], v[102:105]
	v_exp_f32_e32 v61, v61
	v_mfma_f32_16x16x32_bf16 v[106:109], v[160:163], v[144:147], v[106:109]
	v_exp_f32_e32 v62, v62
	v_mfma_f32_16x16x32_bf16 v[110:113], v[164:167], v[144:147], v[110:113]
	v_exp_f32_e32 v63, v63
	v_mfma_f32_16x16x32_bf16 v[114:117], v[152:155], v[148:151], v[114:117]
	v_mfma_f32_16x16x32_bf16 v[118:121], v[156:159], v[148:151], v[118:121]
	v_exp_f32_e32 v64, v64
	v_mfma_f32_16x16x32_bf16 v[122:125], v[160:163], v[148:151], v[122:125]
	v_exp_f32_e32 v65, v65
	v_mfma_f32_16x16x32_bf16 v[126:129], v[164:167], v[148:151], v[126:129]
	v_add_f32_e32 v58, 1.0, v58
	s_waitcnt vmcnt(7) lgkmcnt(0)
	s_barrier
	v_mfma_f32_16x16x32_bf16 v[66:69], v[184:187], v[168:171], v[66:69]
	ds_read_b128 v[136:139], v219 offset:0
	v_mfma_f32_16x16x32_bf16 v[70:73], v[188:191], v[168:171], v[70:73]
	ds_read_b128 v[140:143], v219 offset:2048
	v_mfma_f32_16x16x32_bf16 v[74:77], v[192:195], v[168:171], v[74:77]
	ds_read_b128 v[144:147], v219 offset:4096
	v_add_f32_e32 v59, 1.0, v59
	v_mfma_f32_16x16x32_bf16 v[78:81], v[196:199], v[168:171], v[78:81]
	ds_read_b128 v[148:151], v219 offset:6144
	v_mfma_f32_16x16x32_bf16 v[82:85], v[184:187], v[172:175], v[82:85]
	ds_read_b128 v[152:155], v231 offset:0
	v_add_f32_e32 v60, 1.0, v60
	v_mfma_f32_16x16x32_bf16 v[86:89], v[188:191], v[172:175], v[86:89]
	ds_read_b128 v[156:159], v231 offset:2048
	v_mfma_f32_16x16x32_bf16 v[90:93], v[192:195], v[172:175], v[90:93]
	ds_read_b128 v[160:163], v231 offset:4096
	v_add_f32_e32 v61, 1.0, v61
	v_mfma_f32_16x16x32_bf16 v[94:97], v[196:199], v[172:175], v[94:97]
	ds_read_b128 v[164:167], v231 offset:6144
	s_mov_b32 m0, s8
	v_mfma_f32_16x16x32_bf16 v[98:101], v[184:187], v[176:179], v[98:101]
	global_load_lds_dwordx4 v200, s[4:5]
	s_add_u32 m0, s8, 0x400
	v_mfma_f32_16x16x32_bf16 v[102:105], v[188:191], v[176:179], v[102:105]
	global_load_lds_dwordx4 v201, s[4:5]
	v_add_f32_e32 v62, 1.0, v62
	s_add_u32 m0, s8, 0x800
	v_mfma_f32_16x16x32_bf16 v[106:109], v[192:195], v[176:179], v[106:109]
	global_load_lds_dwordx4 v202, s[4:5]
	s_add_u32 m0, s8, 0xc00
	v_mfma_f32_16x16x32_bf16 v[110:113], v[196:199], v[176:179], v[110:113]
	global_load_lds_dwordx4 v203, s[4:5]
	v_add_f32_e32 v63, 1.0, v63
	s_mov_b32 m0, s9
	v_mfma_f32_16x16x32_bf16 v[114:117], v[184:187], v[180:183], v[114:117]
	global_load_lds_dwordx4 v204, s[6:7]
	s_add_u32 m0, s9, 0x400
	v_mfma_f32_16x16x32_bf16 v[118:121], v[188:191], v[180:183], v[118:121]
	global_load_lds_dwordx4 v205, s[6:7]
	v_add_f32_e32 v64, 1.0, v64
	v_mfma_f32_16x16x32_bf16 v[122:125], v[192:195], v[180:183], v[122:125]
	s_add_u32 s4, s4, 0x80
	s_addc_u32 s5, s5, 0
	v_mfma_f32_16x16x32_bf16 v[126:129], v[196:199], v[180:183], v[126:129]
	s_add_u32 s6, s6, 0x80
	s_addc_u32 s7, s7, 0
	v_add_f32_e32 v65, 1.0, v65
	s_waitcnt lgkmcnt(0)
	v_mfma_f32_16x16x32_bf16 v[66:69], v[152:155], v[136:139], v[66:69]
	ds_read_b128 v[168:171], v228 offset:0
	v_mfma_f32_16x16x32_bf16 v[70:73], v[156:159], v[136:139], v[70:73]
	ds_read_b128 v[172:175], v228 offset:2048
	v_rcp_f32_e32 v58, v58
	v_mfma_f32_16x16x32_bf16 v[74:77], v[160:163], v[136:139], v[74:77]
	ds_read_b128 v[176:179], v228 offset:4096
	v_rcp_f32_e32 v59, v59
	v_mfma_f32_16x16x32_bf16 v[78:81], v[164:167], v[136:139], v[78:81]
	ds_read_b128 v[180:183], v228 offset:6144
	v_rcp_f32_e32 v60, v60
	v_mfma_f32_16x16x32_bf16 v[82:85], v[152:155], v[140:143], v[82:85]
	ds_read_b128 v[184:187], v234 offset:0
	v_mfma_f32_16x16x32_bf16 v[86:89], v[156:159], v[140:143], v[86:89]
	ds_read_b128 v[188:191], v234 offset:2048
	v_rcp_f32_e32 v61, v61
	v_mfma_f32_16x16x32_bf16 v[90:93], v[160:163], v[140:143], v[90:93]
	ds_read_b128 v[192:195], v234 offset:4096
	v_rcp_f32_e32 v62, v62
	v_mfma_f32_16x16x32_bf16 v[94:97], v[164:167], v[140:143], v[94:97]
	ds_read_b128 v[196:199], v234 offset:6144
	v_rcp_f32_e32 v63, v63
	v_mfma_f32_16x16x32_bf16 v[98:101], v[152:155], v[144:147], v[98:101]
	v_mfma_f32_16x16x32_bf16 v[102:105], v[156:159], v[144:147], v[102:105]
	v_rcp_f32_e32 v64, v64
	v_mfma_f32_16x16x32_bf16 v[106:109], v[160:163], v[144:147], v[106:109]
	v_rcp_f32_e32 v65, v65
	v_mfma_f32_16x16x32_bf16 v[110:113], v[164:167], v[144:147], v[110:113]
	v_cvt_pk_bf16_f32 v58, v58, v59
	v_mfma_f32_16x16x32_bf16 v[114:117], v[152:155], v[148:151], v[114:117]
	v_mfma_f32_16x16x32_bf16 v[118:121], v[156:159], v[148:151], v[118:121]
	v_cvt_pk_bf16_f32 v59, v60, v61
	v_mfma_f32_16x16x32_bf16 v[122:125], v[160:163], v[148:151], v[122:125]
	v_cvt_pk_bf16_f32 v60, v62, v63
	v_mfma_f32_16x16x32_bf16 v[126:129], v[164:167], v[148:151], v[126:129]
	v_cvt_pk_bf16_f32 v61, v64, v65
	s_waitcnt vmcnt(6) lgkmcnt(0)
	s_barrier
	v_mfma_f32_16x16x32_bf16 v[66:69], v[184:187], v[168:171], v[66:69]
	ds_read_b128 v[136:139], v224 offset:0
	v_mfma_f32_16x16x32_bf16 v[70:73], v[188:191], v[168:171], v[70:73]
	ds_read_b128 v[140:143], v224 offset:2048
	v_mfma_f32_16x16x32_bf16 v[74:77], v[192:195], v[168:171], v[74:77]
	ds_read_b128 v[144:147], v224 offset:4096
	v_mfma_f32_16x16x32_bf16 v[78:81], v[196:199], v[168:171], v[78:81]
	ds_read_b128 v[148:151], v224 offset:6144
	v_mfma_f32_16x16x32_bf16 v[82:85], v[184:187], v[172:175], v[82:85]
	ds_read_b128 v[152:155], v232 offset:0
	v_mfma_f32_16x16x32_bf16 v[86:89], v[188:191], v[172:175], v[86:89]
	ds_read_b128 v[156:159], v232 offset:2048
	v_mfma_f32_16x16x32_bf16 v[90:93], v[192:195], v[172:175], v[90:93]
	ds_read_b128 v[160:163], v232 offset:4096
	v_mfma_f32_16x16x32_bf16 v[94:97], v[196:199], v[172:175], v[94:97]
	ds_read_b128 v[164:167], v232 offset:6144
	s_add_u32 m0, s8, 0xc000
	v_mfma_f32_16x16x32_bf16 v[98:101], v[184:187], v[176:179], v[98:101]
	global_load_lds_dwordx4 v200, s[4:5]
	s_add_u32 m0, s8, 0xc400
	v_mfma_f32_16x16x32_bf16 v[102:105], v[188:191], v[176:179], v[102:105]
	global_load_lds_dwordx4 v201, s[4:5]
	s_add_u32 m0, s8, 0xc800
	v_mfma_f32_16x16x32_bf16 v[106:109], v[192:195], v[176:179], v[106:109]
	global_load_lds_dwordx4 v202, s[4:5]
	s_add_u32 m0, s8, 0xcc00
	v_mfma_f32_16x16x32_bf16 v[110:113], v[196:199], v[176:179], v[110:113]
	global_load_lds_dwordx4 v203, s[4:5]
	s_add_u32 m0, s9, 0xc000
	v_mfma_f32_16x16x32_bf16 v[114:117], v[184:187], v[180:183], v[114:117]
	global_load_lds_dwordx4 v204, s[6:7]
	s_add_u32 m0, s9, 0xc400
	v_mfma_f32_16x16x32_bf16 v[118:121], v[188:191], v[180:183], v[118:121]
	global_load_lds_dwordx4 v205, s[6:7]
	v_mfma_f32_16x16x32_bf16 v[122:125], v[192:195], v[180:183], v[122:125]
	s_add_u32 s4, s4, 0x80
	s_addc_u32 s5, s5, 0
	v_mfma_f32_16x16x32_bf16 v[126:129], v[196:199], v[180:183], v[126:129]
	s_add_u32 s6, s6, 0x80
	s_addc_u32 s7, s7, 0
	global_store_dwordx4 v241, v[58:61], s[10:11] offset:3072 sc1
	s_waitcnt lgkmcnt(0)
	v_mfma_f32_16x16x32_bf16 v[2:5], v[152:155], v[136:139], 0
	ds_read_b128 v[168:171], v229 offset:0
	v_mfma_f32_16x16x32_bf16 v[6:9], v[156:159], v[136:139], 0
	ds_read_b128 v[172:175], v229 offset:2048
	s_add_u32 s10, s28, s13
	s_addc_u32 s11, s29, 0
	v_mfma_f32_16x16x32_bf16 v[10:13], v[160:163], v[136:139], 0
	ds_read_b128 v[176:179], v229 offset:4096
	s_add_u32 s13, s13, 0x10000
	v_mfma_f32_16x16x32_bf16 v[14:17], v[164:167], v[136:139], 0
	ds_read_b128 v[180:183], v229 offset:6144
	v_mul_f32_e32 v66, s12, v66
	v_mfma_f32_16x16x32_bf16 v[18:21], v[152:155], v[140:143], 0
	ds_read_b128 v[184:187], v235 offset:0
	v_mfma_f32_16x16x32_bf16 v[22:25], v[156:159], v[140:143], 0
	ds_read_b128 v[188:191], v235 offset:2048
	v_mul_f32_e32 v67, s12, v67
	v_mfma_f32_16x16x32_bf16 v[26:29], v[160:163], v[140:143], 0
	ds_read_b128 v[192:195], v235 offset:4096
	v_mul_f32_e32 v68, s12, v68
	v_mfma_f32_16x16x32_bf16 v[30:33], v[164:167], v[140:143], 0
	ds_read_b128 v[196:199], v235 offset:6144
	v_mul_f32_e32 v69, s12, v69
	v_mfma_f32_16x16x32_bf16 v[34:37], v[152:155], v[144:147], 0
	v_mfma_f32_16x16x32_bf16 v[38:41], v[156:159], v[144:147], 0
	v_mul_f32_e32 v70, s12, v70
	v_mfma_f32_16x16x32_bf16 v[42:45], v[160:163], v[144:147], 0
	v_mul_f32_e32 v71, s12, v71
	v_mfma_f32_16x16x32_bf16 v[46:49], v[164:167], v[144:147], 0
	v_mul_f32_e32 v72, s12, v72
	v_mfma_f32_16x16x32_bf16 v[50:53], v[152:155], v[148:151], 0
	v_mfma_f32_16x16x32_bf16 v[54:57], v[156:159], v[148:151], 0
	v_mul_f32_e32 v73, s12, v73
	v_mfma_f32_16x16x32_bf16 v[58:61], v[160:163], v[148:151], 0
	v_exp_f32_e32 v66, v66
	v_mfma_f32_16x16x32_bf16 v[62:65], v[164:167], v[148:151], 0
	v_exp_f32_e32 v67, v67
	s_waitcnt vmcnt(7) lgkmcnt(0)
	s_barrier
	v_mfma_f32_16x16x32_bf16 v[2:5], v[184:187], v[168:171], v[2:5]
	ds_read_b128 v[136:139], v218 offset:0
	v_mfma_f32_16x16x32_bf16 v[6:9], v[188:191], v[168:171], v[6:9]
	ds_read_b128 v[140:143], v218 offset:2048
	v_mfma_f32_16x16x32_bf16 v[10:13], v[192:195], v[168:171], v[10:13]
	ds_read_b128 v[144:147], v218 offset:4096
	v_exp_f32_e32 v68, v68
	v_mfma_f32_16x16x32_bf16 v[14:17], v[196:199], v[168:171], v[14:17]
	ds_read_b128 v[148:151], v218 offset:6144
	v_mfma_f32_16x16x32_bf16 v[18:21], v[184:187], v[172:175], v[18:21]
	ds_read_b128 v[152:155], v230 offset:0
	v_exp_f32_e32 v69, v69
	v_mfma_f32_16x16x32_bf16 v[22:25], v[188:191], v[172:175], v[22:25]
	ds_read_b128 v[156:159], v230 offset:2048
	v_mfma_f32_16x16x32_bf16 v[26:29], v[192:195], v[172:175], v[26:29]
	ds_read_b128 v[160:163], v230 offset:4096
	v_exp_f32_e32 v70, v70
	v_mfma_f32_16x16x32_bf16 v[30:33], v[196:199], v[172:175], v[30:33]
	ds_read_b128 v[164:167], v230 offset:6144
	s_add_u32 m0, s8, 0x18000
	v_mfma_f32_16x16x32_bf16 v[34:37], v[184:187], v[176:179], v[34:37]
	global_load_lds_dwordx4 v200, s[4:5]
	s_add_u32 m0, s8, 0x18400
	v_mfma_f32_16x16x32_bf16 v[38:41], v[188:191], v[176:179], v[38:41]
	global_load_lds_dwordx4 v201, s[4:5]
	v_exp_f32_e32 v71, v71
	s_add_u32 m0, s8, 0x18800
	v_mfma_f32_16x16x32_bf16 v[42:45], v[192:195], v[176:179], v[42:45]
	global_load_lds_dwordx4 v202, s[4:5]
	s_add_u32 m0, s8, 0x18c00
	v_mfma_f32_16x16x32_bf16 v[46:49], v[196:199], v[176:179], v[46:49]
	global_load_lds_dwordx4 v203, s[4:5]
	v_exp_f32_e32 v72, v72
	s_add_u32 m0, s9, 0x18000
	v_mfma_f32_16x16x32_bf16 v[50:53], v[184:187], v[180:183], v[50:53]
	global_load_lds_dwordx4 v204, s[6:7]
	s_add_u32 m0, s9, 0x18400
	v_mfma_f32_16x16x32_bf16 v[54:57], v[188:191], v[180:183], v[54:57]
	global_load_lds_dwordx4 v205, s[6:7]
	v_exp_f32_e32 v73, v73
	v_mfma_f32_16x16x32_bf16 v[58:61], v[192:195], v[180:183], v[58:61]
	s_add_u32 s4, s4, 0x80
	s_addc_u32 s5, s5, 0
	v_mfma_f32_16x16x32_bf16 v[62:65], v[196:199], v[180:183], v[62:65]
	s_add_u32 s6, s6, 0x80
	s_addc_u32 s7, s7, 0
	v_add_f32_e32 v66, 1.0, v66
	s_waitcnt lgkmcnt(0)
	v_mfma_f32_16x16x32_bf16 v[2:5], v[152:155], v[136:139], v[2:5]
	ds_read_b128 v[168:171], v225 offset:0
	v_mfma_f32_16x16x32_bf16 v[6:9], v[156:159], v[136:139], v[6:9]
	ds_read_b128 v[172:175], v225 offset:2048
	v_add_f32_e32 v67, 1.0, v67
	v_mfma_f32_16x16x32_bf16 v[10:13], v[160:163], v[136:139], v[10:13]
	ds_read_b128 v[176:179], v225 offset:4096
	v_add_f32_e32 v68, 1.0, v68
	v_mfma_f32_16x16x32_bf16 v[14:17], v[164:167], v[136:139], v[14:17]
	ds_read_b128 v[180:183], v225 offset:6144
	v_add_f32_e32 v69, 1.0, v69
	v_mfma_f32_16x16x32_bf16 v[18:21], v[152:155], v[140:143], v[18:21]
	ds_read_b128 v[184:187], v233 offset:0
	v_mfma_f32_16x16x32_bf16 v[22:25], v[156:159], v[140:143], v[22:25]
	ds_read_b128 v[188:191], v233 offset:2048
	v_add_f32_e32 v70, 1.0, v70
	v_mfma_f32_16x16x32_bf16 v[26:29], v[160:163], v[140:143], v[26:29]
	ds_read_b128 v[192:195], v233 offset:4096
	v_add_f32_e32 v71, 1.0, v71
	v_mfma_f32_16x16x32_bf16 v[30:33], v[164:167], v[140:143], v[30:33]
	ds_read_b128 v[196:199], v233 offset:6144
	v_add_f32_e32 v72, 1.0, v72
	v_mfma_f32_16x16x32_bf16 v[34:37], v[152:155], v[144:147], v[34:37]
	v_mfma_f32_16x16x32_bf16 v[38:41], v[156:159], v[144:147], v[38:41]
	v_add_f32_e32 v73, 1.0, v73
	v_mfma_f32_16x16x32_bf16 v[42:45], v[160:163], v[144:147], v[42:45]
	v_rcp_f32_e32 v66, v66
	v_mfma_f32_16x16x32_bf16 v[46:49], v[164:167], v[144:147], v[46:49]
	v_rcp_f32_e32 v67, v67
	v_mfma_f32_16x16x32_bf16 v[50:53], v[152:155], v[148:151], v[50:53]
	v_mfma_f32_16x16x32_bf16 v[54:57], v[156:159], v[148:151], v[54:57]
	v_rcp_f32_e32 v68, v68
	v_mfma_f32_16x16x32_bf16 v[58:61], v[160:163], v[148:151], v[58:61]
	v_rcp_f32_e32 v69, v69
	v_mfma_f32_16x16x32_bf16 v[62:65], v[164:167], v[148:151], v[62:65]
	v_rcp_f32_e32 v70, v70
	s_waitcnt vmcnt(7) lgkmcnt(0)
	s_barrier
	v_mfma_f32_16x16x32_bf16 v[2:5], v[184:187], v[168:171], v[2:5]
	ds_read_b128 v[136:139], v219 offset:0
	v_mfma_f32_16x16x32_bf16 v[6:9], v[188:191], v[168:171], v[6:9]
	ds_read_b128 v[140:143], v219 offset:2048
	v_mfma_f32_16x16x32_bf16 v[10:13], v[192:195], v[168:171], v[10:13]
	ds_read_b128 v[144:147], v219 offset:4096
	v_rcp_f32_e32 v71, v71
	v_mfma_f32_16x16x32_bf16 v[14:17], v[196:199], v[168:171], v[14:17]
	ds_read_b128 v[148:151], v219 offset:6144
	v_mfma_f32_16x16x32_bf16 v[18:21], v[184:187], v[172:175], v[18:21]
	ds_read_b128 v[152:155], v231 offset:0
	v_rcp_f32_e32 v72, v72
	v_mfma_f32_16x16x32_bf16 v[22:25], v[188:191], v[172:175], v[22:25]
	ds_read_b128 v[156:159], v231 offset:2048
	v_mfma_f32_16x16x32_bf16 v[26:29], v[192:195], v[172:175], v[26:29]
	ds_read_b128 v[160:163], v231 offset:4096
	v_rcp_f32_e32 v73, v73
	v_mfma_f32_16x16x32_bf16 v[30:33], v[196:199], v[172:175], v[30:33]
	ds_read_b128 v[164:167], v231 offset:6144
	s_mov_b32 m0, s8
	v_mfma_f32_16x16x32_bf16 v[34:37], v[184:187], v[176:179], v[34:37]
	global_load_lds_dwordx4 v200, s[4:5]
	s_add_u32 m0, s8, 0x400
	v_mfma_f32_16x16x32_bf16 v[38:41], v[188:191], v[176:179], v[38:41]
	global_load_lds_dwordx4 v201, s[4:5]
	v_cvt_pk_bf16_f32 v66, v66, v67
	s_add_u32 m0, s8, 0x800
	v_mfma_f32_16x16x32_bf16 v[42:45], v[192:195], v[176:179], v[42:45]
	global_load_lds_dwordx4 v202, s[4:5]
	s_add_u32 m0, s8, 0xc00
	v_mfma_f32_16x16x32_bf16 v[46:49], v[196:199], v[176:179], v[46:49]
	global_load_lds_dwordx4 v203, s[4:5]
	v_cvt_pk_bf16_f32 v67, v68, v69
	s_mov_b32 m0, s9
	v_mfma_f32_16x16x32_bf16 v[50:53], v[184:187], v[180:183], v[50:53]
	global_load_lds_dwordx4 v204, s[6:7]
	s_add_u32 m0, s9, 0x400
	v_mfma_f32_16x16x32_bf16 v[54:57], v[188:191], v[180:183], v[54:57]
	global_load_lds_dwordx4 v205, s[6:7]
	v_cvt_pk_bf16_f32 v68, v70, v71
	v_mfma_f32_16x16x32_bf16 v[58:61], v[192:195], v[180:183], v[58:61]
	s_add_u32 s4, s4, 0x80
	s_addc_u32 s5, s5, 0
	v_mfma_f32_16x16x32_bf16 v[62:65], v[196:199], v[180:183], v[62:65]
	s_add_u32 s6, s6, 0x80
	s_addc_u32 s7, s7, 0
	v_cvt_pk_bf16_f32 v69, v72, v73
	s_waitcnt lgkmcnt(0)
	v_mfma_f32_16x16x32_bf16 v[2:5], v[152:155], v[136:139], v[2:5]
	ds_read_b128 v[168:171], v228 offset:0
	v_mfma_f32_16x16x32_bf16 v[6:9], v[156:159], v[136:139], v[6:9]
	ds_read_b128 v[172:175], v228 offset:2048
	global_store_dwordx4 v240, v[66:69], s[10:11] offset:0 sc1
	v_mfma_f32_16x16x32_bf16 v[10:13], v[160:163], v[136:139], v[10:13]
	ds_read_b128 v[176:179], v228 offset:4096
	v_mul_f32_e32 v74, s12, v74
	v_mfma_f32_16x16x32_bf16 v[14:17], v[164:167], v[136:139], v[14:17]
	ds_read_b128 v[180:183], v228 offset:6144
	v_mul_f32_e32 v75, s12, v75
	v_mfma_f32_16x16x32_bf16 v[18:21], v[152:155], v[140:143], v[18:21]
	ds_read_b128 v[184:187], v234 offset:0
	v_mfma_f32_16x16x32_bf16 v[22:25], v[156:159], v[140:143], v[22:25]
	ds_read_b128 v[188:191], v234 offset:2048
	v_mul_f32_e32 v76, s12, v76
	v_mfma_f32_16x16x32_bf16 v[26:29], v[160:163], v[140:143], v[26:29]
	ds_read_b128 v[192:195], v234 offset:4096
	v_mul_f32_e32 v77, s12, v77
	v_mfma_f32_16x16x32_bf16 v[30:33], v[164:167], v[140:143], v[30:33]
	ds_read_b128 v[196:199], v234 offset:6144
	v_mul_f32_e32 v78, s12, v78
	v_mfma_f32_16x16x32_bf16 v[34:37], v[152:155], v[144:147], v[34:37]
	v_mfma_f32_16x16x32_bf16 v[38:41], v[156:159], v[144:147], v[38:41]
	v_mul_f32_e32 v79, s12, v79
	v_mfma_f32_16x16x32_bf16 v[42:45], v[160:163], v[144:147], v[42:45]
	v_mul_f32_e32 v80, s12, v80
	v_mfma_f32_16x16x32_bf16 v[46:49], v[164:167], v[144:147], v[46:49]
	v_mul_f32_e32 v81, s12, v81
	v_mfma_f32_16x16x32_bf16 v[50:53], v[152:155], v[148:151], v[50:53]
	v_mfma_f32_16x16x32_bf16 v[54:57], v[156:159], v[148:151], v[54:57]
	v_exp_f32_e32 v74, v74
	v_mfma_f32_16x16x32_bf16 v[58:61], v[160:163], v[148:151], v[58:61]
	v_exp_f32_e32 v75, v75
	v_mfma_f32_16x16x32_bf16 v[62:65], v[164:167], v[148:151], v[62:65]
	v_exp_f32_e32 v76, v76
	s_waitcnt vmcnt(7) lgkmcnt(0)
	s_barrier
	v_mfma_f32_16x16x32_bf16 v[2:5], v[184:187], v[168:171], v[2:5]
	ds_read_b128 v[136:139], v224 offset:0
	v_mfma_f32_16x16x32_bf16 v[6:9], v[188:191], v[168:171], v[6:9]
	ds_read_b128 v[140:143], v224 offset:2048
	v_mfma_f32_16x16x32_bf16 v[10:13], v[192:195], v[168:171], v[10:13]
	ds_read_b128 v[144:147], v224 offset:4096
	v_exp_f32_e32 v77, v77
	v_mfma_f32_16x16x32_bf16 v[14:17], v[196:199], v[168:171], v[14:17]
	ds_read_b128 v[148:151], v224 offset:6144
	v_mfma_f32_16x16x32_bf16 v[18:21], v[184:187], v[172:175], v[18:21]
	ds_read_b128 v[152:155], v232 offset:0
	v_exp_f32_e32 v78, v78
	v_mfma_f32_16x16x32_bf16 v[22:25], v[188:191], v[172:175], v[22:25]
	ds_read_b128 v[156:159], v232 offset:2048
	v_mfma_f32_16x16x32_bf16 v[26:29], v[192:195], v[172:175], v[26:29]
	ds_read_b128 v[160:163], v232 offset:4096
	v_exp_f32_e32 v79, v79
	v_mfma_f32_16x16x32_bf16 v[30:33], v[196:199], v[172:175], v[30:33]
	ds_read_b128 v[164:167], v232 offset:6144
	s_add_u32 m0, s8, 0xc000
	v_mfma_f32_16x16x32_bf16 v[34:37], v[184:187], v[176:179], v[34:37]
	global_load_lds_dwordx4 v200, s[4:5]
	s_add_u32 m0, s8, 0xc400
	v_mfma_f32_16x16x32_bf16 v[38:41], v[188:191], v[176:179], v[38:41]
	global_load_lds_dwordx4 v201, s[4:5]
	v_exp_f32_e32 v80, v80
	s_add_u32 m0, s8, 0xc800
	v_mfma_f32_16x16x32_bf16 v[42:45], v[192:195], v[176:179], v[42:45]
	global_load_lds_dwordx4 v202, s[4:5]
	s_add_u32 m0, s8, 0xcc00
	v_mfma_f32_16x16x32_bf16 v[46:49], v[196:199], v[176:179], v[46:49]
	global_load_lds_dwordx4 v203, s[4:5]
	v_exp_f32_e32 v81, v81
	s_add_u32 m0, s9, 0xc000
	v_mfma_f32_16x16x32_bf16 v[50:53], v[184:187], v[180:183], v[50:53]
	global_load_lds_dwordx4 v204, s[6:7]
	s_add_u32 m0, s9, 0xc400
	v_mfma_f32_16x16x32_bf16 v[54:57], v[188:191], v[180:183], v[54:57]
	global_load_lds_dwordx4 v205, s[6:7]
	v_add_f32_e32 v74, 1.0, v74
	v_mfma_f32_16x16x32_bf16 v[58:61], v[192:195], v[180:183], v[58:61]
	s_add_u32 s4, s4, 0x80
	s_addc_u32 s5, s5, 0
	v_mfma_f32_16x16x32_bf16 v[62:65], v[196:199], v[180:183], v[62:65]
	s_add_u32 s6, s6, 0x80
	s_addc_u32 s7, s7, 0
	v_add_f32_e32 v75, 1.0, v75
	s_waitcnt lgkmcnt(0)
	v_mfma_f32_16x16x32_bf16 v[2:5], v[152:155], v[136:139], v[2:5]
	ds_read_b128 v[168:171], v229 offset:0
	v_mfma_f32_16x16x32_bf16 v[6:9], v[156:159], v[136:139], v[6:9]
	ds_read_b128 v[172:175], v229 offset:2048
	v_add_f32_e32 v76, 1.0, v76
	v_mfma_f32_16x16x32_bf16 v[10:13], v[160:163], v[136:139], v[10:13]
	ds_read_b128 v[176:179], v229 offset:4096
	v_add_f32_e32 v77, 1.0, v77
	v_mfma_f32_16x16x32_bf16 v[14:17], v[164:167], v[136:139], v[14:17]
	ds_read_b128 v[180:183], v229 offset:6144
	v_add_f32_e32 v78, 1.0, v78
	v_mfma_f32_16x16x32_bf16 v[18:21], v[152:155], v[140:143], v[18:21]
	ds_read_b128 v[184:187], v235 offset:0
	v_mfma_f32_16x16x32_bf16 v[22:25], v[156:159], v[140:143], v[22:25]
	ds_read_b128 v[188:191], v235 offset:2048
	v_add_f32_e32 v79, 1.0, v79
	v_mfma_f32_16x16x32_bf16 v[26:29], v[160:163], v[140:143], v[26:29]
	ds_read_b128 v[192:195], v235 offset:4096
	v_add_f32_e32 v80, 1.0, v80
	v_mfma_f32_16x16x32_bf16 v[30:33], v[164:167], v[140:143], v[30:33]
	ds_read_b128 v[196:199], v235 offset:6144
	v_add_f32_e32 v81, 1.0, v81
	v_mfma_f32_16x16x32_bf16 v[34:37], v[152:155], v[144:147], v[34:37]
	v_mfma_f32_16x16x32_bf16 v[38:41], v[156:159], v[144:147], v[38:41]
	v_rcp_f32_e32 v74, v74
	v_mfma_f32_16x16x32_bf16 v[42:45], v[160:163], v[144:147], v[42:45]
	v_rcp_f32_e32 v75, v75
	v_mfma_f32_16x16x32_bf16 v[46:49], v[164:167], v[144:147], v[46:49]
	v_rcp_f32_e32 v76, v76
	v_mfma_f32_16x16x32_bf16 v[50:53], v[152:155], v[148:151], v[50:53]
	v_mfma_f32_16x16x32_bf16 v[54:57], v[156:159], v[148:151], v[54:57]
	v_rcp_f32_e32 v77, v77
	v_mfma_f32_16x16x32_bf16 v[58:61], v[160:163], v[148:151], v[58:61]
	v_rcp_f32_e32 v78, v78
	v_mfma_f32_16x16x32_bf16 v[62:65], v[164:167], v[148:151], v[62:65]
	v_rcp_f32_e32 v79, v79
	s_waitcnt vmcnt(7) lgkmcnt(0)
	s_barrier
	v_mfma_f32_16x16x32_bf16 v[2:5], v[184:187], v[168:171], v[2:5]
	ds_read_b128 v[136:139], v218 offset:0
	v_mfma_f32_16x16x32_bf16 v[6:9], v[188:191], v[168:171], v[6:9]
	ds_read_b128 v[140:143], v218 offset:2048
	v_mfma_f32_16x16x32_bf16 v[10:13], v[192:195], v[168:171], v[10:13]
	ds_read_b128 v[144:147], v218 offset:4096
	v_rcp_f32_e32 v80, v80
	v_mfma_f32_16x16x32_bf16 v[14:17], v[196:199], v[168:171], v[14:17]
	ds_read_b128 v[148:151], v218 offset:6144
	v_mfma_f32_16x16x32_bf16 v[18:21], v[184:187], v[172:175], v[18:21]
	ds_read_b128 v[152:155], v230 offset:0
	v_rcp_f32_e32 v81, v81
	v_mfma_f32_16x16x32_bf16 v[22:25], v[188:191], v[172:175], v[22:25]
	ds_read_b128 v[156:159], v230 offset:2048
	v_mfma_f32_16x16x32_bf16 v[26:29], v[192:195], v[172:175], v[26:29]
	ds_read_b128 v[160:163], v230 offset:4096
	v_cvt_pk_bf16_f32 v74, v74, v75
	v_mfma_f32_16x16x32_bf16 v[30:33], v[196:199], v[172:175], v[30:33]
	ds_read_b128 v[164:167], v230 offset:6144
	s_add_u32 m0, s8, 0x18000
	v_mfma_f32_16x16x32_bf16 v[34:37], v[184:187], v[176:179], v[34:37]
	global_load_lds_dwordx4 v200, s[4:5]
	s_add_u32 m0, s8, 0x18400
	v_mfma_f32_16x16x32_bf16 v[38:41], v[188:191], v[176:179], v[38:41]
	global_load_lds_dwordx4 v201, s[4:5]
	v_cvt_pk_bf16_f32 v75, v76, v77
	s_add_u32 m0, s8, 0x18800
	v_mfma_f32_16x16x32_bf16 v[42:45], v[192:195], v[176:179], v[42:45]
	global_load_lds_dwordx4 v202, s[4:5]
	s_add_u32 m0, s8, 0x18c00
	v_mfma_f32_16x16x32_bf16 v[46:49], v[196:199], v[176:179], v[46:49]
	global_load_lds_dwordx4 v203, s[4:5]
	v_cvt_pk_bf16_f32 v76, v78, v79
	s_add_u32 m0, s9, 0x18000
	v_mfma_f32_16x16x32_bf16 v[50:53], v[184:187], v[180:183], v[50:53]
	global_load_lds_dwordx4 v204, s[6:7]
	s_add_u32 m0, s9, 0x18400
	v_mfma_f32_16x16x32_bf16 v[54:57], v[188:191], v[180:183], v[54:57]
	global_load_lds_dwordx4 v205, s[6:7]
	v_cvt_pk_bf16_f32 v77, v80, v81
	v_mfma_f32_16x16x32_bf16 v[58:61], v[192:195], v[180:183], v[58:61]
	s_add_u32 s4, s4, 0x80
	s_addc_u32 s5, s5, 0
	v_mfma_f32_16x16x32_bf16 v[62:65], v[196:199], v[180:183], v[62:65]
	s_add_u32 s6, s6, 0x80
	s_addc_u32 s7, s7, 0
	global_store_dwordx4 v240, v[74:77], s[10:11] offset:1024 sc1
	s_waitcnt lgkmcnt(0)
	v_mfma_f32_16x16x32_bf16 v[2:5], v[152:155], v[136:139], v[2:5]
	ds_read_b128 v[168:171], v225 offset:0
	v_mfma_f32_16x16x32_bf16 v[6:9], v[156:159], v[136:139], v[6:9]
	ds_read_b128 v[172:175], v225 offset:2048
	v_mul_f32_e32 v82, s12, v82
	v_mfma_f32_16x16x32_bf16 v[10:13], v[160:163], v[136:139], v[10:13]
	ds_read_b128 v[176:179], v225 offset:4096
	v_mul_f32_e32 v83, s12, v83
	v_mfma_f32_16x16x32_bf16 v[14:17], v[164:167], v[136:139], v[14:17]
	ds_read_b128 v[180:183], v225 offset:6144
	v_mul_f32_e32 v84, s12, v84
	v_mfma_f32_16x16x32_bf16 v[18:21], v[152:155], v[140:143], v[18:21]
	ds_read_b128 v[184:187], v233 offset:0
	v_mfma_f32_16x16x32_bf16 v[22:25], v[156:159], v[140:143], v[22:25]
	ds_read_b128 v[188:191], v233 offset:2048
	v_mul_f32_e32 v85, s12, v85
	v_mfma_f32_16x16x32_bf16 v[26:29], v[160:163], v[140:143], v[26:29]
	ds_read_b128 v[192:195], v233 offset:4096
	v_mul_f32_e32 v86, s12, v86
	v_mfma_f32_16x16x32_bf16 v[30:33], v[164:167], v[140:143], v[30:33]
	ds_read_b128 v[196:199], v233 offset:6144
	v_mul_f32_e32 v87, s12, v87
	v_mfma_f32_16x16x32_bf16 v[34:37], v[152:155], v[144:147], v[34:37]
	v_mfma_f32_16x16x32_bf16 v[38:41], v[156:159], v[144:147], v[38:41]
	v_mul_f32_e32 v88, s12, v88
	v_mfma_f32_16x16x32_bf16 v[42:45], v[160:163], v[144:147], v[42:45]
	v_mul_f32_e32 v89, s12, v89
	v_mfma_f32_16x16x32_bf16 v[46:49], v[164:167], v[144:147], v[46:49]
	v_exp_f32_e32 v82, v82
	v_mfma_f32_16x16x32_bf16 v[50:53], v[152:155], v[148:151], v[50:53]
	v_mfma_f32_16x16x32_bf16 v[54:57], v[156:159], v[148:151], v[54:57]
	v_exp_f32_e32 v83, v83
	v_mfma_f32_16x16x32_bf16 v[58:61], v[160:163], v[148:151], v[58:61]
	v_exp_f32_e32 v84, v84
	v_mfma_f32_16x16x32_bf16 v[62:65], v[164:167], v[148:151], v[62:65]
	v_exp_f32_e32 v85, v85
	s_waitcnt vmcnt(7) lgkmcnt(0)
	s_barrier
	v_mfma_f32_16x16x32_bf16 v[2:5], v[184:187], v[168:171], v[2:5]
	ds_read_b128 v[136:139], v219 offset:0
	v_mfma_f32_16x16x32_bf16 v[6:9], v[188:191], v[168:171], v[6:9]
	ds_read_b128 v[140:143], v219 offset:2048
	v_mfma_f32_16x16x32_bf16 v[10:13], v[192:195], v[168:171], v[10:13]
	ds_read_b128 v[144:147], v219 offset:4096
	v_exp_f32_e32 v86, v86
	v_mfma_f32_16x16x32_bf16 v[14:17], v[196:199], v[168:171], v[14:17]
	ds_read_b128 v[148:151], v219 offset:6144
	v_mfma_f32_16x16x32_bf16 v[18:21], v[184:187], v[172:175], v[18:21]
	ds_read_b128 v[152:155], v231 offset:0
	v_exp_f32_e32 v87, v87
	v_mfma_f32_16x16x32_bf16 v[22:25], v[188:191], v[172:175], v[22:25]
	ds_read_b128 v[156:159], v231 offset:2048
	v_mfma_f32_16x16x32_bf16 v[26:29], v[192:195], v[172:175], v[26:29]
	ds_read_b128 v[160:163], v231 offset:4096
	v_exp_f32_e32 v88, v88
	v_mfma_f32_16x16x32_bf16 v[30:33], v[196:199], v[172:175], v[30:33]
	ds_read_b128 v[164:167], v231 offset:6144
	s_mov_b32 m0, s8
	v_mfma_f32_16x16x32_bf16 v[34:37], v[184:187], v[176:179], v[34:37]
	global_load_lds_dwordx4 v200, s[4:5]
	s_add_u32 m0, s8, 0x400
	v_mfma_f32_16x16x32_bf16 v[38:41], v[188:191], v[176:179], v[38:41]
	global_load_lds_dwordx4 v201, s[4:5]
	v_exp_f32_e32 v89, v89
	s_add_u32 m0, s8, 0x800
	v_mfma_f32_16x16x32_bf16 v[42:45], v[192:195], v[176:179], v[42:45]
	global_load_lds_dwordx4 v202, s[4:5]
	s_add_u32 m0, s8, 0xc00
	v_mfma_f32_16x16x32_bf16 v[46:49], v[196:199], v[176:179], v[46:49]
	global_load_lds_dwordx4 v203, s[4:5]
	v_add_f32_e32 v82, 1.0, v82
	s_mov_b32 m0, s9
	v_mfma_f32_16x16x32_bf16 v[50:53], v[184:187], v[180:183], v[50:53]
	global_load_lds_dwordx4 v204, s[6:7]
	s_add_u32 m0, s9, 0x400
	v_mfma_f32_16x16x32_bf16 v[54:57], v[188:191], v[180:183], v[54:57]
	global_load_lds_dwordx4 v205, s[6:7]
	v_add_f32_e32 v83, 1.0, v83
	v_mfma_f32_16x16x32_bf16 v[58:61], v[192:195], v[180:183], v[58:61]
	s_add_u32 s4, s4, 0x80
	s_addc_u32 s5, s5, 0
	v_mfma_f32_16x16x32_bf16 v[62:65], v[196:199], v[180:183], v[62:65]
	s_add_u32 s6, s6, 0x80
	s_addc_u32 s7, s7, 0
	v_add_f32_e32 v84, 1.0, v84
	s_waitcnt lgkmcnt(0)
	v_mfma_f32_16x16x32_bf16 v[2:5], v[152:155], v[136:139], v[2:5]
	ds_read_b128 v[168:171], v228 offset:0
	v_mfma_f32_16x16x32_bf16 v[6:9], v[156:159], v[136:139], v[6:9]
	ds_read_b128 v[172:175], v228 offset:2048
	v_add_f32_e32 v85, 1.0, v85
	v_mfma_f32_16x16x32_bf16 v[10:13], v[160:163], v[136:139], v[10:13]
	ds_read_b128 v[176:179], v228 offset:4096
	v_add_f32_e32 v86, 1.0, v86
	v_mfma_f32_16x16x32_bf16 v[14:17], v[164:167], v[136:139], v[14:17]
	ds_read_b128 v[180:183], v228 offset:6144
	v_add_f32_e32 v87, 1.0, v87
	v_mfma_f32_16x16x32_bf16 v[18:21], v[152:155], v[140:143], v[18:21]
	ds_read_b128 v[184:187], v234 offset:0
	v_mfma_f32_16x16x32_bf16 v[22:25], v[156:159], v[140:143], v[22:25]
	ds_read_b128 v[188:191], v234 offset:2048
	v_add_f32_e32 v88, 1.0, v88
	v_mfma_f32_16x16x32_bf16 v[26:29], v[160:163], v[140:143], v[26:29]
	ds_read_b128 v[192:195], v234 offset:4096
	v_add_f32_e32 v89, 1.0, v89
	v_mfma_f32_16x16x32_bf16 v[30:33], v[164:167], v[140:143], v[30:33]
	ds_read_b128 v[196:199], v234 offset:6144
	v_rcp_f32_e32 v82, v82
	v_mfma_f32_16x16x32_bf16 v[34:37], v[152:155], v[144:147], v[34:37]
	v_mfma_f32_16x16x32_bf16 v[38:41], v[156:159], v[144:147], v[38:41]
	v_rcp_f32_e32 v83, v83
	v_mfma_f32_16x16x32_bf16 v[42:45], v[160:163], v[144:147], v[42:45]
	v_rcp_f32_e32 v84, v84
	v_mfma_f32_16x16x32_bf16 v[46:49], v[164:167], v[144:147], v[46:49]
	v_rcp_f32_e32 v85, v85
	v_mfma_f32_16x16x32_bf16 v[50:53], v[152:155], v[148:151], v[50:53]
	v_mfma_f32_16x16x32_bf16 v[54:57], v[156:159], v[148:151], v[54:57]
	v_rcp_f32_e32 v86, v86
	v_mfma_f32_16x16x32_bf16 v[58:61], v[160:163], v[148:151], v[58:61]
	v_rcp_f32_e32 v87, v87
	v_mfma_f32_16x16x32_bf16 v[62:65], v[164:167], v[148:151], v[62:65]
	v_rcp_f32_e32 v88, v88
	s_waitcnt vmcnt(7) lgkmcnt(0)
	s_barrier
	v_mfma_f32_16x16x32_bf16 v[2:5], v[184:187], v[168:171], v[2:5]
	ds_read_b128 v[136:139], v224 offset:0
	v_mfma_f32_16x16x32_bf16 v[6:9], v[188:191], v[168:171], v[6:9]
	ds_read_b128 v[140:143], v224 offset:2048
	v_mfma_f32_16x16x32_bf16 v[10:13], v[192:195], v[168:171], v[10:13]
	ds_read_b128 v[144:147], v224 offset:4096
	v_rcp_f32_e32 v89, v89
	v_mfma_f32_16x16x32_bf16 v[14:17], v[196:199], v[168:171], v[14:17]
	ds_read_b128 v[148:151], v224 offset:6144
	v_mfma_f32_16x16x32_bf16 v[18:21], v[184:187], v[172:175], v[18:21]
	ds_read_b128 v[152:155], v232 offset:0
	v_cvt_pk_bf16_f32 v82, v82, v83
	v_mfma_f32_16x16x32_bf16 v[22:25], v[188:191], v[172:175], v[22:25]
	ds_read_b128 v[156:159], v232 offset:2048
	v_mfma_f32_16x16x32_bf16 v[26:29], v[192:195], v[172:175], v[26:29]
	ds_read_b128 v[160:163], v232 offset:4096
	v_cvt_pk_bf16_f32 v83, v84, v85
	v_mfma_f32_16x16x32_bf16 v[30:33], v[196:199], v[172:175], v[30:33]
	ds_read_b128 v[164:167], v232 offset:6144
	s_add_u32 m0, s8, 0xc000
	v_mfma_f32_16x16x32_bf16 v[34:37], v[184:187], v[176:179], v[34:37]
	global_load_lds_dwordx4 v200, s[4:5]
	s_add_u32 m0, s8, 0xc400
	v_mfma_f32_16x16x32_bf16 v[38:41], v[188:191], v[176:179], v[38:41]
	global_load_lds_dwordx4 v201, s[4:5]
	v_cvt_pk_bf16_f32 v84, v86, v87
	s_add_u32 m0, s8, 0xc800
	v_mfma_f32_16x16x32_bf16 v[42:45], v[192:195], v[176:179], v[42:45]
	global_load_lds_dwordx4 v202, s[4:5]
	s_add_u32 m0, s8, 0xcc00
	v_mfma_f32_16x16x32_bf16 v[46:49], v[196:199], v[176:179], v[46:49]
	global_load_lds_dwordx4 v203, s[4:5]
	v_cvt_pk_bf16_f32 v85, v88, v89
	s_add_u32 m0, s9, 0xc000
	v_mfma_f32_16x16x32_bf16 v[50:53], v[184:187], v[180:183], v[50:53]
	global_load_lds_dwordx4 v204, s[6:7]
	s_add_u32 m0, s9, 0xc400
	v_mfma_f32_16x16x32_bf16 v[54:57], v[188:191], v[180:183], v[54:57]
	global_load_lds_dwordx4 v205, s[6:7]
	global_store_dwordx4 v240, v[82:85], s[10:11] offset:2048 sc1
	v_mfma_f32_16x16x32_bf16 v[58:61], v[192:195], v[180:183], v[58:61]
	s_add_u32 s4, s4, 0x80
	s_addc_u32 s5, s5, 0
	v_mfma_f32_16x16x32_bf16 v[62:65], v[196:199], v[180:183], v[62:65]
	s_add_u32 s6, s6, 0x80
	s_addc_u32 s7, s7, 0
	v_mul_f32_e32 v90, s12, v90
	s_waitcnt lgkmcnt(0)
	v_mfma_f32_16x16x32_bf16 v[2:5], v[152:155], v[136:139], v[2:5]
	ds_read_b128 v[168:171], v229 offset:0
	v_mfma_f32_16x16x32_bf16 v[6:9], v[156:159], v[136:139], v[6:9]
	ds_read_b128 v[172:175], v229 offset:2048
	v_mul_f32_e32 v91, s12, v91
	v_mfma_f32_16x16x32_bf16 v[10:13], v[160:163], v[136:139], v[10:13]
	ds_read_b128 v[176:179], v229 offset:4096
	v_mul_f32_e32 v92, s12, v92
	v_mfma_f32_16x16x32_bf16 v[14:17], v[164:167], v[136:139], v[14:17]
	ds_read_b128 v[180:183], v229 offset:6144
	v_mul_f32_e32 v93, s12, v93
	v_mfma_f32_16x16x32_bf16 v[18:21], v[152:155], v[140:143], v[18:21]
	ds_read_b128 v[184:187], v235 offset:0
	v_mfma_f32_16x16x32_bf16 v[22:25], v[156:159], v[140:143], v[22:25]
	ds_read_b128 v[188:191], v235 offset:2048
	v_mul_f32_e32 v94, s12, v94
	v_mfma_f32_16x16x32_bf16 v[26:29], v[160:163], v[140:143], v[26:29]
	ds_read_b128 v[192:195], v235 offset:4096
	v_mul_f32_e32 v95, s12, v95
	v_mfma_f32_16x16x32_bf16 v[30:33], v[164:167], v[140:143], v[30:33]
	ds_read_b128 v[196:199], v235 offset:6144
	v_mul_f32_e32 v96, s12, v96
	v_mfma_f32_16x16x32_bf16 v[34:37], v[152:155], v[144:147], v[34:37]
	v_mfma_f32_16x16x32_bf16 v[38:41], v[156:159], v[144:147], v[38:41]
	v_mul_f32_e32 v97, s12, v97
	v_mfma_f32_16x16x32_bf16 v[42:45], v[160:163], v[144:147], v[42:45]
	v_exp_f32_e32 v90, v90
	v_mfma_f32_16x16x32_bf16 v[46:49], v[164:167], v[144:147], v[46:49]
	v_exp_f32_e32 v91, v91
	v_mfma_f32_16x16x32_bf16 v[50:53], v[152:155], v[148:151], v[50:53]
	v_mfma_f32_16x16x32_bf16 v[54:57], v[156:159], v[148:151], v[54:57]
	v_exp_f32_e32 v92, v92
	v_mfma_f32_16x16x32_bf16 v[58:61], v[160:163], v[148:151], v[58:61]
	v_exp_f32_e32 v93, v93
	v_mfma_f32_16x16x32_bf16 v[62:65], v[164:167], v[148:151], v[62:65]
	v_exp_f32_e32 v94, v94
	s_waitcnt vmcnt(7) lgkmcnt(0)
	s_barrier
	v_mfma_f32_16x16x32_bf16 v[2:5], v[184:187], v[168:171], v[2:5]
	ds_read_b128 v[136:139], v218 offset:0
	v_mfma_f32_16x16x32_bf16 v[6:9], v[188:191], v[168:171], v[6:9]
	ds_read_b128 v[140:143], v218 offset:2048
	v_mfma_f32_16x16x32_bf16 v[10:13], v[192:195], v[168:171], v[10:13]
	ds_read_b128 v[144:147], v218 offset:4096
	v_exp_f32_e32 v95, v95
	v_mfma_f32_16x16x32_bf16 v[14:17], v[196:199], v[168:171], v[14:17]
	ds_read_b128 v[148:151], v218 offset:6144
	v_mfma_f32_16x16x32_bf16 v[18:21], v[184:187], v[172:175], v[18:21]
	ds_read_b128 v[152:155], v230 offset:0
	v_exp_f32_e32 v96, v96
	v_mfma_f32_16x16x32_bf16 v[22:25], v[188:191], v[172:175], v[22:25]
	ds_read_b128 v[156:159], v230 offset:2048
	v_mfma_f32_16x16x32_bf16 v[26:29], v[192:195], v[172:175], v[26:29]
	ds_read_b128 v[160:163], v230 offset:4096
	v_exp_f32_e32 v97, v97
	v_mfma_f32_16x16x32_bf16 v[30:33], v[196:199], v[172:175], v[30:33]
	ds_read_b128 v[164:167], v230 offset:6144
	s_add_u32 m0, s8, 0x18000
	v_mfma_f32_16x16x32_bf16 v[34:37], v[184:187], v[176:179], v[34:37]
	global_load_lds_dwordx4 v200, s[4:5]
	s_add_u32 m0, s8, 0x18400
	v_mfma_f32_16x16x32_bf16 v[38:41], v[188:191], v[176:179], v[38:41]
	global_load_lds_dwordx4 v201, s[4:5]
	v_add_f32_e32 v90, 1.0, v90
	s_add_u32 m0, s8, 0x18800
	v_mfma_f32_16x16x32_bf16 v[42:45], v[192:195], v[176:179], v[42:45]
	global_load_lds_dwordx4 v202, s[4:5]
	s_add_u32 m0, s8, 0x18c00
	v_mfma_f32_16x16x32_bf16 v[46:49], v[196:199], v[176:179], v[46:49]
	global_load_lds_dwordx4 v203, s[4:5]
	v_add_f32_e32 v91, 1.0, v91
	s_add_u32 m0, s9, 0x18000
	v_mfma_f32_16x16x32_bf16 v[50:53], v[184:187], v[180:183], v[50:53]
	global_load_lds_dwordx4 v204, s[6:7]
	s_add_u32 m0, s9, 0x18400
	v_mfma_f32_16x16x32_bf16 v[54:57], v[188:191], v[180:183], v[54:57]
	global_load_lds_dwordx4 v205, s[6:7]
	v_add_f32_e32 v92, 1.0, v92
	v_mfma_f32_16x16x32_bf16 v[58:61], v[192:195], v[180:183], v[58:61]
	s_add_u32 s4, s4, 0x80
	s_addc_u32 s5, s5, 0
	v_mfma_f32_16x16x32_bf16 v[62:65], v[196:199], v[180:183], v[62:65]
	s_add_u32 s6, s6, 0x80
	s_addc_u32 s7, s7, 0
	v_add_f32_e32 v93, 1.0, v93
	s_waitcnt lgkmcnt(0)
	v_mfma_f32_16x16x32_bf16 v[2:5], v[152:155], v[136:139], v[2:5]
	ds_read_b128 v[168:171], v225 offset:0
	v_mfma_f32_16x16x32_bf16 v[6:9], v[156:159], v[136:139], v[6:9]
	ds_read_b128 v[172:175], v225 offset:2048
	v_add_f32_e32 v94, 1.0, v94
	v_mfma_f32_16x16x32_bf16 v[10:13], v[160:163], v[136:139], v[10:13]
	ds_read_b128 v[176:179], v225 offset:4096
	v_add_f32_e32 v95, 1.0, v95
	v_mfma_f32_16x16x32_bf16 v[14:17], v[164:167], v[136:139], v[14:17]
	ds_read_b128 v[180:183], v225 offset:6144
	v_add_f32_e32 v96, 1.0, v96
	v_mfma_f32_16x16x32_bf16 v[18:21], v[152:155], v[140:143], v[18:21]
	ds_read_b128 v[184:187], v233 offset:0
	v_mfma_f32_16x16x32_bf16 v[22:25], v[156:159], v[140:143], v[22:25]
	ds_read_b128 v[188:191], v233 offset:2048
	v_add_f32_e32 v97, 1.0, v97
	v_mfma_f32_16x16x32_bf16 v[26:29], v[160:163], v[140:143], v[26:29]
	ds_read_b128 v[192:195], v233 offset:4096
	v_rcp_f32_e32 v90, v90
	v_mfma_f32_16x16x32_bf16 v[30:33], v[164:167], v[140:143], v[30:33]
	ds_read_b128 v[196:199], v233 offset:6144
	v_rcp_f32_e32 v91, v91
	v_mfma_f32_16x16x32_bf16 v[34:37], v[152:155], v[144:147], v[34:37]
	v_mfma_f32_16x16x32_bf16 v[38:41], v[156:159], v[144:147], v[38:41]
	v_rcp_f32_e32 v92, v92
	v_mfma_f32_16x16x32_bf16 v[42:45], v[160:163], v[144:147], v[42:45]
	v_rcp_f32_e32 v93, v93
	v_mfma_f32_16x16x32_bf16 v[46:49], v[164:167], v[144:147], v[46:49]
	v_rcp_f32_e32 v94, v94
	v_mfma_f32_16x16x32_bf16 v[50:53], v[152:155], v[148:151], v[50:53]
	v_mfma_f32_16x16x32_bf16 v[54:57], v[156:159], v[148:151], v[54:57]
	v_rcp_f32_e32 v95, v95
	v_mfma_f32_16x16x32_bf16 v[58:61], v[160:163], v[148:151], v[58:61]
	v_rcp_f32_e32 v96, v96
	v_mfma_f32_16x16x32_bf16 v[62:65], v[164:167], v[148:151], v[62:65]
	v_rcp_f32_e32 v97, v97
	s_waitcnt vmcnt(7) lgkmcnt(0)
	s_barrier
	v_mfma_f32_16x16x32_bf16 v[2:5], v[184:187], v[168:171], v[2:5]
	ds_read_b128 v[136:139], v219 offset:0
	v_mfma_f32_16x16x32_bf16 v[6:9], v[188:191], v[168:171], v[6:9]
	ds_read_b128 v[140:143], v219 offset:2048
	v_mfma_f32_16x16x32_bf16 v[10:13], v[192:195], v[168:171], v[10:13]
	ds_read_b128 v[144:147], v219 offset:4096
	v_cvt_pk_bf16_f32 v90, v90, v91
	v_mfma_f32_16x16x32_bf16 v[14:17], v[196:199], v[168:171], v[14:17]
	ds_read_b128 v[148:151], v219 offset:6144
	v_mfma_f32_16x16x32_bf16 v[18:21], v[184:187], v[172:175], v[18:21]
	ds_read_b128 v[152:155], v231 offset:0
	v_cvt_pk_bf16_f32 v91, v92, v93
	v_mfma_f32_16x16x32_bf16 v[22:25], v[188:191], v[172:175], v[22:25]
	ds_read_b128 v[156:159], v231 offset:2048
	v_mfma_f32_16x16x32_bf16 v[26:29], v[192:195], v[172:175], v[26:29]
	ds_read_b128 v[160:163], v231 offset:4096
	v_cvt_pk_bf16_f32 v92, v94, v95
	v_mfma_f32_16x16x32_bf16 v[30:33], v[196:199], v[172:175], v[30:33]
	ds_read_b128 v[164:167], v231 offset:6144
	s_mov_b32 m0, s8
	v_mfma_f32_16x16x32_bf16 v[34:37], v[184:187], v[176:179], v[34:37]
	global_load_lds_dwordx4 v200, s[4:5]
	s_add_u32 m0, s8, 0x400
	v_mfma_f32_16x16x32_bf16 v[38:41], v[188:191], v[176:179], v[38:41]
	global_load_lds_dwordx4 v201, s[4:5]
	v_cvt_pk_bf16_f32 v93, v96, v97
	s_add_u32 m0, s8, 0x800
	v_mfma_f32_16x16x32_bf16 v[42:45], v[192:195], v[176:179], v[42:45]
	global_load_lds_dwordx4 v202, s[4:5]
	s_add_u32 m0, s8, 0xc00
	v_mfma_f32_16x16x32_bf16 v[46:49], v[196:199], v[176:179], v[46:49]
	global_load_lds_dwordx4 v203, s[4:5]
	global_store_dwordx4 v240, v[90:93], s[10:11] offset:3072 sc1
	s_mov_b32 m0, s9
	v_mfma_f32_16x16x32_bf16 v[50:53], v[184:187], v[180:183], v[50:53]
	global_load_lds_dwordx4 v204, s[6:7]
	s_add_u32 m0, s9, 0x400
	v_mfma_f32_16x16x32_bf16 v[54:57], v[188:191], v[180:183], v[54:57]
	global_load_lds_dwordx4 v205, s[6:7]
	v_mul_f32_e32 v98, s12, v98
	v_mfma_f32_16x16x32_bf16 v[58:61], v[192:195], v[180:183], v[58:61]
	s_add_u32 s4, s4, 0x80
	s_addc_u32 s5, s5, 0
	v_mfma_f32_16x16x32_bf16 v[62:65], v[196:199], v[180:183], v[62:65]
	s_add_u32 s6, s6, 0x80
	s_addc_u32 s7, s7, 0
	v_mul_f32_e32 v99, s12, v99
	s_waitcnt lgkmcnt(0)
	v_mfma_f32_16x16x32_bf16 v[2:5], v[152:155], v[136:139], v[2:5]
	ds_read_b128 v[168:171], v228 offset:0
	v_mfma_f32_16x16x32_bf16 v[6:9], v[156:159], v[136:139], v[6:9]
	ds_read_b128 v[172:175], v228 offset:2048
	v_mul_f32_e32 v100, s12, v100
	v_mfma_f32_16x16x32_bf16 v[10:13], v[160:163], v[136:139], v[10:13]
	ds_read_b128 v[176:179], v228 offset:4096
	v_mul_f32_e32 v101, s12, v101
	v_mfma_f32_16x16x32_bf16 v[14:17], v[164:167], v[136:139], v[14:17]
	ds_read_b128 v[180:183], v228 offset:6144
	v_mul_f32_e32 v102, s12, v102
	v_mfma_f32_16x16x32_bf16 v[18:21], v[152:155], v[140:143], v[18:21]
	ds_read_b128 v[184:187], v234 offset:0
	v_mfma_f32_16x16x32_bf16 v[22:25], v[156:159], v[140:143], v[22:25]
	ds_read_b128 v[188:191], v234 offset:2048
	v_mul_f32_e32 v103, s12, v103
	v_mfma_f32_16x16x32_bf16 v[26:29], v[160:163], v[140:143], v[26:29]
	ds_read_b128 v[192:195], v234 offset:4096
	v_mul_f32_e32 v104, s12, v104
	v_mfma_f32_16x16x32_bf16 v[30:33], v[164:167], v[140:143], v[30:33]
	ds_read_b128 v[196:199], v234 offset:6144
	v_mul_f32_e32 v105, s12, v105
	v_mfma_f32_16x16x32_bf16 v[34:37], v[152:155], v[144:147], v[34:37]
	v_mfma_f32_16x16x32_bf16 v[38:41], v[156:159], v[144:147], v[38:41]
	v_exp_f32_e32 v98, v98
	v_mfma_f32_16x16x32_bf16 v[42:45], v[160:163], v[144:147], v[42:45]
	v_exp_f32_e32 v99, v99
	v_mfma_f32_16x16x32_bf16 v[46:49], v[164:167], v[144:147], v[46:49]
	v_exp_f32_e32 v100, v100
	v_mfma_f32_16x16x32_bf16 v[50:53], v[152:155], v[148:151], v[50:53]
	v_mfma_f32_16x16x32_bf16 v[54:57], v[156:159], v[148:151], v[54:57]
	v_exp_f32_e32 v101, v101
	v_mfma_f32_16x16x32_bf16 v[58:61], v[160:163], v[148:151], v[58:61]
	v_exp_f32_e32 v102, v102
	v_mfma_f32_16x16x32_bf16 v[62:65], v[164:167], v[148:151], v[62:65]
	v_exp_f32_e32 v103, v103
	s_waitcnt vmcnt(7) lgkmcnt(0)
	s_barrier
	v_mfma_f32_16x16x32_bf16 v[2:5], v[184:187], v[168:171], v[2:5]
	ds_read_b128 v[136:139], v224 offset:0
	v_mfma_f32_16x16x32_bf16 v[6:9], v[188:191], v[168:171], v[6:9]
	ds_read_b128 v[140:143], v224 offset:2048
	v_mfma_f32_16x16x32_bf16 v[10:13], v[192:195], v[168:171], v[10:13]
	ds_read_b128 v[144:147], v224 offset:4096
	v_exp_f32_e32 v104, v104
	v_mfma_f32_16x16x32_bf16 v[14:17], v[196:199], v[168:171], v[14:17]
	ds_read_b128 v[148:151], v224 offset:6144
	v_mfma_f32_16x16x32_bf16 v[18:21], v[184:187], v[172:175], v[18:21]
	ds_read_b128 v[152:155], v232 offset:0
	v_exp_f32_e32 v105, v105
	v_mfma_f32_16x16x32_bf16 v[22:25], v[188:191], v[172:175], v[22:25]
	ds_read_b128 v[156:159], v232 offset:2048
	v_mfma_f32_16x16x32_bf16 v[26:29], v[192:195], v[172:175], v[26:29]
	ds_read_b128 v[160:163], v232 offset:4096
	v_add_f32_e32 v98, 1.0, v98
	v_mfma_f32_16x16x32_bf16 v[30:33], v[196:199], v[172:175], v[30:33]
	ds_read_b128 v[164:167], v232 offset:6144
	s_add_u32 m0, s8, 0xc000
	v_mfma_f32_16x16x32_bf16 v[34:37], v[184:187], v[176:179], v[34:37]
	global_load_lds_dwordx4 v200, s[4:5]
	s_add_u32 m0, s8, 0xc400
	v_mfma_f32_16x16x32_bf16 v[38:41], v[188:191], v[176:179], v[38:41]
	global_load_lds_dwordx4 v201, s[4:5]
	v_add_f32_e32 v99, 1.0, v99
	s_add_u32 m0, s8, 0xc800
	v_mfma_f32_16x16x32_bf16 v[42:45], v[192:195], v[176:179], v[42:45]
	global_load_lds_dwordx4 v202, s[4:5]
	s_add_u32 m0, s8, 0xcc00
	v_mfma_f32_16x16x32_bf16 v[46:49], v[196:199], v[176:179], v[46:49]
	global_load_lds_dwordx4 v203, s[4:5]
	v_add_f32_e32 v100, 1.0, v100
	s_add_u32 m0, s9, 0xc000
	v_mfma_f32_16x16x32_bf16 v[50:53], v[184:187], v[180:183], v[50:53]
	global_load_lds_dwordx4 v204, s[6:7]
	s_add_u32 m0, s9, 0xc400
	v_mfma_f32_16x16x32_bf16 v[54:57], v[188:191], v[180:183], v[54:57]
	global_load_lds_dwordx4 v205, s[6:7]
	v_add_f32_e32 v101, 1.0, v101
	v_mfma_f32_16x16x32_bf16 v[58:61], v[192:195], v[180:183], v[58:61]
	s_add_u32 s4, s4, 0x80
	s_addc_u32 s5, s5, 0
	v_mfma_f32_16x16x32_bf16 v[62:65], v[196:199], v[180:183], v[62:65]
	s_add_u32 s6, s6, 0x80
	s_addc_u32 s7, s7, 0
	v_add_f32_e32 v102, 1.0, v102
	s_waitcnt lgkmcnt(0)
	v_mfma_f32_16x16x32_bf16 v[2:5], v[152:155], v[136:139], v[2:5]
	ds_read_b128 v[168:171], v229 offset:0
	v_mfma_f32_16x16x32_bf16 v[6:9], v[156:159], v[136:139], v[6:9]
	ds_read_b128 v[172:175], v229 offset:2048
	v_add_f32_e32 v103, 1.0, v103
	v_mfma_f32_16x16x32_bf16 v[10:13], v[160:163], v[136:139], v[10:13]
	ds_read_b128 v[176:179], v229 offset:4096
	v_add_f32_e32 v104, 1.0, v104
	v_mfma_f32_16x16x32_bf16 v[14:17], v[164:167], v[136:139], v[14:17]
	ds_read_b128 v[180:183], v229 offset:6144
	v_add_f32_e32 v105, 1.0, v105
	v_mfma_f32_16x16x32_bf16 v[18:21], v[152:155], v[140:143], v[18:21]
	ds_read_b128 v[184:187], v235 offset:0
	v_mfma_f32_16x16x32_bf16 v[22:25], v[156:159], v[140:143], v[22:25]
	ds_read_b128 v[188:191], v235 offset:2048
	v_rcp_f32_e32 v98, v98
	v_mfma_f32_16x16x32_bf16 v[26:29], v[160:163], v[140:143], v[26:29]
	ds_read_b128 v[192:195], v235 offset:4096
	v_rcp_f32_e32 v99, v99
	v_mfma_f32_16x16x32_bf16 v[30:33], v[164:167], v[140:143], v[30:33]
	ds_read_b128 v[196:199], v235 offset:6144
	v_rcp_f32_e32 v100, v100
	v_mfma_f32_16x16x32_bf16 v[34:37], v[152:155], v[144:147], v[34:37]
	v_mfma_f32_16x16x32_bf16 v[38:41], v[156:159], v[144:147], v[38:41]
	v_rcp_f32_e32 v101, v101
	v_mfma_f32_16x16x32_bf16 v[42:45], v[160:163], v[144:147], v[42:45]
	v_rcp_f32_e32 v102, v102
	v_mfma_f32_16x16x32_bf16 v[46:49], v[164:167], v[144:147], v[46:49]
	v_rcp_f32_e32 v103, v103
	v_mfma_f32_16x16x32_bf16 v[50:53], v[152:155], v[148:151], v[50:53]
	v_mfma_f32_16x16x32_bf16 v[54:57], v[156:159], v[148:151], v[54:57]
	v_rcp_f32_e32 v104, v104
	v_mfma_f32_16x16x32_bf16 v[58:61], v[160:163], v[148:151], v[58:61]
	v_rcp_f32_e32 v105, v105
	v_mfma_f32_16x16x32_bf16 v[62:65], v[164:167], v[148:151], v[62:65]
	v_cvt_pk_bf16_f32 v98, v98, v99
	s_waitcnt vmcnt(6) lgkmcnt(0)
	s_barrier
	v_mfma_f32_16x16x32_bf16 v[2:5], v[184:187], v[168:171], v[2:5]
	ds_read_b128 v[136:139], v218 offset:0
	v_mfma_f32_16x16x32_bf16 v[6:9], v[188:191], v[168:171], v[6:9]
	ds_read_b128 v[140:143], v218 offset:2048
	v_mfma_f32_16x16x32_bf16 v[10:13], v[192:195], v[168:171], v[10:13]
	ds_read_b128 v[144:147], v218 offset:4096
	v_cvt_pk_bf16_f32 v99, v100, v101
	v_mfma_f32_16x16x32_bf16 v[14:17], v[196:199], v[168:171], v[14:17]
	ds_read_b128 v[148:151], v218 offset:6144
	v_mfma_f32_16x16x32_bf16 v[18:21], v[184:187], v[172:175], v[18:21]
	ds_read_b128 v[152:155], v230 offset:0
	v_cvt_pk_bf16_f32 v100, v102, v103
	v_mfma_f32_16x16x32_bf16 v[22:25], v[188:191], v[172:175], v[22:25]
	ds_read_b128 v[156:159], v230 offset:2048
	v_mfma_f32_16x16x32_bf16 v[26:29], v[192:195], v[172:175], v[26:29]
	ds_read_b128 v[160:163], v230 offset:4096
	v_cvt_pk_bf16_f32 v101, v104, v105
	v_mfma_f32_16x16x32_bf16 v[30:33], v[196:199], v[172:175], v[30:33]
	ds_read_b128 v[164:167], v230 offset:6144
	s_add_u32 m0, s8, 0x18000
	v_mfma_f32_16x16x32_bf16 v[34:37], v[184:187], v[176:179], v[34:37]
	global_load_lds_dwordx4 v200, s[4:5]
	s_add_u32 m0, s8, 0x18400
	v_mfma_f32_16x16x32_bf16 v[38:41], v[188:191], v[176:179], v[38:41]
	global_load_lds_dwordx4 v201, s[4:5]
	global_store_dwordx4 v241, v[98:101], s[10:11] offset:0 sc1
	s_add_u32 m0, s8, 0x18800
	v_mfma_f32_16x16x32_bf16 v[42:45], v[192:195], v[176:179], v[42:45]
	global_load_lds_dwordx4 v202, s[4:5]
	s_add_u32 m0, s8, 0x18c00
	v_mfma_f32_16x16x32_bf16 v[46:49], v[196:199], v[176:179], v[46:49]
	global_load_lds_dwordx4 v203, s[4:5]
	v_mul_f32_e32 v106, s12, v106
	s_add_u32 m0, s9, 0x18000
	v_mfma_f32_16x16x32_bf16 v[50:53], v[184:187], v[180:183], v[50:53]
	global_load_lds_dwordx4 v204, s[6:7]
	s_add_u32 m0, s9, 0x18400
	v_mfma_f32_16x16x32_bf16 v[54:57], v[188:191], v[180:183], v[54:57]
	global_load_lds_dwordx4 v205, s[6:7]
	v_mul_f32_e32 v107, s12, v107
	v_mfma_f32_16x16x32_bf16 v[58:61], v[192:195], v[180:183], v[58:61]
	s_add_u32 s4, s4, 0x80
	s_addc_u32 s5, s5, 0
	v_mfma_f32_16x16x32_bf16 v[62:65], v[196:199], v[180:183], v[62:65]
	s_add_u32 s6, s6, 0x80
	s_addc_u32 s7, s7, 0
	v_mul_f32_e32 v108, s12, v108
	s_waitcnt lgkmcnt(0)
	v_mfma_f32_16x16x32_bf16 v[2:5], v[152:155], v[136:139], v[2:5]
	ds_read_b128 v[168:171], v225 offset:0
	v_mfma_f32_16x16x32_bf16 v[6:9], v[156:159], v[136:139], v[6:9]
	ds_read_b128 v[172:175], v225 offset:2048
	v_mul_f32_e32 v109, s12, v109
	v_mfma_f32_16x16x32_bf16 v[10:13], v[160:163], v[136:139], v[10:13]
	ds_read_b128 v[176:179], v225 offset:4096
	v_mul_f32_e32 v110, s12, v110
	v_mfma_f32_16x16x32_bf16 v[14:17], v[164:167], v[136:139], v[14:17]
	ds_read_b128 v[180:183], v225 offset:6144
	v_mul_f32_e32 v111, s12, v111
	v_mfma_f32_16x16x32_bf16 v[18:21], v[152:155], v[140:143], v[18:21]
	ds_read_b128 v[184:187], v233 offset:0
	v_mfma_f32_16x16x32_bf16 v[22:25], v[156:159], v[140:143], v[22:25]
	ds_read_b128 v[188:191], v233 offset:2048
	v_mul_f32_e32 v112, s12, v112
	v_mfma_f32_16x16x32_bf16 v[26:29], v[160:163], v[140:143], v[26:29]
	ds_read_b128 v[192:195], v233 offset:4096
	v_mul_f32_e32 v113, s12, v113
	v_mfma_f32_16x16x32_bf16 v[30:33], v[164:167], v[140:143], v[30:33]
	ds_read_b128 v[196:199], v233 offset:6144
	v_exp_f32_e32 v106, v106
	v_mfma_f32_16x16x32_bf16 v[34:37], v[152:155], v[144:147], v[34:37]
	v_mfma_f32_16x16x32_bf16 v[38:41], v[156:159], v[144:147], v[38:41]
	v_exp_f32_e32 v107, v107
	v_mfma_f32_16x16x32_bf16 v[42:45], v[160:163], v[144:147], v[42:45]
	v_exp_f32_e32 v108, v108
	v_mfma_f32_16x16x32_bf16 v[46:49], v[164:167], v[144:147], v[46:49]
	v_exp_f32_e32 v109, v109
	v_mfma_f32_16x16x32_bf16 v[50:53], v[152:155], v[148:151], v[50:53]
	v_mfma_f32_16x16x32_bf16 v[54:57], v[156:159], v[148:151], v[54:57]
	v_exp_f32_e32 v110, v110
	v_mfma_f32_16x16x32_bf16 v[58:61], v[160:163], v[148:151], v[58:61]
	v_exp_f32_e32 v111, v111
	v_mfma_f32_16x16x32_bf16 v[62:65], v[164:167], v[148:151], v[62:65]
	v_exp_f32_e32 v112, v112
	s_waitcnt vmcnt(7) lgkmcnt(0)
	s_barrier
	v_mfma_f32_16x16x32_bf16 v[2:5], v[184:187], v[168:171], v[2:5]
	ds_read_b128 v[136:139], v219 offset:0
	v_mfma_f32_16x16x32_bf16 v[6:9], v[188:191], v[168:171], v[6:9]
	ds_read_b128 v[140:143], v219 offset:2048
	v_mfma_f32_16x16x32_bf16 v[10:13], v[192:195], v[168:171], v[10:13]
	ds_read_b128 v[144:147], v219 offset:4096
	v_exp_f32_e32 v113, v113
	v_mfma_f32_16x16x32_bf16 v[14:17], v[196:199], v[168:171], v[14:17]
	ds_read_b128 v[148:151], v219 offset:6144
	v_mfma_f32_16x16x32_bf16 v[18:21], v[184:187], v[172:175], v[18:21]
	ds_read_b128 v[152:155], v231 offset:0
	v_add_f32_e32 v106, 1.0, v106
	v_mfma_f32_16x16x32_bf16 v[22:25], v[188:191], v[172:175], v[22:25]
	ds_read_b128 v[156:159], v231 offset:2048
	v_mfma_f32_16x16x32_bf16 v[26:29], v[192:195], v[172:175], v[26:29]
	ds_read_b128 v[160:163], v231 offset:4096
	v_add_f32_e32 v107, 1.0, v107
	v_mfma_f32_16x16x32_bf16 v[30:33], v[196:199], v[172:175], v[30:33]
	ds_read_b128 v[164:167], v231 offset:6144
	s_mov_b32 m0, s8
	v_mfma_f32_16x16x32_bf16 v[34:37], v[184:187], v[176:179], v[34:37]
	global_load_lds_dwordx4 v200, s[4:5]
	s_add_u32 m0, s8, 0x400
	v_mfma_f32_16x16x32_bf16 v[38:41], v[188:191], v[176:179], v[38:41]
	global_load_lds_dwordx4 v201, s[4:5]
	v_add_f32_e32 v108, 1.0, v108
	s_add_u32 m0, s8, 0x800
	v_mfma_f32_16x16x32_bf16 v[42:45], v[192:195], v[176:179], v[42:45]
	global_load_lds_dwordx4 v202, s[4:5]
	s_add_u32 m0, s8, 0xc00
	v_mfma_f32_16x16x32_bf16 v[46:49], v[196:199], v[176:179], v[46:49]
	global_load_lds_dwordx4 v203, s[4:5]
	v_add_f32_e32 v109, 1.0, v109
	s_mov_b32 m0, s9
	v_mfma_f32_16x16x32_bf16 v[50:53], v[184:187], v[180:183], v[50:53]
	global_load_lds_dwordx4 v204, s[6:7]
	s_add_u32 m0, s9, 0x400
	v_mfma_f32_16x16x32_bf16 v[54:57], v[188:191], v[180:183], v[54:57]
	global_load_lds_dwordx4 v205, s[6:7]
	v_add_f32_e32 v110, 1.0, v110
	v_mfma_f32_16x16x32_bf16 v[58:61], v[192:195], v[180:183], v[58:61]
	s_add_u32 s4, s4, 0x80
	s_addc_u32 s5, s5, 0
	v_mfma_f32_16x16x32_bf16 v[62:65], v[196:199], v[180:183], v[62:65]
	s_add_u32 s6, s6, 0x80
	s_addc_u32 s7, s7, 0
	v_add_f32_e32 v111, 1.0, v111
	s_waitcnt lgkmcnt(0)
	v_mfma_f32_16x16x32_bf16 v[2:5], v[152:155], v[136:139], v[2:5]
	ds_read_b128 v[168:171], v228 offset:0
	v_mfma_f32_16x16x32_bf16 v[6:9], v[156:159], v[136:139], v[6:9]
	ds_read_b128 v[172:175], v228 offset:2048
	v_add_f32_e32 v112, 1.0, v112
	v_mfma_f32_16x16x32_bf16 v[10:13], v[160:163], v[136:139], v[10:13]
	ds_read_b128 v[176:179], v228 offset:4096
	v_add_f32_e32 v113, 1.0, v113
	v_mfma_f32_16x16x32_bf16 v[14:17], v[164:167], v[136:139], v[14:17]
	ds_read_b128 v[180:183], v228 offset:6144
	v_rcp_f32_e32 v106, v106
	v_mfma_f32_16x16x32_bf16 v[18:21], v[152:155], v[140:143], v[18:21]
	ds_read_b128 v[184:187], v234 offset:0
	v_mfma_f32_16x16x32_bf16 v[22:25], v[156:159], v[140:143], v[22:25]
	ds_read_b128 v[188:191], v234 offset:2048
	v_rcp_f32_e32 v107, v107
	v_mfma_f32_16x16x32_bf16 v[26:29], v[160:163], v[140:143], v[26:29]
	ds_read_b128 v[192:195], v234 offset:4096
	v_rcp_f32_e32 v108, v108
	v_mfma_f32_16x16x32_bf16 v[30:33], v[164:167], v[140:143], v[30:33]
	ds_read_b128 v[196:199], v234 offset:6144
	v_rcp_f32_e32 v109, v109
	v_mfma_f32_16x16x32_bf16 v[34:37], v[152:155], v[144:147], v[34:37]
	v_mfma_f32_16x16x32_bf16 v[38:41], v[156:159], v[144:147], v[38:41]
	v_rcp_f32_e32 v110, v110
	v_mfma_f32_16x16x32_bf16 v[42:45], v[160:163], v[144:147], v[42:45]
	v_rcp_f32_e32 v111, v111
	v_mfma_f32_16x16x32_bf16 v[46:49], v[164:167], v[144:147], v[46:49]
	v_rcp_f32_e32 v112, v112
	v_mfma_f32_16x16x32_bf16 v[50:53], v[152:155], v[148:151], v[50:53]
	v_mfma_f32_16x16x32_bf16 v[54:57], v[156:159], v[148:151], v[54:57]
	v_rcp_f32_e32 v113, v113
	v_mfma_f32_16x16x32_bf16 v[58:61], v[160:163], v[148:151], v[58:61]
	v_cvt_pk_bf16_f32 v106, v106, v107
	v_mfma_f32_16x16x32_bf16 v[62:65], v[164:167], v[148:151], v[62:65]
	v_cvt_pk_bf16_f32 v107, v108, v109
	s_waitcnt vmcnt(6) lgkmcnt(0)
	s_barrier
	v_mfma_f32_16x16x32_bf16 v[2:5], v[184:187], v[168:171], v[2:5]
	ds_read_b128 v[136:139], v224 offset:0
	v_mfma_f32_16x16x32_bf16 v[6:9], v[188:191], v[168:171], v[6:9]
	ds_read_b128 v[140:143], v224 offset:2048
	v_mfma_f32_16x16x32_bf16 v[10:13], v[192:195], v[168:171], v[10:13]
	ds_read_b128 v[144:147], v224 offset:4096
	v_cvt_pk_bf16_f32 v108, v110, v111
	v_mfma_f32_16x16x32_bf16 v[14:17], v[196:199], v[168:171], v[14:17]
	ds_read_b128 v[148:151], v224 offset:6144
	v_mfma_f32_16x16x32_bf16 v[18:21], v[184:187], v[172:175], v[18:21]
	ds_read_b128 v[152:155], v232 offset:0
	v_cvt_pk_bf16_f32 v109, v112, v113
	v_mfma_f32_16x16x32_bf16 v[22:25], v[188:191], v[172:175], v[22:25]
	ds_read_b128 v[156:159], v232 offset:2048
	v_mfma_f32_16x16x32_bf16 v[26:29], v[192:195], v[172:175], v[26:29]
	ds_read_b128 v[160:163], v232 offset:4096
	global_store_dwordx4 v241, v[106:109], s[10:11] offset:1024 sc1
	v_mfma_f32_16x16x32_bf16 v[30:33], v[196:199], v[172:175], v[30:33]
	ds_read_b128 v[164:167], v232 offset:6144
	s_add_u32 m0, s8, 0xc000
	v_mfma_f32_16x16x32_bf16 v[34:37], v[184:187], v[176:179], v[34:37]
	global_load_lds_dwordx4 v200, s[4:5]
	s_add_u32 m0, s8, 0xc400
	v_mfma_f32_16x16x32_bf16 v[38:41], v[188:191], v[176:179], v[38:41]
	global_load_lds_dwordx4 v201, s[4:5]
	v_mul_f32_e32 v114, s12, v114
	s_add_u32 m0, s8, 0xc800
	v_mfma_f32_16x16x32_bf16 v[42:45], v[192:195], v[176:179], v[42:45]
	global_load_lds_dwordx4 v202, s[4:5]
	s_add_u32 m0, s8, 0xcc00
	v_mfma_f32_16x16x32_bf16 v[46:49], v[196:199], v[176:179], v[46:49]
	global_load_lds_dwordx4 v203, s[4:5]
	v_mul_f32_e32 v115, s12, v115
	s_add_u32 m0, s9, 0xc000
	v_mfma_f32_16x16x32_bf16 v[50:53], v[184:187], v[180:183], v[50:53]
	global_load_lds_dwordx4 v204, s[6:7]
	s_add_u32 m0, s9, 0xc400
	v_mfma_f32_16x16x32_bf16 v[54:57], v[188:191], v[180:183], v[54:57]
	global_load_lds_dwordx4 v205, s[6:7]
	v_mul_f32_e32 v116, s12, v116
	v_mfma_f32_16x16x32_bf16 v[58:61], v[192:195], v[180:183], v[58:61]
	s_add_u32 s4, s4, 0x80
	s_addc_u32 s5, s5, 0
	v_mfma_f32_16x16x32_bf16 v[62:65], v[196:199], v[180:183], v[62:65]
	s_add_u32 s6, s6, 0x80
	s_addc_u32 s7, s7, 0
	v_mul_f32_e32 v117, s12, v117
	s_waitcnt lgkmcnt(0)
	v_mfma_f32_16x16x32_bf16 v[2:5], v[152:155], v[136:139], v[2:5]
	ds_read_b128 v[168:171], v229 offset:0
	v_mfma_f32_16x16x32_bf16 v[6:9], v[156:159], v[136:139], v[6:9]
	ds_read_b128 v[172:175], v229 offset:2048
	v_mul_f32_e32 v118, s12, v118
	v_mfma_f32_16x16x32_bf16 v[10:13], v[160:163], v[136:139], v[10:13]
	ds_read_b128 v[176:179], v229 offset:4096
	v_mul_f32_e32 v119, s12, v119
	v_mfma_f32_16x16x32_bf16 v[14:17], v[164:167], v[136:139], v[14:17]
	ds_read_b128 v[180:183], v229 offset:6144
	v_mul_f32_e32 v120, s12, v120
	v_mfma_f32_16x16x32_bf16 v[18:21], v[152:155], v[140:143], v[18:21]
	ds_read_b128 v[184:187], v235 offset:0
	v_mfma_f32_16x16x32_bf16 v[22:25], v[156:159], v[140:143], v[22:25]
	ds_read_b128 v[188:191], v235 offset:2048
	v_mul_f32_e32 v121, s12, v121
	v_mfma_f32_16x16x32_bf16 v[26:29], v[160:163], v[140:143], v[26:29]
	ds_read_b128 v[192:195], v235 offset:4096
	v_exp_f32_e32 v114, v114
	v_mfma_f32_16x16x32_bf16 v[30:33], v[164:167], v[140:143], v[30:33]
	ds_read_b128 v[196:199], v235 offset:6144
	v_exp_f32_e32 v115, v115
	v_mfma_f32_16x16x32_bf16 v[34:37], v[152:155], v[144:147], v[34:37]
	v_mfma_f32_16x16x32_bf16 v[38:41], v[156:159], v[144:147], v[38:41]
	v_exp_f32_e32 v116, v116
	v_mfma_f32_16x16x32_bf16 v[42:45], v[160:163], v[144:147], v[42:45]
	v_exp_f32_e32 v117, v117
	v_mfma_f32_16x16x32_bf16 v[46:49], v[164:167], v[144:147], v[46:49]
	v_exp_f32_e32 v118, v118
	v_mfma_f32_16x16x32_bf16 v[50:53], v[152:155], v[148:151], v[50:53]
	v_mfma_f32_16x16x32_bf16 v[54:57], v[156:159], v[148:151], v[54:57]
	v_exp_f32_e32 v119, v119
	v_mfma_f32_16x16x32_bf16 v[58:61], v[160:163], v[148:151], v[58:61]
	v_exp_f32_e32 v120, v120
	v_mfma_f32_16x16x32_bf16 v[62:65], v[164:167], v[148:151], v[62:65]
	v_exp_f32_e32 v121, v121
	s_waitcnt vmcnt(7) lgkmcnt(0)
	s_barrier
	v_mfma_f32_16x16x32_bf16 v[2:5], v[184:187], v[168:171], v[2:5]
	ds_read_b128 v[136:139], v218 offset:0
	v_mfma_f32_16x16x32_bf16 v[6:9], v[188:191], v[168:171], v[6:9]
	ds_read_b128 v[140:143], v218 offset:2048
	v_mfma_f32_16x16x32_bf16 v[10:13], v[192:195], v[168:171], v[10:13]
	ds_read_b128 v[144:147], v218 offset:4096
	v_add_f32_e32 v114, 1.0, v114
	v_mfma_f32_16x16x32_bf16 v[14:17], v[196:199], v[168:171], v[14:17]
	ds_read_b128 v[148:151], v218 offset:6144
	v_mfma_f32_16x16x32_bf16 v[18:21], v[184:187], v[172:175], v[18:21]
	ds_read_b128 v[152:155], v230 offset:0
	v_add_f32_e32 v115, 1.0, v115
	v_mfma_f32_16x16x32_bf16 v[22:25], v[188:191], v[172:175], v[22:25]
	ds_read_b128 v[156:159], v230 offset:2048
	v_mfma_f32_16x16x32_bf16 v[26:29], v[192:195], v[172:175], v[26:29]
	ds_read_b128 v[160:163], v230 offset:4096
	v_add_f32_e32 v116, 1.0, v116
	v_mfma_f32_16x16x32_bf16 v[30:33], v[196:199], v[172:175], v[30:33]
	ds_read_b128 v[164:167], v230 offset:6144
	s_add_u32 m0, s8, 0x18000
	v_mfma_f32_16x16x32_bf16 v[34:37], v[184:187], v[176:179], v[34:37]
	global_load_lds_dwordx4 v200, s[4:5]
	s_add_u32 m0, s8, 0x18400
	v_mfma_f32_16x16x32_bf16 v[38:41], v[188:191], v[176:179], v[38:41]
	global_load_lds_dwordx4 v201, s[4:5]
	v_add_f32_e32 v117, 1.0, v117
	s_add_u32 m0, s8, 0x18800
	v_mfma_f32_16x16x32_bf16 v[42:45], v[192:195], v[176:179], v[42:45]
	global_load_lds_dwordx4 v202, s[4:5]
	s_add_u32 m0, s8, 0x18c00
	v_mfma_f32_16x16x32_bf16 v[46:49], v[196:199], v[176:179], v[46:49]
	global_load_lds_dwordx4 v203, s[4:5]
	v_add_f32_e32 v118, 1.0, v118
	s_add_u32 m0, s9, 0x18000
	v_mfma_f32_16x16x32_bf16 v[50:53], v[184:187], v[180:183], v[50:53]
	global_load_lds_dwordx4 v204, s[6:7]
	s_add_u32 m0, s9, 0x18400
	v_mfma_f32_16x16x32_bf16 v[54:57], v[188:191], v[180:183], v[54:57]
	global_load_lds_dwordx4 v205, s[6:7]
	v_add_f32_e32 v119, 1.0, v119
	v_mfma_f32_16x16x32_bf16 v[58:61], v[192:195], v[180:183], v[58:61]
	s_sub_u32 s4, s4, 0x780
	s_subb_u32 s5, s5, 0
	v_mfma_f32_16x16x32_bf16 v[62:65], v[196:199], v[180:183], v[62:65]
	s_add_u32 s6, s6, 0x3f880
	s_addc_u32 s7, s7, 0
	v_add_f32_e32 v120, 1.0, v120
	s_waitcnt lgkmcnt(0)
	v_mfma_f32_16x16x32_bf16 v[2:5], v[152:155], v[136:139], v[2:5]
	ds_read_b128 v[168:171], v225 offset:0
	v_mfma_f32_16x16x32_bf16 v[6:9], v[156:159], v[136:139], v[6:9]
	ds_read_b128 v[172:175], v225 offset:2048
	v_add_f32_e32 v121, 1.0, v121
	v_mfma_f32_16x16x32_bf16 v[10:13], v[160:163], v[136:139], v[10:13]
	ds_read_b128 v[176:179], v225 offset:4096
	v_rcp_f32_e32 v114, v114
	v_mfma_f32_16x16x32_bf16 v[14:17], v[164:167], v[136:139], v[14:17]
	ds_read_b128 v[180:183], v225 offset:6144
	v_rcp_f32_e32 v115, v115
	v_mfma_f32_16x16x32_bf16 v[18:21], v[152:155], v[140:143], v[18:21]
	ds_read_b128 v[184:187], v233 offset:0
	v_mfma_f32_16x16x32_bf16 v[22:25], v[156:159], v[140:143], v[22:25]
	ds_read_b128 v[188:191], v233 offset:2048
	v_rcp_f32_e32 v116, v116
	v_mfma_f32_16x16x32_bf16 v[26:29], v[160:163], v[140:143], v[26:29]
	ds_read_b128 v[192:195], v233 offset:4096
	v_rcp_f32_e32 v117, v117
	v_mfma_f32_16x16x32_bf16 v[30:33], v[164:167], v[140:143], v[30:33]
	ds_read_b128 v[196:199], v233 offset:6144
	v_rcp_f32_e32 v118, v118
	v_mfma_f32_16x16x32_bf16 v[34:37], v[152:155], v[144:147], v[34:37]
	v_mfma_f32_16x16x32_bf16 v[38:41], v[156:159], v[144:147], v[38:41]
	v_rcp_f32_e32 v119, v119
	v_mfma_f32_16x16x32_bf16 v[42:45], v[160:163], v[144:147], v[42:45]
	v_rcp_f32_e32 v120, v120
	v_mfma_f32_16x16x32_bf16 v[46:49], v[164:167], v[144:147], v[46:49]
	v_rcp_f32_e32 v121, v121
	v_mfma_f32_16x16x32_bf16 v[50:53], v[152:155], v[148:151], v[50:53]
	v_mfma_f32_16x16x32_bf16 v[54:57], v[156:159], v[148:151], v[54:57]
	v_cvt_pk_bf16_f32 v114, v114, v115
	v_mfma_f32_16x16x32_bf16 v[58:61], v[160:163], v[148:151], v[58:61]
	v_cvt_pk_bf16_f32 v115, v116, v117
	v_mfma_f32_16x16x32_bf16 v[62:65], v[164:167], v[148:151], v[62:65]
	v_cvt_pk_bf16_f32 v116, v118, v119
	s_waitcnt vmcnt(6) lgkmcnt(0)
	s_barrier
	v_mfma_f32_16x16x32_bf16 v[2:5], v[184:187], v[168:171], v[2:5]
	ds_read_b128 v[136:139], v219 offset:0
	v_mfma_f32_16x16x32_bf16 v[6:9], v[188:191], v[168:171], v[6:9]
	ds_read_b128 v[140:143], v219 offset:2048
	v_mfma_f32_16x16x32_bf16 v[10:13], v[192:195], v[168:171], v[10:13]
	ds_read_b128 v[144:147], v219 offset:4096
	v_cvt_pk_bf16_f32 v117, v120, v121
	v_mfma_f32_16x16x32_bf16 v[14:17], v[196:199], v[168:171], v[14:17]
	ds_read_b128 v[148:151], v219 offset:6144
	v_mfma_f32_16x16x32_bf16 v[18:21], v[184:187], v[172:175], v[18:21]
	ds_read_b128 v[152:155], v231 offset:0
	global_store_dwordx4 v241, v[114:117], s[10:11] offset:2048 sc1
	v_mfma_f32_16x16x32_bf16 v[22:25], v[188:191], v[172:175], v[22:25]
	ds_read_b128 v[156:159], v231 offset:2048
	v_mfma_f32_16x16x32_bf16 v[26:29], v[192:195], v[172:175], v[26:29]
	ds_read_b128 v[160:163], v231 offset:4096
	v_mul_f32_e32 v122, s12, v122
	v_mfma_f32_16x16x32_bf16 v[30:33], v[196:199], v[172:175], v[30:33]
	ds_read_b128 v[164:167], v231 offset:6144
	s_mov_b32 m0, s8
	v_mfma_f32_16x16x32_bf16 v[34:37], v[184:187], v[176:179], v[34:37]
	global_load_lds_dwordx4 v200, s[4:5]
	s_add_u32 m0, s8, 0x400
	v_mfma_f32_16x16x32_bf16 v[38:41], v[188:191], v[176:179], v[38:41]
	global_load_lds_dwordx4 v201, s[4:5]
	v_mul_f32_e32 v123, s12, v123
	s_add_u32 m0, s8, 0x800
	v_mfma_f32_16x16x32_bf16 v[42:45], v[192:195], v[176:179], v[42:45]
	global_load_lds_dwordx4 v202, s[4:5]
	s_add_u32 m0, s8, 0xc00
	v_mfma_f32_16x16x32_bf16 v[46:49], v[196:199], v[176:179], v[46:49]
	global_load_lds_dwordx4 v203, s[4:5]
	v_mul_f32_e32 v124, s12, v124
	s_mov_b32 m0, s9
	v_mfma_f32_16x16x32_bf16 v[50:53], v[184:187], v[180:183], v[50:53]
	global_load_lds_dwordx4 v204, s[6:7]
	s_add_u32 m0, s9, 0x400
	v_mfma_f32_16x16x32_bf16 v[54:57], v[188:191], v[180:183], v[54:57]
	global_load_lds_dwordx4 v205, s[6:7]
	v_mul_f32_e32 v125, s12, v125
	v_mfma_f32_16x16x32_bf16 v[58:61], v[192:195], v[180:183], v[58:61]
	s_add_u32 s4, s4, 0x80
	s_addc_u32 s5, s5, 0
	v_mfma_f32_16x16x32_bf16 v[62:65], v[196:199], v[180:183], v[62:65]
	s_add_u32 s6, s6, 0x80
	s_addc_u32 s7, s7, 0
	v_mul_f32_e32 v126, s12, v126
	s_waitcnt lgkmcnt(0)
	v_mfma_f32_16x16x32_bf16 v[2:5], v[152:155], v[136:139], v[2:5]
	ds_read_b128 v[168:171], v228 offset:0
	v_mfma_f32_16x16x32_bf16 v[6:9], v[156:159], v[136:139], v[6:9]
	ds_read_b128 v[172:175], v228 offset:2048
	v_mul_f32_e32 v127, s12, v127
	v_mfma_f32_16x16x32_bf16 v[10:13], v[160:163], v[136:139], v[10:13]
	ds_read_b128 v[176:179], v228 offset:4096
	v_mul_f32_e32 v128, s12, v128
	v_mfma_f32_16x16x32_bf16 v[14:17], v[164:167], v[136:139], v[14:17]
	ds_read_b128 v[180:183], v228 offset:6144
	v_mul_f32_e32 v129, s12, v129
	v_mfma_f32_16x16x32_bf16 v[18:21], v[152:155], v[140:143], v[18:21]
	ds_read_b128 v[184:187], v234 offset:0
	v_mfma_f32_16x16x32_bf16 v[22:25], v[156:159], v[140:143], v[22:25]
	ds_read_b128 v[188:191], v234 offset:2048
	v_exp_f32_e32 v122, v122
	v_mfma_f32_16x16x32_bf16 v[26:29], v[160:163], v[140:143], v[26:29]
	ds_read_b128 v[192:195], v234 offset:4096
	v_exp_f32_e32 v123, v123
	v_mfma_f32_16x16x32_bf16 v[30:33], v[164:167], v[140:143], v[30:33]
	ds_read_b128 v[196:199], v234 offset:6144
	v_exp_f32_e32 v124, v124
	v_mfma_f32_16x16x32_bf16 v[34:37], v[152:155], v[144:147], v[34:37]
	v_mfma_f32_16x16x32_bf16 v[38:41], v[156:159], v[144:147], v[38:41]
	v_exp_f32_e32 v125, v125
	v_mfma_f32_16x16x32_bf16 v[42:45], v[160:163], v[144:147], v[42:45]
	v_exp_f32_e32 v126, v126
	v_mfma_f32_16x16x32_bf16 v[46:49], v[164:167], v[144:147], v[46:49]
	v_exp_f32_e32 v127, v127
	v_mfma_f32_16x16x32_bf16 v[50:53], v[152:155], v[148:151], v[50:53]
	v_mfma_f32_16x16x32_bf16 v[54:57], v[156:159], v[148:151], v[54:57]
	v_exp_f32_e32 v128, v128
	v_mfma_f32_16x16x32_bf16 v[58:61], v[160:163], v[148:151], v[58:61]
	v_exp_f32_e32 v129, v129
	v_mfma_f32_16x16x32_bf16 v[62:65], v[164:167], v[148:151], v[62:65]
	v_add_f32_e32 v122, 1.0, v122
	s_waitcnt vmcnt(7) lgkmcnt(0)
	s_barrier
	v_mfma_f32_16x16x32_bf16 v[2:5], v[184:187], v[168:171], v[2:5]
	ds_read_b128 v[136:139], v224 offset:0
	v_mfma_f32_16x16x32_bf16 v[6:9], v[188:191], v[168:171], v[6:9]
	ds_read_b128 v[140:143], v224 offset:2048
	v_mfma_f32_16x16x32_bf16 v[10:13], v[192:195], v[168:171], v[10:13]
	ds_read_b128 v[144:147], v224 offset:4096
	v_add_f32_e32 v123, 1.0, v123
	v_mfma_f32_16x16x32_bf16 v[14:17], v[196:199], v[168:171], v[14:17]
	ds_read_b128 v[148:151], v224 offset:6144
	v_mfma_f32_16x16x32_bf16 v[18:21], v[184:187], v[172:175], v[18:21]
	ds_read_b128 v[152:155], v232 offset:0
	v_add_f32_e32 v124, 1.0, v124
	v_mfma_f32_16x16x32_bf16 v[22:25], v[188:191], v[172:175], v[22:25]
	ds_read_b128 v[156:159], v232 offset:2048
	v_mfma_f32_16x16x32_bf16 v[26:29], v[192:195], v[172:175], v[26:29]
	ds_read_b128 v[160:163], v232 offset:4096
	v_add_f32_e32 v125, 1.0, v125
	v_mfma_f32_16x16x32_bf16 v[30:33], v[196:199], v[172:175], v[30:33]
	ds_read_b128 v[164:167], v232 offset:6144
	s_add_u32 m0, s8, 0xc000
	v_mfma_f32_16x16x32_bf16 v[34:37], v[184:187], v[176:179], v[34:37]
	global_load_lds_dwordx4 v200, s[4:5]
	s_add_u32 m0, s8, 0xc400
	v_mfma_f32_16x16x32_bf16 v[38:41], v[188:191], v[176:179], v[38:41]
	global_load_lds_dwordx4 v201, s[4:5]
	v_add_f32_e32 v126, 1.0, v126
	s_add_u32 m0, s8, 0xc800
	v_mfma_f32_16x16x32_bf16 v[42:45], v[192:195], v[176:179], v[42:45]
	global_load_lds_dwordx4 v202, s[4:5]
	s_add_u32 m0, s8, 0xcc00
	v_mfma_f32_16x16x32_bf16 v[46:49], v[196:199], v[176:179], v[46:49]
	global_load_lds_dwordx4 v203, s[4:5]
	v_add_f32_e32 v127, 1.0, v127
	s_add_u32 m0, s9, 0xc000
	v_mfma_f32_16x16x32_bf16 v[50:53], v[184:187], v[180:183], v[50:53]
	global_load_lds_dwordx4 v204, s[6:7]
	s_add_u32 m0, s9, 0xc400
	v_mfma_f32_16x16x32_bf16 v[54:57], v[188:191], v[180:183], v[54:57]
	global_load_lds_dwordx4 v205, s[6:7]
	v_add_f32_e32 v128, 1.0, v128
	v_mfma_f32_16x16x32_bf16 v[58:61], v[192:195], v[180:183], v[58:61]
	s_add_u32 s4, s4, 0x80
	s_addc_u32 s5, s5, 0
	v_mfma_f32_16x16x32_bf16 v[62:65], v[196:199], v[180:183], v[62:65]
	s_add_u32 s6, s6, 0x80
	s_addc_u32 s7, s7, 0
	v_add_f32_e32 v129, 1.0, v129
	s_waitcnt lgkmcnt(0)
	v_mfma_f32_16x16x32_bf16 v[2:5], v[152:155], v[136:139], v[2:5]
	ds_read_b128 v[168:171], v229 offset:0
	v_mfma_f32_16x16x32_bf16 v[6:9], v[156:159], v[136:139], v[6:9]
	ds_read_b128 v[172:175], v229 offset:2048
	v_rcp_f32_e32 v122, v122
	v_mfma_f32_16x16x32_bf16 v[10:13], v[160:163], v[136:139], v[10:13]
	ds_read_b128 v[176:179], v229 offset:4096
	v_rcp_f32_e32 v123, v123
	v_mfma_f32_16x16x32_bf16 v[14:17], v[164:167], v[136:139], v[14:17]
	ds_read_b128 v[180:183], v229 offset:6144
	v_rcp_f32_e32 v124, v124
	v_mfma_f32_16x16x32_bf16 v[18:21], v[152:155], v[140:143], v[18:21]
	ds_read_b128 v[184:187], v235 offset:0
	v_mfma_f32_16x16x32_bf16 v[22:25], v[156:159], v[140:143], v[22:25]
	ds_read_b128 v[188:191], v235 offset:2048
	v_rcp_f32_e32 v125, v125
	v_mfma_f32_16x16x32_bf16 v[26:29], v[160:163], v[140:143], v[26:29]
	ds_read_b128 v[192:195], v235 offset:4096
	v_rcp_f32_e32 v126, v126
	v_mfma_f32_16x16x32_bf16 v[30:33], v[164:167], v[140:143], v[30:33]
	ds_read_b128 v[196:199], v235 offset:6144
	v_rcp_f32_e32 v127, v127
	v_mfma_f32_16x16x32_bf16 v[34:37], v[152:155], v[144:147], v[34:37]
	v_mfma_f32_16x16x32_bf16 v[38:41], v[156:159], v[144:147], v[38:41]
	v_rcp_f32_e32 v128, v128
	v_mfma_f32_16x16x32_bf16 v[42:45], v[160:163], v[144:147], v[42:45]
	v_rcp_f32_e32 v129, v129
	v_mfma_f32_16x16x32_bf16 v[46:49], v[164:167], v[144:147], v[46:49]
	v_cvt_pk_bf16_f32 v122, v122, v123
	v_mfma_f32_16x16x32_bf16 v[50:53], v[152:155], v[148:151], v[50:53]
	v_mfma_f32_16x16x32_bf16 v[54:57], v[156:159], v[148:151], v[54:57]
	v_cvt_pk_bf16_f32 v123, v124, v125
	v_mfma_f32_16x16x32_bf16 v[58:61], v[160:163], v[148:151], v[58:61]
	v_cvt_pk_bf16_f32 v124, v126, v127
	v_mfma_f32_16x16x32_bf16 v[62:65], v[164:167], v[148:151], v[62:65]
	v_cvt_pk_bf16_f32 v125, v128, v129
	s_waitcnt vmcnt(6) lgkmcnt(0)
	s_barrier
	v_mfma_f32_16x16x32_bf16 v[2:5], v[184:187], v[168:171], v[2:5]
	ds_read_b128 v[136:139], v218 offset:0
	v_mfma_f32_16x16x32_bf16 v[6:9], v[188:191], v[168:171], v[6:9]
	ds_read_b128 v[140:143], v218 offset:2048
	v_mfma_f32_16x16x32_bf16 v[10:13], v[192:195], v[168:171], v[10:13]
	ds_read_b128 v[144:147], v218 offset:4096
	v_mfma_f32_16x16x32_bf16 v[14:17], v[196:199], v[168:171], v[14:17]
	ds_read_b128 v[148:151], v218 offset:6144
	v_mfma_f32_16x16x32_bf16 v[18:21], v[184:187], v[172:175], v[18:21]
	ds_read_b128 v[152:155], v230 offset:0
	v_mfma_f32_16x16x32_bf16 v[22:25], v[188:191], v[172:175], v[22:25]
	ds_read_b128 v[156:159], v230 offset:2048
	v_mfma_f32_16x16x32_bf16 v[26:29], v[192:195], v[172:175], v[26:29]
	ds_read_b128 v[160:163], v230 offset:4096
	v_mfma_f32_16x16x32_bf16 v[30:33], v[196:199], v[172:175], v[30:33]
	ds_read_b128 v[164:167], v230 offset:6144
	s_add_u32 m0, s8, 0x18000
	v_mfma_f32_16x16x32_bf16 v[34:37], v[184:187], v[176:179], v[34:37]
	global_load_lds_dwordx4 v200, s[4:5]
	s_add_u32 m0, s8, 0x18400
	v_mfma_f32_16x16x32_bf16 v[38:41], v[188:191], v[176:179], v[38:41]
	global_load_lds_dwordx4 v201, s[4:5]
	s_add_u32 m0, s8, 0x18800
	v_mfma_f32_16x16x32_bf16 v[42:45], v[192:195], v[176:179], v[42:45]
	global_load_lds_dwordx4 v202, s[4:5]
	s_add_u32 m0, s8, 0x18c00
	v_mfma_f32_16x16x32_bf16 v[46:49], v[196:199], v[176:179], v[46:49]
	global_load_lds_dwordx4 v203, s[4:5]
	s_add_u32 m0, s9, 0x18000
	v_mfma_f32_16x16x32_bf16 v[50:53], v[184:187], v[180:183], v[50:53]
	global_load_lds_dwordx4 v204, s[6:7]
	s_add_u32 m0, s9, 0x18400
	v_mfma_f32_16x16x32_bf16 v[54:57], v[188:191], v[180:183], v[54:57]
	global_load_lds_dwordx4 v205, s[6:7]
	v_mfma_f32_16x16x32_bf16 v[58:61], v[192:195], v[180:183], v[58:61]
	s_add_u32 s4, s4, 0x80
	s_addc_u32 s5, s5, 0
	v_mfma_f32_16x16x32_bf16 v[62:65], v[196:199], v[180:183], v[62:65]
	s_add_u32 s6, s6, 0x80
	s_addc_u32 s7, s7, 0
	global_store_dwordx4 v241, v[122:125], s[10:11] offset:3072 sc1
	s_waitcnt lgkmcnt(0)
	v_mfma_f32_16x16x32_bf16 v[66:69], v[152:155], v[136:139], 0
	ds_read_b128 v[168:171], v225 offset:0
	v_mfma_f32_16x16x32_bf16 v[70:73], v[156:159], v[136:139], 0
	ds_read_b128 v[172:175], v225 offset:2048
	s_add_u32 s10, s28, s13
	s_addc_u32 s11, s29, 0
	v_mfma_f32_16x16x32_bf16 v[74:77], v[160:163], v[136:139], 0
	ds_read_b128 v[176:179], v225 offset:4096
	s_add_u32 s13, s13, 0x10000
	v_mfma_f32_16x16x32_bf16 v[78:81], v[164:167], v[136:139], 0
	ds_read_b128 v[180:183], v225 offset:6144
	v_mul_f32_e32 v2, s12, v2
	v_mfma_f32_16x16x32_bf16 v[82:85], v[152:155], v[140:143], 0
	ds_read_b128 v[184:187], v233 offset:0
	v_mfma_f32_16x16x32_bf16 v[86:89], v[156:159], v[140:143], 0
	ds_read_b128 v[188:191], v233 offset:2048
	v_mul_f32_e32 v3, s12, v3
	v_mfma_f32_16x16x32_bf16 v[90:93], v[160:163], v[140:143], 0
	ds_read_b128 v[192:195], v233 offset:4096
	v_mul_f32_e32 v4, s12, v4
	v_mfma_f32_16x16x32_bf16 v[94:97], v[164:167], v[140:143], 0
	ds_read_b128 v[196:199], v233 offset:6144
	v_mul_f32_e32 v5, s12, v5
	v_mfma_f32_16x16x32_bf16 v[98:101], v[152:155], v[144:147], 0
	v_mfma_f32_16x16x32_bf16 v[102:105], v[156:159], v[144:147], 0
	v_mul_f32_e32 v6, s12, v6
	v_mfma_f32_16x16x32_bf16 v[106:109], v[160:163], v[144:147], 0
	v_mul_f32_e32 v7, s12, v7
	v_mfma_f32_16x16x32_bf16 v[110:113], v[164:167], v[144:147], 0
	v_mul_f32_e32 v8, s12, v8
	v_mfma_f32_16x16x32_bf16 v[114:117], v[152:155], v[148:151], 0
	v_mfma_f32_16x16x32_bf16 v[118:121], v[156:159], v[148:151], 0
	v_mul_f32_e32 v9, s12, v9
	v_mfma_f32_16x16x32_bf16 v[122:125], v[160:163], v[148:151], 0
	v_exp_f32_e32 v2, v2
	v_mfma_f32_16x16x32_bf16 v[126:129], v[164:167], v[148:151], 0
	v_exp_f32_e32 v3, v3
	s_waitcnt vmcnt(7) lgkmcnt(0)
	s_barrier
	v_mfma_f32_16x16x32_bf16 v[66:69], v[184:187], v[168:171], v[66:69]
	ds_read_b128 v[136:139], v219 offset:0
	v_mfma_f32_16x16x32_bf16 v[70:73], v[188:191], v[168:171], v[70:73]
	ds_read_b128 v[140:143], v219 offset:2048
	v_mfma_f32_16x16x32_bf16 v[74:77], v[192:195], v[168:171], v[74:77]
	ds_read_b128 v[144:147], v219 offset:4096
	v_exp_f32_e32 v4, v4
	v_mfma_f32_16x16x32_bf16 v[78:81], v[196:199], v[168:171], v[78:81]
	ds_read_b128 v[148:151], v219 offset:6144
	v_mfma_f32_16x16x32_bf16 v[82:85], v[184:187], v[172:175], v[82:85]
	ds_read_b128 v[152:155], v231 offset:0
	v_exp_f32_e32 v5, v5
	v_mfma_f32_16x16x32_bf16 v[86:89], v[188:191], v[172:175], v[86:89]
	ds_read_b128 v[156:159], v231 offset:2048
	v_mfma_f32_16x16x32_bf16 v[90:93], v[192:195], v[172:175], v[90:93]
	ds_read_b128 v[160:163], v231 offset:4096
	v_exp_f32_e32 v6, v6
	v_mfma_f32_16x16x32_bf16 v[94:97], v[196:199], v[172:175], v[94:97]
	ds_read_b128 v[164:167], v231 offset:6144
	s_mov_b32 m0, s8
	v_mfma_f32_16x16x32_bf16 v[98:101], v[184:187], v[176:179], v[98:101]
	global_load_lds_dwordx4 v200, s[4:5]
	s_add_u32 m0, s8, 0x400
	v_mfma_f32_16x16x32_bf16 v[102:105], v[188:191], v[176:179], v[102:105]
	global_load_lds_dwordx4 v201, s[4:5]
	v_exp_f32_e32 v7, v7
	s_add_u32 m0, s8, 0x800
	v_mfma_f32_16x16x32_bf16 v[106:109], v[192:195], v[176:179], v[106:109]
	global_load_lds_dwordx4 v202, s[4:5]
	s_add_u32 m0, s8, 0xc00
	v_mfma_f32_16x16x32_bf16 v[110:113], v[196:199], v[176:179], v[110:113]
	global_load_lds_dwordx4 v203, s[4:5]
	v_exp_f32_e32 v8, v8
	s_mov_b32 m0, s9
	v_mfma_f32_16x16x32_bf16 v[114:117], v[184:187], v[180:183], v[114:117]
	global_load_lds_dwordx4 v204, s[6:7]
	s_add_u32 m0, s9, 0x400
	v_mfma_f32_16x16x32_bf16 v[118:121], v[188:191], v[180:183], v[118:121]
	global_load_lds_dwordx4 v205, s[6:7]
	v_exp_f32_e32 v9, v9
	v_mfma_f32_16x16x32_bf16 v[122:125], v[192:195], v[180:183], v[122:125]
	s_add_u32 s4, s4, 0x80
	s_addc_u32 s5, s5, 0
	v_mfma_f32_16x16x32_bf16 v[126:129], v[196:199], v[180:183], v[126:129]
	s_add_u32 s6, s6, 0x80
	s_addc_u32 s7, s7, 0
	v_add_f32_e32 v2, 1.0, v2
	s_waitcnt lgkmcnt(0)
	v_mfma_f32_16x16x32_bf16 v[66:69], v[152:155], v[136:139], v[66:69]
	ds_read_b128 v[168:171], v228 offset:0
	v_mfma_f32_16x16x32_bf16 v[70:73], v[156:159], v[136:139], v[70:73]
	ds_read_b128 v[172:175], v228 offset:2048
	v_add_f32_e32 v3, 1.0, v3
	v_mfma_f32_16x16x32_bf16 v[74:77], v[160:163], v[136:139], v[74:77]
	ds_read_b128 v[176:179], v228 offset:4096
	v_add_f32_e32 v4, 1.0, v4
	v_mfma_f32_16x16x32_bf16 v[78:81], v[164:167], v[136:139], v[78:81]
	ds_read_b128 v[180:183], v228 offset:6144
	v_add_f32_e32 v5, 1.0, v5
	v_mfma_f32_16x16x32_bf16 v[82:85], v[152:155], v[140:143], v[82:85]
	ds_read_b128 v[184:187], v234 offset:0
	v_mfma_f32_16x16x32_bf16 v[86:89], v[156:159], v[140:143], v[86:89]
	ds_read_b128 v[188:191], v234 offset:2048
	v_add_f32_e32 v6, 1.0, v6
	v_mfma_f32_16x16x32_bf16 v[90:93], v[160:163], v[140:143], v[90:93]
	ds_read_b128 v[192:195], v234 offset:4096
	v_add_f32_e32 v7, 1.0, v7
	v_mfma_f32_16x16x32_bf16 v[94:97], v[164:167], v[140:143], v[94:97]
	ds_read_b128 v[196:199], v234 offset:6144
	v_add_f32_e32 v8, 1.0, v8
	v_mfma_f32_16x16x32_bf16 v[98:101], v[152:155], v[144:147], v[98:101]
	v_mfma_f32_16x16x32_bf16 v[102:105], v[156:159], v[144:147], v[102:105]
	v_add_f32_e32 v9, 1.0, v9
	v_mfma_f32_16x16x32_bf16 v[106:109], v[160:163], v[144:147], v[106:109]
	v_rcp_f32_e32 v2, v2
	v_mfma_f32_16x16x32_bf16 v[110:113], v[164:167], v[144:147], v[110:113]
	v_rcp_f32_e32 v3, v3
	v_mfma_f32_16x16x32_bf16 v[114:117], v[152:155], v[148:151], v[114:117]
	v_mfma_f32_16x16x32_bf16 v[118:121], v[156:159], v[148:151], v[118:121]
	v_rcp_f32_e32 v4, v4
	v_mfma_f32_16x16x32_bf16 v[122:125], v[160:163], v[148:151], v[122:125]
	v_rcp_f32_e32 v5, v5
	v_mfma_f32_16x16x32_bf16 v[126:129], v[164:167], v[148:151], v[126:129]
	v_rcp_f32_e32 v6, v6
	s_waitcnt vmcnt(7) lgkmcnt(0)
	s_barrier
	v_mfma_f32_16x16x32_bf16 v[66:69], v[184:187], v[168:171], v[66:69]
	ds_read_b128 v[136:139], v224 offset:0
	v_mfma_f32_16x16x32_bf16 v[70:73], v[188:191], v[168:171], v[70:73]
	ds_read_b128 v[140:143], v224 offset:2048
	v_mfma_f32_16x16x32_bf16 v[74:77], v[192:195], v[168:171], v[74:77]
	ds_read_b128 v[144:147], v224 offset:4096
	v_rcp_f32_e32 v7, v7
	v_mfma_f32_16x16x32_bf16 v[78:81], v[196:199], v[168:171], v[78:81]
	ds_read_b128 v[148:151], v224 offset:6144
	v_mfma_f32_16x16x32_bf16 v[82:85], v[184:187], v[172:175], v[82:85]
	ds_read_b128 v[152:155], v232 offset:0
	v_rcp_f32_e32 v8, v8
	v_mfma_f32_16x16x32_bf16 v[86:89], v[188:191], v[172:175], v[86:89]
	ds_read_b128 v[156:159], v232 offset:2048
	v_mfma_f32_16x16x32_bf16 v[90:93], v[192:195], v[172:175], v[90:93]
	ds_read_b128 v[160:163], v232 offset:4096
	v_rcp_f32_e32 v9, v9
	v_mfma_f32_16x16x32_bf16 v[94:97], v[196:199], v[172:175], v[94:97]
	ds_read_b128 v[164:167], v232 offset:6144
	s_add_u32 m0, s8, 0xc000
	v_mfma_f32_16x16x32_bf16 v[98:101], v[184:187], v[176:179], v[98:101]
	global_load_lds_dwordx4 v200, s[4:5]
	s_add_u32 m0, s8, 0xc400
	v_mfma_f32_16x16x32_bf16 v[102:105], v[188:191], v[176:179], v[102:105]
	global_load_lds_dwordx4 v201, s[4:5]
	v_cvt_pk_bf16_f32 v2, v2, v3
	s_add_u32 m0, s8, 0xc800
	v_mfma_f32_16x16x32_bf16 v[106:109], v[192:195], v[176:179], v[106:109]
	global_load_lds_dwordx4 v202, s[4:5]
	s_add_u32 m0, s8, 0xcc00
	v_mfma_f32_16x16x32_bf16 v[110:113], v[196:199], v[176:179], v[110:113]
	global_load_lds_dwordx4 v203, s[4:5]
	v_cvt_pk_bf16_f32 v3, v4, v5
	s_add_u32 m0, s9, 0xc000
	v_mfma_f32_16x16x32_bf16 v[114:117], v[184:187], v[180:183], v[114:117]
	global_load_lds_dwordx4 v204, s[6:7]
	s_add_u32 m0, s9, 0xc400
	v_mfma_f32_16x16x32_bf16 v[118:121], v[188:191], v[180:183], v[118:121]
	global_load_lds_dwordx4 v205, s[6:7]
	v_cvt_pk_bf16_f32 v4, v6, v7
	v_mfma_f32_16x16x32_bf16 v[122:125], v[192:195], v[180:183], v[122:125]
	s_add_u32 s4, s4, 0x80
	s_addc_u32 s5, s5, 0
	v_mfma_f32_16x16x32_bf16 v[126:129], v[196:199], v[180:183], v[126:129]
	s_add_u32 s6, s6, 0x80
	s_addc_u32 s7, s7, 0
	v_cvt_pk_bf16_f32 v5, v8, v9
	s_waitcnt lgkmcnt(0)
	v_mfma_f32_16x16x32_bf16 v[66:69], v[152:155], v[136:139], v[66:69]
	ds_read_b128 v[168:171], v229 offset:0
	v_mfma_f32_16x16x32_bf16 v[70:73], v[156:159], v[136:139], v[70:73]
	ds_read_b128 v[172:175], v229 offset:2048
	global_store_dwordx4 v240, v[2:5], s[10:11] offset:0 sc1
	v_mfma_f32_16x16x32_bf16 v[74:77], v[160:163], v[136:139], v[74:77]
	ds_read_b128 v[176:179], v229 offset:4096
	v_mul_f32_e32 v10, s12, v10
	v_mfma_f32_16x16x32_bf16 v[78:81], v[164:167], v[136:139], v[78:81]
	ds_read_b128 v[180:183], v229 offset:6144
	v_mul_f32_e32 v11, s12, v11
	v_mfma_f32_16x16x32_bf16 v[82:85], v[152:155], v[140:143], v[82:85]
	ds_read_b128 v[184:187], v235 offset:0
	v_mfma_f32_16x16x32_bf16 v[86:89], v[156:159], v[140:143], v[86:89]
	ds_read_b128 v[188:191], v235 offset:2048
	v_mul_f32_e32 v12, s12, v12
	v_mfma_f32_16x16x32_bf16 v[90:93], v[160:163], v[140:143], v[90:93]
	ds_read_b128 v[192:195], v235 offset:4096
	v_mul_f32_e32 v13, s12, v13
	v_mfma_f32_16x16x32_bf16 v[94:97], v[164:167], v[140:143], v[94:97]
	ds_read_b128 v[196:199], v235 offset:6144
	v_mul_f32_e32 v14, s12, v14
	v_mfma_f32_16x16x32_bf16 v[98:101], v[152:155], v[144:147], v[98:101]
	v_mfma_f32_16x16x32_bf16 v[102:105], v[156:159], v[144:147], v[102:105]
	v_mul_f32_e32 v15, s12, v15
	v_mfma_f32_16x16x32_bf16 v[106:109], v[160:163], v[144:147], v[106:109]
	v_mul_f32_e32 v16, s12, v16
	v_mfma_f32_16x16x32_bf16 v[110:113], v[164:167], v[144:147], v[110:113]
	v_mul_f32_e32 v17, s12, v17
	v_mfma_f32_16x16x32_bf16 v[114:117], v[152:155], v[148:151], v[114:117]
	v_mfma_f32_16x16x32_bf16 v[118:121], v[156:159], v[148:151], v[118:121]
	v_exp_f32_e32 v10, v10
	v_mfma_f32_16x16x32_bf16 v[122:125], v[160:163], v[148:151], v[122:125]
	v_exp_f32_e32 v11, v11
	v_mfma_f32_16x16x32_bf16 v[126:129], v[164:167], v[148:151], v[126:129]
	v_exp_f32_e32 v12, v12
	s_waitcnt vmcnt(7) lgkmcnt(0)
	s_barrier
	v_mfma_f32_16x16x32_bf16 v[66:69], v[184:187], v[168:171], v[66:69]
	ds_read_b128 v[136:139], v218 offset:0
	v_mfma_f32_16x16x32_bf16 v[70:73], v[188:191], v[168:171], v[70:73]
	ds_read_b128 v[140:143], v218 offset:2048
	v_mfma_f32_16x16x32_bf16 v[74:77], v[192:195], v[168:171], v[74:77]
	ds_read_b128 v[144:147], v218 offset:4096
	v_exp_f32_e32 v13, v13
	v_mfma_f32_16x16x32_bf16 v[78:81], v[196:199], v[168:171], v[78:81]
	ds_read_b128 v[148:151], v218 offset:6144
	v_mfma_f32_16x16x32_bf16 v[82:85], v[184:187], v[172:175], v[82:85]
	ds_read_b128 v[152:155], v230 offset:0
	v_exp_f32_e32 v14, v14
	v_mfma_f32_16x16x32_bf16 v[86:89], v[188:191], v[172:175], v[86:89]
	ds_read_b128 v[156:159], v230 offset:2048
	v_mfma_f32_16x16x32_bf16 v[90:93], v[192:195], v[172:175], v[90:93]
	ds_read_b128 v[160:163], v230 offset:4096
	v_exp_f32_e32 v15, v15
	v_mfma_f32_16x16x32_bf16 v[94:97], v[196:199], v[172:175], v[94:97]
	ds_read_b128 v[164:167], v230 offset:6144
	s_add_u32 m0, s8, 0x18000
	v_mfma_f32_16x16x32_bf16 v[98:101], v[184:187], v[176:179], v[98:101]
	global_load_lds_dwordx4 v200, s[4:5]
	s_add_u32 m0, s8, 0x18400
	v_mfma_f32_16x16x32_bf16 v[102:105], v[188:191], v[176:179], v[102:105]
	global_load_lds_dwordx4 v201, s[4:5]
	v_exp_f32_e32 v16, v16
	s_add_u32 m0, s8, 0x18800
	v_mfma_f32_16x16x32_bf16 v[106:109], v[192:195], v[176:179], v[106:109]
	global_load_lds_dwordx4 v202, s[4:5]
	s_add_u32 m0, s8, 0x18c00
	v_mfma_f32_16x16x32_bf16 v[110:113], v[196:199], v[176:179], v[110:113]
	global_load_lds_dwordx4 v203, s[4:5]
	v_exp_f32_e32 v17, v17
	s_add_u32 m0, s9, 0x18000
	v_mfma_f32_16x16x32_bf16 v[114:117], v[184:187], v[180:183], v[114:117]
	global_load_lds_dwordx4 v204, s[6:7]
	s_add_u32 m0, s9, 0x18400
	v_mfma_f32_16x16x32_bf16 v[118:121], v[188:191], v[180:183], v[118:121]
	global_load_lds_dwordx4 v205, s[6:7]
	v_add_f32_e32 v10, 1.0, v10
	v_mfma_f32_16x16x32_bf16 v[122:125], v[192:195], v[180:183], v[122:125]
	s_add_u32 s4, s4, 0x80
	s_addc_u32 s5, s5, 0
	v_mfma_f32_16x16x32_bf16 v[126:129], v[196:199], v[180:183], v[126:129]
	s_add_u32 s6, s6, 0x80
	s_addc_u32 s7, s7, 0
	v_add_f32_e32 v11, 1.0, v11
	s_waitcnt lgkmcnt(0)
	v_mfma_f32_16x16x32_bf16 v[66:69], v[152:155], v[136:139], v[66:69]
	ds_read_b128 v[168:171], v225 offset:0
	v_mfma_f32_16x16x32_bf16 v[70:73], v[156:159], v[136:139], v[70:73]
	ds_read_b128 v[172:175], v225 offset:2048
	v_add_f32_e32 v12, 1.0, v12
	v_mfma_f32_16x16x32_bf16 v[74:77], v[160:163], v[136:139], v[74:77]
	ds_read_b128 v[176:179], v225 offset:4096
	v_add_f32_e32 v13, 1.0, v13
	v_mfma_f32_16x16x32_bf16 v[78:81], v[164:167], v[136:139], v[78:81]
	ds_read_b128 v[180:183], v225 offset:6144
	v_add_f32_e32 v14, 1.0, v14
	v_mfma_f32_16x16x32_bf16 v[82:85], v[152:155], v[140:143], v[82:85]
	ds_read_b128 v[184:187], v233 offset:0
	v_mfma_f32_16x16x32_bf16 v[86:89], v[156:159], v[140:143], v[86:89]
	ds_read_b128 v[188:191], v233 offset:2048
	v_add_f32_e32 v15, 1.0, v15
	v_mfma_f32_16x16x32_bf16 v[90:93], v[160:163], v[140:143], v[90:93]
	ds_read_b128 v[192:195], v233 offset:4096
	v_add_f32_e32 v16, 1.0, v16
	v_mfma_f32_16x16x32_bf16 v[94:97], v[164:167], v[140:143], v[94:97]
	ds_read_b128 v[196:199], v233 offset:6144
	v_add_f32_e32 v17, 1.0, v17
	v_mfma_f32_16x16x32_bf16 v[98:101], v[152:155], v[144:147], v[98:101]
	v_mfma_f32_16x16x32_bf16 v[102:105], v[156:159], v[144:147], v[102:105]
	v_rcp_f32_e32 v10, v10
	v_mfma_f32_16x16x32_bf16 v[106:109], v[160:163], v[144:147], v[106:109]
	v_rcp_f32_e32 v11, v11
	v_mfma_f32_16x16x32_bf16 v[110:113], v[164:167], v[144:147], v[110:113]
	v_rcp_f32_e32 v12, v12
	v_mfma_f32_16x16x32_bf16 v[114:117], v[152:155], v[148:151], v[114:117]
	v_mfma_f32_16x16x32_bf16 v[118:121], v[156:159], v[148:151], v[118:121]
	v_rcp_f32_e32 v13, v13
	v_mfma_f32_16x16x32_bf16 v[122:125], v[160:163], v[148:151], v[122:125]
	v_rcp_f32_e32 v14, v14
	v_mfma_f32_16x16x32_bf16 v[126:129], v[164:167], v[148:151], v[126:129]
	v_rcp_f32_e32 v15, v15
	s_waitcnt vmcnt(7) lgkmcnt(0)
	s_barrier
	v_mfma_f32_16x16x32_bf16 v[66:69], v[184:187], v[168:171], v[66:69]
	ds_read_b128 v[136:139], v219 offset:0
	v_mfma_f32_16x16x32_bf16 v[70:73], v[188:191], v[168:171], v[70:73]
	ds_read_b128 v[140:143], v219 offset:2048
	v_mfma_f32_16x16x32_bf16 v[74:77], v[192:195], v[168:171], v[74:77]
	ds_read_b128 v[144:147], v219 offset:4096
	v_rcp_f32_e32 v16, v16
	v_mfma_f32_16x16x32_bf16 v[78:81], v[196:199], v[168:171], v[78:81]
	ds_read_b128 v[148:151], v219 offset:6144
	v_mfma_f32_16x16x32_bf16 v[82:85], v[184:187], v[172:175], v[82:85]
	ds_read_b128 v[152:155], v231 offset:0
	v_rcp_f32_e32 v17, v17
	v_mfma_f32_16x16x32_bf16 v[86:89], v[188:191], v[172:175], v[86:89]
	ds_read_b128 v[156:159], v231 offset:2048
	v_mfma_f32_16x16x32_bf16 v[90:93], v[192:195], v[172:175], v[90:93]
	ds_read_b128 v[160:163], v231 offset:4096
	v_cvt_pk_bf16_f32 v10, v10, v11
	v_mfma_f32_16x16x32_bf16 v[94:97], v[196:199], v[172:175], v[94:97]
	ds_read_b128 v[164:167], v231 offset:6144
	s_mov_b32 m0, s8
	v_mfma_f32_16x16x32_bf16 v[98:101], v[184:187], v[176:179], v[98:101]
	global_load_lds_dwordx4 v200, s[4:5]
	s_add_u32 m0, s8, 0x400
	v_mfma_f32_16x16x32_bf16 v[102:105], v[188:191], v[176:179], v[102:105]
	global_load_lds_dwordx4 v201, s[4:5]
	v_cvt_pk_bf16_f32 v11, v12, v13
	s_add_u32 m0, s8, 0x800
	v_mfma_f32_16x16x32_bf16 v[106:109], v[192:195], v[176:179], v[106:109]
	global_load_lds_dwordx4 v202, s[4:5]
	s_add_u32 m0, s8, 0xc00
	v_mfma_f32_16x16x32_bf16 v[110:113], v[196:199], v[176:179], v[110:113]
	global_load_lds_dwordx4 v203, s[4:5]
	v_cvt_pk_bf16_f32 v12, v14, v15
	s_mov_b32 m0, s9
	v_mfma_f32_16x16x32_bf16 v[114:117], v[184:187], v[180:183], v[114:117]
	global_load_lds_dwordx4 v204, s[6:7]
	s_add_u32 m0, s9, 0x400
	v_mfma_f32_16x16x32_bf16 v[118:121], v[188:191], v[180:183], v[118:121]
	global_load_lds_dwordx4 v205, s[6:7]
	v_cvt_pk_bf16_f32 v13, v16, v17
	v_mfma_f32_16x16x32_bf16 v[122:125], v[192:195], v[180:183], v[122:125]
	s_add_u32 s4, s4, 0x80
	s_addc_u32 s5, s5, 0
	v_mfma_f32_16x16x32_bf16 v[126:129], v[196:199], v[180:183], v[126:129]
	s_add_u32 s6, s6, 0x80
	s_addc_u32 s7, s7, 0
	global_store_dwordx4 v240, v[10:13], s[10:11] offset:1024 sc1
	s_waitcnt lgkmcnt(0)
	v_mfma_f32_16x16x32_bf16 v[66:69], v[152:155], v[136:139], v[66:69]
	ds_read_b128 v[168:171], v228 offset:0
	v_mfma_f32_16x16x32_bf16 v[70:73], v[156:159], v[136:139], v[70:73]
	ds_read_b128 v[172:175], v228 offset:2048
	v_mul_f32_e32 v18, s12, v18
	v_mfma_f32_16x16x32_bf16 v[74:77], v[160:163], v[136:139], v[74:77]
	ds_read_b128 v[176:179], v228 offset:4096
	v_mul_f32_e32 v19, s12, v19
	v_mfma_f32_16x16x32_bf16 v[78:81], v[164:167], v[136:139], v[78:81]
	ds_read_b128 v[180:183], v228 offset:6144
	v_mul_f32_e32 v20, s12, v20
	v_mfma_f32_16x16x32_bf16 v[82:85], v[152:155], v[140:143], v[82:85]
	ds_read_b128 v[184:187], v234 offset:0
	v_mfma_f32_16x16x32_bf16 v[86:89], v[156:159], v[140:143], v[86:89]
	ds_read_b128 v[188:191], v234 offset:2048
	v_mul_f32_e32 v21, s12, v21
	v_mfma_f32_16x16x32_bf16 v[90:93], v[160:163], v[140:143], v[90:93]
	ds_read_b128 v[192:195], v234 offset:4096
	v_mul_f32_e32 v22, s12, v22
	v_mfma_f32_16x16x32_bf16 v[94:97], v[164:167], v[140:143], v[94:97]
	ds_read_b128 v[196:199], v234 offset:6144
	v_mul_f32_e32 v23, s12, v23
	v_mfma_f32_16x16x32_bf16 v[98:101], v[152:155], v[144:147], v[98:101]
	v_mfma_f32_16x16x32_bf16 v[102:105], v[156:159], v[144:147], v[102:105]
	v_mul_f32_e32 v24, s12, v24
	v_mfma_f32_16x16x32_bf16 v[106:109], v[160:163], v[144:147], v[106:109]
	v_mul_f32_e32 v25, s12, v25
	v_mfma_f32_16x16x32_bf16 v[110:113], v[164:167], v[144:147], v[110:113]
	v_exp_f32_e32 v18, v18
	v_mfma_f32_16x16x32_bf16 v[114:117], v[152:155], v[148:151], v[114:117]
	v_mfma_f32_16x16x32_bf16 v[118:121], v[156:159], v[148:151], v[118:121]
	v_exp_f32_e32 v19, v19
	v_mfma_f32_16x16x32_bf16 v[122:125], v[160:163], v[148:151], v[122:125]
	v_exp_f32_e32 v20, v20
	v_mfma_f32_16x16x32_bf16 v[126:129], v[164:167], v[148:151], v[126:129]
	v_exp_f32_e32 v21, v21
	s_waitcnt vmcnt(7) lgkmcnt(0)
	s_barrier
	v_mfma_f32_16x16x32_bf16 v[66:69], v[184:187], v[168:171], v[66:69]
	ds_read_b128 v[136:139], v224 offset:0
	v_mfma_f32_16x16x32_bf16 v[70:73], v[188:191], v[168:171], v[70:73]
	ds_read_b128 v[140:143], v224 offset:2048
	v_mfma_f32_16x16x32_bf16 v[74:77], v[192:195], v[168:171], v[74:77]
	ds_read_b128 v[144:147], v224 offset:4096
	v_exp_f32_e32 v22, v22
	v_mfma_f32_16x16x32_bf16 v[78:81], v[196:199], v[168:171], v[78:81]
	ds_read_b128 v[148:151], v224 offset:6144
	v_mfma_f32_16x16x32_bf16 v[82:85], v[184:187], v[172:175], v[82:85]
	ds_read_b128 v[152:155], v232 offset:0
	v_exp_f32_e32 v23, v23
	v_mfma_f32_16x16x32_bf16 v[86:89], v[188:191], v[172:175], v[86:89]
	ds_read_b128 v[156:159], v232 offset:2048
	v_mfma_f32_16x16x32_bf16 v[90:93], v[192:195], v[172:175], v[90:93]
	ds_read_b128 v[160:163], v232 offset:4096
	v_exp_f32_e32 v24, v24
	v_mfma_f32_16x16x32_bf16 v[94:97], v[196:199], v[172:175], v[94:97]
	ds_read_b128 v[164:167], v232 offset:6144
	s_add_u32 m0, s8, 0xc000
	v_mfma_f32_16x16x32_bf16 v[98:101], v[184:187], v[176:179], v[98:101]
	global_load_lds_dwordx4 v200, s[4:5]
	s_add_u32 m0, s8, 0xc400
	v_mfma_f32_16x16x32_bf16 v[102:105], v[188:191], v[176:179], v[102:105]
	global_load_lds_dwordx4 v201, s[4:5]
	v_exp_f32_e32 v25, v25
	s_add_u32 m0, s8, 0xc800
	v_mfma_f32_16x16x32_bf16 v[106:109], v[192:195], v[176:179], v[106:109]
	global_load_lds_dwordx4 v202, s[4:5]
	s_add_u32 m0, s8, 0xcc00
	v_mfma_f32_16x16x32_bf16 v[110:113], v[196:199], v[176:179], v[110:113]
	global_load_lds_dwordx4 v203, s[4:5]
	v_add_f32_e32 v18, 1.0, v18
	s_add_u32 m0, s9, 0xc000
	v_mfma_f32_16x16x32_bf16 v[114:117], v[184:187], v[180:183], v[114:117]
	global_load_lds_dwordx4 v204, s[6:7]
	s_add_u32 m0, s9, 0xc400
	v_mfma_f32_16x16x32_bf16 v[118:121], v[188:191], v[180:183], v[118:121]
	global_load_lds_dwordx4 v205, s[6:7]
	v_add_f32_e32 v19, 1.0, v19
	v_mfma_f32_16x16x32_bf16 v[122:125], v[192:195], v[180:183], v[122:125]
	s_add_u32 s4, s4, 0x80
	s_addc_u32 s5, s5, 0
	v_mfma_f32_16x16x32_bf16 v[126:129], v[196:199], v[180:183], v[126:129]
	s_add_u32 s6, s6, 0x80
	s_addc_u32 s7, s7, 0
	v_add_f32_e32 v20, 1.0, v20
	s_waitcnt lgkmcnt(0)
	v_mfma_f32_16x16x32_bf16 v[66:69], v[152:155], v[136:139], v[66:69]
	ds_read_b128 v[168:171], v229 offset:0
	v_mfma_f32_16x16x32_bf16 v[70:73], v[156:159], v[136:139], v[70:73]
	ds_read_b128 v[172:175], v229 offset:2048
	v_add_f32_e32 v21, 1.0, v21
	v_mfma_f32_16x16x32_bf16 v[74:77], v[160:163], v[136:139], v[74:77]
	ds_read_b128 v[176:179], v229 offset:4096
	v_add_f32_e32 v22, 1.0, v22
	v_mfma_f32_16x16x32_bf16 v[78:81], v[164:167], v[136:139], v[78:81]
	ds_read_b128 v[180:183], v229 offset:6144
	v_add_f32_e32 v23, 1.0, v23
	v_mfma_f32_16x16x32_bf16 v[82:85], v[152:155], v[140:143], v[82:85]
	ds_read_b128 v[184:187], v235 offset:0
	v_mfma_f32_16x16x32_bf16 v[86:89], v[156:159], v[140:143], v[86:89]
	ds_read_b128 v[188:191], v235 offset:2048
	v_add_f32_e32 v24, 1.0, v24
	v_mfma_f32_16x16x32_bf16 v[90:93], v[160:163], v[140:143], v[90:93]
	ds_read_b128 v[192:195], v235 offset:4096
	v_add_f32_e32 v25, 1.0, v25
	v_mfma_f32_16x16x32_bf16 v[94:97], v[164:167], v[140:143], v[94:97]
	ds_read_b128 v[196:199], v235 offset:6144
	v_rcp_f32_e32 v18, v18
	v_mfma_f32_16x16x32_bf16 v[98:101], v[152:155], v[144:147], v[98:101]
	v_mfma_f32_16x16x32_bf16 v[102:105], v[156:159], v[144:147], v[102:105]
	v_rcp_f32_e32 v19, v19
	v_mfma_f32_16x16x32_bf16 v[106:109], v[160:163], v[144:147], v[106:109]
	v_rcp_f32_e32 v20, v20
	v_mfma_f32_16x16x32_bf16 v[110:113], v[164:167], v[144:147], v[110:113]
	v_rcp_f32_e32 v21, v21
	v_mfma_f32_16x16x32_bf16 v[114:117], v[152:155], v[148:151], v[114:117]
	v_mfma_f32_16x16x32_bf16 v[118:121], v[156:159], v[148:151], v[118:121]
	v_rcp_f32_e32 v22, v22
	v_mfma_f32_16x16x32_bf16 v[122:125], v[160:163], v[148:151], v[122:125]
	v_rcp_f32_e32 v23, v23
	v_mfma_f32_16x16x32_bf16 v[126:129], v[164:167], v[148:151], v[126:129]
	v_rcp_f32_e32 v24, v24
	s_waitcnt vmcnt(7) lgkmcnt(0)
	s_barrier
	v_mfma_f32_16x16x32_bf16 v[66:69], v[184:187], v[168:171], v[66:69]
	ds_read_b128 v[136:139], v218 offset:0
	v_mfma_f32_16x16x32_bf16 v[70:73], v[188:191], v[168:171], v[70:73]
	ds_read_b128 v[140:143], v218 offset:2048
	v_mfma_f32_16x16x32_bf16 v[74:77], v[192:195], v[168:171], v[74:77]
	ds_read_b128 v[144:147], v218 offset:4096
	v_rcp_f32_e32 v25, v25
	v_mfma_f32_16x16x32_bf16 v[78:81], v[196:199], v[168:171], v[78:81]
	ds_read_b128 v[148:151], v218 offset:6144
	v_mfma_f32_16x16x32_bf16 v[82:85], v[184:187], v[172:175], v[82:85]
	ds_read_b128 v[152:155], v230 offset:0
	v_cvt_pk_bf16_f32 v18, v18, v19
	v_mfma_f32_16x16x32_bf16 v[86:89], v[188:191], v[172:175], v[86:89]
	ds_read_b128 v[156:159], v230 offset:2048
	v_mfma_f32_16x16x32_bf16 v[90:93], v[192:195], v[172:175], v[90:93]
	ds_read_b128 v[160:163], v230 offset:4096
	v_cvt_pk_bf16_f32 v19, v20, v21
	v_mfma_f32_16x16x32_bf16 v[94:97], v[196:199], v[172:175], v[94:97]
	ds_read_b128 v[164:167], v230 offset:6144
	s_add_u32 m0, s8, 0x18000
	v_mfma_f32_16x16x32_bf16 v[98:101], v[184:187], v[176:179], v[98:101]
	global_load_lds_dwordx4 v200, s[4:5]
	s_add_u32 m0, s8, 0x18400
	v_mfma_f32_16x16x32_bf16 v[102:105], v[188:191], v[176:179], v[102:105]
	global_load_lds_dwordx4 v201, s[4:5]
	v_cvt_pk_bf16_f32 v20, v22, v23
	s_add_u32 m0, s8, 0x18800
	v_mfma_f32_16x16x32_bf16 v[106:109], v[192:195], v[176:179], v[106:109]
	global_load_lds_dwordx4 v202, s[4:5]
	s_add_u32 m0, s8, 0x18c00
	v_mfma_f32_16x16x32_bf16 v[110:113], v[196:199], v[176:179], v[110:113]
	global_load_lds_dwordx4 v203, s[4:5]
	v_cvt_pk_bf16_f32 v21, v24, v25
	s_add_u32 m0, s9, 0x18000
	v_mfma_f32_16x16x32_bf16 v[114:117], v[184:187], v[180:183], v[114:117]
	global_load_lds_dwordx4 v204, s[6:7]
	s_add_u32 m0, s9, 0x18400
	v_mfma_f32_16x16x32_bf16 v[118:121], v[188:191], v[180:183], v[118:121]
	global_load_lds_dwordx4 v205, s[6:7]
	global_store_dwordx4 v240, v[18:21], s[10:11] offset:2048 sc1
	v_mfma_f32_16x16x32_bf16 v[122:125], v[192:195], v[180:183], v[122:125]
	s_add_u32 s4, s4, 0x80
	s_addc_u32 s5, s5, 0
	v_mfma_f32_16x16x32_bf16 v[126:129], v[196:199], v[180:183], v[126:129]
	s_add_u32 s6, s6, 0x80
	s_addc_u32 s7, s7, 0
	v_mul_f32_e32 v26, s12, v26
	s_waitcnt lgkmcnt(0)
	v_mfma_f32_16x16x32_bf16 v[66:69], v[152:155], v[136:139], v[66:69]
	ds_read_b128 v[168:171], v225 offset:0
	v_mfma_f32_16x16x32_bf16 v[70:73], v[156:159], v[136:139], v[70:73]
	ds_read_b128 v[172:175], v225 offset:2048
	v_mul_f32_e32 v27, s12, v27
	v_mfma_f32_16x16x32_bf16 v[74:77], v[160:163], v[136:139], v[74:77]
	ds_read_b128 v[176:179], v225 offset:4096
	v_mul_f32_e32 v28, s12, v28
	v_mfma_f32_16x16x32_bf16 v[78:81], v[164:167], v[136:139], v[78:81]
	ds_read_b128 v[180:183], v225 offset:6144
	v_mul_f32_e32 v29, s12, v29
	v_mfma_f32_16x16x32_bf16 v[82:85], v[152:155], v[140:143], v[82:85]
	ds_read_b128 v[184:187], v233 offset:0
	v_mfma_f32_16x16x32_bf16 v[86:89], v[156:159], v[140:143], v[86:89]
	ds_read_b128 v[188:191], v233 offset:2048
	v_mul_f32_e32 v30, s12, v30
	v_mfma_f32_16x16x32_bf16 v[90:93], v[160:163], v[140:143], v[90:93]
	ds_read_b128 v[192:195], v233 offset:4096
	v_mul_f32_e32 v31, s12, v31
	v_mfma_f32_16x16x32_bf16 v[94:97], v[164:167], v[140:143], v[94:97]
	ds_read_b128 v[196:199], v233 offset:6144
	v_mul_f32_e32 v32, s12, v32
	v_mfma_f32_16x16x32_bf16 v[98:101], v[152:155], v[144:147], v[98:101]
	v_mfma_f32_16x16x32_bf16 v[102:105], v[156:159], v[144:147], v[102:105]
	v_mul_f32_e32 v33, s12, v33
	v_mfma_f32_16x16x32_bf16 v[106:109], v[160:163], v[144:147], v[106:109]
	v_exp_f32_e32 v26, v26
	v_mfma_f32_16x16x32_bf16 v[110:113], v[164:167], v[144:147], v[110:113]
	v_exp_f32_e32 v27, v27
	v_mfma_f32_16x16x32_bf16 v[114:117], v[152:155], v[148:151], v[114:117]
	v_mfma_f32_16x16x32_bf16 v[118:121], v[156:159], v[148:151], v[118:121]
	v_exp_f32_e32 v28, v28
	v_mfma_f32_16x16x32_bf16 v[122:125], v[160:163], v[148:151], v[122:125]
	v_exp_f32_e32 v29, v29
	v_mfma_f32_16x16x32_bf16 v[126:129], v[164:167], v[148:151], v[126:129]
	v_exp_f32_e32 v30, v30
	s_waitcnt vmcnt(7) lgkmcnt(0)
	s_barrier
	v_mfma_f32_16x16x32_bf16 v[66:69], v[184:187], v[168:171], v[66:69]
	ds_read_b128 v[136:139], v219 offset:0
	v_mfma_f32_16x16x32_bf16 v[70:73], v[188:191], v[168:171], v[70:73]
	ds_read_b128 v[140:143], v219 offset:2048
	v_mfma_f32_16x16x32_bf16 v[74:77], v[192:195], v[168:171], v[74:77]
	ds_read_b128 v[144:147], v219 offset:4096
	v_exp_f32_e32 v31, v31
	v_mfma_f32_16x16x32_bf16 v[78:81], v[196:199], v[168:171], v[78:81]
	ds_read_b128 v[148:151], v219 offset:6144
	v_mfma_f32_16x16x32_bf16 v[82:85], v[184:187], v[172:175], v[82:85]
	ds_read_b128 v[152:155], v231 offset:0
	v_exp_f32_e32 v32, v32
	v_mfma_f32_16x16x32_bf16 v[86:89], v[188:191], v[172:175], v[86:89]
	ds_read_b128 v[156:159], v231 offset:2048
	v_mfma_f32_16x16x32_bf16 v[90:93], v[192:195], v[172:175], v[90:93]
	ds_read_b128 v[160:163], v231 offset:4096
	v_exp_f32_e32 v33, v33
	v_mfma_f32_16x16x32_bf16 v[94:97], v[196:199], v[172:175], v[94:97]
	ds_read_b128 v[164:167], v231 offset:6144
	s_mov_b32 m0, s8
	v_mfma_f32_16x16x32_bf16 v[98:101], v[184:187], v[176:179], v[98:101]
	global_load_lds_dwordx4 v200, s[4:5]
	s_add_u32 m0, s8, 0x400
	v_mfma_f32_16x16x32_bf16 v[102:105], v[188:191], v[176:179], v[102:105]
	global_load_lds_dwordx4 v201, s[4:5]
	v_add_f32_e32 v26, 1.0, v26
	s_add_u32 m0, s8, 0x800
	v_mfma_f32_16x16x32_bf16 v[106:109], v[192:195], v[176:179], v[106:109]
	global_load_lds_dwordx4 v202, s[4:5]
	s_add_u32 m0, s8, 0xc00
	v_mfma_f32_16x16x32_bf16 v[110:113], v[196:199], v[176:179], v[110:113]
	global_load_lds_dwordx4 v203, s[4:5]
	v_add_f32_e32 v27, 1.0, v27
	s_mov_b32 m0, s9
	v_mfma_f32_16x16x32_bf16 v[114:117], v[184:187], v[180:183], v[114:117]
	global_load_lds_dwordx4 v204, s[6:7]
	s_add_u32 m0, s9, 0x400
	v_mfma_f32_16x16x32_bf16 v[118:121], v[188:191], v[180:183], v[118:121]
	global_load_lds_dwordx4 v205, s[6:7]
	v_add_f32_e32 v28, 1.0, v28
	v_mfma_f32_16x16x32_bf16 v[122:125], v[192:195], v[180:183], v[122:125]
	s_add_u32 s4, s4, 0x80
	s_addc_u32 s5, s5, 0
	v_mfma_f32_16x16x32_bf16 v[126:129], v[196:199], v[180:183], v[126:129]
	s_add_u32 s6, s6, 0x80
	s_addc_u32 s7, s7, 0
	v_add_f32_e32 v29, 1.0, v29
	s_waitcnt lgkmcnt(0)
	v_mfma_f32_16x16x32_bf16 v[66:69], v[152:155], v[136:139], v[66:69]
	ds_read_b128 v[168:171], v228 offset:0
	v_mfma_f32_16x16x32_bf16 v[70:73], v[156:159], v[136:139], v[70:73]
	ds_read_b128 v[172:175], v228 offset:2048
	v_add_f32_e32 v30, 1.0, v30
	v_mfma_f32_16x16x32_bf16 v[74:77], v[160:163], v[136:139], v[74:77]
	ds_read_b128 v[176:179], v228 offset:4096
	v_add_f32_e32 v31, 1.0, v31
	v_mfma_f32_16x16x32_bf16 v[78:81], v[164:167], v[136:139], v[78:81]
	ds_read_b128 v[180:183], v228 offset:6144
	v_add_f32_e32 v32, 1.0, v32
	v_mfma_f32_16x16x32_bf16 v[82:85], v[152:155], v[140:143], v[82:85]
	ds_read_b128 v[184:187], v234 offset:0
	v_mfma_f32_16x16x32_bf16 v[86:89], v[156:159], v[140:143], v[86:89]
	ds_read_b128 v[188:191], v234 offset:2048
	v_add_f32_e32 v33, 1.0, v33
	v_mfma_f32_16x16x32_bf16 v[90:93], v[160:163], v[140:143], v[90:93]
	ds_read_b128 v[192:195], v234 offset:4096
	v_rcp_f32_e32 v26, v26
	v_mfma_f32_16x16x32_bf16 v[94:97], v[164:167], v[140:143], v[94:97]
	ds_read_b128 v[196:199], v234 offset:6144
	v_rcp_f32_e32 v27, v27
	v_mfma_f32_16x16x32_bf16 v[98:101], v[152:155], v[144:147], v[98:101]
	v_mfma_f32_16x16x32_bf16 v[102:105], v[156:159], v[144:147], v[102:105]
	v_rcp_f32_e32 v28, v28
	v_mfma_f32_16x16x32_bf16 v[106:109], v[160:163], v[144:147], v[106:109]
	v_rcp_f32_e32 v29, v29
	v_mfma_f32_16x16x32_bf16 v[110:113], v[164:167], v[144:147], v[110:113]
	v_rcp_f32_e32 v30, v30
	v_mfma_f32_16x16x32_bf16 v[114:117], v[152:155], v[148:151], v[114:117]
	v_mfma_f32_16x16x32_bf16 v[118:121], v[156:159], v[148:151], v[118:121]
	v_rcp_f32_e32 v31, v31
	v_mfma_f32_16x16x32_bf16 v[122:125], v[160:163], v[148:151], v[122:125]
	v_rcp_f32_e32 v32, v32
	v_mfma_f32_16x16x32_bf16 v[126:129], v[164:167], v[148:151], v[126:129]
	v_rcp_f32_e32 v33, v33
	s_waitcnt vmcnt(7) lgkmcnt(0)
	s_barrier
	v_mfma_f32_16x16x32_bf16 v[66:69], v[184:187], v[168:171], v[66:69]
	ds_read_b128 v[136:139], v224 offset:0
	v_mfma_f32_16x16x32_bf16 v[70:73], v[188:191], v[168:171], v[70:73]
	ds_read_b128 v[140:143], v224 offset:2048
	v_mfma_f32_16x16x32_bf16 v[74:77], v[192:195], v[168:171], v[74:77]
	ds_read_b128 v[144:147], v224 offset:4096
	v_cvt_pk_bf16_f32 v26, v26, v27
	v_mfma_f32_16x16x32_bf16 v[78:81], v[196:199], v[168:171], v[78:81]
	ds_read_b128 v[148:151], v224 offset:6144
	v_mfma_f32_16x16x32_bf16 v[82:85], v[184:187], v[172:175], v[82:85]
	ds_read_b128 v[152:155], v232 offset:0
	v_cvt_pk_bf16_f32 v27, v28, v29
	v_mfma_f32_16x16x32_bf16 v[86:89], v[188:191], v[172:175], v[86:89]
	ds_read_b128 v[156:159], v232 offset:2048
	v_mfma_f32_16x16x32_bf16 v[90:93], v[192:195], v[172:175], v[90:93]
	ds_read_b128 v[160:163], v232 offset:4096
	v_cvt_pk_bf16_f32 v28, v30, v31
	v_mfma_f32_16x16x32_bf16 v[94:97], v[196:199], v[172:175], v[94:97]
	ds_read_b128 v[164:167], v232 offset:6144
	s_add_u32 m0, s8, 0xc000
	v_mfma_f32_16x16x32_bf16 v[98:101], v[184:187], v[176:179], v[98:101]
	global_load_lds_dwordx4 v200, s[4:5]
	s_add_u32 m0, s8, 0xc400
	v_mfma_f32_16x16x32_bf16 v[102:105], v[188:191], v[176:179], v[102:105]
	global_load_lds_dwordx4 v201, s[4:5]
	v_cvt_pk_bf16_f32 v29, v32, v33
	s_add_u32 m0, s8, 0xc800
	v_mfma_f32_16x16x32_bf16 v[106:109], v[192:195], v[176:179], v[106:109]
	global_load_lds_dwordx4 v202, s[4:5]
	s_add_u32 m0, s8, 0xcc00
	v_mfma_f32_16x16x32_bf16 v[110:113], v[196:199], v[176:179], v[110:113]
	global_load_lds_dwordx4 v203, s[4:5]
	global_store_dwordx4 v240, v[26:29], s[10:11] offset:3072 sc1
	s_add_u32 m0, s9, 0xc000
	v_mfma_f32_16x16x32_bf16 v[114:117], v[184:187], v[180:183], v[114:117]
	global_load_lds_dwordx4 v204, s[6:7]
	s_add_u32 m0, s9, 0xc400
	v_mfma_f32_16x16x32_bf16 v[118:121], v[188:191], v[180:183], v[118:121]
	global_load_lds_dwordx4 v205, s[6:7]
	v_mul_f32_e32 v34, s12, v34
	v_mfma_f32_16x16x32_bf16 v[122:125], v[192:195], v[180:183], v[122:125]
	s_add_u32 s4, s4, 0x80
	s_addc_u32 s5, s5, 0
	v_mfma_f32_16x16x32_bf16 v[126:129], v[196:199], v[180:183], v[126:129]
	s_add_u32 s6, s6, 0x80
	s_addc_u32 s7, s7, 0
	v_mul_f32_e32 v35, s12, v35
	s_waitcnt lgkmcnt(0)
	v_mfma_f32_16x16x32_bf16 v[66:69], v[152:155], v[136:139], v[66:69]
	ds_read_b128 v[168:171], v229 offset:0
	v_mfma_f32_16x16x32_bf16 v[70:73], v[156:159], v[136:139], v[70:73]
	ds_read_b128 v[172:175], v229 offset:2048
	v_mul_f32_e32 v36, s12, v36
	v_mfma_f32_16x16x32_bf16 v[74:77], v[160:163], v[136:139], v[74:77]
	ds_read_b128 v[176:179], v229 offset:4096
	v_mul_f32_e32 v37, s12, v37
	v_mfma_f32_16x16x32_bf16 v[78:81], v[164:167], v[136:139], v[78:81]
	ds_read_b128 v[180:183], v229 offset:6144
	v_mul_f32_e32 v38, s12, v38
	v_mfma_f32_16x16x32_bf16 v[82:85], v[152:155], v[140:143], v[82:85]
	ds_read_b128 v[184:187], v235 offset:0
	v_mfma_f32_16x16x32_bf16 v[86:89], v[156:159], v[140:143], v[86:89]
	ds_read_b128 v[188:191], v235 offset:2048
	v_mul_f32_e32 v39, s12, v39
	v_mfma_f32_16x16x32_bf16 v[90:93], v[160:163], v[140:143], v[90:93]
	ds_read_b128 v[192:195], v235 offset:4096
	v_mul_f32_e32 v40, s12, v40
	v_mfma_f32_16x16x32_bf16 v[94:97], v[164:167], v[140:143], v[94:97]
	ds_read_b128 v[196:199], v235 offset:6144
	v_mul_f32_e32 v41, s12, v41
	v_mfma_f32_16x16x32_bf16 v[98:101], v[152:155], v[144:147], v[98:101]
	v_mfma_f32_16x16x32_bf16 v[102:105], v[156:159], v[144:147], v[102:105]
	v_exp_f32_e32 v34, v34
	v_mfma_f32_16x16x32_bf16 v[106:109], v[160:163], v[144:147], v[106:109]
	v_exp_f32_e32 v35, v35
	v_mfma_f32_16x16x32_bf16 v[110:113], v[164:167], v[144:147], v[110:113]
	v_exp_f32_e32 v36, v36
	v_mfma_f32_16x16x32_bf16 v[114:117], v[152:155], v[148:151], v[114:117]
	v_mfma_f32_16x16x32_bf16 v[118:121], v[156:159], v[148:151], v[118:121]
	v_exp_f32_e32 v37, v37
	v_mfma_f32_16x16x32_bf16 v[122:125], v[160:163], v[148:151], v[122:125]
	v_exp_f32_e32 v38, v38
	v_mfma_f32_16x16x32_bf16 v[126:129], v[164:167], v[148:151], v[126:129]
	v_exp_f32_e32 v39, v39
	s_waitcnt vmcnt(7) lgkmcnt(0)
	s_barrier
	v_mfma_f32_16x16x32_bf16 v[66:69], v[184:187], v[168:171], v[66:69]
	ds_read_b128 v[136:139], v218 offset:0
	v_mfma_f32_16x16x32_bf16 v[70:73], v[188:191], v[168:171], v[70:73]
	ds_read_b128 v[140:143], v218 offset:2048
	v_mfma_f32_16x16x32_bf16 v[74:77], v[192:195], v[168:171], v[74:77]
	ds_read_b128 v[144:147], v218 offset:4096
	v_exp_f32_e32 v40, v40
	v_mfma_f32_16x16x32_bf16 v[78:81], v[196:199], v[168:171], v[78:81]
	ds_read_b128 v[148:151], v218 offset:6144
	v_mfma_f32_16x16x32_bf16 v[82:85], v[184:187], v[172:175], v[82:85]
	ds_read_b128 v[152:155], v230 offset:0
	v_exp_f32_e32 v41, v41
	v_mfma_f32_16x16x32_bf16 v[86:89], v[188:191], v[172:175], v[86:89]
	ds_read_b128 v[156:159], v230 offset:2048
	v_mfma_f32_16x16x32_bf16 v[90:93], v[192:195], v[172:175], v[90:93]
	ds_read_b128 v[160:163], v230 offset:4096
	v_add_f32_e32 v34, 1.0, v34
	v_mfma_f32_16x16x32_bf16 v[94:97], v[196:199], v[172:175], v[94:97]
	ds_read_b128 v[164:167], v230 offset:6144
	s_add_u32 m0, s8, 0x18000
	v_mfma_f32_16x16x32_bf16 v[98:101], v[184:187], v[176:179], v[98:101]
	global_load_lds_dwordx4 v200, s[4:5]
	s_add_u32 m0, s8, 0x18400
	v_mfma_f32_16x16x32_bf16 v[102:105], v[188:191], v[176:179], v[102:105]
	global_load_lds_dwordx4 v201, s[4:5]
	v_add_f32_e32 v35, 1.0, v35
	s_add_u32 m0, s8, 0x18800
	v_mfma_f32_16x16x32_bf16 v[106:109], v[192:195], v[176:179], v[106:109]
	global_load_lds_dwordx4 v202, s[4:5]
	s_add_u32 m0, s8, 0x18c00
	v_mfma_f32_16x16x32_bf16 v[110:113], v[196:199], v[176:179], v[110:113]
	global_load_lds_dwordx4 v203, s[4:5]
	v_add_f32_e32 v36, 1.0, v36
	s_add_u32 m0, s9, 0x18000
	v_mfma_f32_16x16x32_bf16 v[114:117], v[184:187], v[180:183], v[114:117]
	global_load_lds_dwordx4 v204, s[6:7]
	s_add_u32 m0, s9, 0x18400
	v_mfma_f32_16x16x32_bf16 v[118:121], v[188:191], v[180:183], v[118:121]
	global_load_lds_dwordx4 v205, s[6:7]
	v_add_f32_e32 v37, 1.0, v37
	v_mfma_f32_16x16x32_bf16 v[122:125], v[192:195], v[180:183], v[122:125]
	s_add_u32 s4, s4, 0x80
	s_addc_u32 s5, s5, 0
	v_mfma_f32_16x16x32_bf16 v[126:129], v[196:199], v[180:183], v[126:129]
	s_add_u32 s6, s6, 0x80
	s_addc_u32 s7, s7, 0
	v_add_f32_e32 v38, 1.0, v38
	s_waitcnt lgkmcnt(0)
	v_mfma_f32_16x16x32_bf16 v[66:69], v[152:155], v[136:139], v[66:69]
	ds_read_b128 v[168:171], v225 offset:0
	v_mfma_f32_16x16x32_bf16 v[70:73], v[156:159], v[136:139], v[70:73]
	ds_read_b128 v[172:175], v225 offset:2048
	v_add_f32_e32 v39, 1.0, v39
	v_mfma_f32_16x16x32_bf16 v[74:77], v[160:163], v[136:139], v[74:77]
	ds_read_b128 v[176:179], v225 offset:4096
	v_add_f32_e32 v40, 1.0, v40
	v_mfma_f32_16x16x32_bf16 v[78:81], v[164:167], v[136:139], v[78:81]
	ds_read_b128 v[180:183], v225 offset:6144
	v_add_f32_e32 v41, 1.0, v41
	v_mfma_f32_16x16x32_bf16 v[82:85], v[152:155], v[140:143], v[82:85]
	ds_read_b128 v[184:187], v233 offset:0
	v_mfma_f32_16x16x32_bf16 v[86:89], v[156:159], v[140:143], v[86:89]
	ds_read_b128 v[188:191], v233 offset:2048
	v_rcp_f32_e32 v34, v34
	v_mfma_f32_16x16x32_bf16 v[90:93], v[160:163], v[140:143], v[90:93]
	ds_read_b128 v[192:195], v233 offset:4096
	v_rcp_f32_e32 v35, v35
	v_mfma_f32_16x16x32_bf16 v[94:97], v[164:167], v[140:143], v[94:97]
	ds_read_b128 v[196:199], v233 offset:6144
	v_rcp_f32_e32 v36, v36
	v_mfma_f32_16x16x32_bf16 v[98:101], v[152:155], v[144:147], v[98:101]
	v_mfma_f32_16x16x32_bf16 v[102:105], v[156:159], v[144:147], v[102:105]
	v_rcp_f32_e32 v37, v37
	v_mfma_f32_16x16x32_bf16 v[106:109], v[160:163], v[144:147], v[106:109]
	v_rcp_f32_e32 v38, v38
	v_mfma_f32_16x16x32_bf16 v[110:113], v[164:167], v[144:147], v[110:113]
	v_rcp_f32_e32 v39, v39
	v_mfma_f32_16x16x32_bf16 v[114:117], v[152:155], v[148:151], v[114:117]
	v_mfma_f32_16x16x32_bf16 v[118:121], v[156:159], v[148:151], v[118:121]
	v_rcp_f32_e32 v40, v40
	v_mfma_f32_16x16x32_bf16 v[122:125], v[160:163], v[148:151], v[122:125]
	v_rcp_f32_e32 v41, v41
	v_mfma_f32_16x16x32_bf16 v[126:129], v[164:167], v[148:151], v[126:129]
	v_cvt_pk_bf16_f32 v34, v34, v35
	s_waitcnt vmcnt(6) lgkmcnt(0)
	s_barrier
	v_mfma_f32_16x16x32_bf16 v[66:69], v[184:187], v[168:171], v[66:69]
	ds_read_b128 v[136:139], v219 offset:0
	v_mfma_f32_16x16x32_bf16 v[70:73], v[188:191], v[168:171], v[70:73]
	ds_read_b128 v[140:143], v219 offset:2048
	v_mfma_f32_16x16x32_bf16 v[74:77], v[192:195], v[168:171], v[74:77]
	ds_read_b128 v[144:147], v219 offset:4096
	v_cvt_pk_bf16_f32 v35, v36, v37
	v_mfma_f32_16x16x32_bf16 v[78:81], v[196:199], v[168:171], v[78:81]
	ds_read_b128 v[148:151], v219 offset:6144
	v_mfma_f32_16x16x32_bf16 v[82:85], v[184:187], v[172:175], v[82:85]
	ds_read_b128 v[152:155], v231 offset:0
	v_cvt_pk_bf16_f32 v36, v38, v39
	v_mfma_f32_16x16x32_bf16 v[86:89], v[188:191], v[172:175], v[86:89]
	ds_read_b128 v[156:159], v231 offset:2048
	v_mfma_f32_16x16x32_bf16 v[90:93], v[192:195], v[172:175], v[90:93]
	ds_read_b128 v[160:163], v231 offset:4096
	v_cvt_pk_bf16_f32 v37, v40, v41
	v_mfma_f32_16x16x32_bf16 v[94:97], v[196:199], v[172:175], v[94:97]
	ds_read_b128 v[164:167], v231 offset:6144
	s_mov_b32 m0, s8
	v_mfma_f32_16x16x32_bf16 v[98:101], v[184:187], v[176:179], v[98:101]
	global_load_lds_dwordx4 v200, s[4:5]
	s_add_u32 m0, s8, 0x400
	v_mfma_f32_16x16x32_bf16 v[102:105], v[188:191], v[176:179], v[102:105]
	global_load_lds_dwordx4 v201, s[4:5]
	global_store_dwordx4 v241, v[34:37], s[10:11] offset:0 sc1
	s_add_u32 m0, s8, 0x800
	v_mfma_f32_16x16x32_bf16 v[106:109], v[192:195], v[176:179], v[106:109]
	global_load_lds_dwordx4 v202, s[4:5]
	s_add_u32 m0, s8, 0xc00
	v_mfma_f32_16x16x32_bf16 v[110:113], v[196:199], v[176:179], v[110:113]
	global_load_lds_dwordx4 v203, s[4:5]
	v_mul_f32_e32 v42, s12, v42
	s_mov_b32 m0, s9
	v_mfma_f32_16x16x32_bf16 v[114:117], v[184:187], v[180:183], v[114:117]
	global_load_lds_dwordx4 v204, s[6:7]
	s_add_u32 m0, s9, 0x400
	v_mfma_f32_16x16x32_bf16 v[118:121], v[188:191], v[180:183], v[118:121]
	global_load_lds_dwordx4 v205, s[6:7]
	v_mul_f32_e32 v43, s12, v43
	v_mfma_f32_16x16x32_bf16 v[122:125], v[192:195], v[180:183], v[122:125]
	s_add_u32 s4, s4, 0x80
	s_addc_u32 s5, s5, 0
	v_mfma_f32_16x16x32_bf16 v[126:129], v[196:199], v[180:183], v[126:129]
	s_add_u32 s6, s6, 0x80
	s_addc_u32 s7, s7, 0
	v_mul_f32_e32 v44, s12, v44
	s_waitcnt lgkmcnt(0)
	v_mfma_f32_16x16x32_bf16 v[66:69], v[152:155], v[136:139], v[66:69]
	ds_read_b128 v[168:171], v228 offset:0
	v_mfma_f32_16x16x32_bf16 v[70:73], v[156:159], v[136:139], v[70:73]
	ds_read_b128 v[172:175], v228 offset:2048
	v_mul_f32_e32 v45, s12, v45
	v_mfma_f32_16x16x32_bf16 v[74:77], v[160:163], v[136:139], v[74:77]
	ds_read_b128 v[176:179], v228 offset:4096
	v_mul_f32_e32 v46, s12, v46
	v_mfma_f32_16x16x32_bf16 v[78:81], v[164:167], v[136:139], v[78:81]
	ds_read_b128 v[180:183], v228 offset:6144
	v_mul_f32_e32 v47, s12, v47
	v_mfma_f32_16x16x32_bf16 v[82:85], v[152:155], v[140:143], v[82:85]
	ds_read_b128 v[184:187], v234 offset:0
	v_mfma_f32_16x16x32_bf16 v[86:89], v[156:159], v[140:143], v[86:89]
	ds_read_b128 v[188:191], v234 offset:2048
	v_mul_f32_e32 v48, s12, v48
	v_mfma_f32_16x16x32_bf16 v[90:93], v[160:163], v[140:143], v[90:93]
	ds_read_b128 v[192:195], v234 offset:4096
	v_mul_f32_e32 v49, s12, v49
	v_mfma_f32_16x16x32_bf16 v[94:97], v[164:167], v[140:143], v[94:97]
	ds_read_b128 v[196:199], v234 offset:6144
	v_exp_f32_e32 v42, v42
	v_mfma_f32_16x16x32_bf16 v[98:101], v[152:155], v[144:147], v[98:101]
	v_mfma_f32_16x16x32_bf16 v[102:105], v[156:159], v[144:147], v[102:105]
	v_exp_f32_e32 v43, v43
	v_mfma_f32_16x16x32_bf16 v[106:109], v[160:163], v[144:147], v[106:109]
	v_exp_f32_e32 v44, v44
	v_mfma_f32_16x16x32_bf16 v[110:113], v[164:167], v[144:147], v[110:113]
	v_exp_f32_e32 v45, v45
	v_mfma_f32_16x16x32_bf16 v[114:117], v[152:155], v[148:151], v[114:117]
	v_mfma_f32_16x16x32_bf16 v[118:121], v[156:159], v[148:151], v[118:121]
	v_exp_f32_e32 v46, v46
	v_mfma_f32_16x16x32_bf16 v[122:125], v[160:163], v[148:151], v[122:125]
	v_exp_f32_e32 v47, v47
	v_mfma_f32_16x16x32_bf16 v[126:129], v[164:167], v[148:151], v[126:129]
	v_exp_f32_e32 v48, v48
	s_waitcnt vmcnt(7) lgkmcnt(0)
	s_barrier
	v_mfma_f32_16x16x32_bf16 v[66:69], v[184:187], v[168:171], v[66:69]
	ds_read_b128 v[136:139], v224 offset:0
	v_mfma_f32_16x16x32_bf16 v[70:73], v[188:191], v[168:171], v[70:73]
	ds_read_b128 v[140:143], v224 offset:2048
	v_mfma_f32_16x16x32_bf16 v[74:77], v[192:195], v[168:171], v[74:77]
	ds_read_b128 v[144:147], v224 offset:4096
	v_exp_f32_e32 v49, v49
	v_mfma_f32_16x16x32_bf16 v[78:81], v[196:199], v[168:171], v[78:81]
	ds_read_b128 v[148:151], v224 offset:6144
	v_mfma_f32_16x16x32_bf16 v[82:85], v[184:187], v[172:175], v[82:85]
	ds_read_b128 v[152:155], v232 offset:0
	v_add_f32_e32 v42, 1.0, v42
	v_mfma_f32_16x16x32_bf16 v[86:89], v[188:191], v[172:175], v[86:89]
	ds_read_b128 v[156:159], v232 offset:2048
	v_mfma_f32_16x16x32_bf16 v[90:93], v[192:195], v[172:175], v[90:93]
	ds_read_b128 v[160:163], v232 offset:4096
	v_add_f32_e32 v43, 1.0, v43
	v_mfma_f32_16x16x32_bf16 v[94:97], v[196:199], v[172:175], v[94:97]
	ds_read_b128 v[164:167], v232 offset:6144
	s_add_u32 m0, s8, 0xc000
	v_mfma_f32_16x16x32_bf16 v[98:101], v[184:187], v[176:179], v[98:101]
	global_load_lds_dwordx4 v200, s[4:5]
	s_add_u32 m0, s8, 0xc400
	v_mfma_f32_16x16x32_bf16 v[102:105], v[188:191], v[176:179], v[102:105]
	global_load_lds_dwordx4 v201, s[4:5]
	v_add_f32_e32 v44, 1.0, v44
	s_add_u32 m0, s8, 0xc800
	v_mfma_f32_16x16x32_bf16 v[106:109], v[192:195], v[176:179], v[106:109]
	global_load_lds_dwordx4 v202, s[4:5]
	s_add_u32 m0, s8, 0xcc00
	v_mfma_f32_16x16x32_bf16 v[110:113], v[196:199], v[176:179], v[110:113]
	global_load_lds_dwordx4 v203, s[4:5]
	v_add_f32_e32 v45, 1.0, v45
	s_add_u32 m0, s9, 0xc000
	v_mfma_f32_16x16x32_bf16 v[114:117], v[184:187], v[180:183], v[114:117]
	global_load_lds_dwordx4 v204, s[6:7]
	s_add_u32 m0, s9, 0xc400
	v_mfma_f32_16x16x32_bf16 v[118:121], v[188:191], v[180:183], v[118:121]
	global_load_lds_dwordx4 v205, s[6:7]
	v_add_f32_e32 v46, 1.0, v46
	v_mfma_f32_16x16x32_bf16 v[122:125], v[192:195], v[180:183], v[122:125]
	s_add_u32 s4, s4, 0x80
	s_addc_u32 s5, s5, 0
	v_mfma_f32_16x16x32_bf16 v[126:129], v[196:199], v[180:183], v[126:129]
	s_add_u32 s6, s6, 0x80
	s_addc_u32 s7, s7, 0
	v_add_f32_e32 v47, 1.0, v47
	s_waitcnt lgkmcnt(0)
	v_mfma_f32_16x16x32_bf16 v[66:69], v[152:155], v[136:139], v[66:69]
	ds_read_b128 v[168:171], v229 offset:0
	v_mfma_f32_16x16x32_bf16 v[70:73], v[156:159], v[136:139], v[70:73]
	ds_read_b128 v[172:175], v229 offset:2048
	v_add_f32_e32 v48, 1.0, v48
	v_mfma_f32_16x16x32_bf16 v[74:77], v[160:163], v[136:139], v[74:77]
	ds_read_b128 v[176:179], v229 offset:4096
	v_add_f32_e32 v49, 1.0, v49
	v_mfma_f32_16x16x32_bf16 v[78:81], v[164:167], v[136:139], v[78:81]
	ds_read_b128 v[180:183], v229 offset:6144
	v_rcp_f32_e32 v42, v42
	v_mfma_f32_16x16x32_bf16 v[82:85], v[152:155], v[140:143], v[82:85]
	ds_read_b128 v[184:187], v235 offset:0
	v_mfma_f32_16x16x32_bf16 v[86:89], v[156:159], v[140:143], v[86:89]
	ds_read_b128 v[188:191], v235 offset:2048
	v_rcp_f32_e32 v43, v43
	v_mfma_f32_16x16x32_bf16 v[90:93], v[160:163], v[140:143], v[90:93]
	ds_read_b128 v[192:195], v235 offset:4096
	v_rcp_f32_e32 v44, v44
	v_mfma_f32_16x16x32_bf16 v[94:97], v[164:167], v[140:143], v[94:97]
	ds_read_b128 v[196:199], v235 offset:6144
	v_rcp_f32_e32 v45, v45
	v_mfma_f32_16x16x32_bf16 v[98:101], v[152:155], v[144:147], v[98:101]
	v_mfma_f32_16x16x32_bf16 v[102:105], v[156:159], v[144:147], v[102:105]
	v_rcp_f32_e32 v46, v46
	v_mfma_f32_16x16x32_bf16 v[106:109], v[160:163], v[144:147], v[106:109]
	v_rcp_f32_e32 v47, v47
	v_mfma_f32_16x16x32_bf16 v[110:113], v[164:167], v[144:147], v[110:113]
	v_rcp_f32_e32 v48, v48
	v_mfma_f32_16x16x32_bf16 v[114:117], v[152:155], v[148:151], v[114:117]
	v_mfma_f32_16x16x32_bf16 v[118:121], v[156:159], v[148:151], v[118:121]
	v_rcp_f32_e32 v49, v49
	v_mfma_f32_16x16x32_bf16 v[122:125], v[160:163], v[148:151], v[122:125]
	v_cvt_pk_bf16_f32 v42, v42, v43
	v_mfma_f32_16x16x32_bf16 v[126:129], v[164:167], v[148:151], v[126:129]
	v_cvt_pk_bf16_f32 v43, v44, v45
	s_waitcnt vmcnt(6) lgkmcnt(0)
	s_barrier
	v_mfma_f32_16x16x32_bf16 v[66:69], v[184:187], v[168:171], v[66:69]
	ds_read_b128 v[136:139], v218 offset:0
	v_mfma_f32_16x16x32_bf16 v[70:73], v[188:191], v[168:171], v[70:73]
	ds_read_b128 v[140:143], v218 offset:2048
	v_mfma_f32_16x16x32_bf16 v[74:77], v[192:195], v[168:171], v[74:77]
	ds_read_b128 v[144:147], v218 offset:4096
	v_cvt_pk_bf16_f32 v44, v46, v47
	v_mfma_f32_16x16x32_bf16 v[78:81], v[196:199], v[168:171], v[78:81]
	ds_read_b128 v[148:151], v218 offset:6144
	v_mfma_f32_16x16x32_bf16 v[82:85], v[184:187], v[172:175], v[82:85]
	ds_read_b128 v[152:155], v230 offset:0
	v_cvt_pk_bf16_f32 v45, v48, v49
	v_mfma_f32_16x16x32_bf16 v[86:89], v[188:191], v[172:175], v[86:89]
	ds_read_b128 v[156:159], v230 offset:2048
	v_mfma_f32_16x16x32_bf16 v[90:93], v[192:195], v[172:175], v[90:93]
	ds_read_b128 v[160:163], v230 offset:4096
	global_store_dwordx4 v241, v[42:45], s[10:11] offset:1024 sc1
	v_mfma_f32_16x16x32_bf16 v[94:97], v[196:199], v[172:175], v[94:97]
	ds_read_b128 v[164:167], v230 offset:6144
	s_add_u32 m0, s8, 0x18000
	v_mfma_f32_16x16x32_bf16 v[98:101], v[184:187], v[176:179], v[98:101]
	global_load_lds_dwordx4 v200, s[4:5]
	s_add_u32 m0, s8, 0x18400
	v_mfma_f32_16x16x32_bf16 v[102:105], v[188:191], v[176:179], v[102:105]
	global_load_lds_dwordx4 v201, s[4:5]
	v_mul_f32_e32 v50, s12, v50
	s_add_u32 m0, s8, 0x18800
	v_mfma_f32_16x16x32_bf16 v[106:109], v[192:195], v[176:179], v[106:109]
	global_load_lds_dwordx4 v202, s[4:5]
	s_add_u32 m0, s8, 0x18c00
	v_mfma_f32_16x16x32_bf16 v[110:113], v[196:199], v[176:179], v[110:113]
	global_load_lds_dwordx4 v203, s[4:5]
	v_mul_f32_e32 v51, s12, v51
	s_add_u32 m0, s9, 0x18000
	v_mfma_f32_16x16x32_bf16 v[114:117], v[184:187], v[180:183], v[114:117]
	global_load_lds_dwordx4 v204, s[6:7]
	s_add_u32 m0, s9, 0x18400
	v_mfma_f32_16x16x32_bf16 v[118:121], v[188:191], v[180:183], v[118:121]
	global_load_lds_dwordx4 v205, s[6:7]
	v_mul_f32_e32 v52, s12, v52
	v_mfma_f32_16x16x32_bf16 v[122:125], v[192:195], v[180:183], v[122:125]
	s_add_u32 s4, s4, 0x80
	s_addc_u32 s5, s5, 0
	v_mfma_f32_16x16x32_bf16 v[126:129], v[196:199], v[180:183], v[126:129]
	s_add_u32 s6, s6, 0x80
	s_addc_u32 s7, s7, 0
	v_mul_f32_e32 v53, s12, v53
	s_waitcnt lgkmcnt(0)
	v_mfma_f32_16x16x32_bf16 v[66:69], v[152:155], v[136:139], v[66:69]
	ds_read_b128 v[168:171], v225 offset:0
	v_mfma_f32_16x16x32_bf16 v[70:73], v[156:159], v[136:139], v[70:73]
	ds_read_b128 v[172:175], v225 offset:2048
	v_mul_f32_e32 v54, s12, v54
	v_mfma_f32_16x16x32_bf16 v[74:77], v[160:163], v[136:139], v[74:77]
	ds_read_b128 v[176:179], v225 offset:4096
	v_mul_f32_e32 v55, s12, v55
	v_mfma_f32_16x16x32_bf16 v[78:81], v[164:167], v[136:139], v[78:81]
	ds_read_b128 v[180:183], v225 offset:6144
	v_mul_f32_e32 v56, s12, v56
	v_mfma_f32_16x16x32_bf16 v[82:85], v[152:155], v[140:143], v[82:85]
	ds_read_b128 v[184:187], v233 offset:0
	v_mfma_f32_16x16x32_bf16 v[86:89], v[156:159], v[140:143], v[86:89]
	ds_read_b128 v[188:191], v233 offset:2048
	v_mul_f32_e32 v57, s12, v57
	v_mfma_f32_16x16x32_bf16 v[90:93], v[160:163], v[140:143], v[90:93]
	ds_read_b128 v[192:195], v233 offset:4096
	v_exp_f32_e32 v50, v50
	v_mfma_f32_16x16x32_bf16 v[94:97], v[164:167], v[140:143], v[94:97]
	ds_read_b128 v[196:199], v233 offset:6144
	v_exp_f32_e32 v51, v51
	v_mfma_f32_16x16x32_bf16 v[98:101], v[152:155], v[144:147], v[98:101]
	v_mfma_f32_16x16x32_bf16 v[102:105], v[156:159], v[144:147], v[102:105]
	v_exp_f32_e32 v52, v52
	v_mfma_f32_16x16x32_bf16 v[106:109], v[160:163], v[144:147], v[106:109]
	v_exp_f32_e32 v53, v53
	v_mfma_f32_16x16x32_bf16 v[110:113], v[164:167], v[144:147], v[110:113]
	v_exp_f32_e32 v54, v54
	v_mfma_f32_16x16x32_bf16 v[114:117], v[152:155], v[148:151], v[114:117]
	v_mfma_f32_16x16x32_bf16 v[118:121], v[156:159], v[148:151], v[118:121]
	v_exp_f32_e32 v55, v55
	v_mfma_f32_16x16x32_bf16 v[122:125], v[160:163], v[148:151], v[122:125]
	v_exp_f32_e32 v56, v56
	v_mfma_f32_16x16x32_bf16 v[126:129], v[164:167], v[148:151], v[126:129]
	v_exp_f32_e32 v57, v57
	s_waitcnt vmcnt(7) lgkmcnt(0)
	s_barrier
	v_mfma_f32_16x16x32_bf16 v[66:69], v[184:187], v[168:171], v[66:69]
	ds_read_b128 v[136:139], v219 offset:0
	v_mfma_f32_16x16x32_bf16 v[70:73], v[188:191], v[168:171], v[70:73]
	ds_read_b128 v[140:143], v219 offset:2048
	v_mfma_f32_16x16x32_bf16 v[74:77], v[192:195], v[168:171], v[74:77]
	ds_read_b128 v[144:147], v219 offset:4096
	v_add_f32_e32 v50, 1.0, v50
	v_mfma_f32_16x16x32_bf16 v[78:81], v[196:199], v[168:171], v[78:81]
	ds_read_b128 v[148:151], v219 offset:6144
	v_mfma_f32_16x16x32_bf16 v[82:85], v[184:187], v[172:175], v[82:85]
	ds_read_b128 v[152:155], v231 offset:0
	v_add_f32_e32 v51, 1.0, v51
	v_mfma_f32_16x16x32_bf16 v[86:89], v[188:191], v[172:175], v[86:89]
	ds_read_b128 v[156:159], v231 offset:2048
	v_mfma_f32_16x16x32_bf16 v[90:93], v[192:195], v[172:175], v[90:93]
	ds_read_b128 v[160:163], v231 offset:4096
	v_add_f32_e32 v52, 1.0, v52
	v_mfma_f32_16x16x32_bf16 v[94:97], v[196:199], v[172:175], v[94:97]
	ds_read_b128 v[164:167], v231 offset:6144
	s_mov_b32 m0, s8
	v_mfma_f32_16x16x32_bf16 v[98:101], v[184:187], v[176:179], v[98:101]
	global_load_lds_dwordx4 v200, s[4:5]
	s_add_u32 m0, s8, 0x400
	v_mfma_f32_16x16x32_bf16 v[102:105], v[188:191], v[176:179], v[102:105]
	global_load_lds_dwordx4 v201, s[4:5]
	v_add_f32_e32 v53, 1.0, v53
	s_add_u32 m0, s8, 0x800
	v_mfma_f32_16x16x32_bf16 v[106:109], v[192:195], v[176:179], v[106:109]
	global_load_lds_dwordx4 v202, s[4:5]
	s_add_u32 m0, s8, 0xc00
	v_mfma_f32_16x16x32_bf16 v[110:113], v[196:199], v[176:179], v[110:113]
	global_load_lds_dwordx4 v203, s[4:5]
	v_add_f32_e32 v54, 1.0, v54
	s_mov_b32 m0, s9
	v_mfma_f32_16x16x32_bf16 v[114:117], v[184:187], v[180:183], v[114:117]
	global_load_lds_dwordx4 v204, s[6:7]
	s_add_u32 m0, s9, 0x400
	v_mfma_f32_16x16x32_bf16 v[118:121], v[188:191], v[180:183], v[118:121]
	global_load_lds_dwordx4 v205, s[6:7]
	v_add_f32_e32 v55, 1.0, v55
	v_mfma_f32_16x16x32_bf16 v[122:125], v[192:195], v[180:183], v[122:125]
	s_sub_u32 s4, s4, 0x780
	s_subb_u32 s5, s5, 0
	v_mfma_f32_16x16x32_bf16 v[126:129], v[196:199], v[180:183], v[126:129]
	s_add_u32 s6, s6, 0x3f880
	s_addc_u32 s7, s7, 0
	v_add_f32_e32 v56, 1.0, v56
	s_waitcnt lgkmcnt(0)
	v_mfma_f32_16x16x32_bf16 v[66:69], v[152:155], v[136:139], v[66:69]
	ds_read_b128 v[168:171], v228 offset:0
	v_mfma_f32_16x16x32_bf16 v[70:73], v[156:159], v[136:139], v[70:73]
	ds_read_b128 v[172:175], v228 offset:2048
	v_add_f32_e32 v57, 1.0, v57
	v_mfma_f32_16x16x32_bf16 v[74:77], v[160:163], v[136:139], v[74:77]
	ds_read_b128 v[176:179], v228 offset:4096
	v_rcp_f32_e32 v50, v50
	v_mfma_f32_16x16x32_bf16 v[78:81], v[164:167], v[136:139], v[78:81]
	ds_read_b128 v[180:183], v228 offset:6144
	v_rcp_f32_e32 v51, v51
	v_mfma_f32_16x16x32_bf16 v[82:85], v[152:155], v[140:143], v[82:85]
	ds_read_b128 v[184:187], v234 offset:0
	v_mfma_f32_16x16x32_bf16 v[86:89], v[156:159], v[140:143], v[86:89]
	ds_read_b128 v[188:191], v234 offset:2048
	v_rcp_f32_e32 v52, v52
	v_mfma_f32_16x16x32_bf16 v[90:93], v[160:163], v[140:143], v[90:93]
	ds_read_b128 v[192:195], v234 offset:4096
	v_rcp_f32_e32 v53, v53
	v_mfma_f32_16x16x32_bf16 v[94:97], v[164:167], v[140:143], v[94:97]
	ds_read_b128 v[196:199], v234 offset:6144
	v_rcp_f32_e32 v54, v54
	v_mfma_f32_16x16x32_bf16 v[98:101], v[152:155], v[144:147], v[98:101]
	v_mfma_f32_16x16x32_bf16 v[102:105], v[156:159], v[144:147], v[102:105]
	v_rcp_f32_e32 v55, v55
	v_mfma_f32_16x16x32_bf16 v[106:109], v[160:163], v[144:147], v[106:109]
	v_rcp_f32_e32 v56, v56
	v_mfma_f32_16x16x32_bf16 v[110:113], v[164:167], v[144:147], v[110:113]
	v_rcp_f32_e32 v57, v57
	v_mfma_f32_16x16x32_bf16 v[114:117], v[152:155], v[148:151], v[114:117]
	v_mfma_f32_16x16x32_bf16 v[118:121], v[156:159], v[148:151], v[118:121]
	v_cvt_pk_bf16_f32 v50, v50, v51
	v_mfma_f32_16x16x32_bf16 v[122:125], v[160:163], v[148:151], v[122:125]
	v_cvt_pk_bf16_f32 v51, v52, v53
	v_mfma_f32_16x16x32_bf16 v[126:129], v[164:167], v[148:151], v[126:129]
	v_cvt_pk_bf16_f32 v52, v54, v55
	s_waitcnt vmcnt(6) lgkmcnt(0)
	s_barrier
	v_mfma_f32_16x16x32_bf16 v[66:69], v[184:187], v[168:171], v[66:69]
	ds_read_b128 v[136:139], v224 offset:0
	v_mfma_f32_16x16x32_bf16 v[70:73], v[188:191], v[168:171], v[70:73]
	ds_read_b128 v[140:143], v224 offset:2048
	v_mfma_f32_16x16x32_bf16 v[74:77], v[192:195], v[168:171], v[74:77]
	ds_read_b128 v[144:147], v224 offset:4096
	v_cvt_pk_bf16_f32 v53, v56, v57
	v_mfma_f32_16x16x32_bf16 v[78:81], v[196:199], v[168:171], v[78:81]
	ds_read_b128 v[148:151], v224 offset:6144
	v_mfma_f32_16x16x32_bf16 v[82:85], v[184:187], v[172:175], v[82:85]
	ds_read_b128 v[152:155], v232 offset:0
	global_store_dwordx4 v241, v[50:53], s[10:11] offset:2048 sc1
	v_mfma_f32_16x16x32_bf16 v[86:89], v[188:191], v[172:175], v[86:89]
	ds_read_b128 v[156:159], v232 offset:2048
	v_mfma_f32_16x16x32_bf16 v[90:93], v[192:195], v[172:175], v[90:93]
	ds_read_b128 v[160:163], v232 offset:4096
	v_mul_f32_e32 v58, s12, v58
	v_mfma_f32_16x16x32_bf16 v[94:97], v[196:199], v[172:175], v[94:97]
	ds_read_b128 v[164:167], v232 offset:6144
	v_mfma_f32_16x16x32_bf16 v[98:101], v[184:187], v[176:179], v[98:101]
	v_mfma_f32_16x16x32_bf16 v[102:105], v[188:191], v[176:179], v[102:105]
	v_mul_f32_e32 v59, s12, v59
	v_mfma_f32_16x16x32_bf16 v[106:109], v[192:195], v[176:179], v[106:109]
	v_mfma_f32_16x16x32_bf16 v[110:113], v[196:199], v[176:179], v[110:113]
	v_mul_f32_e32 v60, s12, v60
	v_mfma_f32_16x16x32_bf16 v[114:117], v[184:187], v[180:183], v[114:117]
	v_mfma_f32_16x16x32_bf16 v[118:121], v[188:191], v[180:183], v[118:121]
	v_mul_f32_e32 v61, s12, v61
	v_mfma_f32_16x16x32_bf16 v[122:125], v[192:195], v[180:183], v[122:125]
	v_mfma_f32_16x16x32_bf16 v[126:129], v[196:199], v[180:183], v[126:129]
	v_mul_f32_e32 v62, s12, v62
	s_waitcnt lgkmcnt(0)
	v_mfma_f32_16x16x32_bf16 v[66:69], v[152:155], v[136:139], v[66:69]
	ds_read_b128 v[168:171], v229 offset:0
	v_mfma_f32_16x16x32_bf16 v[70:73], v[156:159], v[136:139], v[70:73]
	ds_read_b128 v[172:175], v229 offset:2048
	v_mul_f32_e32 v63, s12, v63
	v_mfma_f32_16x16x32_bf16 v[74:77], v[160:163], v[136:139], v[74:77]
	ds_read_b128 v[176:179], v229 offset:4096
	v_mul_f32_e32 v64, s12, v64
	v_mfma_f32_16x16x32_bf16 v[78:81], v[164:167], v[136:139], v[78:81]
	ds_read_b128 v[180:183], v229 offset:6144
	v_mul_f32_e32 v65, s12, v65
	v_mfma_f32_16x16x32_bf16 v[82:85], v[152:155], v[140:143], v[82:85]
	ds_read_b128 v[184:187], v235 offset:0
	v_mfma_f32_16x16x32_bf16 v[86:89], v[156:159], v[140:143], v[86:89]
	ds_read_b128 v[188:191], v235 offset:2048
	v_exp_f32_e32 v58, v58
	v_mfma_f32_16x16x32_bf16 v[90:93], v[160:163], v[140:143], v[90:93]
	ds_read_b128 v[192:195], v235 offset:4096
	v_exp_f32_e32 v59, v59
	v_mfma_f32_16x16x32_bf16 v[94:97], v[164:167], v[140:143], v[94:97]
	ds_read_b128 v[196:199], v235 offset:6144
	v_exp_f32_e32 v60, v60
	v_mfma_f32_16x16x32_bf16 v[98:101], v[152:155], v[144:147], v[98:101]
	v_mfma_f32_16x16x32_bf16 v[102:105], v[156:159], v[144:147], v[102:105]
	v_exp_f32_e32 v61, v61
	v_mfma_f32_16x16x32_bf16 v[106:109], v[160:163], v[144:147], v[106:109]
	v_exp_f32_e32 v62, v62
	v_mfma_f32_16x16x32_bf16 v[110:113], v[164:167], v[144:147], v[110:113]
	v_exp_f32_e32 v63, v63
	v_mfma_f32_16x16x32_bf16 v[114:117], v[152:155], v[148:151], v[114:117]
	v_mfma_f32_16x16x32_bf16 v[118:121], v[156:159], v[148:151], v[118:121]
	v_exp_f32_e32 v64, v64
	v_mfma_f32_16x16x32_bf16 v[122:125], v[160:163], v[148:151], v[122:125]
	v_exp_f32_e32 v65, v65
	v_mfma_f32_16x16x32_bf16 v[126:129], v[164:167], v[148:151], v[126:129]
	v_add_f32_e32 v58, 1.0, v58
	s_waitcnt vmcnt(1) lgkmcnt(0)
	s_barrier
	v_mfma_f32_16x16x32_bf16 v[66:69], v[184:187], v[168:171], v[66:69]
	ds_read_b128 v[136:139], v218 offset:0
	v_mfma_f32_16x16x32_bf16 v[70:73], v[188:191], v[168:171], v[70:73]
	ds_read_b128 v[140:143], v218 offset:2048
	v_mfma_f32_16x16x32_bf16 v[74:77], v[192:195], v[168:171], v[74:77]
	ds_read_b128 v[144:147], v218 offset:4096
	v_add_f32_e32 v59, 1.0, v59
	v_mfma_f32_16x16x32_bf16 v[78:81], v[196:199], v[168:171], v[78:81]
	ds_read_b128 v[148:151], v218 offset:6144
	v_mfma_f32_16x16x32_bf16 v[82:85], v[184:187], v[172:175], v[82:85]
	ds_read_b128 v[152:155], v230 offset:0
	v_add_f32_e32 v60, 1.0, v60
	v_mfma_f32_16x16x32_bf16 v[86:89], v[188:191], v[172:175], v[86:89]
	ds_read_b128 v[156:159], v230 offset:2048
	v_mfma_f32_16x16x32_bf16 v[90:93], v[192:195], v[172:175], v[90:93]
	ds_read_b128 v[160:163], v230 offset:4096
	v_add_f32_e32 v61, 1.0, v61
	v_mfma_f32_16x16x32_bf16 v[94:97], v[196:199], v[172:175], v[94:97]
	ds_read_b128 v[164:167], v230 offset:6144
	v_mfma_f32_16x16x32_bf16 v[98:101], v[184:187], v[176:179], v[98:101]
	v_mfma_f32_16x16x32_bf16 v[102:105], v[188:191], v[176:179], v[102:105]
	v_add_f32_e32 v62, 1.0, v62
	v_mfma_f32_16x16x32_bf16 v[106:109], v[192:195], v[176:179], v[106:109]
	v_mfma_f32_16x16x32_bf16 v[110:113], v[196:199], v[176:179], v[110:113]
	v_add_f32_e32 v63, 1.0, v63
	v_mfma_f32_16x16x32_bf16 v[114:117], v[184:187], v[180:183], v[114:117]
	v_mfma_f32_16x16x32_bf16 v[118:121], v[188:191], v[180:183], v[118:121]
	v_add_f32_e32 v64, 1.0, v64
	v_mfma_f32_16x16x32_bf16 v[122:125], v[192:195], v[180:183], v[122:125]
	v_mfma_f32_16x16x32_bf16 v[126:129], v[196:199], v[180:183], v[126:129]
	v_add_f32_e32 v65, 1.0, v65
	s_waitcnt lgkmcnt(0)
	v_mfma_f32_16x16x32_bf16 v[66:69], v[152:155], v[136:139], v[66:69]
	ds_read_b128 v[168:171], v225 offset:0
	v_mfma_f32_16x16x32_bf16 v[70:73], v[156:159], v[136:139], v[70:73]
	ds_read_b128 v[172:175], v225 offset:2048
	v_rcp_f32_e32 v58, v58
	v_mfma_f32_16x16x32_bf16 v[74:77], v[160:163], v[136:139], v[74:77]
	ds_read_b128 v[176:179], v225 offset:4096
	v_rcp_f32_e32 v59, v59
	v_mfma_f32_16x16x32_bf16 v[78:81], v[164:167], v[136:139], v[78:81]
	ds_read_b128 v[180:183], v225 offset:6144
	v_rcp_f32_e32 v60, v60
	v_mfma_f32_16x16x32_bf16 v[82:85], v[152:155], v[140:143], v[82:85]
	ds_read_b128 v[184:187], v233 offset:0
	v_mfma_f32_16x16x32_bf16 v[86:89], v[156:159], v[140:143], v[86:89]
	ds_read_b128 v[188:191], v233 offset:2048
	v_rcp_f32_e32 v61, v61
	v_mfma_f32_16x16x32_bf16 v[90:93], v[160:163], v[140:143], v[90:93]
	ds_read_b128 v[192:195], v233 offset:4096
	v_rcp_f32_e32 v62, v62
	v_mfma_f32_16x16x32_bf16 v[94:97], v[164:167], v[140:143], v[94:97]
	ds_read_b128 v[196:199], v233 offset:6144
	v_rcp_f32_e32 v63, v63
	v_mfma_f32_16x16x32_bf16 v[98:101], v[152:155], v[144:147], v[98:101]
	v_mfma_f32_16x16x32_bf16 v[102:105], v[156:159], v[144:147], v[102:105]
	v_rcp_f32_e32 v64, v64
	v_mfma_f32_16x16x32_bf16 v[106:109], v[160:163], v[144:147], v[106:109]
	v_rcp_f32_e32 v65, v65
	v_mfma_f32_16x16x32_bf16 v[110:113], v[164:167], v[144:147], v[110:113]
	v_cvt_pk_bf16_f32 v58, v58, v59
	v_mfma_f32_16x16x32_bf16 v[114:117], v[152:155], v[148:151], v[114:117]
	v_mfma_f32_16x16x32_bf16 v[118:121], v[156:159], v[148:151], v[118:121]
	v_cvt_pk_bf16_f32 v59, v60, v61
	v_mfma_f32_16x16x32_bf16 v[122:125], v[160:163], v[148:151], v[122:125]
	v_cvt_pk_bf16_f32 v60, v62, v63
	v_mfma_f32_16x16x32_bf16 v[126:129], v[164:167], v[148:151], v[126:129]
	v_cvt_pk_bf16_f32 v61, v64, v65
	s_waitcnt lgkmcnt(0)
	v_mfma_f32_16x16x32_bf16 v[66:69], v[184:187], v[168:171], v[66:69]
	v_mfma_f32_16x16x32_bf16 v[70:73], v[188:191], v[168:171], v[70:73]
	v_mfma_f32_16x16x32_bf16 v[74:77], v[192:195], v[168:171], v[74:77]
	v_mfma_f32_16x16x32_bf16 v[78:81], v[196:199], v[168:171], v[78:81]
	v_mfma_f32_16x16x32_bf16 v[82:85], v[184:187], v[172:175], v[82:85]
	v_mfma_f32_16x16x32_bf16 v[86:89], v[188:191], v[172:175], v[86:89]
	v_mfma_f32_16x16x32_bf16 v[90:93], v[192:195], v[172:175], v[90:93]
	v_mfma_f32_16x16x32_bf16 v[94:97], v[196:199], v[172:175], v[94:97]
	v_mfma_f32_16x16x32_bf16 v[98:101], v[184:187], v[176:179], v[98:101]
	v_mfma_f32_16x16x32_bf16 v[102:105], v[188:191], v[176:179], v[102:105]
	v_mfma_f32_16x16x32_bf16 v[106:109], v[192:195], v[176:179], v[106:109]
	v_mfma_f32_16x16x32_bf16 v[110:113], v[196:199], v[176:179], v[110:113]
	v_mfma_f32_16x16x32_bf16 v[114:117], v[184:187], v[180:183], v[114:117]
	v_mfma_f32_16x16x32_bf16 v[118:121], v[188:191], v[180:183], v[118:121]
	v_mfma_f32_16x16x32_bf16 v[122:125], v[192:195], v[180:183], v[122:125]
	v_mfma_f32_16x16x32_bf16 v[126:129], v[196:199], v[180:183], v[126:129]
	global_store_dwordx4 v241, v[58:61], s[10:11] offset:3072 sc1
	s_add_u32 s10, s28, s13
	s_addc_u32 s11, s29, 0
	s_add_u32 s13, s13, 0x10000
	v_mul_f32_e32 v66, s12, v66
	v_mul_f32_e32 v67, s12, v67
	v_mul_f32_e32 v68, s12, v68
	v_mul_f32_e32 v69, s12, v69
	v_mul_f32_e32 v70, s12, v70
	v_mul_f32_e32 v71, s12, v71
	v_mul_f32_e32 v72, s12, v72
	v_mul_f32_e32 v73, s12, v73
	v_exp_f32_e32 v66, v66
	v_exp_f32_e32 v67, v67
	v_exp_f32_e32 v68, v68
	v_exp_f32_e32 v69, v69
	v_exp_f32_e32 v70, v70
	v_exp_f32_e32 v71, v71
	v_exp_f32_e32 v72, v72
	v_exp_f32_e32 v73, v73
	v_add_f32_e32 v66, 1.0, v66
	v_add_f32_e32 v67, 1.0, v67
	v_add_f32_e32 v68, 1.0, v68
	v_add_f32_e32 v69, 1.0, v69
	v_add_f32_e32 v70, 1.0, v70
	v_add_f32_e32 v71, 1.0, v71
	v_add_f32_e32 v72, 1.0, v72
	v_add_f32_e32 v73, 1.0, v73
	v_rcp_f32_e32 v66, v66
	v_rcp_f32_e32 v67, v67
	v_rcp_f32_e32 v68, v68
	v_rcp_f32_e32 v69, v69
	v_rcp_f32_e32 v70, v70
	v_rcp_f32_e32 v71, v71
	v_rcp_f32_e32 v72, v72
	v_rcp_f32_e32 v73, v73
	v_cvt_pk_bf16_f32 v66, v66, v67
	v_cvt_pk_bf16_f32 v67, v68, v69
	v_cvt_pk_bf16_f32 v68, v70, v71
	v_cvt_pk_bf16_f32 v69, v72, v73
	global_store_dwordx4 v240, v[66:69], s[10:11] offset:0 sc1
	v_mul_f32_e32 v74, s12, v74
	v_mul_f32_e32 v75, s12, v75
	v_mul_f32_e32 v76, s12, v76
	v_mul_f32_e32 v77, s12, v77
	v_mul_f32_e32 v78, s12, v78
	v_mul_f32_e32 v79, s12, v79
	v_mul_f32_e32 v80, s12, v80
	v_mul_f32_e32 v81, s12, v81
	v_exp_f32_e32 v74, v74
	v_exp_f32_e32 v75, v75
	v_exp_f32_e32 v76, v76
	v_exp_f32_e32 v77, v77
	v_exp_f32_e32 v78, v78
	v_exp_f32_e32 v79, v79
	v_exp_f32_e32 v80, v80
	v_exp_f32_e32 v81, v81
	v_add_f32_e32 v74, 1.0, v74
	v_add_f32_e32 v75, 1.0, v75
	v_add_f32_e32 v76, 1.0, v76
	v_add_f32_e32 v77, 1.0, v77
	v_add_f32_e32 v78, 1.0, v78
	v_add_f32_e32 v79, 1.0, v79
	v_add_f32_e32 v80, 1.0, v80
	v_add_f32_e32 v81, 1.0, v81
	v_rcp_f32_e32 v74, v74
	v_rcp_f32_e32 v75, v75
	v_rcp_f32_e32 v76, v76
	v_rcp_f32_e32 v77, v77
	v_rcp_f32_e32 v78, v78
	v_rcp_f32_e32 v79, v79
	v_rcp_f32_e32 v80, v80
	v_rcp_f32_e32 v81, v81
	v_cvt_pk_bf16_f32 v74, v74, v75
	v_cvt_pk_bf16_f32 v75, v76, v77
	v_cvt_pk_bf16_f32 v76, v78, v79
	v_cvt_pk_bf16_f32 v77, v80, v81
	global_store_dwordx4 v240, v[74:77], s[10:11] offset:1024 sc1
	v_mul_f32_e32 v82, s12, v82
	v_mul_f32_e32 v83, s12, v83
	v_mul_f32_e32 v84, s12, v84
	v_mul_f32_e32 v85, s12, v85
	v_mul_f32_e32 v86, s12, v86
	v_mul_f32_e32 v87, s12, v87
	v_mul_f32_e32 v88, s12, v88
	v_mul_f32_e32 v89, s12, v89
	v_exp_f32_e32 v82, v82
	v_exp_f32_e32 v83, v83
	v_exp_f32_e32 v84, v84
	v_exp_f32_e32 v85, v85
	v_exp_f32_e32 v86, v86
	v_exp_f32_e32 v87, v87
	v_exp_f32_e32 v88, v88
	v_exp_f32_e32 v89, v89
	v_add_f32_e32 v82, 1.0, v82
	v_add_f32_e32 v83, 1.0, v83
	v_add_f32_e32 v84, 1.0, v84
	v_add_f32_e32 v85, 1.0, v85
	v_add_f32_e32 v86, 1.0, v86
	v_add_f32_e32 v87, 1.0, v87
	v_add_f32_e32 v88, 1.0, v88
	v_add_f32_e32 v89, 1.0, v89
	v_rcp_f32_e32 v82, v82
	v_rcp_f32_e32 v83, v83
	v_rcp_f32_e32 v84, v84
	v_rcp_f32_e32 v85, v85
	v_rcp_f32_e32 v86, v86
	v_rcp_f32_e32 v87, v87
	v_rcp_f32_e32 v88, v88
	v_rcp_f32_e32 v89, v89
	v_cvt_pk_bf16_f32 v82, v82, v83
	v_cvt_pk_bf16_f32 v83, v84, v85
	v_cvt_pk_bf16_f32 v84, v86, v87
	v_cvt_pk_bf16_f32 v85, v88, v89
	global_store_dwordx4 v240, v[82:85], s[10:11] offset:2048 sc1
	v_mul_f32_e32 v90, s12, v90
	v_mul_f32_e32 v91, s12, v91
	v_mul_f32_e32 v92, s12, v92
	v_mul_f32_e32 v93, s12, v93
	v_mul_f32_e32 v94, s12, v94
	v_mul_f32_e32 v95, s12, v95
	v_mul_f32_e32 v96, s12, v96
	v_mul_f32_e32 v97, s12, v97
	v_exp_f32_e32 v90, v90
	v_exp_f32_e32 v91, v91
	v_exp_f32_e32 v92, v92
	v_exp_f32_e32 v93, v93
	v_exp_f32_e32 v94, v94
	v_exp_f32_e32 v95, v95
	v_exp_f32_e32 v96, v96
	v_exp_f32_e32 v97, v97
	v_add_f32_e32 v90, 1.0, v90
	v_add_f32_e32 v91, 1.0, v91
	v_add_f32_e32 v92, 1.0, v92
	v_add_f32_e32 v93, 1.0, v93
	v_add_f32_e32 v94, 1.0, v94
	v_add_f32_e32 v95, 1.0, v95
	v_add_f32_e32 v96, 1.0, v96
	v_add_f32_e32 v97, 1.0, v97
	v_rcp_f32_e32 v90, v90
	v_rcp_f32_e32 v91, v91
	v_rcp_f32_e32 v92, v92
	v_rcp_f32_e32 v93, v93
	v_rcp_f32_e32 v94, v94
	v_rcp_f32_e32 v95, v95
	v_rcp_f32_e32 v96, v96
	v_rcp_f32_e32 v97, v97
	v_cvt_pk_bf16_f32 v90, v90, v91
	v_cvt_pk_bf16_f32 v91, v92, v93
	v_cvt_pk_bf16_f32 v92, v94, v95
	v_cvt_pk_bf16_f32 v93, v96, v97
	global_store_dwordx4 v240, v[90:93], s[10:11] offset:3072 sc1
	v_mul_f32_e32 v98, s12, v98
	v_mul_f32_e32 v99, s12, v99
	v_mul_f32_e32 v100, s12, v100
	v_mul_f32_e32 v101, s12, v101
	v_mul_f32_e32 v102, s12, v102
	v_mul_f32_e32 v103, s12, v103
	v_mul_f32_e32 v104, s12, v104
	v_mul_f32_e32 v105, s12, v105
	v_exp_f32_e32 v98, v98
	v_exp_f32_e32 v99, v99
	v_exp_f32_e32 v100, v100
	v_exp_f32_e32 v101, v101
	v_exp_f32_e32 v102, v102
	v_exp_f32_e32 v103, v103
	v_exp_f32_e32 v104, v104
	v_exp_f32_e32 v105, v105
	v_add_f32_e32 v98, 1.0, v98
	v_add_f32_e32 v99, 1.0, v99
	v_add_f32_e32 v100, 1.0, v100
	v_add_f32_e32 v101, 1.0, v101
	v_add_f32_e32 v102, 1.0, v102
	v_add_f32_e32 v103, 1.0, v103
	v_add_f32_e32 v104, 1.0, v104
	v_add_f32_e32 v105, 1.0, v105
	v_rcp_f32_e32 v98, v98
	v_rcp_f32_e32 v99, v99
	v_rcp_f32_e32 v100, v100
	v_rcp_f32_e32 v101, v101
	v_rcp_f32_e32 v102, v102
	v_rcp_f32_e32 v103, v103
	v_rcp_f32_e32 v104, v104
	v_rcp_f32_e32 v105, v105
	v_cvt_pk_bf16_f32 v98, v98, v99
	v_cvt_pk_bf16_f32 v99, v100, v101
	v_cvt_pk_bf16_f32 v100, v102, v103
	v_cvt_pk_bf16_f32 v101, v104, v105
	global_store_dwordx4 v241, v[98:101], s[10:11] offset:0 sc1
	v_mul_f32_e32 v106, s12, v106
	v_mul_f32_e32 v107, s12, v107
	v_mul_f32_e32 v108, s12, v108
	v_mul_f32_e32 v109, s12, v109
	v_mul_f32_e32 v110, s12, v110
	v_mul_f32_e32 v111, s12, v111
	v_mul_f32_e32 v112, s12, v112
	v_mul_f32_e32 v113, s12, v113
	v_exp_f32_e32 v106, v106
	v_exp_f32_e32 v107, v107
	v_exp_f32_e32 v108, v108
	v_exp_f32_e32 v109, v109
	v_exp_f32_e32 v110, v110
	v_exp_f32_e32 v111, v111
	v_exp_f32_e32 v112, v112
	v_exp_f32_e32 v113, v113
	v_add_f32_e32 v106, 1.0, v106
	v_add_f32_e32 v107, 1.0, v107
	v_add_f32_e32 v108, 1.0, v108
	v_add_f32_e32 v109, 1.0, v109
	v_add_f32_e32 v110, 1.0, v110
	v_add_f32_e32 v111, 1.0, v111
	v_add_f32_e32 v112, 1.0, v112
	v_add_f32_e32 v113, 1.0, v113
	v_rcp_f32_e32 v106, v106
	v_rcp_f32_e32 v107, v107
	v_rcp_f32_e32 v108, v108
	v_rcp_f32_e32 v109, v109
	v_rcp_f32_e32 v110, v110
	v_rcp_f32_e32 v111, v111
	v_rcp_f32_e32 v112, v112
	v_rcp_f32_e32 v113, v113
	v_cvt_pk_bf16_f32 v106, v106, v107
	v_cvt_pk_bf16_f32 v107, v108, v109
	v_cvt_pk_bf16_f32 v108, v110, v111
	v_cvt_pk_bf16_f32 v109, v112, v113
	global_store_dwordx4 v241, v[106:109], s[10:11] offset:1024 sc1
	v_mul_f32_e32 v114, s12, v114
	v_mul_f32_e32 v115, s12, v115
	v_mul_f32_e32 v116, s12, v116
	v_mul_f32_e32 v117, s12, v117
	v_mul_f32_e32 v118, s12, v118
	v_mul_f32_e32 v119, s12, v119
	v_mul_f32_e32 v120, s12, v120
	v_mul_f32_e32 v121, s12, v121
	v_exp_f32_e32 v114, v114
	v_exp_f32_e32 v115, v115
	v_exp_f32_e32 v116, v116
	v_exp_f32_e32 v117, v117
	v_exp_f32_e32 v118, v118
	v_exp_f32_e32 v119, v119
	v_exp_f32_e32 v120, v120
	v_exp_f32_e32 v121, v121
	v_add_f32_e32 v114, 1.0, v114
	v_add_f32_e32 v115, 1.0, v115
	v_add_f32_e32 v116, 1.0, v116
	v_add_f32_e32 v117, 1.0, v117
	v_add_f32_e32 v118, 1.0, v118
	v_add_f32_e32 v119, 1.0, v119
	v_add_f32_e32 v120, 1.0, v120
	v_add_f32_e32 v121, 1.0, v121
	v_rcp_f32_e32 v114, v114
	v_rcp_f32_e32 v115, v115
	v_rcp_f32_e32 v116, v116
	v_rcp_f32_e32 v117, v117
	v_rcp_f32_e32 v118, v118
	v_rcp_f32_e32 v119, v119
	v_rcp_f32_e32 v120, v120
	v_rcp_f32_e32 v121, v121
	v_cvt_pk_bf16_f32 v114, v114, v115
	v_cvt_pk_bf16_f32 v115, v116, v117
	v_cvt_pk_bf16_f32 v116, v118, v119
	v_cvt_pk_bf16_f32 v117, v120, v121
	global_store_dwordx4 v241, v[114:117], s[10:11] offset:2048 sc1
	v_mul_f32_e32 v122, s12, v122
	v_mul_f32_e32 v123, s12, v123
	v_mul_f32_e32 v124, s12, v124
	v_mul_f32_e32 v125, s12, v125
	v_mul_f32_e32 v126, s12, v126
	v_mul_f32_e32 v127, s12, v127
	v_mul_f32_e32 v128, s12, v128
	v_mul_f32_e32 v129, s12, v129
	v_exp_f32_e32 v122, v122
	v_exp_f32_e32 v123, v123
	v_exp_f32_e32 v124, v124
	v_exp_f32_e32 v125, v125
	v_exp_f32_e32 v126, v126
	v_exp_f32_e32 v127, v127
	v_exp_f32_e32 v128, v128
	v_exp_f32_e32 v129, v129
	v_add_f32_e32 v122, 1.0, v122
	v_add_f32_e32 v123, 1.0, v123
	v_add_f32_e32 v124, 1.0, v124
	v_add_f32_e32 v125, 1.0, v125
	v_add_f32_e32 v126, 1.0, v126
	v_add_f32_e32 v127, 1.0, v127
	v_add_f32_e32 v128, 1.0, v128
	v_add_f32_e32 v129, 1.0, v129
	v_rcp_f32_e32 v122, v122
	v_rcp_f32_e32 v123, v123
	v_rcp_f32_e32 v124, v124
	v_rcp_f32_e32 v125, v125
	v_rcp_f32_e32 v126, v126
	v_rcp_f32_e32 v127, v127
	v_rcp_f32_e32 v128, v128
	v_rcp_f32_e32 v129, v129
	v_cvt_pk_bf16_f32 v122, v122, v123
	v_cvt_pk_bf16_f32 v123, v124, v125
	v_cvt_pk_bf16_f32 v124, v126, v127
	v_cvt_pk_bf16_f32 v125, v128, v129
	global_store_dwordx4 v241, v[122:125], s[10:11] offset:3072 sc1
	s_waitcnt vmcnt(0)
	s_barrier
	s_and_b32 s0, s2, 7
	s_lshl_b32 s0, s0, 2
	s_lshr_b32 s1, s2, 3
	s_and_b32 s1, s1, 3
	s_add_u32 s0, s0, s1
	s_lshl_b32 s1, s80, 5
	s_add_u32 s0, s0, s1
	s_add_u32 s0, s0, 64
	s_lshl_b32 s0, s0, 2
	v_readlane_b32 s22, v253, 2
	v_readlane_b32 s23, v253, 3
	s_nop 0
	s_add_u32 s22, s22, s0
	s_addc_u32 s23, s23, 0
	v_cmp_eq_u32_e32 vcc, 0, v0
	s_and_saveexec_b64 s[24:25], vcc
	v_mov_b32_e32 v1, 1
	global_atomic_add v131, v1, s[22:23]
	s_or_b64 exec, exec, s[24:25]
	v_mov_b32_e32 v236, s20
	v_mov_b32_e32 v237, s21
	v_mov_b32_e32 v238, 0x200f0
	ds_write_b64 v238, v[236:237]
	s_setprio 0
	s_waitcnt vmcnt(0)
	v_readlane_b32 s60, v254, 32
	v_readlane_b32 s58, v254, 46
	s_mov_b32 s64, s44
	s_mov_b32 s72, s67
	s_cmpk_gt_u32 s50, 0xff
	v_readlane_b32 s61, v254, 33
	v_readlane_b32 s59, v254, 47
	s_movk_i32 s73, 0xf0
	v_readlane_b32 s79, v254, 50

.LBB0_880:
	s_andn2_b64 vcc, exec, s[0:1]
	s_cbranch_vccnz .LBB0_891
	s_lshl_b32 s96, s80, 20
	s_mov_b64 s[4:5], s[96:97]
	s_mov_b32 s13, s2
	v_mov_b32_e32 v205, 0x200f0
	ds_read_b64 v[250:251], v205
	v_and_b32_e32 v198, 63, v0
	v_lshrrev_b32_e32 v199, 6, v0
	v_lshrrev_b32_e32 v200, 3, v198
	v_lshrrev_b32_e32 v201, 4, v198
	s_nop 0
	v_readfirstlane_b32 s0, v199
	v_add_u32_e32 v132, 0, v201
	v_xor_b32_e32 v132, v132, v198
	v_and_b32_e32 v132, 7, v132
	v_lshlrev_b32_e32 v132, 4, v132
	v_lshl_add_u32 v130, v199, 5, v200
	v_add_u32_e32 v130, 0, v130
	v_mul_u32_u24_e32 v130, 0x800, v130
	v_add_u32_e32 v132, v132, v130
	v_add_u32_e32 v133, 4, v201
	v_xor_b32_e32 v133, v133, v198
	v_and_b32_e32 v133, 7, v133
	v_lshlrev_b32_e32 v133, 4, v133
	v_lshl_add_u32 v130, v199, 5, v200
	v_add_u32_e32 v130, 8, v130
	v_mul_u32_u24_e32 v130, 0x800, v130
	v_add_u32_e32 v133, v133, v130
	v_add_u32_e32 v134, 8, v201
	v_xor_b32_e32 v134, v134, v198
	v_and_b32_e32 v134, 7, v134
	v_lshlrev_b32_e32 v134, 4, v134
	v_lshl_add_u32 v130, v199, 5, v200
	v_add_u32_e32 v130, 16, v130
	v_mul_u32_u24_e32 v130, 0x800, v130
	v_add_u32_e32 v134, v134, v130
	v_add_u32_e32 v135, 12, v201
	v_xor_b32_e32 v135, v135, v198
	v_and_b32_e32 v135, 7, v135
	v_lshlrev_b32_e32 v135, 4, v135
	v_lshl_add_u32 v130, v199, 5, v200
	v_add_u32_e32 v130, 24, v130
	v_mul_u32_u24_e32 v130, 0x800, v130
	v_add_u32_e32 v135, v135, v130
	v_add_u32_e32 v136, 0, v201
	v_xor_b32_e32 v136, v136, v198
	v_and_b32_e32 v136, 7, v136
	v_lshlrev_b32_e32 v136, 4, v136
	v_lshl_add_u32 v130, v199, 4, v200
	v_add_u32_e32 v130, 0, v130
	v_mul_u32_u24_e32 v130, 0x200, v130
	v_add_u32_e32 v136, v136, v130
	v_add_u32_e32 v137, 4, v201
	v_xor_b32_e32 v137, v137, v198
	v_and_b32_e32 v137, 7, v137
	v_lshlrev_b32_e32 v137, 4, v137
	v_lshl_add_u32 v130, v199, 4, v200
	v_add_u32_e32 v130, 8, v130
	v_mul_u32_u24_e32 v130, 0x200, v130
	v_add_u32_e32 v137, v137, v130
	v_and_b32_e32 v200, 15, v198
	v_lshrrev_b32_e32 v130, 1, v200
	v_xor_b32_e32 v130, v130, v201
	v_lshlrev_b32_e32 v130, 4, v130
	v_lshrrev_b32_e32 v198, 1, v199
	v_lshl_add_u32 v198, v198, 6, v200
	v_lshl_add_u32 v198, v198, 7, v130
	v_and_b32_e32 v199, 1, v199
	v_lshl_add_u32 v199, v199, 6, v200
	v_lshl_add_u32 v199, v199, 7, v130
	v_add_u32_e32 v138, 0x100, v198
	v_xor_b32_e32 v141, 64, v138
	v_add_u32_e32 v144, 0x8100, v199
	v_xor_b32_e32 v147, 64, v144
	v_add_u32_e32 v139, 0xc100, v198
	v_xor_b32_e32 v142, 64, v139
	v_add_u32_e32 v145, 0x14100, v199
	v_xor_b32_e32 v196, 64, v145
	v_add_u32_e32 v140, 0x18100, v198
	v_xor_b32_e32 v143, 64, v140
	v_add_u32_e32 v146, 0x20100, v199
	v_xor_b32_e32 v197, 64, v146
	s_lshl_b32 s1, s0, 12
	s_add_u32 s10, s1, 0x100
	s_lshl_b32 s1, s0, 11
	s_add_u32 s11, s1, 0x8100
	v_mov_b32_e32 v2, 0
	v_mov_b32_e32 v3, 0
	v_mov_b32_e32 v4, 0
	v_mov_b32_e32 v5, 0
	v_mov_b32_e32 v6, 0
	v_mov_b32_e32 v7, 0
	v_mov_b32_e32 v8, 0
	v_mov_b32_e32 v9, 0
	v_mov_b32_e32 v10, 0
	v_mov_b32_e32 v11, 0
	v_mov_b32_e32 v12, 0
	v_mov_b32_e32 v13, 0
	v_mov_b32_e32 v14, 0
	v_mov_b32_e32 v15, 0
	v_mov_b32_e32 v16, 0
	v_mov_b32_e32 v17, 0
	v_mov_b32_e32 v18, 0
	v_mov_b32_e32 v19, 0
	v_mov_b32_e32 v20, 0
	v_mov_b32_e32 v21, 0
	v_mov_b32_e32 v22, 0
	v_mov_b32_e32 v23, 0
	v_mov_b32_e32 v24, 0
	v_mov_b32_e32 v25, 0
	v_mov_b32_e32 v26, 0
	v_mov_b32_e32 v27, 0
	v_mov_b32_e32 v28, 0
	v_mov_b32_e32 v29, 0
	v_mov_b32_e32 v30, 0
	v_mov_b32_e32 v31, 0
	v_mov_b32_e32 v32, 0
	v_mov_b32_e32 v33, 0
	v_mov_b32_e32 v34, 0
	v_mov_b32_e32 v35, 0
	v_mov_b32_e32 v36, 0
	v_mov_b32_e32 v37, 0
	v_mov_b32_e32 v38, 0
	v_mov_b32_e32 v39, 0
	v_mov_b32_e32 v40, 0
	v_mov_b32_e32 v41, 0
	v_mov_b32_e32 v42, 0
	v_mov_b32_e32 v43, 0
	v_mov_b32_e32 v44, 0
	v_mov_b32_e32 v45, 0
	v_mov_b32_e32 v46, 0
	v_mov_b32_e32 v47, 0
	v_mov_b32_e32 v48, 0
	v_mov_b32_e32 v49, 0
	v_mov_b32_e32 v50, 0
	v_mov_b32_e32 v51, 0
	v_mov_b32_e32 v52, 0
	v_mov_b32_e32 v53, 0
	v_mov_b32_e32 v54, 0
	v_mov_b32_e32 v55, 0
	v_mov_b32_e32 v56, 0
	v_mov_b32_e32 v57, 0
	v_mov_b32_e32 v58, 0
	v_mov_b32_e32 v59, 0
	v_mov_b32_e32 v60, 0
	v_mov_b32_e32 v61, 0
	v_mov_b32_e32 v62, 0
	v_mov_b32_e32 v63, 0
	v_mov_b32_e32 v64, 0
	v_mov_b32_e32 v65, 0
	s_cmp_lt_u32 s0, 4
	s_cbranch_scc1 .Lgprio_2
	s_setprio 1
.Lgprio_2:
	v_readfirstlane_b32 s0, v0
	s_cmp_lt_u32 s0, 64
	s_cbranch_scc0 .Lc2_go
	v_readlane_b32 s6, v253, 2
	v_readlane_b32 s7, v253, 3
	s_lshl_b32 s1, s80, 2
	s_add_u32 s1, s1, 24
	s_add_u32 s8, s6, s1
	s_addc_u32 s9, s7, 0
	s_and_b32 s0, s2, 31
	s_lshl_b32 s1, s80, 5
	s_add_u32 s0, s0, s1
	s_add_u32 s0, s0, 64
	s_lshl_b32 s0, s0, 2
	s_add_u32 s6, s6, s0
	s_addc_u32 s7, s7, 0
	s_mov_b32 s14, 0

.Lc2_exit:
	s_setprio 0

.LBB0_904:
	s_or_b64 exec, exec, s[0:1]
	s_ashr_i32 s20, s15, 5
	s_ashr_i32 s15, s14, 31
	v_mov_b32_e32 v43, v0
	s_barrier
	v_mov_b32_e32 v86, 0x200f0
	ds_read_b64 v[250:251], v86
	v_and_b32_e32 v86, 63, v0
	v_lshrrev_b32_e32 v87, 6, v0
	v_lshrrev_b32_e32 v88, 3, v86
	v_lshrrev_b32_e32 v89, 4, v86
	s_nop 0
	v_readfirstlane_b32 s0, v87
	v_add_u32_e32 v66, 0, v89
	v_xor_b32_e32 v66, v66, v86
	v_and_b32_e32 v66, 7, v66
	v_lshlrev_b32_e32 v66, 4, v66
	v_lshl_add_u32 v130, v87, 5, v88
	v_add_u32_e32 v130, 0, v130
	v_mul_u32_u24_e32 v130, 0x800, v130
	v_add_u32_e32 v66, v66, v130
	v_add_u32_e32 v67, 4, v89
	v_xor_b32_e32 v67, v67, v86
	v_and_b32_e32 v67, 7, v67
	v_lshlrev_b32_e32 v67, 4, v67
	v_lshl_add_u32 v130, v87, 5, v88
	v_add_u32_e32 v130, 8, v130
	v_mul_u32_u24_e32 v130, 0x800, v130
	v_add_u32_e32 v67, v67, v130
	v_add_u32_e32 v68, 8, v89
	v_xor_b32_e32 v68, v68, v86
	v_and_b32_e32 v68, 7, v68
	v_lshlrev_b32_e32 v68, 4, v68
	v_lshl_add_u32 v130, v87, 5, v88
	v_add_u32_e32 v130, 16, v130
	v_mul_u32_u24_e32 v130, 0x800, v130
	v_add_u32_e32 v68, v68, v130
	v_add_u32_e32 v69, 12, v89
	v_xor_b32_e32 v69, v69, v86
	v_and_b32_e32 v69, 7, v69
	v_lshlrev_b32_e32 v69, 4, v69
	v_lshl_add_u32 v130, v87, 5, v88
	v_add_u32_e32 v130, 24, v130
	v_mul_u32_u24_e32 v130, 0x800, v130
	v_add_u32_e32 v69, v69, v130
	v_add_u32_e32 v70, 0, v89
	v_xor_b32_e32 v70, v70, v86
	v_and_b32_e32 v70, 7, v70
	v_lshlrev_b32_e32 v70, 4, v70
	v_lshl_add_u32 v130, v87, 4, v88
	v_add_u32_e32 v130, 0, v130
	v_mul_u32_u24_e32 v130, 0x800, v130
	v_add_u32_e32 v70, v70, v130
	v_add_u32_e32 v71, 4, v89
	v_xor_b32_e32 v71, v71, v86
	v_and_b32_e32 v71, 7, v71
	v_lshlrev_b32_e32 v71, 4, v71
	v_lshl_add_u32 v130, v87, 4, v88
	v_add_u32_e32 v130, 8, v130
	v_mul_u32_u24_e32 v130, 0x800, v130
	v_add_u32_e32 v71, v71, v130
	v_and_b32_e32 v88, 15, v86
	v_lshrrev_b32_e32 v130, 1, v88
	v_xor_b32_e32 v130, v130, v89
	v_lshlrev_b32_e32 v130, 4, v130
	v_lshrrev_b32_e32 v86, 1, v87
	v_lshl_add_u32 v86, v86, 6, v88
	v_lshl_add_u32 v86, v86, 7, v130
	v_and_b32_e32 v87, 1, v87
	v_lshl_add_u32 v87, v87, 6, v88
	v_lshl_add_u32 v87, v87, 7, v130
	v_add_u32_e32 v72, 0x100, v86
	v_xor_b32_e32 v75, 64, v72
	v_add_u32_e32 v80, 0x8100, v87
	v_xor_b32_e32 v83, 64, v80
	v_add_u32_e32 v73, 0xc100, v86
	v_xor_b32_e32 v76, 64, v73
	v_add_u32_e32 v81, 0x14100, v87
	v_xor_b32_e32 v84, 64, v81
	v_add_u32_e32 v74, 0x18100, v86
	v_xor_b32_e32 v77, 64, v74
	v_add_u32_e32 v82, 0x20100, v87
	v_xor_b32_e32 v85, 64, v82
	s_lshl_b32 s1, s0, 12
	s_add_u32 s20, s1, 0x100
	s_add_u32 s21, s1, 0xc100
	s_add_u32 s22, s1, 0x18100
	s_lshl_b32 s1, s0, 11
	s_add_u32 s54, s1, 0x8100
	s_add_u32 s55, s1, 0x14100
	s_add_u32 s56, s1, 0x20100
	v_mov_b32_e32 v2, 0
	v_mov_b32_e32 v3, 0
	v_mov_b32_e32 v4, 0
	v_mov_b32_e32 v5, 0
	v_mov_b32_e32 v6, 0
	v_mov_b32_e32 v7, 0
	v_mov_b32_e32 v8, 0
	v_mov_b32_e32 v9, 0
	v_mov_b32_e32 v10, 0
	v_mov_b32_e32 v11, 0
	v_mov_b32_e32 v12, 0
	v_mov_b32_e32 v13, 0
	v_mov_b32_e32 v14, 0
	v_mov_b32_e32 v15, 0
	v_mov_b32_e32 v16, 0
	v_mov_b32_e32 v17, 0
	v_mov_b32_e32 v18, 0
	v_mov_b32_e32 v19, 0
	v_mov_b32_e32 v20, 0
	v_mov_b32_e32 v21, 0
	v_mov_b32_e32 v22, 0
	v_mov_b32_e32 v23, 0
	v_mov_b32_e32 v24, 0
	v_mov_b32_e32 v25, 0
	v_mov_b32_e32 v26, 0
	v_mov_b32_e32 v27, 0
	v_mov_b32_e32 v28, 0
	v_mov_b32_e32 v29, 0
	v_mov_b32_e32 v30, 0
	v_mov_b32_e32 v31, 0
	v_mov_b32_e32 v32, 0
	v_mov_b32_e32 v33, 0
	v_mov_b32_e32 v34, 0
	v_mov_b32_e32 v35, 0
	v_mov_b32_e32 v36, 0
	v_mov_b32_e32 v37, 0
	v_mov_b32_e32 v38, 0
	v_mov_b32_e32 v39, 0
	v_mov_b32_e32 v40, 0
	v_mov_b32_e32 v41, 0
	v_mov_b32_e32 v42, 0
	v_mov_b32_e32 v43, 0
	v_mov_b32_e32 v44, 0
	v_mov_b32_e32 v45, 0
	v_mov_b32_e32 v46, 0
	v_mov_b32_e32 v47, 0
	v_mov_b32_e32 v48, 0
	v_mov_b32_e32 v49, 0
	v_mov_b32_e32 v50, 0
	v_mov_b32_e32 v51, 0
	v_mov_b32_e32 v52, 0
	v_mov_b32_e32 v53, 0
	v_mov_b32_e32 v54, 0
	v_mov_b32_e32 v55, 0
	v_mov_b32_e32 v56, 0
	v_mov_b32_e32 v57, 0
	v_mov_b32_e32 v58, 0
	v_mov_b32_e32 v59, 0
	v_mov_b32_e32 v60, 0
	v_mov_b32_e32 v61, 0
	v_mov_b32_e32 v62, 0
	v_mov_b32_e32 v63, 0
	v_mov_b32_e32 v64, 0
	v_mov_b32_e32 v65, 0
	s_cmp_lt_u32 s0, 4
	s_cbranch_scc1 .Lgprio_3
	s_setprio 1
.Lgprio_3:
	s_and_b32 s1, s53, 31
	v_readlane_b32 s8, v253, 28
	v_readlane_b32 s9, v253, 29
	s_lshl_b32 s1, s1, 19
	s_nop 0
	s_add_u32 s8, s8, s1
	s_addc_u32 s9, s9, 0
	s_lshr_b32 s1, s53, 5
	v_readlane_b32 s14, v254, 6
	v_readlane_b32 s15, v254, 7
	s_lshl_b32 s1, s1, 18
	s_lshl_b32 s57, s50, 16
	s_add_u32 s1, s1, s57
	s_add_u32 s14, s14, s1
	s_addc_u32 s15, s15, 0
	s_waitcnt lgkmcnt(0)
	s_barrier
	s_mov_b32 m0, s20
	s_nop 0
	global_load_lds_dwordx4 v66, s[8:9]
	s_add_u32 m0, s20, 0x400
	s_nop 0
	global_load_lds_dwordx4 v67, s[8:9]
	s_add_u32 m0, s20, 0x800
	s_nop 0
	global_load_lds_dwordx4 v68, s[8:9]
	s_add_u32 m0, s20, 0xc00
	s_nop 0
	global_load_lds_dwordx4 v69, s[8:9]
	s_mov_b32 m0, s54
	s_nop 0
	global_load_lds_dwordx4 v70, s[14:15]
	s_add_u32 m0, s54, 0x400
	s_nop 0
	global_load_lds_dwordx4 v71, s[14:15]
	s_add_u32 s8, s8, 0x80
	s_addc_u32 s9, s9, 0
	s_add_u32 s14, s14, 0x80
	s_addc_u32 s15, s15, 0
	s_mov_b32 m0, s21
	s_nop 0
	global_load_lds_dwordx4 v66, s[8:9]
	s_add_u32 m0, s21, 0x400
	s_nop 0
	global_load_lds_dwordx4 v67, s[8:9]
	s_add_u32 m0, s21, 0x800
	s_nop 0
	global_load_lds_dwordx4 v68, s[8:9]
	s_add_u32 m0, s21, 0xc00
	s_nop 0
	global_load_lds_dwordx4 v69, s[8:9]
	s_mov_b32 m0, s55
	s_nop 0
	global_load_lds_dwordx4 v70, s[14:15]
	s_add_u32 m0, s55, 0x400
	s_nop 0
	global_load_lds_dwordx4 v71, s[14:15]
	s_add_u32 s8, s8, 0x80
	s_addc_u32 s9, s9, 0
	s_add_u32 s14, s14, 0x80
	s_addc_u32 s15, s15, 0
	s_waitcnt vmcnt(6)
	s_barrier
	ds_read_b128 v[148:151], v72 offset:0
	ds_read_b128 v[152:155], v72 offset:2048
	ds_read_b128 v[156:159], v72 offset:4096
	ds_read_b128 v[160:163], v72 offset:6144
	ds_read_b128 v[164:167], v80 offset:0
	ds_read_b128 v[168:171], v80 offset:2048
	ds_read_b128 v[172:175], v80 offset:4096
	ds_read_b128 v[176:179], v80 offset:6144
	ds_read_b128 v[180:183], v75 offset:0
	ds_read_b128 v[184:187], v75 offset:2048
	ds_read_b128 v[188:191], v75 offset:4096
	ds_read_b128 v[192:195], v75 offset:6144
	ds_read_b128 v[228:231], v83 offset:0
	ds_read_b128 v[232:235], v83 offset:2048
	ds_read_b128 v[236:239], v83 offset:4096
	ds_read_b128 v[240:243], v83 offset:6144
	s_waitcnt lgkmcnt(8)
	v_mfma_f32_16x16x32_bf16 v[2:5], v[164:167], v[148:151], v[2:5]
	s_mov_b32 m0, s22
	v_mfma_f32_16x16x32_bf16 v[6:9], v[168:171], v[148:151], v[6:9]
	global_load_lds_dwordx4 v66, s[8:9]
	v_mfma_f32_16x16x32_bf16 v[10:13], v[172:175], v[148:151], v[10:13]
	s_add_u32 m0, s22, 0x400
	v_mfma_f32_16x16x32_bf16 v[14:17], v[176:179], v[148:151], v[14:17]
	global_load_lds_dwordx4 v67, s[8:9]
	v_mfma_f32_16x16x32_bf16 v[18:21], v[164:167], v[152:155], v[18:21]
	s_add_u32 m0, s22, 0x800
	v_mfma_f32_16x16x32_bf16 v[22:25], v[168:171], v[152:155], v[22:25]
	global_load_lds_dwordx4 v68, s[8:9]
	v_mfma_f32_16x16x32_bf16 v[26:29], v[172:175], v[152:155], v[26:29]
	s_add_u32 m0, s22, 0xc00
	v_mfma_f32_16x16x32_bf16 v[30:33], v[176:179], v[152:155], v[30:33]
	global_load_lds_dwordx4 v69, s[8:9]
	v_mfma_f32_16x16x32_bf16 v[34:37], v[164:167], v[156:159], v[34:37]
	s_mov_b32 m0, s56
	v_mfma_f32_16x16x32_bf16 v[38:41], v[168:171], v[156:159], v[38:41]
	global_load_lds_dwordx4 v70, s[14:15]
	v_mfma_f32_16x16x32_bf16 v[42:45], v[172:175], v[156:159], v[42:45]
	s_add_u32 m0, s56, 0x400
	v_mfma_f32_16x16x32_bf16 v[46:49], v[176:179], v[156:159], v[46:49]
	global_load_lds_dwordx4 v71, s[14:15]
	v_mfma_f32_16x16x32_bf16 v[50:53], v[164:167], v[160:163], v[50:53]
	v_mfma_f32_16x16x32_bf16 v[54:57], v[168:171], v[160:163], v[54:57]
	v_mfma_f32_16x16x32_bf16 v[58:61], v[172:175], v[160:163], v[58:61]
	v_mfma_f32_16x16x32_bf16 v[62:65], v[176:179], v[160:163], v[62:65]
	s_waitcnt lgkmcnt(0)
	v_mfma_f32_16x16x32_bf16 v[2:5], v[228:231], v[180:183], v[2:5]
	v_mfma_f32_16x16x32_bf16 v[6:9], v[232:235], v[180:183], v[6:9]
	v_mfma_f32_16x16x32_bf16 v[10:13], v[236:239], v[180:183], v[10:13]
	v_mfma_f32_16x16x32_bf16 v[14:17], v[240:243], v[180:183], v[14:17]
	v_mfma_f32_16x16x32_bf16 v[18:21], v[228:231], v[184:187], v[18:21]
	v_mfma_f32_16x16x32_bf16 v[22:25], v[232:235], v[184:187], v[22:25]
	v_mfma_f32_16x16x32_bf16 v[26:29], v[236:239], v[184:187], v[26:29]
	v_mfma_f32_16x16x32_bf16 v[30:33], v[240:243], v[184:187], v[30:33]
	v_mfma_f32_16x16x32_bf16 v[34:37], v[228:231], v[188:191], v[34:37]
	v_mfma_f32_16x16x32_bf16 v[38:41], v[232:235], v[188:191], v[38:41]
	v_mfma_f32_16x16x32_bf16 v[42:45], v[236:239], v[188:191], v[42:45]
	v_mfma_f32_16x16x32_bf16 v[46:49], v[240:243], v[188:191], v[46:49]
	v_mfma_f32_16x16x32_bf16 v[50:53], v[228:231], v[192:195], v[50:53]
	v_mfma_f32_16x16x32_bf16 v[54:57], v[232:235], v[192:195], v[54:57]
	v_mfma_f32_16x16x32_bf16 v[58:61], v[236:239], v[192:195], v[58:61]
	v_mfma_f32_16x16x32_bf16 v[62:65], v[240:243], v[192:195], v[62:65]
	s_add_u32 s8, s8, 0x80
	s_addc_u32 s9, s9, 0
	s_add_u32 s14, s14, 0x80
	s_addc_u32 s15, s15, 0
	s_waitcnt vmcnt(6)
	s_barrier
	ds_read_b128 v[148:151], v73 offset:0
	ds_read_b128 v[152:155], v73 offset:2048
	ds_read_b128 v[156:159], v73 offset:4096
	ds_read_b128 v[160:163], v73 offset:6144
	ds_read_b128 v[164:167], v81 offset:0
	ds_read_b128 v[168:171], v81 offset:2048
	ds_read_b128 v[172:175], v81 offset:4096
	ds_read_b128 v[176:179], v81 offset:6144
	ds_read_b128 v[180:183], v76 offset:0
	ds_read_b128 v[184:187], v76 offset:2048
	ds_read_b128 v[188:191], v76 offset:4096
	ds_read_b128 v[192:195], v76 offset:6144
	ds_read_b128 v[228:231], v84 offset:0
	ds_read_b128 v[232:235], v84 offset:2048
	ds_read_b128 v[236:239], v84 offset:4096
	ds_read_b128 v[240:243], v84 offset:6144
	s_waitcnt lgkmcnt(8)
	v_mfma_f32_16x16x32_bf16 v[2:5], v[164:167], v[148:151], v[2:5]
	s_mov_b32 m0, s20
	v_mfma_f32_16x16x32_bf16 v[6:9], v[168:171], v[148:151], v[6:9]
	global_load_lds_dwordx4 v66, s[8:9]
	v_mfma_f32_16x16x32_bf16 v[10:13], v[172:175], v[148:151], v[10:13]
	s_add_u32 m0, s20, 0x400
	v_mfma_f32_16x16x32_bf16 v[14:17], v[176:179], v[148:151], v[14:17]
	global_load_lds_dwordx4 v67, s[8:9]
	v_mfma_f32_16x16x32_bf16 v[18:21], v[164:167], v[152:155], v[18:21]
	s_add_u32 m0, s20, 0x800
	v_mfma_f32_16x16x32_bf16 v[22:25], v[168:171], v[152:155], v[22:25]
	global_load_lds_dwordx4 v68, s[8:9]
	v_mfma_f32_16x16x32_bf16 v[26:29], v[172:175], v[152:155], v[26:29]
	s_add_u32 m0, s20, 0xc00
	v_mfma_f32_16x16x32_bf16 v[30:33], v[176:179], v[152:155], v[30:33]
	global_load_lds_dwordx4 v69, s[8:9]
	v_mfma_f32_16x16x32_bf16 v[34:37], v[164:167], v[156:159], v[34:37]
	s_mov_b32 m0, s54
	v_mfma_f32_16x16x32_bf16 v[38:41], v[168:171], v[156:159], v[38:41]
	global_load_lds_dwordx4 v70, s[14:15]
	v_mfma_f32_16x16x32_bf16 v[42:45], v[172:175], v[156:159], v[42:45]
	s_add_u32 m0, s54, 0x400
	v_mfma_f32_16x16x32_bf16 v[46:49], v[176:179], v[156:159], v[46:49]
	global_load_lds_dwordx4 v71, s[14:15]
	v_mfma_f32_16x16x32_bf16 v[50:53], v[164:167], v[160:163], v[50:53]
	v_mfma_f32_16x16x32_bf16 v[54:57], v[168:171], v[160:163], v[54:57]
	v_mfma_f32_16x16x32_bf16 v[58:61], v[172:175], v[160:163], v[58:61]
	v_mfma_f32_16x16x32_bf16 v[62:65], v[176:179], v[160:163], v[62:65]
	s_waitcnt lgkmcnt(0)
	v_mfma_f32_16x16x32_bf16 v[2:5], v[228:231], v[180:183], v[2:5]
	v_mfma_f32_16x16x32_bf16 v[6:9], v[232:235], v[180:183], v[6:9]
	v_mfma_f32_16x16x32_bf16 v[10:13], v[236:239], v[180:183], v[10:13]
	v_mfma_f32_16x16x32_bf16 v[14:17], v[240:243], v[180:183], v[14:17]
	v_mfma_f32_16x16x32_bf16 v[18:21], v[228:231], v[184:187], v[18:21]
	v_mfma_f32_16x16x32_bf16 v[22:25], v[232:235], v[184:187], v[22:25]
	v_mfma_f32_16x16x32_bf16 v[26:29], v[236:239], v[184:187], v[26:29]
	v_mfma_f32_16x16x32_bf16 v[30:33], v[240:243], v[184:187], v[30:33]
	v_mfma_f32_16x16x32_bf16 v[34:37], v[228:231], v[188:191], v[34:37]
	v_mfma_f32_16x16x32_bf16 v[38:41], v[232:235], v[188:191], v[38:41]
	v_mfma_f32_16x16x32_bf16 v[42:45], v[236:239], v[188:191], v[42:45]
	v_mfma_f32_16x16x32_bf16 v[46:49], v[240:243], v[188:191], v[46:49]
	v_mfma_f32_16x16x32_bf16 v[50:53], v[228:231], v[192:195], v[50:53]
	v_mfma_f32_16x16x32_bf16 v[54:57], v[232:235], v[192:195], v[54:57]
	v_mfma_f32_16x16x32_bf16 v[58:61], v[236:239], v[192:195], v[58:61]
	v_mfma_f32_16x16x32_bf16 v[62:65], v[240:243], v[192:195], v[62:65]
	s_add_u32 s8, s8, 0x80
	s_addc_u32 s9, s9, 0
	s_add_u32 s14, s14, 0x80
	s_addc_u32 s15, s15, 0
	s_waitcnt vmcnt(6)
	s_barrier
	ds_read_b128 v[148:151], v74 offset:0
	ds_read_b128 v[152:155], v74 offset:2048
	ds_read_b128 v[156:159], v74 offset:4096
	ds_read_b128 v[160:163], v74 offset:6144
	ds_read_b128 v[164:167], v82 offset:0
	ds_read_b128 v[168:171], v82 offset:2048
	ds_read_b128 v[172:175], v82 offset:4096
	ds_read_b128 v[176:179], v82 offset:6144
	ds_read_b128 v[180:183], v77 offset:0
	ds_read_b128 v[184:187], v77 offset:2048
	ds_read_b128 v[188:191], v77 offset:4096
	ds_read_b128 v[192:195], v77 offset:6144
	ds_read_b128 v[228:231], v85 offset:0
	ds_read_b128 v[232:235], v85 offset:2048
	ds_read_b128 v[236:239], v85 offset:4096
	ds_read_b128 v[240:243], v85 offset:6144
	s_waitcnt lgkmcnt(8)
	v_mfma_f32_16x16x32_bf16 v[2:5], v[164:167], v[148:151], v[2:5]
	s_mov_b32 m0, s21
	v_mfma_f32_16x16x32_bf16 v[6:9], v[168:171], v[148:151], v[6:9]
	global_load_lds_dwordx4 v66, s[8:9]
	v_mfma_f32_16x16x32_bf16 v[10:13], v[172:175], v[148:151], v[10:13]
	s_add_u32 m0, s21, 0x400
	v_mfma_f32_16x16x32_bf16 v[14:17], v[176:179], v[148:151], v[14:17]
	global_load_lds_dwordx4 v67, s[8:9]
	v_mfma_f32_16x16x32_bf16 v[18:21], v[164:167], v[152:155], v[18:21]
	s_add_u32 m0, s21, 0x800
	v_mfma_f32_16x16x32_bf16 v[22:25], v[168:171], v[152:155], v[22:25]
	global_load_lds_dwordx4 v68, s[8:9]
	v_mfma_f32_16x16x32_bf16 v[26:29], v[172:175], v[152:155], v[26:29]
	s_add_u32 m0, s21, 0xc00
	v_mfma_f32_16x16x32_bf16 v[30:33], v[176:179], v[152:155], v[30:33]
	global_load_lds_dwordx4 v69, s[8:9]
	v_mfma_f32_16x16x32_bf16 v[34:37], v[164:167], v[156:159], v[34:37]
	s_mov_b32 m0, s55
	v_mfma_f32_16x16x32_bf16 v[38:41], v[168:171], v[156:159], v[38:41]
	global_load_lds_dwordx4 v70, s[14:15]
	v_mfma_f32_16x16x32_bf16 v[42:45], v[172:175], v[156:159], v[42:45]
	s_add_u32 m0, s55, 0x400
	v_mfma_f32_16x16x32_bf16 v[46:49], v[176:179], v[156:159], v[46:49]
	global_load_lds_dwordx4 v71, s[14:15]
	v_mfma_f32_16x16x32_bf16 v[50:53], v[164:167], v[160:163], v[50:53]
	v_mfma_f32_16x16x32_bf16 v[54:57], v[168:171], v[160:163], v[54:57]
	v_mfma_f32_16x16x32_bf16 v[58:61], v[172:175], v[160:163], v[58:61]
	v_mfma_f32_16x16x32_bf16 v[62:65], v[176:179], v[160:163], v[62:65]
	s_waitcnt lgkmcnt(0)
	v_mfma_f32_16x16x32_bf16 v[2:5], v[228:231], v[180:183], v[2:5]
	v_mfma_f32_16x16x32_bf16 v[6:9], v[232:235], v[180:183], v[6:9]
	v_mfma_f32_16x16x32_bf16 v[10:13], v[236:239], v[180:183], v[10:13]
	v_mfma_f32_16x16x32_bf16 v[14:17], v[240:243], v[180:183], v[14:17]
	v_mfma_f32_16x16x32_bf16 v[18:21], v[228:231], v[184:187], v[18:21]
	v_mfma_f32_16x16x32_bf16 v[22:25], v[232:235], v[184:187], v[22:25]
	v_mfma_f32_16x16x32_bf16 v[26:29], v[236:239], v[184:187], v[26:29]
	v_mfma_f32_16x16x32_bf16 v[30:33], v[240:243], v[184:187], v[30:33]
	v_mfma_f32_16x16x32_bf16 v[34:37], v[228:231], v[188:191], v[34:37]
	v_mfma_f32_16x16x32_bf16 v[38:41], v[232:235], v[188:191], v[38:41]
	v_mfma_f32_16x16x32_bf16 v[42:45], v[236:239], v[188:191], v[42:45]
	v_mfma_f32_16x16x32_bf16 v[46:49], v[240:243], v[188:191], v[46:49]
	v_mfma_f32_16x16x32_bf16 v[50:53], v[228:231], v[192:195], v[50:53]
	v_mfma_f32_16x16x32_bf16 v[54:57], v[232:235], v[192:195], v[54:57]
	v_mfma_f32_16x16x32_bf16 v[58:61], v[236:239], v[192:195], v[58:61]
	v_mfma_f32_16x16x32_bf16 v[62:65], v[240:243], v[192:195], v[62:65]
	s_add_u32 s8, s8, 0x80
	s_addc_u32 s9, s9, 0
	s_add_u32 s14, s14, 0x80
	s_addc_u32 s15, s15, 0
	s_waitcnt vmcnt(6)
	s_barrier
	ds_read_b128 v[148:151], v72 offset:0
	ds_read_b128 v[152:155], v72 offset:2048
	ds_read_b128 v[156:159], v72 offset:4096
	ds_read_b128 v[160:163], v72 offset:6144
	ds_read_b128 v[164:167], v80 offset:0
	ds_read_b128 v[168:171], v80 offset:2048
	ds_read_b128 v[172:175], v80 offset:4096
	ds_read_b128 v[176:179], v80 offset:6144
	ds_read_b128 v[180:183], v75 offset:0
	ds_read_b128 v[184:187], v75 offset:2048
	ds_read_b128 v[188:191], v75 offset:4096
	ds_read_b128 v[192:195], v75 offset:6144
	ds_read_b128 v[228:231], v83 offset:0
	ds_read_b128 v[232:235], v83 offset:2048
	ds_read_b128 v[236:239], v83 offset:4096
	ds_read_b128 v[240:243], v83 offset:6144
	s_waitcnt lgkmcnt(8)
	v_mfma_f32_16x16x32_bf16 v[2:5], v[164:167], v[148:151], v[2:5]
	s_mov_b32 m0, s22
	v_mfma_f32_16x16x32_bf16 v[6:9], v[168:171], v[148:151], v[6:9]
	global_load_lds_dwordx4 v66, s[8:9]
	v_mfma_f32_16x16x32_bf16 v[10:13], v[172:175], v[148:151], v[10:13]
	s_add_u32 m0, s22, 0x400
	v_mfma_f32_16x16x32_bf16 v[14:17], v[176:179], v[148:151], v[14:17]
	global_load_lds_dwordx4 v67, s[8:9]
	v_mfma_f32_16x16x32_bf16 v[18:21], v[164:167], v[152:155], v[18:21]
	s_add_u32 m0, s22, 0x800
	v_mfma_f32_16x16x32_bf16 v[22:25], v[168:171], v[152:155], v[22:25]
	global_load_lds_dwordx4 v68, s[8:9]
	v_mfma_f32_16x16x32_bf16 v[26:29], v[172:175], v[152:155], v[26:29]
	s_add_u32 m0, s22, 0xc00
	v_mfma_f32_16x16x32_bf16 v[30:33], v[176:179], v[152:155], v[30:33]
	global_load_lds_dwordx4 v69, s[8:9]
	v_mfma_f32_16x16x32_bf16 v[34:37], v[164:167], v[156:159], v[34:37]
	s_mov_b32 m0, s56
	v_mfma_f32_16x16x32_bf16 v[38:41], v[168:171], v[156:159], v[38:41]
	global_load_lds_dwordx4 v70, s[14:15]
	v_mfma_f32_16x16x32_bf16 v[42:45], v[172:175], v[156:159], v[42:45]
	s_add_u32 m0, s56, 0x400
	v_mfma_f32_16x16x32_bf16 v[46:49], v[176:179], v[156:159], v[46:49]
	global_load_lds_dwordx4 v71, s[14:15]
	v_mfma_f32_16x16x32_bf16 v[50:53], v[164:167], v[160:163], v[50:53]
	v_mfma_f32_16x16x32_bf16 v[54:57], v[168:171], v[160:163], v[54:57]
	v_mfma_f32_16x16x32_bf16 v[58:61], v[172:175], v[160:163], v[58:61]
	v_mfma_f32_16x16x32_bf16 v[62:65], v[176:179], v[160:163], v[62:65]
	s_waitcnt lgkmcnt(0)
	v_mfma_f32_16x16x32_bf16 v[2:5], v[228:231], v[180:183], v[2:5]
	v_mfma_f32_16x16x32_bf16 v[6:9], v[232:235], v[180:183], v[6:9]
	v_mfma_f32_16x16x32_bf16 v[10:13], v[236:239], v[180:183], v[10:13]
	v_mfma_f32_16x16x32_bf16 v[14:17], v[240:243], v[180:183], v[14:17]
	v_mfma_f32_16x16x32_bf16 v[18:21], v[228:231], v[184:187], v[18:21]
	v_mfma_f32_16x16x32_bf16 v[22:25], v[232:235], v[184:187], v[22:25]
	v_mfma_f32_16x16x32_bf16 v[26:29], v[236:239], v[184:187], v[26:29]
	v_mfma_f32_16x16x32_bf16 v[30:33], v[240:243], v[184:187], v[30:33]
	v_mfma_f32_16x16x32_bf16 v[34:37], v[228:231], v[188:191], v[34:37]
	v_mfma_f32_16x16x32_bf16 v[38:41], v[232:235], v[188:191], v[38:41]
	v_mfma_f32_16x16x32_bf16 v[42:45], v[236:239], v[188:191], v[42:45]
	v_mfma_f32_16x16x32_bf16 v[46:49], v[240:243], v[188:191], v[46:49]
	v_mfma_f32_16x16x32_bf16 v[50:53], v[228:231], v[192:195], v[50:53]
	v_mfma_f32_16x16x32_bf16 v[54:57], v[232:235], v[192:195], v[54:57]
	v_mfma_f32_16x16x32_bf16 v[58:61], v[236:239], v[192:195], v[58:61]
	v_mfma_f32_16x16x32_bf16 v[62:65], v[240:243], v[192:195], v[62:65]
	s_add_u32 s8, s8, 0x80
	s_addc_u32 s9, s9, 0
	s_add_u32 s14, s14, 0x80
	s_addc_u32 s15, s15, 0
	s_waitcnt vmcnt(6)
	s_barrier
	ds_read_b128 v[148:151], v73 offset:0
	ds_read_b128 v[152:155], v73 offset:2048
	ds_read_b128 v[156:159], v73 offset:4096
	ds_read_b128 v[160:163], v73 offset:6144
	ds_read_b128 v[164:167], v81 offset:0
	ds_read_b128 v[168:171], v81 offset:2048
	ds_read_b128 v[172:175], v81 offset:4096
	ds_read_b128 v[176:179], v81 offset:6144
	ds_read_b128 v[180:183], v76 offset:0
	ds_read_b128 v[184:187], v76 offset:2048
	ds_read_b128 v[188:191], v76 offset:4096
	ds_read_b128 v[192:195], v76 offset:6144
	ds_read_b128 v[228:231], v84 offset:0
	ds_read_b128 v[232:235], v84 offset:2048
	ds_read_b128 v[236:239], v84 offset:4096
	ds_read_b128 v[240:243], v84 offset:6144
	s_waitcnt lgkmcnt(8)
	v_mfma_f32_16x16x32_bf16 v[2:5], v[164:167], v[148:151], v[2:5]
	s_mov_b32 m0, s20
	v_mfma_f32_16x16x32_bf16 v[6:9], v[168:171], v[148:151], v[6:9]
	global_load_lds_dwordx4 v66, s[8:9]
	v_mfma_f32_16x16x32_bf16 v[10:13], v[172:175], v[148:151], v[10:13]
	s_add_u32 m0, s20, 0x400
	v_mfma_f32_16x16x32_bf16 v[14:17], v[176:179], v[148:151], v[14:17]
	global_load_lds_dwordx4 v67, s[8:9]
	v_mfma_f32_16x16x32_bf16 v[18:21], v[164:167], v[152:155], v[18:21]
	s_add_u32 m0, s20, 0x800
	v_mfma_f32_16x16x32_bf16 v[22:25], v[168:171], v[152:155], v[22:25]
	global_load_lds_dwordx4 v68, s[8:9]
	v_mfma_f32_16x16x32_bf16 v[26:29], v[172:175], v[152:155], v[26:29]
	s_add_u32 m0, s20, 0xc00
	v_mfma_f32_16x16x32_bf16 v[30:33], v[176:179], v[152:155], v[30:33]
	global_load_lds_dwordx4 v69, s[8:9]
	v_mfma_f32_16x16x32_bf16 v[34:37], v[164:167], v[156:159], v[34:37]
	s_mov_b32 m0, s54
	v_mfma_f32_16x16x32_bf16 v[38:41], v[168:171], v[156:159], v[38:41]
	global_load_lds_dwordx4 v70, s[14:15]
	v_mfma_f32_16x16x32_bf16 v[42:45], v[172:175], v[156:159], v[42:45]
	s_add_u32 m0, s54, 0x400
	v_mfma_f32_16x16x32_bf16 v[46:49], v[176:179], v[156:159], v[46:49]
	global_load_lds_dwordx4 v71, s[14:15]
	v_mfma_f32_16x16x32_bf16 v[50:53], v[164:167], v[160:163], v[50:53]
	v_mfma_f32_16x16x32_bf16 v[54:57], v[168:171], v[160:163], v[54:57]
	v_mfma_f32_16x16x32_bf16 v[58:61], v[172:175], v[160:163], v[58:61]
	v_mfma_f32_16x16x32_bf16 v[62:65], v[176:179], v[160:163], v[62:65]
	s_waitcnt lgkmcnt(0)
	v_mfma_f32_16x16x32_bf16 v[2:5], v[228:231], v[180:183], v[2:5]
	v_mfma_f32_16x16x32_bf16 v[6:9], v[232:235], v[180:183], v[6:9]
	v_mfma_f32_16x16x32_bf16 v[10:13], v[236:239], v[180:183], v[10:13]
	v_mfma_f32_16x16x32_bf16 v[14:17], v[240:243], v[180:183], v[14:17]
	v_mfma_f32_16x16x32_bf16 v[18:21], v[228:231], v[184:187], v[18:21]
	v_mfma_f32_16x16x32_bf16 v[22:25], v[232:235], v[184:187], v[22:25]
	v_mfma_f32_16x16x32_bf16 v[26:29], v[236:239], v[184:187], v[26:29]
	v_mfma_f32_16x16x32_bf16 v[30:33], v[240:243], v[184:187], v[30:33]
	v_mfma_f32_16x16x32_bf16 v[34:37], v[228:231], v[188:191], v[34:37]
	v_mfma_f32_16x16x32_bf16 v[38:41], v[232:235], v[188:191], v[38:41]
	v_mfma_f32_16x16x32_bf16 v[42:45], v[236:239], v[188:191], v[42:45]
	v_mfma_f32_16x16x32_bf16 v[46:49], v[240:243], v[188:191], v[46:49]
	v_mfma_f32_16x16x32_bf16 v[50:53], v[228:231], v[192:195], v[50:53]
	v_mfma_f32_16x16x32_bf16 v[54:57], v[232:235], v[192:195], v[54:57]
	v_mfma_f32_16x16x32_bf16 v[58:61], v[236:239], v[192:195], v[58:61]
	v_mfma_f32_16x16x32_bf16 v[62:65], v[240:243], v[192:195], v[62:65]
	s_add_u32 s8, s8, 0x80
	s_addc_u32 s9, s9, 0
	s_add_u32 s14, s14, 0x80
	s_addc_u32 s15, s15, 0
	s_waitcnt vmcnt(6)
	s_barrier
	ds_read_b128 v[148:151], v74 offset:0
	ds_read_b128 v[152:155], v74 offset:2048
	ds_read_b128 v[156:159], v74 offset:4096
	ds_read_b128 v[160:163], v74 offset:6144
	ds_read_b128 v[164:167], v82 offset:0
	ds_read_b128 v[168:171], v82 offset:2048
	ds_read_b128 v[172:175], v82 offset:4096
	ds_read_b128 v[176:179], v82 offset:6144
	ds_read_b128 v[180:183], v77 offset:0
	ds_read_b128 v[184:187], v77 offset:2048
	ds_read_b128 v[188:191], v77 offset:4096
	ds_read_b128 v[192:195], v77 offset:6144
	ds_read_b128 v[228:231], v85 offset:0
	ds_read_b128 v[232:235], v85 offset:2048
	ds_read_b128 v[236:239], v85 offset:4096
	ds_read_b128 v[240:243], v85 offset:6144
	s_waitcnt lgkmcnt(8)
	v_mfma_f32_16x16x32_bf16 v[2:5], v[164:167], v[148:151], v[2:5]
	s_mov_b32 m0, s21
	v_mfma_f32_16x16x32_bf16 v[6:9], v[168:171], v[148:151], v[6:9]
	global_load_lds_dwordx4 v66, s[8:9]
	v_mfma_f32_16x16x32_bf16 v[10:13], v[172:175], v[148:151], v[10:13]
	s_add_u32 m0, s21, 0x400
	v_mfma_f32_16x16x32_bf16 v[14:17], v[176:179], v[148:151], v[14:17]
	global_load_lds_dwordx4 v67, s[8:9]
	v_mfma_f32_16x16x32_bf16 v[18:21], v[164:167], v[152:155], v[18:21]
	s_add_u32 m0, s21, 0x800
	v_mfma_f32_16x16x32_bf16 v[22:25], v[168:171], v[152:155], v[22:25]
	global_load_lds_dwordx4 v68, s[8:9]
	v_mfma_f32_16x16x32_bf16 v[26:29], v[172:175], v[152:155], v[26:29]
	s_add_u32 m0, s21, 0xc00
	v_mfma_f32_16x16x32_bf16 v[30:33], v[176:179], v[152:155], v[30:33]
	global_load_lds_dwordx4 v69, s[8:9]
	v_mfma_f32_16x16x32_bf16 v[34:37], v[164:167], v[156:159], v[34:37]
	s_mov_b32 m0, s55
	v_mfma_f32_16x16x32_bf16 v[38:41], v[168:171], v[156:159], v[38:41]
	global_load_lds_dwordx4 v70, s[14:15]
	v_mfma_f32_16x16x32_bf16 v[42:45], v[172:175], v[156:159], v[42:45]
	s_add_u32 m0, s55, 0x400
	v_mfma_f32_16x16x32_bf16 v[46:49], v[176:179], v[156:159], v[46:49]
	global_load_lds_dwordx4 v71, s[14:15]
	v_mfma_f32_16x16x32_bf16 v[50:53], v[164:167], v[160:163], v[50:53]
	v_mfma_f32_16x16x32_bf16 v[54:57], v[168:171], v[160:163], v[54:57]
	v_mfma_f32_16x16x32_bf16 v[58:61], v[172:175], v[160:163], v[58:61]
	v_mfma_f32_16x16x32_bf16 v[62:65], v[176:179], v[160:163], v[62:65]
	s_waitcnt lgkmcnt(0)
	v_mfma_f32_16x16x32_bf16 v[2:5], v[228:231], v[180:183], v[2:5]
	v_mfma_f32_16x16x32_bf16 v[6:9], v[232:235], v[180:183], v[6:9]
	v_mfma_f32_16x16x32_bf16 v[10:13], v[236:239], v[180:183], v[10:13]
	v_mfma_f32_16x16x32_bf16 v[14:17], v[240:243], v[180:183], v[14:17]
	v_mfma_f32_16x16x32_bf16 v[18:21], v[228:231], v[184:187], v[18:21]
	v_mfma_f32_16x16x32_bf16 v[22:25], v[232:235], v[184:187], v[22:25]
	v_mfma_f32_16x16x32_bf16 v[26:29], v[236:239], v[184:187], v[26:29]
	v_mfma_f32_16x16x32_bf16 v[30:33], v[240:243], v[184:187], v[30:33]
	v_mfma_f32_16x16x32_bf16 v[34:37], v[228:231], v[188:191], v[34:37]
	v_mfma_f32_16x16x32_bf16 v[38:41], v[232:235], v[188:191], v[38:41]
	v_mfma_f32_16x16x32_bf16 v[42:45], v[236:239], v[188:191], v[42:45]
	v_mfma_f32_16x16x32_bf16 v[46:49], v[240:243], v[188:191], v[46:49]
	v_mfma_f32_16x16x32_bf16 v[50:53], v[228:231], v[192:195], v[50:53]
	v_mfma_f32_16x16x32_bf16 v[54:57], v[232:235], v[192:195], v[54:57]
	v_mfma_f32_16x16x32_bf16 v[58:61], v[236:239], v[192:195], v[58:61]
	v_mfma_f32_16x16x32_bf16 v[62:65], v[240:243], v[192:195], v[62:65]
	s_add_u32 s8, s8, 0x80
	s_addc_u32 s9, s9, 0
	s_add_u32 s14, s14, 0x80
	s_addc_u32 s15, s15, 0
	s_waitcnt vmcnt(6)
	s_barrier
	ds_read_b128 v[148:151], v72 offset:0
	ds_read_b128 v[152:155], v72 offset:2048
	ds_read_b128 v[156:159], v72 offset:4096
	ds_read_b128 v[160:163], v72 offset:6144
	ds_read_b128 v[164:167], v80 offset:0
	ds_read_b128 v[168:171], v80 offset:2048
	ds_read_b128 v[172:175], v80 offset:4096
	ds_read_b128 v[176:179], v80 offset:6144
	ds_read_b128 v[180:183], v75 offset:0
	ds_read_b128 v[184:187], v75 offset:2048
	ds_read_b128 v[188:191], v75 offset:4096
	ds_read_b128 v[192:195], v75 offset:6144
	ds_read_b128 v[228:231], v83 offset:0
	ds_read_b128 v[232:235], v83 offset:2048
	ds_read_b128 v[236:239], v83 offset:4096
	ds_read_b128 v[240:243], v83 offset:6144
	s_waitcnt lgkmcnt(8)
	v_mfma_f32_16x16x32_bf16 v[2:5], v[164:167], v[148:151], v[2:5]
	s_mov_b32 m0, s22
	v_mfma_f32_16x16x32_bf16 v[6:9], v[168:171], v[148:151], v[6:9]
	global_load_lds_dwordx4 v66, s[8:9]
	v_mfma_f32_16x16x32_bf16 v[10:13], v[172:175], v[148:151], v[10:13]
	s_add_u32 m0, s22, 0x400
	v_mfma_f32_16x16x32_bf16 v[14:17], v[176:179], v[148:151], v[14:17]
	global_load_lds_dwordx4 v67, s[8:9]
	v_mfma_f32_16x16x32_bf16 v[18:21], v[164:167], v[152:155], v[18:21]
	s_add_u32 m0, s22, 0x800
	v_mfma_f32_16x16x32_bf16 v[22:25], v[168:171], v[152:155], v[22:25]
	global_load_lds_dwordx4 v68, s[8:9]
	v_mfma_f32_16x16x32_bf16 v[26:29], v[172:175], v[152:155], v[26:29]
	s_add_u32 m0, s22, 0xc00
	v_mfma_f32_16x16x32_bf16 v[30:33], v[176:179], v[152:155], v[30:33]
	global_load_lds_dwordx4 v69, s[8:9]
	v_mfma_f32_16x16x32_bf16 v[34:37], v[164:167], v[156:159], v[34:37]
	s_mov_b32 m0, s56
	v_mfma_f32_16x16x32_bf16 v[38:41], v[168:171], v[156:159], v[38:41]
	global_load_lds_dwordx4 v70, s[14:15]
	v_mfma_f32_16x16x32_bf16 v[42:45], v[172:175], v[156:159], v[42:45]
	s_add_u32 m0, s56, 0x400
	v_mfma_f32_16x16x32_bf16 v[46:49], v[176:179], v[156:159], v[46:49]
	global_load_lds_dwordx4 v71, s[14:15]
	v_mfma_f32_16x16x32_bf16 v[50:53], v[164:167], v[160:163], v[50:53]
	v_mfma_f32_16x16x32_bf16 v[54:57], v[168:171], v[160:163], v[54:57]
	v_mfma_f32_16x16x32_bf16 v[58:61], v[172:175], v[160:163], v[58:61]
	v_mfma_f32_16x16x32_bf16 v[62:65], v[176:179], v[160:163], v[62:65]
	s_waitcnt lgkmcnt(0)
	v_mfma_f32_16x16x32_bf16 v[2:5], v[228:231], v[180:183], v[2:5]
	v_mfma_f32_16x16x32_bf16 v[6:9], v[232:235], v[180:183], v[6:9]
	v_mfma_f32_16x16x32_bf16 v[10:13], v[236:239], v[180:183], v[10:13]
	v_mfma_f32_16x16x32_bf16 v[14:17], v[240:243], v[180:183], v[14:17]
	v_mfma_f32_16x16x32_bf16 v[18:21], v[228:231], v[184:187], v[18:21]
	v_mfma_f32_16x16x32_bf16 v[22:25], v[232:235], v[184:187], v[22:25]
	v_mfma_f32_16x16x32_bf16 v[26:29], v[236:239], v[184:187], v[26:29]
	v_mfma_f32_16x16x32_bf16 v[30:33], v[240:243], v[184:187], v[30:33]
	v_mfma_f32_16x16x32_bf16 v[34:37], v[228:231], v[188:191], v[34:37]
	v_mfma_f32_16x16x32_bf16 v[38:41], v[232:235], v[188:191], v[38:41]
	v_mfma_f32_16x16x32_bf16 v[42:45], v[236:239], v[188:191], v[42:45]
	v_mfma_f32_16x16x32_bf16 v[46:49], v[240:243], v[188:191], v[46:49]
	v_mfma_f32_16x16x32_bf16 v[50:53], v[228:231], v[192:195], v[50:53]
	v_mfma_f32_16x16x32_bf16 v[54:57], v[232:235], v[192:195], v[54:57]
	v_mfma_f32_16x16x32_bf16 v[58:61], v[236:239], v[192:195], v[58:61]
	v_mfma_f32_16x16x32_bf16 v[62:65], v[240:243], v[192:195], v[62:65]
	s_add_u32 s8, s8, 0x80
	s_addc_u32 s9, s9, 0
	s_add_u32 s14, s14, 0x80
	s_addc_u32 s15, s15, 0
	s_waitcnt vmcnt(6)
	s_barrier
	ds_read_b128 v[148:151], v73 offset:0
	ds_read_b128 v[152:155], v73 offset:2048
	ds_read_b128 v[156:159], v73 offset:4096
	ds_read_b128 v[160:163], v73 offset:6144
	ds_read_b128 v[164:167], v81 offset:0
	ds_read_b128 v[168:171], v81 offset:2048
	ds_read_b128 v[172:175], v81 offset:4096
	ds_read_b128 v[176:179], v81 offset:6144
	ds_read_b128 v[180:183], v76 offset:0
	ds_read_b128 v[184:187], v76 offset:2048
	ds_read_b128 v[188:191], v76 offset:4096
	ds_read_b128 v[192:195], v76 offset:6144
	ds_read_b128 v[228:231], v84 offset:0
	ds_read_b128 v[232:235], v84 offset:2048
	ds_read_b128 v[236:239], v84 offset:4096
	ds_read_b128 v[240:243], v84 offset:6144
	s_waitcnt lgkmcnt(8)
	v_mfma_f32_16x16x32_bf16 v[2:5], v[164:167], v[148:151], v[2:5]
	s_mov_b32 m0, s20
	v_mfma_f32_16x16x32_bf16 v[6:9], v[168:171], v[148:151], v[6:9]
	global_load_lds_dwordx4 v66, s[8:9]
	v_mfma_f32_16x16x32_bf16 v[10:13], v[172:175], v[148:151], v[10:13]
	s_add_u32 m0, s20, 0x400
	v_mfma_f32_16x16x32_bf16 v[14:17], v[176:179], v[148:151], v[14:17]
	global_load_lds_dwordx4 v67, s[8:9]
	v_mfma_f32_16x16x32_bf16 v[18:21], v[164:167], v[152:155], v[18:21]
	s_add_u32 m0, s20, 0x800
	v_mfma_f32_16x16x32_bf16 v[22:25], v[168:171], v[152:155], v[22:25]
	global_load_lds_dwordx4 v68, s[8:9]
	v_mfma_f32_16x16x32_bf16 v[26:29], v[172:175], v[152:155], v[26:29]
	s_add_u32 m0, s20, 0xc00
	v_mfma_f32_16x16x32_bf16 v[30:33], v[176:179], v[152:155], v[30:33]
	global_load_lds_dwordx4 v69, s[8:9]
	v_mfma_f32_16x16x32_bf16 v[34:37], v[164:167], v[156:159], v[34:37]
	s_mov_b32 m0, s54
	v_mfma_f32_16x16x32_bf16 v[38:41], v[168:171], v[156:159], v[38:41]
	global_load_lds_dwordx4 v70, s[14:15]
	v_mfma_f32_16x16x32_bf16 v[42:45], v[172:175], v[156:159], v[42:45]
	s_add_u32 m0, s54, 0x400
	v_mfma_f32_16x16x32_bf16 v[46:49], v[176:179], v[156:159], v[46:49]
	global_load_lds_dwordx4 v71, s[14:15]
	v_mfma_f32_16x16x32_bf16 v[50:53], v[164:167], v[160:163], v[50:53]
	v_mfma_f32_16x16x32_bf16 v[54:57], v[168:171], v[160:163], v[54:57]
	v_mfma_f32_16x16x32_bf16 v[58:61], v[172:175], v[160:163], v[58:61]
	v_mfma_f32_16x16x32_bf16 v[62:65], v[176:179], v[160:163], v[62:65]
	s_waitcnt lgkmcnt(0)
	v_mfma_f32_16x16x32_bf16 v[2:5], v[228:231], v[180:183], v[2:5]
	v_mfma_f32_16x16x32_bf16 v[6:9], v[232:235], v[180:183], v[6:9]
	v_mfma_f32_16x16x32_bf16 v[10:13], v[236:239], v[180:183], v[10:13]
	v_mfma_f32_16x16x32_bf16 v[14:17], v[240:243], v[180:183], v[14:17]
	v_mfma_f32_16x16x32_bf16 v[18:21], v[228:231], v[184:187], v[18:21]
	v_mfma_f32_16x16x32_bf16 v[22:25], v[232:235], v[184:187], v[22:25]
	v_mfma_f32_16x16x32_bf16 v[26:29], v[236:239], v[184:187], v[26:29]
	v_mfma_f32_16x16x32_bf16 v[30:33], v[240:243], v[184:187], v[30:33]
	v_mfma_f32_16x16x32_bf16 v[34:37], v[228:231], v[188:191], v[34:37]
	v_mfma_f32_16x16x32_bf16 v[38:41], v[232:235], v[188:191], v[38:41]
	v_mfma_f32_16x16x32_bf16 v[42:45], v[236:239], v[188:191], v[42:45]
	v_mfma_f32_16x16x32_bf16 v[46:49], v[240:243], v[188:191], v[46:49]
	v_mfma_f32_16x16x32_bf16 v[50:53], v[228:231], v[192:195], v[50:53]
	v_mfma_f32_16x16x32_bf16 v[54:57], v[232:235], v[192:195], v[54:57]
	v_mfma_f32_16x16x32_bf16 v[58:61], v[236:239], v[192:195], v[58:61]
	v_mfma_f32_16x16x32_bf16 v[62:65], v[240:243], v[192:195], v[62:65]
	s_add_u32 s8, s8, 0x80
	s_addc_u32 s9, s9, 0
	s_add_u32 s14, s14, 0x80
	s_addc_u32 s15, s15, 0
	s_waitcnt vmcnt(6)
	s_barrier
	ds_read_b128 v[148:151], v74 offset:0
	ds_read_b128 v[152:155], v74 offset:2048
	ds_read_b128 v[156:159], v74 offset:4096
	ds_read_b128 v[160:163], v74 offset:6144
	ds_read_b128 v[164:167], v82 offset:0
	ds_read_b128 v[168:171], v82 offset:2048
	ds_read_b128 v[172:175], v82 offset:4096
	ds_read_b128 v[176:179], v82 offset:6144
	ds_read_b128 v[180:183], v77 offset:0
	ds_read_b128 v[184:187], v77 offset:2048
	ds_read_b128 v[188:191], v77 offset:4096
	ds_read_b128 v[192:195], v77 offset:6144
	ds_read_b128 v[228:231], v85 offset:0
	ds_read_b128 v[232:235], v85 offset:2048
	ds_read_b128 v[236:239], v85 offset:4096
	ds_read_b128 v[240:243], v85 offset:6144
	s_waitcnt lgkmcnt(8)
	v_mfma_f32_16x16x32_bf16 v[2:5], v[164:167], v[148:151], v[2:5]
	s_mov_b32 m0, s21
	v_mfma_f32_16x16x32_bf16 v[6:9], v[168:171], v[148:151], v[6:9]
	global_load_lds_dwordx4 v66, s[8:9]
	v_mfma_f32_16x16x32_bf16 v[10:13], v[172:175], v[148:151], v[10:13]
	s_add_u32 m0, s21, 0x400
	v_mfma_f32_16x16x32_bf16 v[14:17], v[176:179], v[148:151], v[14:17]
	global_load_lds_dwordx4 v67, s[8:9]
	v_mfma_f32_16x16x32_bf16 v[18:21], v[164:167], v[152:155], v[18:21]
	s_add_u32 m0, s21, 0x800
	v_mfma_f32_16x16x32_bf16 v[22:25], v[168:171], v[152:155], v[22:25]
	global_load_lds_dwordx4 v68, s[8:9]
	v_mfma_f32_16x16x32_bf16 v[26:29], v[172:175], v[152:155], v[26:29]
	s_add_u32 m0, s21, 0xc00
	v_mfma_f32_16x16x32_bf16 v[30:33], v[176:179], v[152:155], v[30:33]
	global_load_lds_dwordx4 v69, s[8:9]
	v_mfma_f32_16x16x32_bf16 v[34:37], v[164:167], v[156:159], v[34:37]
	s_mov_b32 m0, s55
	v_mfma_f32_16x16x32_bf16 v[38:41], v[168:171], v[156:159], v[38:41]
	global_load_lds_dwordx4 v70, s[14:15]
	v_mfma_f32_16x16x32_bf16 v[42:45], v[172:175], v[156:159], v[42:45]
	s_add_u32 m0, s55, 0x400
	v_mfma_f32_16x16x32_bf16 v[46:49], v[176:179], v[156:159], v[46:49]
	global_load_lds_dwordx4 v71, s[14:15]
	v_mfma_f32_16x16x32_bf16 v[50:53], v[164:167], v[160:163], v[50:53]
	v_mfma_f32_16x16x32_bf16 v[54:57], v[168:171], v[160:163], v[54:57]
	v_mfma_f32_16x16x32_bf16 v[58:61], v[172:175], v[160:163], v[58:61]
	v_mfma_f32_16x16x32_bf16 v[62:65], v[176:179], v[160:163], v[62:65]
	s_waitcnt lgkmcnt(0)
	v_mfma_f32_16x16x32_bf16 v[2:5], v[228:231], v[180:183], v[2:5]
	v_mfma_f32_16x16x32_bf16 v[6:9], v[232:235], v[180:183], v[6:9]
	v_mfma_f32_16x16x32_bf16 v[10:13], v[236:239], v[180:183], v[10:13]
	v_mfma_f32_16x16x32_bf16 v[14:17], v[240:243], v[180:183], v[14:17]
	v_mfma_f32_16x16x32_bf16 v[18:21], v[228:231], v[184:187], v[18:21]
	v_mfma_f32_16x16x32_bf16 v[22:25], v[232:235], v[184:187], v[22:25]
	v_mfma_f32_16x16x32_bf16 v[26:29], v[236:239], v[184:187], v[26:29]
	v_mfma_f32_16x16x32_bf16 v[30:33], v[240:243], v[184:187], v[30:33]
	v_mfma_f32_16x16x32_bf16 v[34:37], v[228:231], v[188:191], v[34:37]
	v_mfma_f32_16x16x32_bf16 v[38:41], v[232:235], v[188:191], v[38:41]
	v_mfma_f32_16x16x32_bf16 v[42:45], v[236:239], v[188:191], v[42:45]
	v_mfma_f32_16x16x32_bf16 v[46:49], v[240:243], v[188:191], v[46:49]
	v_mfma_f32_16x16x32_bf16 v[50:53], v[228:231], v[192:195], v[50:53]
	v_mfma_f32_16x16x32_bf16 v[54:57], v[232:235], v[192:195], v[54:57]
	v_mfma_f32_16x16x32_bf16 v[58:61], v[236:239], v[192:195], v[58:61]
	v_mfma_f32_16x16x32_bf16 v[62:65], v[240:243], v[192:195], v[62:65]
	s_add_u32 s8, s8, 0x80
	s_addc_u32 s9, s9, 0
	s_add_u32 s14, s14, 0x80
	s_addc_u32 s15, s15, 0
	s_waitcnt vmcnt(6)
	s_barrier
	ds_read_b128 v[148:151], v72 offset:0
	ds_read_b128 v[152:155], v72 offset:2048
	ds_read_b128 v[156:159], v72 offset:4096
	ds_read_b128 v[160:163], v72 offset:6144
	ds_read_b128 v[164:167], v80 offset:0
	ds_read_b128 v[168:171], v80 offset:2048
	ds_read_b128 v[172:175], v80 offset:4096
	ds_read_b128 v[176:179], v80 offset:6144
	ds_read_b128 v[180:183], v75 offset:0
	ds_read_b128 v[184:187], v75 offset:2048
	ds_read_b128 v[188:191], v75 offset:4096
	ds_read_b128 v[192:195], v75 offset:6144
	ds_read_b128 v[228:231], v83 offset:0
	ds_read_b128 v[232:235], v83 offset:2048
	ds_read_b128 v[236:239], v83 offset:4096
	ds_read_b128 v[240:243], v83 offset:6144
	s_waitcnt lgkmcnt(8)
	v_mfma_f32_16x16x32_bf16 v[2:5], v[164:167], v[148:151], v[2:5]
	s_mov_b32 m0, s22
	v_mfma_f32_16x16x32_bf16 v[6:9], v[168:171], v[148:151], v[6:9]
	global_load_lds_dwordx4 v66, s[8:9]
	v_mfma_f32_16x16x32_bf16 v[10:13], v[172:175], v[148:151], v[10:13]
	s_add_u32 m0, s22, 0x400
	v_mfma_f32_16x16x32_bf16 v[14:17], v[176:179], v[148:151], v[14:17]
	global_load_lds_dwordx4 v67, s[8:9]
	v_mfma_f32_16x16x32_bf16 v[18:21], v[164:167], v[152:155], v[18:21]
	s_add_u32 m0, s22, 0x800
	v_mfma_f32_16x16x32_bf16 v[22:25], v[168:171], v[152:155], v[22:25]
	global_load_lds_dwordx4 v68, s[8:9]
	v_mfma_f32_16x16x32_bf16 v[26:29], v[172:175], v[152:155], v[26:29]
	s_add_u32 m0, s22, 0xc00
	v_mfma_f32_16x16x32_bf16 v[30:33], v[176:179], v[152:155], v[30:33]
	global_load_lds_dwordx4 v69, s[8:9]
	v_mfma_f32_16x16x32_bf16 v[34:37], v[164:167], v[156:159], v[34:37]
	s_mov_b32 m0, s56
	v_mfma_f32_16x16x32_bf16 v[38:41], v[168:171], v[156:159], v[38:41]
	global_load_lds_dwordx4 v70, s[14:15]
	v_mfma_f32_16x16x32_bf16 v[42:45], v[172:175], v[156:159], v[42:45]
	s_add_u32 m0, s56, 0x400
	v_mfma_f32_16x16x32_bf16 v[46:49], v[176:179], v[156:159], v[46:49]
	global_load_lds_dwordx4 v71, s[14:15]
	v_mfma_f32_16x16x32_bf16 v[50:53], v[164:167], v[160:163], v[50:53]
	v_mfma_f32_16x16x32_bf16 v[54:57], v[168:171], v[160:163], v[54:57]
	v_mfma_f32_16x16x32_bf16 v[58:61], v[172:175], v[160:163], v[58:61]
	v_mfma_f32_16x16x32_bf16 v[62:65], v[176:179], v[160:163], v[62:65]
	s_waitcnt lgkmcnt(0)
	v_mfma_f32_16x16x32_bf16 v[2:5], v[228:231], v[180:183], v[2:5]
	v_mfma_f32_16x16x32_bf16 v[6:9], v[232:235], v[180:183], v[6:9]
	v_mfma_f32_16x16x32_bf16 v[10:13], v[236:239], v[180:183], v[10:13]
	v_mfma_f32_16x16x32_bf16 v[14:17], v[240:243], v[180:183], v[14:17]
	v_mfma_f32_16x16x32_bf16 v[18:21], v[228:231], v[184:187], v[18:21]
	v_mfma_f32_16x16x32_bf16 v[22:25], v[232:235], v[184:187], v[22:25]
	v_mfma_f32_16x16x32_bf16 v[26:29], v[236:239], v[184:187], v[26:29]
	v_mfma_f32_16x16x32_bf16 v[30:33], v[240:243], v[184:187], v[30:33]
	v_mfma_f32_16x16x32_bf16 v[34:37], v[228:231], v[188:191], v[34:37]
	v_mfma_f32_16x16x32_bf16 v[38:41], v[232:235], v[188:191], v[38:41]
	v_mfma_f32_16x16x32_bf16 v[42:45], v[236:239], v[188:191], v[42:45]
	v_mfma_f32_16x16x32_bf16 v[46:49], v[240:243], v[188:191], v[46:49]
	v_mfma_f32_16x16x32_bf16 v[50:53], v[228:231], v[192:195], v[50:53]
	v_mfma_f32_16x16x32_bf16 v[54:57], v[232:235], v[192:195], v[54:57]
	v_mfma_f32_16x16x32_bf16 v[58:61], v[236:239], v[192:195], v[58:61]
	v_mfma_f32_16x16x32_bf16 v[62:65], v[240:243], v[192:195], v[62:65]
	s_add_u32 s8, s8, 0x80
	s_addc_u32 s9, s9, 0
	s_add_u32 s14, s14, 0x80
	s_addc_u32 s15, s15, 0
	s_waitcnt vmcnt(6)
	s_barrier
	ds_read_b128 v[148:151], v73 offset:0
	ds_read_b128 v[152:155], v73 offset:2048
	ds_read_b128 v[156:159], v73 offset:4096
	ds_read_b128 v[160:163], v73 offset:6144
	ds_read_b128 v[164:167], v81 offset:0
	ds_read_b128 v[168:171], v81 offset:2048
	ds_read_b128 v[172:175], v81 offset:4096
	ds_read_b128 v[176:179], v81 offset:6144
	ds_read_b128 v[180:183], v76 offset:0
	ds_read_b128 v[184:187], v76 offset:2048
	ds_read_b128 v[188:191], v76 offset:4096
	ds_read_b128 v[192:195], v76 offset:6144
	ds_read_b128 v[228:231], v84 offset:0
	ds_read_b128 v[232:235], v84 offset:2048
	ds_read_b128 v[236:239], v84 offset:4096
	ds_read_b128 v[240:243], v84 offset:6144
	s_waitcnt lgkmcnt(8)
	v_mfma_f32_16x16x32_bf16 v[2:5], v[164:167], v[148:151], v[2:5]
	s_mov_b32 m0, s20
	v_mfma_f32_16x16x32_bf16 v[6:9], v[168:171], v[148:151], v[6:9]
	global_load_lds_dwordx4 v66, s[8:9]
	v_mfma_f32_16x16x32_bf16 v[10:13], v[172:175], v[148:151], v[10:13]
	s_add_u32 m0, s20, 0x400
	v_mfma_f32_16x16x32_bf16 v[14:17], v[176:179], v[148:151], v[14:17]
	global_load_lds_dwordx4 v67, s[8:9]
	v_mfma_f32_16x16x32_bf16 v[18:21], v[164:167], v[152:155], v[18:21]
	s_add_u32 m0, s20, 0x800
	v_mfma_f32_16x16x32_bf16 v[22:25], v[168:171], v[152:155], v[22:25]
	global_load_lds_dwordx4 v68, s[8:9]
	v_mfma_f32_16x16x32_bf16 v[26:29], v[172:175], v[152:155], v[26:29]
	s_add_u32 m0, s20, 0xc00
	v_mfma_f32_16x16x32_bf16 v[30:33], v[176:179], v[152:155], v[30:33]
	global_load_lds_dwordx4 v69, s[8:9]
	v_mfma_f32_16x16x32_bf16 v[34:37], v[164:167], v[156:159], v[34:37]
	s_mov_b32 m0, s54
	v_mfma_f32_16x16x32_bf16 v[38:41], v[168:171], v[156:159], v[38:41]
	global_load_lds_dwordx4 v70, s[14:15]
	v_mfma_f32_16x16x32_bf16 v[42:45], v[172:175], v[156:159], v[42:45]
	s_add_u32 m0, s54, 0x400
	v_mfma_f32_16x16x32_bf16 v[46:49], v[176:179], v[156:159], v[46:49]
	global_load_lds_dwordx4 v71, s[14:15]
	v_mfma_f32_16x16x32_bf16 v[50:53], v[164:167], v[160:163], v[50:53]
	v_mfma_f32_16x16x32_bf16 v[54:57], v[168:171], v[160:163], v[54:57]
	v_mfma_f32_16x16x32_bf16 v[58:61], v[172:175], v[160:163], v[58:61]
	v_mfma_f32_16x16x32_bf16 v[62:65], v[176:179], v[160:163], v[62:65]
	s_waitcnt lgkmcnt(0)
	v_mfma_f32_16x16x32_bf16 v[2:5], v[228:231], v[180:183], v[2:5]
	v_mfma_f32_16x16x32_bf16 v[6:9], v[232:235], v[180:183], v[6:9]
	v_mfma_f32_16x16x32_bf16 v[10:13], v[236:239], v[180:183], v[10:13]
	v_mfma_f32_16x16x32_bf16 v[14:17], v[240:243], v[180:183], v[14:17]
	v_mfma_f32_16x16x32_bf16 v[18:21], v[228:231], v[184:187], v[18:21]
	v_mfma_f32_16x16x32_bf16 v[22:25], v[232:235], v[184:187], v[22:25]
	v_mfma_f32_16x16x32_bf16 v[26:29], v[236:239], v[184:187], v[26:29]
	v_mfma_f32_16x16x32_bf16 v[30:33], v[240:243], v[184:187], v[30:33]
	v_mfma_f32_16x16x32_bf16 v[34:37], v[228:231], v[188:191], v[34:37]
	v_mfma_f32_16x16x32_bf16 v[38:41], v[232:235], v[188:191], v[38:41]
	v_mfma_f32_16x16x32_bf16 v[42:45], v[236:239], v[188:191], v[42:45]
	v_mfma_f32_16x16x32_bf16 v[46:49], v[240:243], v[188:191], v[46:49]
	v_mfma_f32_16x16x32_bf16 v[50:53], v[228:231], v[192:195], v[50:53]
	v_mfma_f32_16x16x32_bf16 v[54:57], v[232:235], v[192:195], v[54:57]
	v_mfma_f32_16x16x32_bf16 v[58:61], v[236:239], v[192:195], v[58:61]
	v_mfma_f32_16x16x32_bf16 v[62:65], v[240:243], v[192:195], v[62:65]
	s_add_u32 s8, s8, 0x80
	s_addc_u32 s9, s9, 0
	s_add_u32 s14, s14, 0x80
	s_addc_u32 s15, s15, 0
	s_waitcnt vmcnt(6)
	s_barrier
	ds_read_b128 v[148:151], v74 offset:0
	ds_read_b128 v[152:155], v74 offset:2048
	ds_read_b128 v[156:159], v74 offset:4096
	ds_read_b128 v[160:163], v74 offset:6144
	ds_read_b128 v[164:167], v82 offset:0
	ds_read_b128 v[168:171], v82 offset:2048
	ds_read_b128 v[172:175], v82 offset:4096
	ds_read_b128 v[176:179], v82 offset:6144
	ds_read_b128 v[180:183], v77 offset:0
	ds_read_b128 v[184:187], v77 offset:2048
	ds_read_b128 v[188:191], v77 offset:4096
	ds_read_b128 v[192:195], v77 offset:6144
	ds_read_b128 v[228:231], v85 offset:0
	ds_read_b128 v[232:235], v85 offset:2048
	ds_read_b128 v[236:239], v85 offset:4096
	ds_read_b128 v[240:243], v85 offset:6144
	s_waitcnt lgkmcnt(8)
	v_mfma_f32_16x16x32_bf16 v[2:5], v[164:167], v[148:151], v[2:5]
	s_mov_b32 m0, s21
	v_mfma_f32_16x16x32_bf16 v[6:9], v[168:171], v[148:151], v[6:9]
	global_load_lds_dwordx4 v66, s[8:9]
	v_mfma_f32_16x16x32_bf16 v[10:13], v[172:175], v[148:151], v[10:13]
	s_add_u32 m0, s21, 0x400
	v_mfma_f32_16x16x32_bf16 v[14:17], v[176:179], v[148:151], v[14:17]
	global_load_lds_dwordx4 v67, s[8:9]
	v_mfma_f32_16x16x32_bf16 v[18:21], v[164:167], v[152:155], v[18:21]
	s_add_u32 m0, s21, 0x800
	v_mfma_f32_16x16x32_bf16 v[22:25], v[168:171], v[152:155], v[22:25]
	global_load_lds_dwordx4 v68, s[8:9]
	v_mfma_f32_16x16x32_bf16 v[26:29], v[172:175], v[152:155], v[26:29]
	s_add_u32 m0, s21, 0xc00
	v_mfma_f32_16x16x32_bf16 v[30:33], v[176:179], v[152:155], v[30:33]
	global_load_lds_dwordx4 v69, s[8:9]
	v_mfma_f32_16x16x32_bf16 v[34:37], v[164:167], v[156:159], v[34:37]
	s_mov_b32 m0, s55
	v_mfma_f32_16x16x32_bf16 v[38:41], v[168:171], v[156:159], v[38:41]
	global_load_lds_dwordx4 v70, s[14:15]
	v_mfma_f32_16x16x32_bf16 v[42:45], v[172:175], v[156:159], v[42:45]
	s_add_u32 m0, s55, 0x400
	v_mfma_f32_16x16x32_bf16 v[46:49], v[176:179], v[156:159], v[46:49]
	global_load_lds_dwordx4 v71, s[14:15]
	v_mfma_f32_16x16x32_bf16 v[50:53], v[164:167], v[160:163], v[50:53]
	v_mfma_f32_16x16x32_bf16 v[54:57], v[168:171], v[160:163], v[54:57]
	v_mfma_f32_16x16x32_bf16 v[58:61], v[172:175], v[160:163], v[58:61]
	v_mfma_f32_16x16x32_bf16 v[62:65], v[176:179], v[160:163], v[62:65]
	s_waitcnt lgkmcnt(0)
	v_mfma_f32_16x16x32_bf16 v[2:5], v[228:231], v[180:183], v[2:5]
	v_mfma_f32_16x16x32_bf16 v[6:9], v[232:235], v[180:183], v[6:9]
	v_mfma_f32_16x16x32_bf16 v[10:13], v[236:239], v[180:183], v[10:13]
	v_mfma_f32_16x16x32_bf16 v[14:17], v[240:243], v[180:183], v[14:17]
	v_mfma_f32_16x16x32_bf16 v[18:21], v[228:231], v[184:187], v[18:21]
	v_mfma_f32_16x16x32_bf16 v[22:25], v[232:235], v[184:187], v[22:25]
	v_mfma_f32_16x16x32_bf16 v[26:29], v[236:239], v[184:187], v[26:29]
	v_mfma_f32_16x16x32_bf16 v[30:33], v[240:243], v[184:187], v[30:33]
	v_mfma_f32_16x16x32_bf16 v[34:37], v[228:231], v[188:191], v[34:37]
	v_mfma_f32_16x16x32_bf16 v[38:41], v[232:235], v[188:191], v[38:41]
	v_mfma_f32_16x16x32_bf16 v[42:45], v[236:239], v[188:191], v[42:45]
	v_mfma_f32_16x16x32_bf16 v[46:49], v[240:243], v[188:191], v[46:49]
	v_mfma_f32_16x16x32_bf16 v[50:53], v[228:231], v[192:195], v[50:53]
	v_mfma_f32_16x16x32_bf16 v[54:57], v[232:235], v[192:195], v[54:57]
	v_mfma_f32_16x16x32_bf16 v[58:61], v[236:239], v[192:195], v[58:61]
	v_mfma_f32_16x16x32_bf16 v[62:65], v[240:243], v[192:195], v[62:65]
	s_add_u32 s8, s8, 0x80
	s_addc_u32 s9, s9, 0
	s_add_u32 s14, s14, 0x80
	s_addc_u32 s15, s15, 0
	s_waitcnt vmcnt(6)
	s_barrier
	ds_read_b128 v[148:151], v72 offset:0
	ds_read_b128 v[152:155], v72 offset:2048
	ds_read_b128 v[156:159], v72 offset:4096
	ds_read_b128 v[160:163], v72 offset:6144
	ds_read_b128 v[164:167], v80 offset:0
	ds_read_b128 v[168:171], v80 offset:2048
	ds_read_b128 v[172:175], v80 offset:4096
	ds_read_b128 v[176:179], v80 offset:6144
	ds_read_b128 v[180:183], v75 offset:0
	ds_read_b128 v[184:187], v75 offset:2048
	ds_read_b128 v[188:191], v75 offset:4096
	ds_read_b128 v[192:195], v75 offset:6144
	ds_read_b128 v[228:231], v83 offset:0
	ds_read_b128 v[232:235], v83 offset:2048
	ds_read_b128 v[236:239], v83 offset:4096
	ds_read_b128 v[240:243], v83 offset:6144
	s_waitcnt lgkmcnt(8)
	v_mfma_f32_16x16x32_bf16 v[2:5], v[164:167], v[148:151], v[2:5]
	s_mov_b32 m0, s22
	v_mfma_f32_16x16x32_bf16 v[6:9], v[168:171], v[148:151], v[6:9]
	global_load_lds_dwordx4 v66, s[8:9]
	v_mfma_f32_16x16x32_bf16 v[10:13], v[172:175], v[148:151], v[10:13]
	s_add_u32 m0, s22, 0x400
	v_mfma_f32_16x16x32_bf16 v[14:17], v[176:179], v[148:151], v[14:17]
	global_load_lds_dwordx4 v67, s[8:9]
	v_mfma_f32_16x16x32_bf16 v[18:21], v[164:167], v[152:155], v[18:21]
	s_add_u32 m0, s22, 0x800
	v_mfma_f32_16x16x32_bf16 v[22:25], v[168:171], v[152:155], v[22:25]
	global_load_lds_dwordx4 v68, s[8:9]
	v_mfma_f32_16x16x32_bf16 v[26:29], v[172:175], v[152:155], v[26:29]
	s_add_u32 m0, s22, 0xc00
	v_mfma_f32_16x16x32_bf16 v[30:33], v[176:179], v[152:155], v[30:33]
	global_load_lds_dwordx4 v69, s[8:9]
	v_mfma_f32_16x16x32_bf16 v[34:37], v[164:167], v[156:159], v[34:37]
	s_mov_b32 m0, s56
	v_mfma_f32_16x16x32_bf16 v[38:41], v[168:171], v[156:159], v[38:41]
	global_load_lds_dwordx4 v70, s[14:15]
	v_mfma_f32_16x16x32_bf16 v[42:45], v[172:175], v[156:159], v[42:45]
	s_add_u32 m0, s56, 0x400
	v_mfma_f32_16x16x32_bf16 v[46:49], v[176:179], v[156:159], v[46:49]
	global_load_lds_dwordx4 v71, s[14:15]
	v_mfma_f32_16x16x32_bf16 v[50:53], v[164:167], v[160:163], v[50:53]
	v_mfma_f32_16x16x32_bf16 v[54:57], v[168:171], v[160:163], v[54:57]
	v_mfma_f32_16x16x32_bf16 v[58:61], v[172:175], v[160:163], v[58:61]
	v_mfma_f32_16x16x32_bf16 v[62:65], v[176:179], v[160:163], v[62:65]
	s_waitcnt lgkmcnt(0)
	v_mfma_f32_16x16x32_bf16 v[2:5], v[228:231], v[180:183], v[2:5]
	v_mfma_f32_16x16x32_bf16 v[6:9], v[232:235], v[180:183], v[6:9]
	v_mfma_f32_16x16x32_bf16 v[10:13], v[236:239], v[180:183], v[10:13]
	v_mfma_f32_16x16x32_bf16 v[14:17], v[240:243], v[180:183], v[14:17]
	v_mfma_f32_16x16x32_bf16 v[18:21], v[228:231], v[184:187], v[18:21]
	v_mfma_f32_16x16x32_bf16 v[22:25], v[232:235], v[184:187], v[22:25]
	v_mfma_f32_16x16x32_bf16 v[26:29], v[236:239], v[184:187], v[26:29]
	v_mfma_f32_16x16x32_bf16 v[30:33], v[240:243], v[184:187], v[30:33]
	v_mfma_f32_16x16x32_bf16 v[34:37], v[228:231], v[188:191], v[34:37]
	v_mfma_f32_16x16x32_bf16 v[38:41], v[232:235], v[188:191], v[38:41]
	v_mfma_f32_16x16x32_bf16 v[42:45], v[236:239], v[188:191], v[42:45]
	v_mfma_f32_16x16x32_bf16 v[46:49], v[240:243], v[188:191], v[46:49]
	v_mfma_f32_16x16x32_bf16 v[50:53], v[228:231], v[192:195], v[50:53]
	v_mfma_f32_16x16x32_bf16 v[54:57], v[232:235], v[192:195], v[54:57]
	v_mfma_f32_16x16x32_bf16 v[58:61], v[236:239], v[192:195], v[58:61]
	v_mfma_f32_16x16x32_bf16 v[62:65], v[240:243], v[192:195], v[62:65]
	s_add_u32 s8, s8, 0x80
	s_addc_u32 s9, s9, 0
	s_add_u32 s14, s14, 0x80
	s_addc_u32 s15, s15, 0
	s_waitcnt vmcnt(6)
	s_barrier
	ds_read_b128 v[148:151], v73 offset:0
	ds_read_b128 v[152:155], v73 offset:2048
	ds_read_b128 v[156:159], v73 offset:4096
	ds_read_b128 v[160:163], v73 offset:6144
	ds_read_b128 v[164:167], v81 offset:0
	ds_read_b128 v[168:171], v81 offset:2048
	ds_read_b128 v[172:175], v81 offset:4096
	ds_read_b128 v[176:179], v81 offset:6144
	ds_read_b128 v[180:183], v76 offset:0
	ds_read_b128 v[184:187], v76 offset:2048
	ds_read_b128 v[188:191], v76 offset:4096
	ds_read_b128 v[192:195], v76 offset:6144
	ds_read_b128 v[228:231], v84 offset:0
	ds_read_b128 v[232:235], v84 offset:2048
	ds_read_b128 v[236:239], v84 offset:4096
	ds_read_b128 v[240:243], v84 offset:6144
	s_waitcnt lgkmcnt(8)
	v_mfma_f32_16x16x32_bf16 v[2:5], v[164:167], v[148:151], v[2:5]
	s_mov_b32 m0, s20
	v_mfma_f32_16x16x32_bf16 v[6:9], v[168:171], v[148:151], v[6:9]
	global_load_lds_dwordx4 v66, s[8:9]
	v_mfma_f32_16x16x32_bf16 v[10:13], v[172:175], v[148:151], v[10:13]
	s_add_u32 m0, s20, 0x400
	v_mfma_f32_16x16x32_bf16 v[14:17], v[176:179], v[148:151], v[14:17]
	global_load_lds_dwordx4 v67, s[8:9]
	v_mfma_f32_16x16x32_bf16 v[18:21], v[164:167], v[152:155], v[18:21]
	s_add_u32 m0, s20, 0x800
	v_mfma_f32_16x16x32_bf16 v[22:25], v[168:171], v[152:155], v[22:25]
	global_load_lds_dwordx4 v68, s[8:9]
	v_mfma_f32_16x16x32_bf16 v[26:29], v[172:175], v[152:155], v[26:29]
	s_add_u32 m0, s20, 0xc00
	v_mfma_f32_16x16x32_bf16 v[30:33], v[176:179], v[152:155], v[30:33]
	global_load_lds_dwordx4 v69, s[8:9]
	v_mfma_f32_16x16x32_bf16 v[34:37], v[164:167], v[156:159], v[34:37]
	s_mov_b32 m0, s54
	v_mfma_f32_16x16x32_bf16 v[38:41], v[168:171], v[156:159], v[38:41]
	global_load_lds_dwordx4 v70, s[14:15]
	v_mfma_f32_16x16x32_bf16 v[42:45], v[172:175], v[156:159], v[42:45]
	s_add_u32 m0, s54, 0x400
	v_mfma_f32_16x16x32_bf16 v[46:49], v[176:179], v[156:159], v[46:49]
	global_load_lds_dwordx4 v71, s[14:15]
	v_mfma_f32_16x16x32_bf16 v[50:53], v[164:167], v[160:163], v[50:53]
	v_mfma_f32_16x16x32_bf16 v[54:57], v[168:171], v[160:163], v[54:57]
	v_mfma_f32_16x16x32_bf16 v[58:61], v[172:175], v[160:163], v[58:61]
	v_mfma_f32_16x16x32_bf16 v[62:65], v[176:179], v[160:163], v[62:65]
	s_waitcnt lgkmcnt(0)
	v_mfma_f32_16x16x32_bf16 v[2:5], v[228:231], v[180:183], v[2:5]
	v_mfma_f32_16x16x32_bf16 v[6:9], v[232:235], v[180:183], v[6:9]
	v_mfma_f32_16x16x32_bf16 v[10:13], v[236:239], v[180:183], v[10:13]
	v_mfma_f32_16x16x32_bf16 v[14:17], v[240:243], v[180:183], v[14:17]
	v_mfma_f32_16x16x32_bf16 v[18:21], v[228:231], v[184:187], v[18:21]
	v_mfma_f32_16x16x32_bf16 v[22:25], v[232:235], v[184:187], v[22:25]
	v_mfma_f32_16x16x32_bf16 v[26:29], v[236:239], v[184:187], v[26:29]
	v_mfma_f32_16x16x32_bf16 v[30:33], v[240:243], v[184:187], v[30:33]
	v_mfma_f32_16x16x32_bf16 v[34:37], v[228:231], v[188:191], v[34:37]
	v_mfma_f32_16x16x32_bf16 v[38:41], v[232:235], v[188:191], v[38:41]
	v_mfma_f32_16x16x32_bf16 v[42:45], v[236:239], v[188:191], v[42:45]
	v_mfma_f32_16x16x32_bf16 v[46:49], v[240:243], v[188:191], v[46:49]
	v_mfma_f32_16x16x32_bf16 v[50:53], v[228:231], v[192:195], v[50:53]
	v_mfma_f32_16x16x32_bf16 v[54:57], v[232:235], v[192:195], v[54:57]
	v_mfma_f32_16x16x32_bf16 v[58:61], v[236:239], v[192:195], v[58:61]
	v_mfma_f32_16x16x32_bf16 v[62:65], v[240:243], v[192:195], v[62:65]
	s_add_u32 s8, s8, 0x80
	s_addc_u32 s9, s9, 0
	s_add_u32 s14, s14, 0x80
	s_addc_u32 s15, s15, 0
	s_waitcnt vmcnt(6)
	s_barrier
	ds_read_b128 v[148:151], v74 offset:0
	ds_read_b128 v[152:155], v74 offset:2048
	ds_read_b128 v[156:159], v74 offset:4096
	ds_read_b128 v[160:163], v74 offset:6144
	ds_read_b128 v[164:167], v82 offset:0
	ds_read_b128 v[168:171], v82 offset:2048
	ds_read_b128 v[172:175], v82 offset:4096
	ds_read_b128 v[176:179], v82 offset:6144
	ds_read_b128 v[180:183], v77 offset:0
	ds_read_b128 v[184:187], v77 offset:2048
	ds_read_b128 v[188:191], v77 offset:4096
	ds_read_b128 v[192:195], v77 offset:6144
	ds_read_b128 v[228:231], v85 offset:0
	ds_read_b128 v[232:235], v85 offset:2048
	ds_read_b128 v[236:239], v85 offset:4096
	ds_read_b128 v[240:243], v85 offset:6144
	s_waitcnt lgkmcnt(8)
	v_mfma_f32_16x16x32_bf16 v[2:5], v[164:167], v[148:151], v[2:5]
	v_mfma_f32_16x16x32_bf16 v[6:9], v[168:171], v[148:151], v[6:9]
	v_mfma_f32_16x16x32_bf16 v[10:13], v[172:175], v[148:151], v[10:13]
	v_mfma_f32_16x16x32_bf16 v[14:17], v[176:179], v[148:151], v[14:17]
	v_mfma_f32_16x16x32_bf16 v[18:21], v[164:167], v[152:155], v[18:21]
	v_mfma_f32_16x16x32_bf16 v[22:25], v[168:171], v[152:155], v[22:25]
	v_mfma_f32_16x16x32_bf16 v[26:29], v[172:175], v[152:155], v[26:29]
	v_mfma_f32_16x16x32_bf16 v[30:33], v[176:179], v[152:155], v[30:33]
	v_mfma_f32_16x16x32_bf16 v[34:37], v[164:167], v[156:159], v[34:37]
	v_mfma_f32_16x16x32_bf16 v[38:41], v[168:171], v[156:159], v[38:41]
	v_mfma_f32_16x16x32_bf16 v[42:45], v[172:175], v[156:159], v[42:45]
	v_mfma_f32_16x16x32_bf16 v[46:49], v[176:179], v[156:159], v[46:49]
	v_mfma_f32_16x16x32_bf16 v[50:53], v[164:167], v[160:163], v[50:53]
	v_mfma_f32_16x16x32_bf16 v[54:57], v[168:171], v[160:163], v[54:57]
	v_mfma_f32_16x16x32_bf16 v[58:61], v[172:175], v[160:163], v[58:61]
	v_mfma_f32_16x16x32_bf16 v[62:65], v[176:179], v[160:163], v[62:65]
	s_waitcnt lgkmcnt(0)
	v_mfma_f32_16x16x32_bf16 v[2:5], v[228:231], v[180:183], v[2:5]
	v_mfma_f32_16x16x32_bf16 v[6:9], v[232:235], v[180:183], v[6:9]
	v_mfma_f32_16x16x32_bf16 v[10:13], v[236:239], v[180:183], v[10:13]
	v_mfma_f32_16x16x32_bf16 v[14:17], v[240:243], v[180:183], v[14:17]
	v_mfma_f32_16x16x32_bf16 v[18:21], v[228:231], v[184:187], v[18:21]
	v_mfma_f32_16x16x32_bf16 v[22:25], v[232:235], v[184:187], v[22:25]
	v_mfma_f32_16x16x32_bf16 v[26:29], v[236:239], v[184:187], v[26:29]
	v_mfma_f32_16x16x32_bf16 v[30:33], v[240:243], v[184:187], v[30:33]
	v_mfma_f32_16x16x32_bf16 v[34:37], v[228:231], v[188:191], v[34:37]
	v_mfma_f32_16x16x32_bf16 v[38:41], v[232:235], v[188:191], v[38:41]
	v_mfma_f32_16x16x32_bf16 v[42:45], v[236:239], v[188:191], v[42:45]
	v_mfma_f32_16x16x32_bf16 v[46:49], v[240:243], v[188:191], v[46:49]
	v_mfma_f32_16x16x32_bf16 v[50:53], v[228:231], v[192:195], v[50:53]
	v_mfma_f32_16x16x32_bf16 v[54:57], v[232:235], v[192:195], v[54:57]
	v_mfma_f32_16x16x32_bf16 v[58:61], v[236:239], v[192:195], v[58:61]
	v_mfma_f32_16x16x32_bf16 v[62:65], v[240:243], v[192:195], v[62:65]
	s_waitcnt vmcnt(0)
	s_barrier
	ds_read_b128 v[148:151], v72 offset:0
	ds_read_b128 v[152:155], v72 offset:2048
	ds_read_b128 v[156:159], v72 offset:4096
	ds_read_b128 v[160:163], v72 offset:6144
	ds_read_b128 v[164:167], v80 offset:0
	ds_read_b128 v[168:171], v80 offset:2048
	ds_read_b128 v[172:175], v80 offset:4096
	ds_read_b128 v[176:179], v80 offset:6144
	ds_read_b128 v[180:183], v75 offset:0
	ds_read_b128 v[184:187], v75 offset:2048
	ds_read_b128 v[188:191], v75 offset:4096
	ds_read_b128 v[192:195], v75 offset:6144
	ds_read_b128 v[228:231], v83 offset:0
	ds_read_b128 v[232:235], v83 offset:2048
	ds_read_b128 v[236:239], v83 offset:4096
	ds_read_b128 v[240:243], v83 offset:6144
	s_waitcnt lgkmcnt(8)
	v_mfma_f32_16x16x32_bf16 v[2:5], v[164:167], v[148:151], v[2:5]
	v_mfma_f32_16x16x32_bf16 v[6:9], v[168:171], v[148:151], v[6:9]
	v_mfma_f32_16x16x32_bf16 v[10:13], v[172:175], v[148:151], v[10:13]
	v_mfma_f32_16x16x32_bf16 v[14:17], v[176:179], v[148:151], v[14:17]
	v_mfma_f32_16x16x32_bf16 v[18:21], v[164:167], v[152:155], v[18:21]
	v_mfma_f32_16x16x32_bf16 v[22:25], v[168:171], v[152:155], v[22:25]
	v_mfma_f32_16x16x32_bf16 v[26:29], v[172:175], v[152:155], v[26:29]
	v_mfma_f32_16x16x32_bf16 v[30:33], v[176:179], v[152:155], v[30:33]
	v_mfma_f32_16x16x32_bf16 v[34:37], v[164:167], v[156:159], v[34:37]
	v_mfma_f32_16x16x32_bf16 v[38:41], v[168:171], v[156:159], v[38:41]
	v_mfma_f32_16x16x32_bf16 v[42:45], v[172:175], v[156:159], v[42:45]
	v_mfma_f32_16x16x32_bf16 v[46:49], v[176:179], v[156:159], v[46:49]
	v_mfma_f32_16x16x32_bf16 v[50:53], v[164:167], v[160:163], v[50:53]
	v_mfma_f32_16x16x32_bf16 v[54:57], v[168:171], v[160:163], v[54:57]
	v_mfma_f32_16x16x32_bf16 v[58:61], v[172:175], v[160:163], v[58:61]
	v_mfma_f32_16x16x32_bf16 v[62:65], v[176:179], v[160:163], v[62:65]
	s_waitcnt lgkmcnt(0)
	v_mfma_f32_16x16x32_bf16 v[2:5], v[228:231], v[180:183], v[2:5]
	v_mfma_f32_16x16x32_bf16 v[6:9], v[232:235], v[180:183], v[6:9]
	v_mfma_f32_16x16x32_bf16 v[10:13], v[236:239], v[180:183], v[10:13]
	v_mfma_f32_16x16x32_bf16 v[14:17], v[240:243], v[180:183], v[14:17]
	v_mfma_f32_16x16x32_bf16 v[18:21], v[228:231], v[184:187], v[18:21]
	v_mfma_f32_16x16x32_bf16 v[22:25], v[232:235], v[184:187], v[22:25]
	v_mfma_f32_16x16x32_bf16 v[26:29], v[236:239], v[184:187], v[26:29]
	v_mfma_f32_16x16x32_bf16 v[30:33], v[240:243], v[184:187], v[30:33]
	v_mfma_f32_16x16x32_bf16 v[34:37], v[228:231], v[188:191], v[34:37]
	v_mfma_f32_16x16x32_bf16 v[38:41], v[232:235], v[188:191], v[38:41]
	v_mfma_f32_16x16x32_bf16 v[42:45], v[236:239], v[188:191], v[42:45]
	v_mfma_f32_16x16x32_bf16 v[46:49], v[240:243], v[188:191], v[46:49]
	v_mfma_f32_16x16x32_bf16 v[50:53], v[228:231], v[192:195], v[50:53]
	v_mfma_f32_16x16x32_bf16 v[54:57], v[232:235], v[192:195], v[54:57]
	v_mfma_f32_16x16x32_bf16 v[58:61], v[236:239], v[192:195], v[58:61]
	v_mfma_f32_16x16x32_bf16 v[62:65], v[240:243], v[192:195], v[62:65]
	s_barrier
	v_mov_b32_e32 v86, 0x200f0
	ds_write_b64 v86, v[250:251]
	s_setprio 0
	s_waitcnt lgkmcnt(0)
	s_nop 7
	s_nop 7
	s_and_b32 s14, s53, 31
	s_lshr_b32 s20, s53, 5
	s_sub_u32 s0, s14, 16
	s_lshr_b32 s0, s0, 2
	s_add_u32 s0, s0, 1
	s_cmp_lt_u32 s14, 16
	s_cselect_b32 s15, 0, s0
	ds_read_b128 v[74:77], v131
	s_add_u32 s0, s52, s15
	s_mul_i32 s0, s0, 0x3000
	s_add_u32 s0, s0, 0x2000
	s_add_u32 s22, s80, s0
	s_addc_u32 s23, s81, 0
	v_and_b32_e32 v66, 63, v0
	v_lshrrev_b32_e32 v67, 6, v0
	v_and_b32_e32 v68, 15, v66
	v_lshrrev_b32_e32 v69, 4, v66
	v_lshrrev_b32_e32 v70, 1, v67
	v_and_b32_e32 v71, 1, v67
	v_lshl_add_u32 v72, v70, 6, v68
	v_lshlrev_b32_e32 v73, 8, v71
	v_lshl_add_u32 v73, v69, 4, v73
	s_lshl_b32 s0, s20, 9
	v_add_u32_e32 v73, s0, v73
	s_waitcnt lgkmcnt(0)
	v_readfirstlane_b32 s8, v74
	v_readfirstlane_b32 s9, v75
	v_readfirstlane_b32 s54, v76
	v_readfirstlane_b32 s55, v77
	s_lshl_b32 s0, s14, 20
	s_cmp_eq_u32 s52, 0
	s_cbranch_scc1 .Ld_epi_l0
	s_mov_b32 s8, s16
	s_mov_b32 s9, s17
	s_branch .Ld_epi_xb
